# out-GEMM epilogue: first half's x-row and gate loads issued before the accumulator dump and barrier; consumer-driven vmcnt waits (variant of v45)
# speedup vs baseline: 1.1003x; 1.0015x over previous
.LBB0_656:
	s_lshr_b32 s6, s10, 3
	s_add_i32 s6, s6, s11
	s_lshl_b32 s8, s6, 19
	v_lshl_add_u64 v[0:1], v[10:11], 0, s[8:9]
	v_add_co_u32_e32 v4, vcc, 0x10000, v0
	s_and_b32 s20, s10, 7
	s_nop 0
	v_addc_co_u32_e32 v5, vcc, 0, v1, vcc
	v_add_co_u32_e32 v6, vcc, 0x20000, v0
	s_lshl_b32 s8, s20, 18
	s_nop 0
	v_addc_co_u32_e32 v7, vcc, 0, v1, vcc
	v_add_co_u32_e32 v18, vcc, 0x30000, v0
	v_lshl_add_u64 v[2:3], v[12:13], 0, s[8:9]
	s_nop 0
	v_addc_co_u32_e32 v19, vcc, 0, v1, vcc
	v_add_co_u32_e32 v20, vcc, 0x40000, v0
	global_load_dwordx4 v[100:103], v[0:1], off
	global_load_dwordx4 v[104:107], v[0:1], off offset:128
	v_addc_co_u32_e32 v21, vcc, 0, v1, vcc
	v_add_co_u32_e32 v22, vcc, 0x50000, v0
	global_load_dwordx4 v[108:111], v[2:3], off
	global_load_dwordx4 v[112:115], v[2:3], off offset:128
	v_addc_co_u32_e32 v23, vcc, 0, v1, vcc
	v_add_co_u32_e32 v24, vcc, 0x60000, v0
	global_load_dwordx4 v[116:119], v[4:5], off
	global_load_dwordx4 v[120:123], v[4:5], off offset:128
	v_addc_co_u32_e32 v25, vcc, 0, v1, vcc
	v_add_co_u32_e32 v26, vcc, 0x70000, v0
	global_load_dwordx4 v[124:127], v[6:7], off
	global_load_dwordx4 v[128:131], v[6:7], off offset:128
	v_addc_co_u32_e32 v27, vcc, 0, v1, vcc
	v_add_co_u32_e32 v28, vcc, s16, v2
	global_load_dwordx4 v[136:139], v[18:19], off
	global_load_dwordx4 v[140:143], v[18:19], off offset:128
	v_addc_co_u32_e32 v29, vcc, 0, v3, vcc
	s_waitcnt vmcnt(14)
	v_add_co_u32_e32 v30, vcc, s17, v2
	global_load_dwordx4 v[144:147], v[20:21], off
	global_load_dwordx4 v[148:151], v[20:21], off offset:128
	v_addc_co_u32_e32 v31, vcc, 0, v3, vcc
	v_add_co_u32_e32 v32, vcc, s18, v2
	global_load_dwordx4 v[152:155], v[22:23], off
	global_load_dwordx4 v[156:159], v[22:23], off offset:128
	global_load_dwordx4 v[160:163], v[24:25], off
	global_load_dwordx4 v[164:167], v[24:25], off offset:128
	global_load_dwordx4 v[168:171], v[26:27], off
	global_load_dwordx4 v[172:175], v[26:27], off offset:128
	global_load_dwordx4 v[176:179], v[28:29], off
	global_load_dwordx4 v[180:183], v[28:29], off offset:128
	v_addc_co_u32_e32 v33, vcc, 0, v3, vcc
	global_load_dwordx4 v[184:187], v[30:31], off
	global_load_dwordx4 v[188:191], v[30:31], off offset:128
	global_load_dwordx4 v[192:195], v[32:33], off
	global_load_dwordx4 v[196:199], v[32:33], off offset:128
	s_lshl_b32 s21, s6, 8
	s_cmp_lt_u32 s6, 32
	s_cselect_b64 s[6:7], -1, 0
	s_add_i32 s8, s21, 0xffffe000
	s_lshr_b32 s8, s8, 12
	s_add_i32 s8, s8, 1
	s_and_b64 s[22:23], s[6:7], exec
	s_cselect_b32 s8, 0, s8
	s_mul_hi_u32 s22, s8, 0x6000
	s_mulk_i32 s8, 0x6000
	s_add_u32 s23, s2, s8
	s_addc_u32 s24, s3, s22
	s_lshl_b32 s8, s20, 9
	s_add_u32 s22, s23, s8
	s_addc_u32 s23, s24, 0
	s_waitcnt vmcnt(23)
	ds_write_b128 v60, v[100:103]
	s_waitcnt vmcnt(21)
	ds_write_b128 v60, v[108:111] offset:36864
	s_waitcnt vmcnt(19)
	ds_write_b128 v60, v[116:119] offset:4608
	s_waitcnt vmcnt(17)
	ds_write_b128 v60, v[124:127] offset:9216
	s_waitcnt vmcnt(15)
	ds_write_b128 v60, v[136:139] offset:13824
	s_waitcnt vmcnt(13)
	ds_write_b128 v60, v[144:147] offset:18432
	s_waitcnt vmcnt(11)
	ds_write_b128 v60, v[152:155] offset:23040
	s_waitcnt vmcnt(9)
	ds_write_b128 v60, v[160:163] offset:27648
	s_waitcnt vmcnt(7)
	ds_write_b128 v60, v[168:171] offset:32256
	s_waitcnt vmcnt(5)
	ds_write_b128 v60, v[176:179] offset:41472
	s_waitcnt vmcnt(3)
	ds_write_b128 v60, v[184:187] offset:46080
	s_waitcnt vmcnt(1)
	ds_write_b128 v60, v[192:195] offset:50688
	s_waitcnt lgkmcnt(0)
	s_barrier
	ds_read_b128 v[100:103], v59
	ds_read_b128 v[108:111], v62 offset:36864
	ds_read_b128 v[116:119], v59 offset:4608
	ds_read_b128 v[124:127], v61
	ds_read_b128 v[136:139], v62 offset:41472
	s_waitcnt lgkmcnt(3)
	v_mfma_f32_32x32x16_bf16 a[112:127], v[100:103], v[108:111], 0
	s_waitcnt lgkmcnt(0)
	v_mfma_f32_32x32x16_bf16 a[96:111], v[100:103], v[136:139], 0
	ds_read_b128 v[100:103], v59 offset:9216
	ds_write_b128 v60, v[104:107] offset:55296
	ds_write_b128 v60, v[120:123] offset:59904
	ds_write_b128 v60, v[128:131] offset:64512
	ds_write_b128 v63, v[140:143] offset:55296
	ds_write_b128 v64, v[148:151] offset:55296
	ds_write_b128 v65, v[156:159] offset:55296
	ds_write_b128 v66, v[164:167] offset:55296
	ds_write_b128 v67, v[172:175] offset:55296
	ds_write_b128 v68, v[112:115]
	ds_write_b128 v68, v[180:183] offset:4608
	ds_write_b128 v68, v[188:191] offset:9216
	s_waitcnt vmcnt(0)
	ds_write_b128 v68, v[196:199] offset:13824
	v_mfma_f32_32x32x16_bf16 a[80:95], v[116:119], v[108:111], 0
	v_mfma_f32_32x32x16_bf16 a[64:79], v[116:119], v[136:139], 0
	s_waitcnt lgkmcnt(12)
	v_mfma_f32_32x32x16_bf16 a[48:63], v[100:103], v[108:111], 0
	v_mfma_f32_32x32x16_bf16 a[32:47], v[100:103], v[136:139], 0
	v_mfma_f32_32x32x16_bf16 a[16:31], v[124:127], v[108:111], 0
	ds_read_b128 v[100:103], v59 offset:32
	ds_read_b128 v[104:107], v62 offset:36896
	ds_read_b128 v[108:111], v62 offset:36928
	ds_read_b128 v[112:115], v59 offset:64
	ds_read_b128 v[116:119], v62 offset:41504
	ds_read_b128 v[120:123], v62 offset:36960
	v_mfma_f32_32x32x16_bf16 a[0:15], v[124:127], v[136:139], 0
	s_waitcnt lgkmcnt(4)
	v_mfma_f32_32x32x16_bf16 a[112:127], v[100:103], v[104:107], a[112:127]
	s_waitcnt lgkmcnt(1)
	v_mfma_f32_32x32x16_bf16 a[96:111], v[100:103], v[116:119], a[96:111]
	ds_read_b128 v[100:103], v59 offset:4640
	ds_read_b128 v[124:127], v59 offset:96
	s_waitcnt lgkmcnt(1)
	v_mfma_f32_32x32x16_bf16 a[80:95], v[100:103], v[104:107], a[80:95]
	v_mfma_f32_32x32x16_bf16 a[64:79], v[100:103], v[116:119], a[64:79]
	ds_read_b128 v[100:103], v59 offset:9248
	ds_read_b128 v[128:131], v59 offset:9280
	s_waitcnt lgkmcnt(1)
	v_mfma_f32_32x32x16_bf16 a[48:63], v[100:103], v[104:107], a[48:63]
	v_mfma_f32_32x32x16_bf16 a[32:47], v[100:103], v[116:119], a[32:47]
	ds_read_b128 v[100:103], v61 offset:32
	ds_read_b128 v[136:139], v59 offset:9312
	s_waitcnt lgkmcnt(1)
	v_mfma_f32_32x32x16_bf16 a[16:31], v[100:103], v[104:107], a[16:31]
	v_mfma_f32_32x32x16_bf16 a[0:15], v[100:103], v[116:119], a[0:15]
	ds_read_b128 v[100:103], v62 offset:41536
	ds_read_b128 v[104:107], v62 offset:41568
	v_mfma_f32_32x32x16_bf16 a[112:127], v[112:115], v[108:111], a[112:127]
	s_waitcnt lgkmcnt(1)
	v_mfma_f32_32x32x16_bf16 a[96:111], v[112:115], v[100:103], a[96:111]
	ds_read_b128 v[112:115], v59 offset:4672
	ds_read_b128 v[116:119], v59 offset:4704
	s_waitcnt lgkmcnt(1)
	v_mfma_f32_32x32x16_bf16 a[80:95], v[112:115], v[108:111], a[80:95]
	v_mfma_f32_32x32x16_bf16 a[64:79], v[112:115], v[100:103], a[64:79]
	v_mfma_f32_32x32x16_bf16 a[48:63], v[128:131], v[108:111], a[48:63]
	v_mfma_f32_32x32x16_bf16 a[32:47], v[128:131], v[100:103], a[32:47]
	ds_read_b128 v[112:115], v61 offset:64
	ds_read_b128 v[128:131], v61 offset:96
	s_waitcnt lgkmcnt(1)
	v_mfma_f32_32x32x16_bf16 a[16:31], v[112:115], v[108:111], a[16:31]
	v_mfma_f32_32x32x16_bf16 a[0:15], v[112:115], v[100:103], a[0:15]
	global_load_dwordx4 v[100:103], v[32:33], off offset:256
	v_mfma_f32_32x32x16_bf16 a[112:127], v[124:127], v[120:123], a[112:127]
	v_mfma_f32_32x32x16_bf16 a[96:111], v[124:127], v[104:107], a[96:111]
	v_mfma_f32_32x32x16_bf16 a[80:95], v[116:119], v[120:123], a[80:95]
	v_mfma_f32_32x32x16_bf16 a[64:79], v[116:119], v[104:107], a[64:79]
	v_mfma_f32_32x32x16_bf16 a[48:63], v[136:139], v[120:123], a[48:63]
	v_mfma_f32_32x32x16_bf16 a[32:47], v[136:139], v[104:107], a[32:47]
	global_load_dwordx4 v[108:111], v[30:31], off offset:256
	global_load_dwordx4 v[112:115], v[18:19], off offset:256
	global_load_dwordx4 v[116:119], v[6:7], off offset:256
	global_load_dwordx4 v[124:127], v[4:5], off offset:256
	global_load_dwordx4 v[136:139], v[0:1], off offset:256
	global_load_dwordx4 v[140:143], v[22:23], off offset:256
	global_load_dwordx4 v[144:147], v[20:21], off offset:256
	s_waitcnt lgkmcnt(0)
	v_mfma_f32_32x32x16_bf16 a[16:31], v[128:131], v[120:123], a[16:31]
	global_load_dwordx4 v[120:123], v[26:27], off offset:256
	global_load_dwordx4 v[148:151], v[24:25], off offset:256
	global_load_dwordx4 v[152:155], v[28:29], off offset:256
	global_load_dwordx4 v[156:159], v[2:3], off offset:256
	s_barrier
	v_mfma_f32_32x32x16_bf16 a[0:15], v[128:131], v[104:107], a[0:15]
	ds_read_b128 v[104:107], v59 offset:55296
	ds_read_b128 v[128:131], v69
	ds_read_b128 v[160:163], v59 offset:59904
	ds_read_b128 v[164:167], v61 offset:55296
	ds_read_b128 v[168:171], v69 offset:4608
	s_waitcnt lgkmcnt(3)
	v_mfma_f32_32x32x16_bf16 a[112:127], v[104:107], v[128:131], a[112:127]
	s_waitcnt lgkmcnt(0)
	v_mfma_f32_32x32x16_bf16 a[96:111], v[104:107], v[168:171], a[96:111]
	ds_read_b128 v[104:107], v59 offset:64512
	s_waitcnt vmcnt(6)
	ds_write_b128 v60, v[136:139]
	ds_write_b128 v60, v[124:127] offset:4608
	ds_write_b128 v60, v[116:119] offset:9216
	ds_write_b128 v60, v[112:115] offset:13824
	s_waitcnt vmcnt(4)
	ds_write_b128 v60, v[144:147] offset:18432
	ds_write_b128 v60, v[140:143] offset:23040
	s_waitcnt vmcnt(2)
	ds_write_b128 v60, v[148:151] offset:27648
	ds_write_b128 v60, v[120:123] offset:32256
	s_waitcnt vmcnt(0)
	ds_write_b128 v60, v[156:159] offset:36864
	ds_write_b128 v60, v[152:155] offset:41472
	ds_write_b128 v60, v[108:111] offset:46080
	ds_write_b128 v60, v[100:103] offset:50688
	v_mfma_f32_32x32x16_bf16 a[80:95], v[160:163], v[128:131], a[80:95]
	v_mfma_f32_32x32x16_bf16 a[64:79], v[160:163], v[168:171], a[64:79]
	s_waitcnt lgkmcnt(12)
	v_mfma_f32_32x32x16_bf16 a[48:63], v[104:107], v[128:131], a[48:63]
	v_mfma_f32_32x32x16_bf16 a[32:47], v[104:107], v[168:171], a[32:47]
	ds_read_b128 v[100:103], v59 offset:55328
	ds_read_b128 v[104:107], v69 offset:32
	ds_read_b128 v[108:111], v69 offset:64
	ds_read_b128 v[112:115], v59 offset:55360
	ds_read_b128 v[116:119], v69 offset:4640
	ds_read_b128 v[120:123], v69 offset:96
	s_waitcnt lgkmcnt(4)
	v_mfma_f32_32x32x16_bf16 a[112:127], v[100:103], v[104:107], a[112:127]
	s_waitcnt lgkmcnt(1)
	v_mfma_f32_32x32x16_bf16 a[96:111], v[100:103], v[116:119], a[96:111]
	ds_read_b128 v[100:103], v59 offset:59936
	ds_read_b128 v[124:127], v59 offset:55392
	v_mfma_f32_32x32x16_bf16 a[16:31], v[164:167], v[128:131], a[16:31]
	v_mfma_f32_32x32x16_bf16 a[0:15], v[164:167], v[168:171], a[0:15]
	s_waitcnt lgkmcnt(1)
	v_mfma_f32_32x32x16_bf16 a[80:95], v[100:103], v[104:107], a[80:95]
	v_mfma_f32_32x32x16_bf16 a[64:79], v[100:103], v[116:119], a[64:79]
	ds_read_b128 v[100:103], v59 offset:64544
	ds_read_b128 v[128:131], v59 offset:64576
	s_waitcnt lgkmcnt(1)
	v_mfma_f32_32x32x16_bf16 a[48:63], v[100:103], v[104:107], a[48:63]
	v_mfma_f32_32x32x16_bf16 a[32:47], v[100:103], v[116:119], a[32:47]
	ds_read_b128 v[100:103], v61 offset:55328
	ds_read_b128 v[136:139], v59 offset:64608
	s_waitcnt lgkmcnt(1)
	v_mfma_f32_32x32x16_bf16 a[16:31], v[100:103], v[104:107], a[16:31]
	v_mfma_f32_32x32x16_bf16 a[0:15], v[100:103], v[116:119], a[0:15]
	ds_read_b128 v[100:103], v69 offset:4672
	ds_read_b128 v[104:107], v69 offset:4704
	v_mfma_f32_32x32x16_bf16 a[112:127], v[112:115], v[108:111], a[112:127]
	s_waitcnt lgkmcnt(1)
	v_mfma_f32_32x32x16_bf16 a[96:111], v[112:115], v[100:103], a[96:111]
	ds_read_b128 v[112:115], v59 offset:59968
	ds_read_b128 v[116:119], v59 offset:60000
	s_waitcnt lgkmcnt(1)
	v_mfma_f32_32x32x16_bf16 a[80:95], v[112:115], v[108:111], a[80:95]
	v_mfma_f32_32x32x16_bf16 a[64:79], v[112:115], v[100:103], a[64:79]
	v_mfma_f32_32x32x16_bf16 a[48:63], v[128:131], v[108:111], a[48:63]
	v_mfma_f32_32x32x16_bf16 a[32:47], v[128:131], v[100:103], a[32:47]
	ds_read_b128 v[112:115], v61 offset:55360
	ds_read_b128 v[128:131], v61 offset:55392
	s_waitcnt lgkmcnt(1)
	v_mfma_f32_32x32x16_bf16 a[16:31], v[112:115], v[108:111], a[16:31]
	v_mfma_f32_32x32x16_bf16 a[0:15], v[112:115], v[100:103], a[0:15]
	v_mfma_f32_32x32x16_bf16 a[112:127], v[124:127], v[120:123], a[112:127]
	v_mfma_f32_32x32x16_bf16 a[96:111], v[124:127], v[104:107], a[96:111]
	v_mfma_f32_32x32x16_bf16 a[80:95], v[116:119], v[120:123], a[80:95]
	v_mfma_f32_32x32x16_bf16 a[64:79], v[116:119], v[104:107], a[64:79]
	global_load_dwordx4 v[100:103], v[4:5], off offset:384
	global_load_dwordx4 v[108:111], v[0:1], off offset:384
	global_load_dwordx4 v[112:115], v[18:19], off offset:384
	global_load_dwordx4 v[116:119], v[6:7], off offset:384
	v_mfma_f32_32x32x16_bf16 a[48:63], v[136:139], v[120:123], a[48:63]
	v_mfma_f32_32x32x16_bf16 a[32:47], v[136:139], v[104:107], a[32:47]
	global_load_dwordx4 v[124:127], v[20:21], off offset:384
	global_load_dwordx4 v[136:139], v[22:23], off offset:384
	global_load_dwordx4 v[140:143], v[26:27], off offset:384
	global_load_dwordx4 v[144:147], v[24:25], off offset:384
	global_load_dwordx4 v[148:151], v[28:29], off offset:384
	global_load_dwordx4 v[152:155], v[2:3], off offset:384
	global_load_dwordx4 v[156:159], v[30:31], off offset:384
	s_waitcnt lgkmcnt(0)
	v_mfma_f32_32x32x16_bf16 a[16:31], v[128:131], v[120:123], a[16:31]
	global_load_dwordx4 v[120:123], v[32:33], off offset:384
	s_barrier
	v_mfma_f32_32x32x16_bf16 a[0:15], v[128:131], v[104:107], a[0:15]
	ds_read_b128 v[104:107], v59
	ds_read_b128 v[128:131], v62 offset:36864
	ds_read_b128 v[160:163], v59 offset:4608
	ds_read_b128 v[164:167], v61
	ds_read_b128 v[168:171], v62 offset:41472
	s_waitcnt lgkmcnt(3)
	v_mfma_f32_32x32x16_bf16 a[112:127], v[104:107], v[128:131], a[112:127]
	s_waitcnt lgkmcnt(0)
	v_mfma_f32_32x32x16_bf16 a[96:111], v[104:107], v[168:171], a[96:111]
	ds_read_b128 v[104:107], v59 offset:9216
	s_waitcnt vmcnt(10)
	ds_write_b128 v60, v[108:111] offset:55296
	ds_write_b128 v60, v[100:103] offset:59904
	s_waitcnt vmcnt(8)
	ds_write_b128 v60, v[116:119] offset:64512
	ds_write_b128 v63, v[112:115] offset:55296
	s_waitcnt vmcnt(7)
	ds_write_b128 v64, v[124:127] offset:55296
	s_waitcnt vmcnt(6)
	ds_write_b128 v65, v[136:139] offset:55296
	s_waitcnt vmcnt(4)
	ds_write_b128 v66, v[144:147] offset:55296
	ds_write_b128 v67, v[140:143] offset:55296
	s_waitcnt vmcnt(2)
	ds_write_b128 v68, v[152:155]
	ds_write_b128 v68, v[148:151] offset:4608
	s_waitcnt vmcnt(1)
	ds_write_b128 v68, v[156:159] offset:9216
	s_waitcnt vmcnt(0)
	ds_write_b128 v68, v[120:123] offset:13824
	v_mfma_f32_32x32x16_bf16 a[80:95], v[160:163], v[128:131], a[80:95]
	v_mfma_f32_32x32x16_bf16 a[64:79], v[160:163], v[168:171], a[64:79]
	s_waitcnt lgkmcnt(12)
	v_mfma_f32_32x32x16_bf16 a[48:63], v[104:107], v[128:131], a[48:63]
	v_mfma_f32_32x32x16_bf16 a[32:47], v[104:107], v[168:171], a[32:47]
	ds_read_b128 v[100:103], v59 offset:32
	ds_read_b128 v[104:107], v62 offset:36896
	ds_read_b128 v[108:111], v62 offset:36928
	ds_read_b128 v[112:115], v59 offset:64
	ds_read_b128 v[116:119], v62 offset:41504
	ds_read_b128 v[120:123], v62 offset:36960
	s_waitcnt lgkmcnt(4)
	v_mfma_f32_32x32x16_bf16 a[112:127], v[100:103], v[104:107], a[112:127]
	s_waitcnt lgkmcnt(1)
	v_mfma_f32_32x32x16_bf16 a[96:111], v[100:103], v[116:119], a[96:111]
	ds_read_b128 v[100:103], v59 offset:4640
	ds_read_b128 v[124:127], v59 offset:96
	v_mfma_f32_32x32x16_bf16 a[16:31], v[164:167], v[128:131], a[16:31]
	v_mfma_f32_32x32x16_bf16 a[0:15], v[164:167], v[168:171], a[0:15]
	s_waitcnt lgkmcnt(1)
	v_mfma_f32_32x32x16_bf16 a[80:95], v[100:103], v[104:107], a[80:95]
	v_mfma_f32_32x32x16_bf16 a[64:79], v[100:103], v[116:119], a[64:79]
	ds_read_b128 v[100:103], v59 offset:9248
	ds_read_b128 v[128:131], v59 offset:9280
	s_waitcnt lgkmcnt(1)
	v_mfma_f32_32x32x16_bf16 a[48:63], v[100:103], v[104:107], a[48:63]
	v_mfma_f32_32x32x16_bf16 a[32:47], v[100:103], v[116:119], a[32:47]
	ds_read_b128 v[100:103], v61 offset:32
	ds_read_b128 v[136:139], v59 offset:9312
	s_waitcnt lgkmcnt(1)
	v_mfma_f32_32x32x16_bf16 a[16:31], v[100:103], v[104:107], a[16:31]
	v_mfma_f32_32x32x16_bf16 a[0:15], v[100:103], v[116:119], a[0:15]
	ds_read_b128 v[100:103], v62 offset:41536
	ds_read_b128 v[104:107], v62 offset:41568
	v_mfma_f32_32x32x16_bf16 a[112:127], v[112:115], v[108:111], a[112:127]
	s_waitcnt lgkmcnt(1)
	v_mfma_f32_32x32x16_bf16 a[96:111], v[112:115], v[100:103], a[96:111]
	ds_read_b128 v[112:115], v59 offset:4672
	ds_read_b128 v[116:119], v59 offset:4704
	s_waitcnt lgkmcnt(1)
	v_mfma_f32_32x32x16_bf16 a[80:95], v[112:115], v[108:111], a[80:95]
	v_mfma_f32_32x32x16_bf16 a[64:79], v[112:115], v[100:103], a[64:79]
	v_mfma_f32_32x32x16_bf16 a[48:63], v[128:131], v[108:111], a[48:63]
	v_mfma_f32_32x32x16_bf16 a[32:47], v[128:131], v[100:103], a[32:47]
	ds_read_b128 v[112:115], v61 offset:64
	ds_read_b128 v[128:131], v61 offset:96
	s_waitcnt lgkmcnt(1)
	v_mfma_f32_32x32x16_bf16 a[16:31], v[112:115], v[108:111], a[16:31]
	v_mfma_f32_32x32x16_bf16 a[0:15], v[112:115], v[100:103], a[0:15]
	global_load_dwordx4 v[100:103], v[32:33], off offset:512
	v_mfma_f32_32x32x16_bf16 a[112:127], v[124:127], v[120:123], a[112:127]
	v_mfma_f32_32x32x16_bf16 a[96:111], v[124:127], v[104:107], a[96:111]
	v_mfma_f32_32x32x16_bf16 a[80:95], v[116:119], v[120:123], a[80:95]
	v_mfma_f32_32x32x16_bf16 a[64:79], v[116:119], v[104:107], a[64:79]
	v_mfma_f32_32x32x16_bf16 a[48:63], v[136:139], v[120:123], a[48:63]
	v_mfma_f32_32x32x16_bf16 a[32:47], v[136:139], v[104:107], a[32:47]
	global_load_dwordx4 v[108:111], v[30:31], off offset:512
	global_load_dwordx4 v[112:115], v[18:19], off offset:512
	global_load_dwordx4 v[116:119], v[6:7], off offset:512
	global_load_dwordx4 v[124:127], v[4:5], off offset:512
	global_load_dwordx4 v[136:139], v[0:1], off offset:512
	global_load_dwordx4 v[140:143], v[22:23], off offset:512
	global_load_dwordx4 v[144:147], v[20:21], off offset:512
	s_waitcnt lgkmcnt(0)
	v_mfma_f32_32x32x16_bf16 a[16:31], v[128:131], v[120:123], a[16:31]
	global_load_dwordx4 v[120:123], v[26:27], off offset:512
	global_load_dwordx4 v[148:151], v[24:25], off offset:512
	global_load_dwordx4 v[152:155], v[28:29], off offset:512
	global_load_dwordx4 v[156:159], v[2:3], off offset:512
	s_barrier
	v_mfma_f32_32x32x16_bf16 a[0:15], v[128:131], v[104:107], a[0:15]
	ds_read_b128 v[104:107], v59 offset:55296
	ds_read_b128 v[128:131], v69
	ds_read_b128 v[160:163], v59 offset:59904
	ds_read_b128 v[164:167], v61 offset:55296
	ds_read_b128 v[168:171], v69 offset:4608
	s_waitcnt lgkmcnt(3)
	v_mfma_f32_32x32x16_bf16 a[112:127], v[104:107], v[128:131], a[112:127]
	s_waitcnt lgkmcnt(0)
	v_mfma_f32_32x32x16_bf16 a[96:111], v[104:107], v[168:171], a[96:111]
	ds_read_b128 v[104:107], v59 offset:64512
	s_waitcnt vmcnt(6)
	ds_write_b128 v60, v[136:139]
	ds_write_b128 v60, v[124:127] offset:4608
	ds_write_b128 v60, v[116:119] offset:9216
	ds_write_b128 v60, v[112:115] offset:13824
	s_waitcnt vmcnt(4)
	ds_write_b128 v60, v[144:147] offset:18432
	ds_write_b128 v60, v[140:143] offset:23040
	s_waitcnt vmcnt(2)
	ds_write_b128 v60, v[148:151] offset:27648
	ds_write_b128 v60, v[120:123] offset:32256
	s_waitcnt vmcnt(0)
	ds_write_b128 v60, v[156:159] offset:36864
	ds_write_b128 v60, v[152:155] offset:41472
	ds_write_b128 v60, v[108:111] offset:46080
	ds_write_b128 v60, v[100:103] offset:50688
	v_mfma_f32_32x32x16_bf16 a[80:95], v[160:163], v[128:131], a[80:95]
	v_mfma_f32_32x32x16_bf16 a[64:79], v[160:163], v[168:171], a[64:79]
	s_waitcnt lgkmcnt(12)
	v_mfma_f32_32x32x16_bf16 a[48:63], v[104:107], v[128:131], a[48:63]
	v_mfma_f32_32x32x16_bf16 a[32:47], v[104:107], v[168:171], a[32:47]
	ds_read_b128 v[100:103], v59 offset:55328
	ds_read_b128 v[104:107], v69 offset:32
	ds_read_b128 v[108:111], v69 offset:64
	ds_read_b128 v[112:115], v59 offset:55360
	ds_read_b128 v[116:119], v69 offset:4640
	ds_read_b128 v[120:123], v69 offset:96
	s_waitcnt lgkmcnt(4)
	v_mfma_f32_32x32x16_bf16 a[112:127], v[100:103], v[104:107], a[112:127]
	s_waitcnt lgkmcnt(1)
	v_mfma_f32_32x32x16_bf16 a[96:111], v[100:103], v[116:119], a[96:111]
	ds_read_b128 v[100:103], v59 offset:59936
	ds_read_b128 v[124:127], v59 offset:55392
	v_mfma_f32_32x32x16_bf16 a[16:31], v[164:167], v[128:131], a[16:31]
	v_mfma_f32_32x32x16_bf16 a[0:15], v[164:167], v[168:171], a[0:15]
	s_waitcnt lgkmcnt(1)
	v_mfma_f32_32x32x16_bf16 a[80:95], v[100:103], v[104:107], a[80:95]
	v_mfma_f32_32x32x16_bf16 a[64:79], v[100:103], v[116:119], a[64:79]
	ds_read_b128 v[100:103], v59 offset:64544
	ds_read_b128 v[128:131], v59 offset:64576
	s_waitcnt lgkmcnt(1)
	v_mfma_f32_32x32x16_bf16 a[48:63], v[100:103], v[104:107], a[48:63]
	v_mfma_f32_32x32x16_bf16 a[32:47], v[100:103], v[116:119], a[32:47]
	ds_read_b128 v[100:103], v61 offset:55328
	ds_read_b128 v[136:139], v59 offset:64608
	s_waitcnt lgkmcnt(1)
	v_mfma_f32_32x32x16_bf16 a[16:31], v[100:103], v[104:107], a[16:31]
	v_mfma_f32_32x32x16_bf16 a[0:15], v[100:103], v[116:119], a[0:15]
	ds_read_b128 v[100:103], v69 offset:4672
	ds_read_b128 v[104:107], v69 offset:4704
	v_mfma_f32_32x32x16_bf16 a[112:127], v[112:115], v[108:111], a[112:127]
	s_waitcnt lgkmcnt(1)
	v_mfma_f32_32x32x16_bf16 a[96:111], v[112:115], v[100:103], a[96:111]
	ds_read_b128 v[112:115], v59 offset:59968
	ds_read_b128 v[116:119], v59 offset:60000
	s_waitcnt lgkmcnt(1)
	v_mfma_f32_32x32x16_bf16 a[80:95], v[112:115], v[108:111], a[80:95]
	v_mfma_f32_32x32x16_bf16 a[64:79], v[112:115], v[100:103], a[64:79]
	v_mfma_f32_32x32x16_bf16 a[48:63], v[128:131], v[108:111], a[48:63]
	v_mfma_f32_32x32x16_bf16 a[32:47], v[128:131], v[100:103], a[32:47]
	ds_read_b128 v[112:115], v61 offset:55360
	ds_read_b128 v[128:131], v61 offset:55392
	s_waitcnt lgkmcnt(1)
	v_mfma_f32_32x32x16_bf16 a[16:31], v[112:115], v[108:111], a[16:31]
	v_mfma_f32_32x32x16_bf16 a[0:15], v[112:115], v[100:103], a[0:15]
	v_mfma_f32_32x32x16_bf16 a[112:127], v[124:127], v[120:123], a[112:127]
	v_mfma_f32_32x32x16_bf16 a[96:111], v[124:127], v[104:107], a[96:111]
	v_mfma_f32_32x32x16_bf16 a[80:95], v[116:119], v[120:123], a[80:95]
	v_mfma_f32_32x32x16_bf16 a[64:79], v[116:119], v[104:107], a[64:79]
	global_load_dwordx4 v[100:103], v[4:5], off offset:640
	global_load_dwordx4 v[108:111], v[0:1], off offset:640
	global_load_dwordx4 v[112:115], v[18:19], off offset:640
	global_load_dwordx4 v[116:119], v[6:7], off offset:640
	v_mfma_f32_32x32x16_bf16 a[48:63], v[136:139], v[120:123], a[48:63]
	v_mfma_f32_32x32x16_bf16 a[32:47], v[136:139], v[104:107], a[32:47]
	global_load_dwordx4 v[124:127], v[20:21], off offset:640
	global_load_dwordx4 v[136:139], v[22:23], off offset:640
	global_load_dwordx4 v[140:143], v[26:27], off offset:640
	global_load_dwordx4 v[144:147], v[24:25], off offset:640
	global_load_dwordx4 v[148:151], v[28:29], off offset:640
	global_load_dwordx4 v[152:155], v[2:3], off offset:640
	global_load_dwordx4 v[156:159], v[30:31], off offset:640
	s_waitcnt lgkmcnt(0)
	v_mfma_f32_32x32x16_bf16 a[16:31], v[128:131], v[120:123], a[16:31]
	global_load_dwordx4 v[120:123], v[32:33], off offset:640
	s_barrier
	v_mfma_f32_32x32x16_bf16 a[0:15], v[128:131], v[104:107], a[0:15]
	ds_read_b128 v[104:107], v59
	ds_read_b128 v[128:131], v62 offset:36864
	ds_read_b128 v[160:163], v59 offset:4608
	ds_read_b128 v[164:167], v61
	ds_read_b128 v[168:171], v62 offset:41472
	s_waitcnt lgkmcnt(3)
	v_mfma_f32_32x32x16_bf16 a[112:127], v[104:107], v[128:131], a[112:127]
	s_waitcnt lgkmcnt(0)
	v_mfma_f32_32x32x16_bf16 a[96:111], v[104:107], v[168:171], a[96:111]
	ds_read_b128 v[104:107], v59 offset:9216
	s_waitcnt vmcnt(10)
	ds_write_b128 v60, v[108:111] offset:55296
	ds_write_b128 v60, v[100:103] offset:59904
	s_waitcnt vmcnt(8)
	ds_write_b128 v60, v[116:119] offset:64512
	ds_write_b128 v63, v[112:115] offset:55296
	s_waitcnt vmcnt(7)
	ds_write_b128 v64, v[124:127] offset:55296
	s_waitcnt vmcnt(6)
	ds_write_b128 v65, v[136:139] offset:55296
	s_waitcnt vmcnt(4)
	ds_write_b128 v66, v[144:147] offset:55296
	ds_write_b128 v67, v[140:143] offset:55296
	s_waitcnt vmcnt(2)
	ds_write_b128 v68, v[152:155]
	ds_write_b128 v68, v[148:151] offset:4608
	s_waitcnt vmcnt(1)
	ds_write_b128 v68, v[156:159] offset:9216
	s_waitcnt vmcnt(0)
	ds_write_b128 v68, v[120:123] offset:13824
	v_mfma_f32_32x32x16_bf16 a[80:95], v[160:163], v[128:131], a[80:95]
	v_mfma_f32_32x32x16_bf16 a[64:79], v[160:163], v[168:171], a[64:79]
	s_waitcnt lgkmcnt(12)
	v_mfma_f32_32x32x16_bf16 a[48:63], v[104:107], v[128:131], a[48:63]
	v_mfma_f32_32x32x16_bf16 a[32:47], v[104:107], v[168:171], a[32:47]
	ds_read_b128 v[100:103], v59 offset:32
	ds_read_b128 v[104:107], v62 offset:36896
	ds_read_b128 v[108:111], v62 offset:36928
	ds_read_b128 v[112:115], v59 offset:64
	ds_read_b128 v[116:119], v62 offset:41504
	ds_read_b128 v[120:123], v62 offset:36960
	s_waitcnt lgkmcnt(4)
	v_mfma_f32_32x32x16_bf16 a[112:127], v[100:103], v[104:107], a[112:127]
	s_waitcnt lgkmcnt(1)
	v_mfma_f32_32x32x16_bf16 a[96:111], v[100:103], v[116:119], a[96:111]
	ds_read_b128 v[100:103], v59 offset:4640
	ds_read_b128 v[124:127], v59 offset:96
	v_mfma_f32_32x32x16_bf16 a[16:31], v[164:167], v[128:131], a[16:31]
	v_mfma_f32_32x32x16_bf16 a[0:15], v[164:167], v[168:171], a[0:15]
	s_waitcnt lgkmcnt(1)
	v_mfma_f32_32x32x16_bf16 a[80:95], v[100:103], v[104:107], a[80:95]
	v_mfma_f32_32x32x16_bf16 a[64:79], v[100:103], v[116:119], a[64:79]
	ds_read_b128 v[100:103], v59 offset:9248
	ds_read_b128 v[128:131], v59 offset:9280
	s_waitcnt lgkmcnt(1)
	v_mfma_f32_32x32x16_bf16 a[48:63], v[100:103], v[104:107], a[48:63]
	v_mfma_f32_32x32x16_bf16 a[32:47], v[100:103], v[116:119], a[32:47]
	ds_read_b128 v[100:103], v61 offset:32
	ds_read_b128 v[136:139], v59 offset:9312
	s_waitcnt lgkmcnt(1)
	v_mfma_f32_32x32x16_bf16 a[16:31], v[100:103], v[104:107], a[16:31]
	v_mfma_f32_32x32x16_bf16 a[0:15], v[100:103], v[116:119], a[0:15]
	ds_read_b128 v[100:103], v62 offset:41536
	ds_read_b128 v[104:107], v62 offset:41568
	v_mfma_f32_32x32x16_bf16 a[112:127], v[112:115], v[108:111], a[112:127]
	s_waitcnt lgkmcnt(1)
	v_mfma_f32_32x32x16_bf16 a[96:111], v[112:115], v[100:103], a[96:111]
	ds_read_b128 v[112:115], v59 offset:4672
	ds_read_b128 v[116:119], v59 offset:4704
	s_waitcnt lgkmcnt(1)
	v_mfma_f32_32x32x16_bf16 a[80:95], v[112:115], v[108:111], a[80:95]
	v_mfma_f32_32x32x16_bf16 a[64:79], v[112:115], v[100:103], a[64:79]
	v_mfma_f32_32x32x16_bf16 a[48:63], v[128:131], v[108:111], a[48:63]
	v_mfma_f32_32x32x16_bf16 a[32:47], v[128:131], v[100:103], a[32:47]
	ds_read_b128 v[112:115], v61 offset:64
	ds_read_b128 v[128:131], v61 offset:96
	s_waitcnt lgkmcnt(1)
	v_mfma_f32_32x32x16_bf16 a[16:31], v[112:115], v[108:111], a[16:31]
	v_mfma_f32_32x32x16_bf16 a[0:15], v[112:115], v[100:103], a[0:15]
	global_load_dwordx4 v[100:103], v[32:33], off offset:768
	v_mfma_f32_32x32x16_bf16 a[112:127], v[124:127], v[120:123], a[112:127]
	v_mfma_f32_32x32x16_bf16 a[96:111], v[124:127], v[104:107], a[96:111]
	v_mfma_f32_32x32x16_bf16 a[80:95], v[116:119], v[120:123], a[80:95]
	v_mfma_f32_32x32x16_bf16 a[64:79], v[116:119], v[104:107], a[64:79]
	v_mfma_f32_32x32x16_bf16 a[48:63], v[136:139], v[120:123], a[48:63]
	v_mfma_f32_32x32x16_bf16 a[32:47], v[136:139], v[104:107], a[32:47]
	global_load_dwordx4 v[108:111], v[30:31], off offset:768
	global_load_dwordx4 v[112:115], v[18:19], off offset:768
	global_load_dwordx4 v[116:119], v[6:7], off offset:768
	global_load_dwordx4 v[124:127], v[4:5], off offset:768
	global_load_dwordx4 v[136:139], v[0:1], off offset:768
	global_load_dwordx4 v[140:143], v[22:23], off offset:768
	global_load_dwordx4 v[144:147], v[20:21], off offset:768
	s_waitcnt lgkmcnt(0)
	v_mfma_f32_32x32x16_bf16 a[16:31], v[128:131], v[120:123], a[16:31]
	global_load_dwordx4 v[120:123], v[26:27], off offset:768
	global_load_dwordx4 v[148:151], v[24:25], off offset:768
	global_load_dwordx4 v[152:155], v[28:29], off offset:768
	global_load_dwordx4 v[156:159], v[2:3], off offset:768
	s_barrier
	v_mfma_f32_32x32x16_bf16 a[0:15], v[128:131], v[104:107], a[0:15]
	ds_read_b128 v[104:107], v59 offset:55296
	ds_read_b128 v[128:131], v69
	ds_read_b128 v[160:163], v59 offset:59904
	ds_read_b128 v[164:167], v61 offset:55296
	ds_read_b128 v[168:171], v69 offset:4608
	s_waitcnt lgkmcnt(3)
	v_mfma_f32_32x32x16_bf16 a[112:127], v[104:107], v[128:131], a[112:127]
	s_waitcnt lgkmcnt(0)
	v_mfma_f32_32x32x16_bf16 a[96:111], v[104:107], v[168:171], a[96:111]
	ds_read_b128 v[104:107], v59 offset:64512
	s_waitcnt vmcnt(6)
	ds_write_b128 v60, v[136:139]
	ds_write_b128 v60, v[124:127] offset:4608
	ds_write_b128 v60, v[116:119] offset:9216
	ds_write_b128 v60, v[112:115] offset:13824
	s_waitcnt vmcnt(4)
	ds_write_b128 v60, v[144:147] offset:18432
	ds_write_b128 v60, v[140:143] offset:23040
	s_waitcnt vmcnt(2)
	ds_write_b128 v60, v[148:151] offset:27648
	ds_write_b128 v60, v[120:123] offset:32256
	s_waitcnt vmcnt(0)
	ds_write_b128 v60, v[156:159] offset:36864
	ds_write_b128 v60, v[152:155] offset:41472
	ds_write_b128 v60, v[108:111] offset:46080
	ds_write_b128 v60, v[100:103] offset:50688
	v_mfma_f32_32x32x16_bf16 a[80:95], v[160:163], v[128:131], a[80:95]
	v_mfma_f32_32x32x16_bf16 a[64:79], v[160:163], v[168:171], a[64:79]
	s_waitcnt lgkmcnt(12)
	v_mfma_f32_32x32x16_bf16 a[48:63], v[104:107], v[128:131], a[48:63]
	v_mfma_f32_32x32x16_bf16 a[32:47], v[104:107], v[168:171], a[32:47]
	ds_read_b128 v[100:103], v59 offset:55328
	ds_read_b128 v[104:107], v69 offset:32
	ds_read_b128 v[108:111], v69 offset:64
	ds_read_b128 v[112:115], v59 offset:55360
	ds_read_b128 v[116:119], v69 offset:4640
	ds_read_b128 v[120:123], v69 offset:96
	s_waitcnt lgkmcnt(4)
	v_mfma_f32_32x32x16_bf16 a[112:127], v[100:103], v[104:107], a[112:127]
	s_waitcnt lgkmcnt(1)
	v_mfma_f32_32x32x16_bf16 a[96:111], v[100:103], v[116:119], a[96:111]
	ds_read_b128 v[100:103], v59 offset:59936
	ds_read_b128 v[124:127], v59 offset:55392
	v_mfma_f32_32x32x16_bf16 a[16:31], v[164:167], v[128:131], a[16:31]
	v_mfma_f32_32x32x16_bf16 a[0:15], v[164:167], v[168:171], a[0:15]
	s_waitcnt lgkmcnt(1)
	v_mfma_f32_32x32x16_bf16 a[80:95], v[100:103], v[104:107], a[80:95]
	v_mfma_f32_32x32x16_bf16 a[64:79], v[100:103], v[116:119], a[64:79]
	ds_read_b128 v[100:103], v59 offset:64544
	ds_read_b128 v[128:131], v59 offset:64576
	s_waitcnt lgkmcnt(1)
	v_mfma_f32_32x32x16_bf16 a[48:63], v[100:103], v[104:107], a[48:63]
	v_mfma_f32_32x32x16_bf16 a[32:47], v[100:103], v[116:119], a[32:47]
	ds_read_b128 v[100:103], v61 offset:55328
	ds_read_b128 v[136:139], v59 offset:64608
	s_waitcnt lgkmcnt(1)
	v_mfma_f32_32x32x16_bf16 a[16:31], v[100:103], v[104:107], a[16:31]
	v_mfma_f32_32x32x16_bf16 a[0:15], v[100:103], v[116:119], a[0:15]
	ds_read_b128 v[100:103], v69 offset:4672
	ds_read_b128 v[104:107], v69 offset:4704
	v_mfma_f32_32x32x16_bf16 a[112:127], v[112:115], v[108:111], a[112:127]
	s_waitcnt lgkmcnt(1)
	v_mfma_f32_32x32x16_bf16 a[96:111], v[112:115], v[100:103], a[96:111]
	ds_read_b128 v[112:115], v59 offset:59968
	ds_read_b128 v[116:119], v59 offset:60000
	s_waitcnt lgkmcnt(1)
	v_mfma_f32_32x32x16_bf16 a[80:95], v[112:115], v[108:111], a[80:95]
	v_mfma_f32_32x32x16_bf16 a[64:79], v[112:115], v[100:103], a[64:79]
	v_mfma_f32_32x32x16_bf16 a[48:63], v[128:131], v[108:111], a[48:63]
	v_mfma_f32_32x32x16_bf16 a[32:47], v[128:131], v[100:103], a[32:47]
	ds_read_b128 v[112:115], v61 offset:55360
	ds_read_b128 v[128:131], v61 offset:55392
	s_waitcnt lgkmcnt(1)
	v_mfma_f32_32x32x16_bf16 a[16:31], v[112:115], v[108:111], a[16:31]
	v_mfma_f32_32x32x16_bf16 a[0:15], v[112:115], v[100:103], a[0:15]
	v_mfma_f32_32x32x16_bf16 a[112:127], v[124:127], v[120:123], a[112:127]
	v_mfma_f32_32x32x16_bf16 a[96:111], v[124:127], v[104:107], a[96:111]
	v_mfma_f32_32x32x16_bf16 a[80:95], v[116:119], v[120:123], a[80:95]
	v_mfma_f32_32x32x16_bf16 a[64:79], v[116:119], v[104:107], a[64:79]
	global_load_dwordx4 v[100:103], v[4:5], off offset:896
	global_load_dwordx4 v[108:111], v[0:1], off offset:896
	global_load_dwordx4 v[112:115], v[18:19], off offset:896
	global_load_dwordx4 v[116:119], v[6:7], off offset:896
	v_mfma_f32_32x32x16_bf16 a[48:63], v[136:139], v[120:123], a[48:63]
	v_mfma_f32_32x32x16_bf16 a[32:47], v[136:139], v[104:107], a[32:47]
	global_load_dwordx4 v[124:127], v[20:21], off offset:896
	global_load_dwordx4 v[136:139], v[22:23], off offset:896
	global_load_dwordx4 v[140:143], v[26:27], off offset:896
	global_load_dwordx4 v[144:147], v[24:25], off offset:896
	global_load_dwordx4 v[148:151], v[28:29], off offset:896
	global_load_dwordx4 v[152:155], v[2:3], off offset:896
	global_load_dwordx4 v[156:159], v[30:31], off offset:896
	s_waitcnt lgkmcnt(0)
	v_mfma_f32_32x32x16_bf16 a[16:31], v[128:131], v[120:123], a[16:31]
	global_load_dwordx4 v[120:123], v[32:33], off offset:896
	s_barrier
	v_mfma_f32_32x32x16_bf16 a[0:15], v[128:131], v[104:107], a[0:15]
	ds_read_b128 v[104:107], v59
	ds_read_b128 v[128:131], v62 offset:36864
	ds_read_b128 v[160:163], v59 offset:4608
	ds_read_b128 v[164:167], v61
	ds_read_b128 v[168:171], v62 offset:41472
	s_waitcnt lgkmcnt(3)
	v_mfma_f32_32x32x16_bf16 a[112:127], v[104:107], v[128:131], a[112:127]
	s_waitcnt lgkmcnt(0)
	v_mfma_f32_32x32x16_bf16 a[96:111], v[104:107], v[168:171], a[96:111]
	ds_read_b128 v[104:107], v59 offset:9216
	s_waitcnt vmcnt(10)
	ds_write_b128 v60, v[108:111] offset:55296
	ds_write_b128 v60, v[100:103] offset:59904
	s_waitcnt vmcnt(8)
	ds_write_b128 v60, v[116:119] offset:64512
	ds_write_b128 v63, v[112:115] offset:55296
	s_waitcnt vmcnt(7)
	ds_write_b128 v64, v[124:127] offset:55296
	s_waitcnt vmcnt(6)
	ds_write_b128 v65, v[136:139] offset:55296
	s_waitcnt vmcnt(4)
	ds_write_b128 v66, v[144:147] offset:55296
	ds_write_b128 v67, v[140:143] offset:55296
	s_waitcnt vmcnt(2)
	ds_write_b128 v68, v[152:155]
	ds_write_b128 v68, v[148:151] offset:4608
	s_waitcnt vmcnt(1)
	ds_write_b128 v68, v[156:159] offset:9216
	s_waitcnt vmcnt(0)
	ds_write_b128 v68, v[120:123] offset:13824
	v_mfma_f32_32x32x16_bf16 a[80:95], v[160:163], v[128:131], a[80:95]
	v_mfma_f32_32x32x16_bf16 a[64:79], v[160:163], v[168:171], a[64:79]
	s_waitcnt lgkmcnt(12)
	v_mfma_f32_32x32x16_bf16 a[48:63], v[104:107], v[128:131], a[48:63]
	v_mfma_f32_32x32x16_bf16 a[32:47], v[104:107], v[168:171], a[32:47]
	ds_read_b128 v[100:103], v59 offset:32
	ds_read_b128 v[104:107], v62 offset:36896
	ds_read_b128 v[108:111], v62 offset:36928
	ds_read_b128 v[112:115], v59 offset:64
	ds_read_b128 v[116:119], v62 offset:41504
	ds_read_b128 v[120:123], v62 offset:36960
	s_waitcnt lgkmcnt(4)
	v_mfma_f32_32x32x16_bf16 a[112:127], v[100:103], v[104:107], a[112:127]
	s_waitcnt lgkmcnt(1)
	v_mfma_f32_32x32x16_bf16 a[96:111], v[100:103], v[116:119], a[96:111]
	ds_read_b128 v[100:103], v59 offset:4640
	ds_read_b128 v[124:127], v59 offset:96
	v_mfma_f32_32x32x16_bf16 a[16:31], v[164:167], v[128:131], a[16:31]
	v_mfma_f32_32x32x16_bf16 a[0:15], v[164:167], v[168:171], a[0:15]
	s_waitcnt lgkmcnt(1)
	v_mfma_f32_32x32x16_bf16 a[80:95], v[100:103], v[104:107], a[80:95]
	v_mfma_f32_32x32x16_bf16 a[64:79], v[100:103], v[116:119], a[64:79]
	ds_read_b128 v[100:103], v59 offset:9248
	ds_read_b128 v[128:131], v59 offset:9280
	s_waitcnt lgkmcnt(1)
	v_mfma_f32_32x32x16_bf16 a[48:63], v[100:103], v[104:107], a[48:63]
	v_mfma_f32_32x32x16_bf16 a[32:47], v[100:103], v[116:119], a[32:47]
	ds_read_b128 v[100:103], v61 offset:32
	ds_read_b128 v[136:139], v59 offset:9312
	s_waitcnt lgkmcnt(1)
	v_mfma_f32_32x32x16_bf16 a[16:31], v[100:103], v[104:107], a[16:31]
	v_mfma_f32_32x32x16_bf16 a[0:15], v[100:103], v[116:119], a[0:15]
	ds_read_b128 v[100:103], v62 offset:41536
	ds_read_b128 v[104:107], v62 offset:41568
	v_mfma_f32_32x32x16_bf16 a[112:127], v[112:115], v[108:111], a[112:127]
	s_waitcnt lgkmcnt(1)
	v_mfma_f32_32x32x16_bf16 a[96:111], v[112:115], v[100:103], a[96:111]
	ds_read_b128 v[112:115], v59 offset:4672
	ds_read_b128 v[116:119], v59 offset:4704
	s_waitcnt lgkmcnt(1)
	v_mfma_f32_32x32x16_bf16 a[80:95], v[112:115], v[108:111], a[80:95]
	v_mfma_f32_32x32x16_bf16 a[64:79], v[112:115], v[100:103], a[64:79]
	v_mfma_f32_32x32x16_bf16 a[48:63], v[128:131], v[108:111], a[48:63]
	v_mfma_f32_32x32x16_bf16 a[32:47], v[128:131], v[100:103], a[32:47]
	ds_read_b128 v[112:115], v61 offset:64
	ds_read_b128 v[128:131], v61 offset:96
	s_waitcnt lgkmcnt(1)
	v_mfma_f32_32x32x16_bf16 a[16:31], v[112:115], v[108:111], a[16:31]
	v_mfma_f32_32x32x16_bf16 a[0:15], v[112:115], v[100:103], a[0:15]
	global_load_dwordx4 v[100:103], v[32:33], off offset:1024
	v_mfma_f32_32x32x16_bf16 a[112:127], v[124:127], v[120:123], a[112:127]
	v_mfma_f32_32x32x16_bf16 a[96:111], v[124:127], v[104:107], a[96:111]
	v_mfma_f32_32x32x16_bf16 a[80:95], v[116:119], v[120:123], a[80:95]
	v_mfma_f32_32x32x16_bf16 a[64:79], v[116:119], v[104:107], a[64:79]
	v_mfma_f32_32x32x16_bf16 a[48:63], v[136:139], v[120:123], a[48:63]
	v_mfma_f32_32x32x16_bf16 a[32:47], v[136:139], v[104:107], a[32:47]
	global_load_dwordx4 v[108:111], v[30:31], off offset:1024
	global_load_dwordx4 v[112:115], v[18:19], off offset:1024
	global_load_dwordx4 v[116:119], v[6:7], off offset:1024
	global_load_dwordx4 v[124:127], v[4:5], off offset:1024
	global_load_dwordx4 v[136:139], v[0:1], off offset:1024
	global_load_dwordx4 v[140:143], v[22:23], off offset:1024
	global_load_dwordx4 v[144:147], v[20:21], off offset:1024
	s_waitcnt lgkmcnt(0)
	v_mfma_f32_32x32x16_bf16 a[16:31], v[128:131], v[120:123], a[16:31]
	global_load_dwordx4 v[120:123], v[26:27], off offset:1024
	global_load_dwordx4 v[148:151], v[24:25], off offset:1024
	global_load_dwordx4 v[152:155], v[28:29], off offset:1024
	global_load_dwordx4 v[156:159], v[2:3], off offset:1024
	s_barrier
	v_mfma_f32_32x32x16_bf16 a[0:15], v[128:131], v[104:107], a[0:15]
	ds_read_b128 v[104:107], v59 offset:55296
	ds_read_b128 v[128:131], v69
	ds_read_b128 v[160:163], v59 offset:59904
	ds_read_b128 v[164:167], v61 offset:55296
	ds_read_b128 v[168:171], v69 offset:4608
	s_waitcnt lgkmcnt(3)
	v_mfma_f32_32x32x16_bf16 a[112:127], v[104:107], v[128:131], a[112:127]
	s_waitcnt lgkmcnt(0)
	v_mfma_f32_32x32x16_bf16 a[96:111], v[104:107], v[168:171], a[96:111]
	ds_read_b128 v[104:107], v59 offset:64512
	s_waitcnt vmcnt(6)
	ds_write_b128 v60, v[136:139]
	ds_write_b128 v60, v[124:127] offset:4608
	ds_write_b128 v60, v[116:119] offset:9216
	ds_write_b128 v60, v[112:115] offset:13824
	s_waitcnt vmcnt(4)
	ds_write_b128 v60, v[144:147] offset:18432
	ds_write_b128 v60, v[140:143] offset:23040
	s_waitcnt vmcnt(2)
	ds_write_b128 v60, v[148:151] offset:27648
	ds_write_b128 v60, v[120:123] offset:32256
	s_waitcnt vmcnt(0)
	ds_write_b128 v60, v[156:159] offset:36864
	ds_write_b128 v60, v[152:155] offset:41472
	ds_write_b128 v60, v[108:111] offset:46080
	ds_write_b128 v60, v[100:103] offset:50688
	v_mfma_f32_32x32x16_bf16 a[80:95], v[160:163], v[128:131], a[80:95]
	v_mfma_f32_32x32x16_bf16 a[64:79], v[160:163], v[168:171], a[64:79]
	s_waitcnt lgkmcnt(12)
	v_mfma_f32_32x32x16_bf16 a[48:63], v[104:107], v[128:131], a[48:63]
	v_mfma_f32_32x32x16_bf16 a[32:47], v[104:107], v[168:171], a[32:47]
	ds_read_b128 v[100:103], v59 offset:55328
	ds_read_b128 v[104:107], v69 offset:32
	ds_read_b128 v[108:111], v69 offset:64
	ds_read_b128 v[112:115], v59 offset:55360
	ds_read_b128 v[116:119], v69 offset:4640
	ds_read_b128 v[120:123], v69 offset:96
	s_waitcnt lgkmcnt(4)
	v_mfma_f32_32x32x16_bf16 a[112:127], v[100:103], v[104:107], a[112:127]
	s_waitcnt lgkmcnt(1)
	v_mfma_f32_32x32x16_bf16 a[96:111], v[100:103], v[116:119], a[96:111]
	ds_read_b128 v[100:103], v59 offset:59936
	ds_read_b128 v[124:127], v59 offset:55392
	v_mfma_f32_32x32x16_bf16 a[16:31], v[164:167], v[128:131], a[16:31]
	v_mfma_f32_32x32x16_bf16 a[0:15], v[164:167], v[168:171], a[0:15]
	s_waitcnt lgkmcnt(1)
	v_mfma_f32_32x32x16_bf16 a[80:95], v[100:103], v[104:107], a[80:95]
	v_mfma_f32_32x32x16_bf16 a[64:79], v[100:103], v[116:119], a[64:79]
	ds_read_b128 v[100:103], v59 offset:64544
	ds_read_b128 v[128:131], v59 offset:64576
	s_waitcnt lgkmcnt(1)
	v_mfma_f32_32x32x16_bf16 a[48:63], v[100:103], v[104:107], a[48:63]
	v_mfma_f32_32x32x16_bf16 a[32:47], v[100:103], v[116:119], a[32:47]
	ds_read_b128 v[100:103], v61 offset:55328
	ds_read_b128 v[136:139], v59 offset:64608
	s_waitcnt lgkmcnt(1)
	v_mfma_f32_32x32x16_bf16 a[16:31], v[100:103], v[104:107], a[16:31]
	v_mfma_f32_32x32x16_bf16 a[0:15], v[100:103], v[116:119], a[0:15]
	ds_read_b128 v[100:103], v69 offset:4672
	ds_read_b128 v[104:107], v69 offset:4704
	v_mfma_f32_32x32x16_bf16 a[112:127], v[112:115], v[108:111], a[112:127]
	s_waitcnt lgkmcnt(1)
	v_mfma_f32_32x32x16_bf16 a[96:111], v[112:115], v[100:103], a[96:111]
	ds_read_b128 v[112:115], v59 offset:59968
	ds_read_b128 v[116:119], v59 offset:60000
	s_waitcnt lgkmcnt(1)
	v_mfma_f32_32x32x16_bf16 a[80:95], v[112:115], v[108:111], a[80:95]
	v_mfma_f32_32x32x16_bf16 a[64:79], v[112:115], v[100:103], a[64:79]
	v_mfma_f32_32x32x16_bf16 a[48:63], v[128:131], v[108:111], a[48:63]
	v_mfma_f32_32x32x16_bf16 a[32:47], v[128:131], v[100:103], a[32:47]
	ds_read_b128 v[112:115], v61 offset:55360
	ds_read_b128 v[128:131], v61 offset:55392
	s_waitcnt lgkmcnt(1)
	v_mfma_f32_32x32x16_bf16 a[16:31], v[112:115], v[108:111], a[16:31]
	v_mfma_f32_32x32x16_bf16 a[0:15], v[112:115], v[100:103], a[0:15]
	v_mfma_f32_32x32x16_bf16 a[112:127], v[124:127], v[120:123], a[112:127]
	v_mfma_f32_32x32x16_bf16 a[96:111], v[124:127], v[104:107], a[96:111]
	v_mfma_f32_32x32x16_bf16 a[80:95], v[116:119], v[120:123], a[80:95]
	v_mfma_f32_32x32x16_bf16 a[64:79], v[116:119], v[104:107], a[64:79]
	global_load_dwordx4 v[100:103], v[4:5], off offset:1152
	global_load_dwordx4 v[108:111], v[0:1], off offset:1152
	global_load_dwordx4 v[112:115], v[18:19], off offset:1152
	global_load_dwordx4 v[116:119], v[6:7], off offset:1152
	v_mfma_f32_32x32x16_bf16 a[48:63], v[136:139], v[120:123], a[48:63]
	v_mfma_f32_32x32x16_bf16 a[32:47], v[136:139], v[104:107], a[32:47]
	global_load_dwordx4 v[124:127], v[20:21], off offset:1152
	global_load_dwordx4 v[136:139], v[22:23], off offset:1152
	global_load_dwordx4 v[140:143], v[26:27], off offset:1152
	global_load_dwordx4 v[144:147], v[24:25], off offset:1152
	global_load_dwordx4 v[148:151], v[28:29], off offset:1152
	global_load_dwordx4 v[152:155], v[2:3], off offset:1152
	global_load_dwordx4 v[156:159], v[30:31], off offset:1152
	s_waitcnt lgkmcnt(0)
	v_mfma_f32_32x32x16_bf16 a[16:31], v[128:131], v[120:123], a[16:31]
	global_load_dwordx4 v[120:123], v[32:33], off offset:1152
	s_barrier
	v_mfma_f32_32x32x16_bf16 a[0:15], v[128:131], v[104:107], a[0:15]
	ds_read_b128 v[104:107], v59
	ds_read_b128 v[128:131], v62 offset:36864
	ds_read_b128 v[160:163], v59 offset:4608
	ds_read_b128 v[164:167], v61
	ds_read_b128 v[168:171], v62 offset:41472
	s_waitcnt lgkmcnt(3)
	v_mfma_f32_32x32x16_bf16 a[112:127], v[104:107], v[128:131], a[112:127]
	s_waitcnt lgkmcnt(0)
	v_mfma_f32_32x32x16_bf16 a[96:111], v[104:107], v[168:171], a[96:111]
	ds_read_b128 v[104:107], v59 offset:9216
	s_waitcnt vmcnt(10)
	ds_write_b128 v60, v[108:111] offset:55296
	ds_write_b128 v60, v[100:103] offset:59904
	s_waitcnt vmcnt(8)
	ds_write_b128 v60, v[116:119] offset:64512
	ds_write_b128 v63, v[112:115] offset:55296
	s_waitcnt vmcnt(7)
	ds_write_b128 v64, v[124:127] offset:55296
	s_waitcnt vmcnt(6)
	ds_write_b128 v65, v[136:139] offset:55296
	s_waitcnt vmcnt(4)
	ds_write_b128 v66, v[144:147] offset:55296
	ds_write_b128 v67, v[140:143] offset:55296
	s_waitcnt vmcnt(2)
	ds_write_b128 v68, v[152:155]
	ds_write_b128 v68, v[148:151] offset:4608
	s_waitcnt vmcnt(1)
	ds_write_b128 v68, v[156:159] offset:9216
	s_waitcnt vmcnt(0)
	ds_write_b128 v68, v[120:123] offset:13824
	v_mfma_f32_32x32x16_bf16 a[80:95], v[160:163], v[128:131], a[80:95]
	v_mfma_f32_32x32x16_bf16 a[64:79], v[160:163], v[168:171], a[64:79]
	s_waitcnt lgkmcnt(12)
	v_mfma_f32_32x32x16_bf16 a[48:63], v[104:107], v[128:131], a[48:63]
	v_mfma_f32_32x32x16_bf16 a[32:47], v[104:107], v[168:171], a[32:47]
	ds_read_b128 v[100:103], v59 offset:32
	ds_read_b128 v[104:107], v62 offset:36896
	ds_read_b128 v[108:111], v62 offset:36928
	ds_read_b128 v[112:115], v59 offset:64
	ds_read_b128 v[116:119], v62 offset:41504
	ds_read_b128 v[120:123], v62 offset:36960
	s_waitcnt lgkmcnt(4)
	v_mfma_f32_32x32x16_bf16 a[112:127], v[100:103], v[104:107], a[112:127]
	s_waitcnt lgkmcnt(1)
	v_mfma_f32_32x32x16_bf16 a[96:111], v[100:103], v[116:119], a[96:111]
	ds_read_b128 v[100:103], v59 offset:4640
	ds_read_b128 v[124:127], v59 offset:96
	v_mfma_f32_32x32x16_bf16 a[16:31], v[164:167], v[128:131], a[16:31]
	v_mfma_f32_32x32x16_bf16 a[0:15], v[164:167], v[168:171], a[0:15]
	s_waitcnt lgkmcnt(1)
	v_mfma_f32_32x32x16_bf16 a[80:95], v[100:103], v[104:107], a[80:95]
	v_mfma_f32_32x32x16_bf16 a[64:79], v[100:103], v[116:119], a[64:79]
	ds_read_b128 v[100:103], v59 offset:9248
	ds_read_b128 v[128:131], v59 offset:9280
	s_waitcnt lgkmcnt(1)
	v_mfma_f32_32x32x16_bf16 a[48:63], v[100:103], v[104:107], a[48:63]
	v_mfma_f32_32x32x16_bf16 a[32:47], v[100:103], v[116:119], a[32:47]
	ds_read_b128 v[100:103], v61 offset:32
	ds_read_b128 v[136:139], v59 offset:9312
	s_waitcnt lgkmcnt(1)
	v_mfma_f32_32x32x16_bf16 a[16:31], v[100:103], v[104:107], a[16:31]
	v_mfma_f32_32x32x16_bf16 a[0:15], v[100:103], v[116:119], a[0:15]
	ds_read_b128 v[100:103], v62 offset:41536
	ds_read_b128 v[104:107], v62 offset:41568
	v_mfma_f32_32x32x16_bf16 a[112:127], v[112:115], v[108:111], a[112:127]
	s_waitcnt lgkmcnt(1)
	v_mfma_f32_32x32x16_bf16 a[96:111], v[112:115], v[100:103], a[96:111]
	ds_read_b128 v[112:115], v59 offset:4672
	ds_read_b128 v[116:119], v59 offset:4704
	s_waitcnt lgkmcnt(1)
	v_mfma_f32_32x32x16_bf16 a[80:95], v[112:115], v[108:111], a[80:95]
	v_mfma_f32_32x32x16_bf16 a[64:79], v[112:115], v[100:103], a[64:79]
	v_mfma_f32_32x32x16_bf16 a[48:63], v[128:131], v[108:111], a[48:63]
	v_mfma_f32_32x32x16_bf16 a[32:47], v[128:131], v[100:103], a[32:47]
	ds_read_b128 v[112:115], v61 offset:64
	ds_read_b128 v[128:131], v61 offset:96
	s_waitcnt lgkmcnt(1)
	v_mfma_f32_32x32x16_bf16 a[16:31], v[112:115], v[108:111], a[16:31]
	v_mfma_f32_32x32x16_bf16 a[0:15], v[112:115], v[100:103], a[0:15]
	global_load_dwordx4 v[100:103], v[32:33], off offset:1280
	v_mfma_f32_32x32x16_bf16 a[112:127], v[124:127], v[120:123], a[112:127]
	v_mfma_f32_32x32x16_bf16 a[96:111], v[124:127], v[104:107], a[96:111]
	v_mfma_f32_32x32x16_bf16 a[80:95], v[116:119], v[120:123], a[80:95]
	v_mfma_f32_32x32x16_bf16 a[64:79], v[116:119], v[104:107], a[64:79]
	v_mfma_f32_32x32x16_bf16 a[48:63], v[136:139], v[120:123], a[48:63]
	v_mfma_f32_32x32x16_bf16 a[32:47], v[136:139], v[104:107], a[32:47]
	global_load_dwordx4 v[108:111], v[30:31], off offset:1280
	global_load_dwordx4 v[112:115], v[18:19], off offset:1280
	global_load_dwordx4 v[116:119], v[6:7], off offset:1280
	global_load_dwordx4 v[124:127], v[4:5], off offset:1280
	global_load_dwordx4 v[136:139], v[0:1], off offset:1280
	global_load_dwordx4 v[140:143], v[22:23], off offset:1280
	global_load_dwordx4 v[144:147], v[20:21], off offset:1280
	s_waitcnt lgkmcnt(0)
	v_mfma_f32_32x32x16_bf16 a[16:31], v[128:131], v[120:123], a[16:31]
	global_load_dwordx4 v[120:123], v[26:27], off offset:1280
	global_load_dwordx4 v[148:151], v[24:25], off offset:1280
	global_load_dwordx4 v[152:155], v[28:29], off offset:1280
	global_load_dwordx4 v[156:159], v[2:3], off offset:1280
	s_barrier
	v_mfma_f32_32x32x16_bf16 a[0:15], v[128:131], v[104:107], a[0:15]
	ds_read_b128 v[104:107], v59 offset:55296
	ds_read_b128 v[128:131], v69
	ds_read_b128 v[160:163], v59 offset:59904
	ds_read_b128 v[164:167], v61 offset:55296
	ds_read_b128 v[168:171], v69 offset:4608
	s_waitcnt lgkmcnt(3)
	v_mfma_f32_32x32x16_bf16 a[112:127], v[104:107], v[128:131], a[112:127]
	s_waitcnt lgkmcnt(0)
	v_mfma_f32_32x32x16_bf16 a[96:111], v[104:107], v[168:171], a[96:111]
	ds_read_b128 v[104:107], v59 offset:64512
	s_waitcnt vmcnt(6)
	ds_write_b128 v60, v[136:139]
	ds_write_b128 v60, v[124:127] offset:4608
	ds_write_b128 v60, v[116:119] offset:9216
	ds_write_b128 v60, v[112:115] offset:13824
	s_waitcnt vmcnt(4)
	ds_write_b128 v60, v[144:147] offset:18432
	ds_write_b128 v60, v[140:143] offset:23040
	s_waitcnt vmcnt(2)
	ds_write_b128 v60, v[148:151] offset:27648
	ds_write_b128 v60, v[120:123] offset:32256
	s_waitcnt vmcnt(0)
	ds_write_b128 v60, v[156:159] offset:36864
	ds_write_b128 v60, v[152:155] offset:41472
	ds_write_b128 v60, v[108:111] offset:46080
	ds_write_b128 v60, v[100:103] offset:50688
	v_mfma_f32_32x32x16_bf16 a[80:95], v[160:163], v[128:131], a[80:95]
	v_mfma_f32_32x32x16_bf16 a[64:79], v[160:163], v[168:171], a[64:79]
	s_waitcnt lgkmcnt(12)
	v_mfma_f32_32x32x16_bf16 a[48:63], v[104:107], v[128:131], a[48:63]
	v_mfma_f32_32x32x16_bf16 a[32:47], v[104:107], v[168:171], a[32:47]
	ds_read_b128 v[100:103], v59 offset:55328
	ds_read_b128 v[104:107], v69 offset:32
	ds_read_b128 v[108:111], v69 offset:64
	ds_read_b128 v[112:115], v59 offset:55360
	ds_read_b128 v[116:119], v69 offset:4640
	ds_read_b128 v[120:123], v69 offset:96
	s_waitcnt lgkmcnt(4)
	v_mfma_f32_32x32x16_bf16 a[112:127], v[100:103], v[104:107], a[112:127]
	s_waitcnt lgkmcnt(1)
	v_mfma_f32_32x32x16_bf16 a[96:111], v[100:103], v[116:119], a[96:111]
	ds_read_b128 v[100:103], v59 offset:59936
	ds_read_b128 v[124:127], v59 offset:55392
	v_mfma_f32_32x32x16_bf16 a[16:31], v[164:167], v[128:131], a[16:31]
	v_mfma_f32_32x32x16_bf16 a[0:15], v[164:167], v[168:171], a[0:15]
	s_waitcnt lgkmcnt(1)
	v_mfma_f32_32x32x16_bf16 a[80:95], v[100:103], v[104:107], a[80:95]
	v_mfma_f32_32x32x16_bf16 a[64:79], v[100:103], v[116:119], a[64:79]
	ds_read_b128 v[100:103], v59 offset:64544
	ds_read_b128 v[128:131], v59 offset:64576
	s_waitcnt lgkmcnt(1)
	v_mfma_f32_32x32x16_bf16 a[48:63], v[100:103], v[104:107], a[48:63]
	v_mfma_f32_32x32x16_bf16 a[32:47], v[100:103], v[116:119], a[32:47]
	ds_read_b128 v[100:103], v61 offset:55328
	ds_read_b128 v[136:139], v59 offset:64608
	s_waitcnt lgkmcnt(1)
	v_mfma_f32_32x32x16_bf16 a[16:31], v[100:103], v[104:107], a[16:31]
	v_mfma_f32_32x32x16_bf16 a[0:15], v[100:103], v[116:119], a[0:15]
	ds_read_b128 v[100:103], v69 offset:4672
	ds_read_b128 v[104:107], v69 offset:4704
	v_mfma_f32_32x32x16_bf16 a[112:127], v[112:115], v[108:111], a[112:127]
	s_waitcnt lgkmcnt(1)
	v_mfma_f32_32x32x16_bf16 a[96:111], v[112:115], v[100:103], a[96:111]
	ds_read_b128 v[112:115], v59 offset:59968
	ds_read_b128 v[116:119], v59 offset:60000
	s_waitcnt lgkmcnt(1)
	v_mfma_f32_32x32x16_bf16 a[80:95], v[112:115], v[108:111], a[80:95]
	v_mfma_f32_32x32x16_bf16 a[64:79], v[112:115], v[100:103], a[64:79]
	v_mfma_f32_32x32x16_bf16 a[48:63], v[128:131], v[108:111], a[48:63]
	v_mfma_f32_32x32x16_bf16 a[32:47], v[128:131], v[100:103], a[32:47]
	ds_read_b128 v[112:115], v61 offset:55360
	ds_read_b128 v[128:131], v61 offset:55392
	s_waitcnt lgkmcnt(1)
	v_mfma_f32_32x32x16_bf16 a[16:31], v[112:115], v[108:111], a[16:31]
	v_mfma_f32_32x32x16_bf16 a[0:15], v[112:115], v[100:103], a[0:15]
	v_mfma_f32_32x32x16_bf16 a[112:127], v[124:127], v[120:123], a[112:127]
	v_mfma_f32_32x32x16_bf16 a[96:111], v[124:127], v[104:107], a[96:111]
	v_mfma_f32_32x32x16_bf16 a[80:95], v[116:119], v[120:123], a[80:95]
	v_mfma_f32_32x32x16_bf16 a[64:79], v[116:119], v[104:107], a[64:79]
	global_load_dwordx4 v[100:103], v[4:5], off offset:1408
	global_load_dwordx4 v[108:111], v[0:1], off offset:1408
	global_load_dwordx4 v[112:115], v[18:19], off offset:1408
	global_load_dwordx4 v[116:119], v[6:7], off offset:1408
	v_mfma_f32_32x32x16_bf16 a[48:63], v[136:139], v[120:123], a[48:63]
	v_mfma_f32_32x32x16_bf16 a[32:47], v[136:139], v[104:107], a[32:47]
	global_load_dwordx4 v[124:127], v[20:21], off offset:1408
	global_load_dwordx4 v[136:139], v[22:23], off offset:1408
	global_load_dwordx4 v[140:143], v[26:27], off offset:1408
	global_load_dwordx4 v[144:147], v[24:25], off offset:1408
	global_load_dwordx4 v[148:151], v[28:29], off offset:1408
	global_load_dwordx4 v[152:155], v[2:3], off offset:1408
	global_load_dwordx4 v[156:159], v[30:31], off offset:1408
	s_waitcnt lgkmcnt(0)
	v_mfma_f32_32x32x16_bf16 a[16:31], v[128:131], v[120:123], a[16:31]
	global_load_dwordx4 v[120:123], v[32:33], off offset:1408
	s_barrier
	v_mfma_f32_32x32x16_bf16 a[0:15], v[128:131], v[104:107], a[0:15]
	ds_read_b128 v[104:107], v59
	ds_read_b128 v[128:131], v62 offset:36864
	ds_read_b128 v[160:163], v59 offset:4608
	ds_read_b128 v[164:167], v61
	ds_read_b128 v[168:171], v62 offset:41472
	s_waitcnt lgkmcnt(3)
	v_mfma_f32_32x32x16_bf16 a[112:127], v[104:107], v[128:131], a[112:127]
	s_waitcnt lgkmcnt(0)
	v_mfma_f32_32x32x16_bf16 a[96:111], v[104:107], v[168:171], a[96:111]
	ds_read_b128 v[104:107], v59 offset:9216
	s_waitcnt vmcnt(10)
	ds_write_b128 v60, v[108:111] offset:55296
	ds_write_b128 v60, v[100:103] offset:59904
	s_waitcnt vmcnt(8)
	ds_write_b128 v60, v[116:119] offset:64512
	ds_write_b128 v63, v[112:115] offset:55296
	s_waitcnt vmcnt(7)
	ds_write_b128 v64, v[124:127] offset:55296
	s_waitcnt vmcnt(6)
	ds_write_b128 v65, v[136:139] offset:55296
	s_waitcnt vmcnt(4)
	ds_write_b128 v66, v[144:147] offset:55296
	ds_write_b128 v67, v[140:143] offset:55296
	s_waitcnt vmcnt(2)
	ds_write_b128 v68, v[152:155]
	ds_write_b128 v68, v[148:151] offset:4608
	s_waitcnt vmcnt(1)
	ds_write_b128 v68, v[156:159] offset:9216
	s_waitcnt vmcnt(0)
	ds_write_b128 v68, v[120:123] offset:13824
	v_mfma_f32_32x32x16_bf16 a[80:95], v[160:163], v[128:131], a[80:95]
	v_mfma_f32_32x32x16_bf16 a[64:79], v[160:163], v[168:171], a[64:79]
	s_waitcnt lgkmcnt(12)
	v_mfma_f32_32x32x16_bf16 a[48:63], v[104:107], v[128:131], a[48:63]
	v_mfma_f32_32x32x16_bf16 a[32:47], v[104:107], v[168:171], a[32:47]
	ds_read_b128 v[100:103], v59 offset:32
	ds_read_b128 v[104:107], v62 offset:36896
	ds_read_b128 v[108:111], v62 offset:36928
	ds_read_b128 v[112:115], v59 offset:64
	ds_read_b128 v[116:119], v62 offset:41504
	ds_read_b128 v[120:123], v62 offset:36960
	s_waitcnt lgkmcnt(4)
	v_mfma_f32_32x32x16_bf16 a[112:127], v[100:103], v[104:107], a[112:127]
	s_waitcnt lgkmcnt(1)
	v_mfma_f32_32x32x16_bf16 a[96:111], v[100:103], v[116:119], a[96:111]
	ds_read_b128 v[100:103], v59 offset:4640
	ds_read_b128 v[124:127], v59 offset:96
	v_mfma_f32_32x32x16_bf16 a[16:31], v[164:167], v[128:131], a[16:31]
	v_mfma_f32_32x32x16_bf16 a[0:15], v[164:167], v[168:171], a[0:15]
	s_waitcnt lgkmcnt(1)
	v_mfma_f32_32x32x16_bf16 a[80:95], v[100:103], v[104:107], a[80:95]
	v_mfma_f32_32x32x16_bf16 a[64:79], v[100:103], v[116:119], a[64:79]
	ds_read_b128 v[100:103], v59 offset:9248
	ds_read_b128 v[128:131], v59 offset:9280
	s_waitcnt lgkmcnt(1)
	v_mfma_f32_32x32x16_bf16 a[48:63], v[100:103], v[104:107], a[48:63]
	v_mfma_f32_32x32x16_bf16 a[32:47], v[100:103], v[116:119], a[32:47]
	ds_read_b128 v[100:103], v61 offset:32
	ds_read_b128 v[136:139], v59 offset:9312
	s_waitcnt lgkmcnt(1)
	v_mfma_f32_32x32x16_bf16 a[16:31], v[100:103], v[104:107], a[16:31]
	v_mfma_f32_32x32x16_bf16 a[0:15], v[100:103], v[116:119], a[0:15]
	ds_read_b128 v[100:103], v62 offset:41536
	ds_read_b128 v[104:107], v62 offset:41568
	v_mfma_f32_32x32x16_bf16 a[112:127], v[112:115], v[108:111], a[112:127]
	s_waitcnt lgkmcnt(1)
	v_mfma_f32_32x32x16_bf16 a[96:111], v[112:115], v[100:103], a[96:111]
	ds_read_b128 v[112:115], v59 offset:4672
	ds_read_b128 v[116:119], v59 offset:4704
	s_waitcnt lgkmcnt(1)
	v_mfma_f32_32x32x16_bf16 a[80:95], v[112:115], v[108:111], a[80:95]
	v_mfma_f32_32x32x16_bf16 a[64:79], v[112:115], v[100:103], a[64:79]
	v_mfma_f32_32x32x16_bf16 a[48:63], v[128:131], v[108:111], a[48:63]
	v_mfma_f32_32x32x16_bf16 a[32:47], v[128:131], v[100:103], a[32:47]
	ds_read_b128 v[112:115], v61 offset:64
	ds_read_b128 v[128:131], v61 offset:96
	s_waitcnt lgkmcnt(1)
	v_mfma_f32_32x32x16_bf16 a[16:31], v[112:115], v[108:111], a[16:31]
	v_mfma_f32_32x32x16_bf16 a[0:15], v[112:115], v[100:103], a[0:15]
	global_load_dwordx4 v[100:103], v[32:33], off offset:1536
	v_mfma_f32_32x32x16_bf16 a[112:127], v[124:127], v[120:123], a[112:127]
	v_mfma_f32_32x32x16_bf16 a[96:111], v[124:127], v[104:107], a[96:111]
	v_mfma_f32_32x32x16_bf16 a[80:95], v[116:119], v[120:123], a[80:95]
	v_mfma_f32_32x32x16_bf16 a[64:79], v[116:119], v[104:107], a[64:79]
	v_mfma_f32_32x32x16_bf16 a[48:63], v[136:139], v[120:123], a[48:63]
	v_mfma_f32_32x32x16_bf16 a[32:47], v[136:139], v[104:107], a[32:47]
	global_load_dwordx4 v[108:111], v[30:31], off offset:1536
	global_load_dwordx4 v[112:115], v[18:19], off offset:1536
	global_load_dwordx4 v[116:119], v[6:7], off offset:1536
	global_load_dwordx4 v[124:127], v[4:5], off offset:1536
	global_load_dwordx4 v[136:139], v[0:1], off offset:1536
	global_load_dwordx4 v[140:143], v[22:23], off offset:1536
	global_load_dwordx4 v[144:147], v[20:21], off offset:1536
	s_waitcnt lgkmcnt(0)
	v_mfma_f32_32x32x16_bf16 a[16:31], v[128:131], v[120:123], a[16:31]
	global_load_dwordx4 v[120:123], v[26:27], off offset:1536
	global_load_dwordx4 v[148:151], v[24:25], off offset:1536
	global_load_dwordx4 v[152:155], v[28:29], off offset:1536
	global_load_dwordx4 v[156:159], v[2:3], off offset:1536
	s_barrier
	v_mfma_f32_32x32x16_bf16 a[0:15], v[128:131], v[104:107], a[0:15]
	ds_read_b128 v[104:107], v59 offset:55296
	ds_read_b128 v[128:131], v69
	ds_read_b128 v[160:163], v59 offset:59904
	ds_read_b128 v[164:167], v61 offset:55296
	ds_read_b128 v[168:171], v69 offset:4608
	s_waitcnt lgkmcnt(3)
	v_mfma_f32_32x32x16_bf16 a[112:127], v[104:107], v[128:131], a[112:127]
	s_waitcnt lgkmcnt(0)
	v_mfma_f32_32x32x16_bf16 a[96:111], v[104:107], v[168:171], a[96:111]
	ds_read_b128 v[104:107], v59 offset:64512
	s_waitcnt vmcnt(6)
	ds_write_b128 v60, v[136:139]
	ds_write_b128 v60, v[124:127] offset:4608
	ds_write_b128 v60, v[116:119] offset:9216
	ds_write_b128 v60, v[112:115] offset:13824
	s_waitcnt vmcnt(4)
	ds_write_b128 v60, v[144:147] offset:18432
	ds_write_b128 v60, v[140:143] offset:23040
	s_waitcnt vmcnt(2)
	ds_write_b128 v60, v[148:151] offset:27648
	ds_write_b128 v60, v[120:123] offset:32256
	s_waitcnt vmcnt(0)
	ds_write_b128 v60, v[156:159] offset:36864
	ds_write_b128 v60, v[152:155] offset:41472
	ds_write_b128 v60, v[108:111] offset:46080
	ds_write_b128 v60, v[100:103] offset:50688
	v_mfma_f32_32x32x16_bf16 a[80:95], v[160:163], v[128:131], a[80:95]
	v_mfma_f32_32x32x16_bf16 a[64:79], v[160:163], v[168:171], a[64:79]
	s_waitcnt lgkmcnt(12)
	v_mfma_f32_32x32x16_bf16 a[48:63], v[104:107], v[128:131], a[48:63]
	v_mfma_f32_32x32x16_bf16 a[32:47], v[104:107], v[168:171], a[32:47]
	ds_read_b128 v[100:103], v59 offset:55328
	ds_read_b128 v[104:107], v69 offset:32
	ds_read_b128 v[108:111], v69 offset:64
	ds_read_b128 v[112:115], v59 offset:55360
	ds_read_b128 v[116:119], v69 offset:4640
	ds_read_b128 v[120:123], v69 offset:96
	s_waitcnt lgkmcnt(4)
	v_mfma_f32_32x32x16_bf16 a[112:127], v[100:103], v[104:107], a[112:127]
	s_waitcnt lgkmcnt(1)
	v_mfma_f32_32x32x16_bf16 a[96:111], v[100:103], v[116:119], a[96:111]
	ds_read_b128 v[100:103], v59 offset:59936
	ds_read_b128 v[124:127], v59 offset:55392
	v_mfma_f32_32x32x16_bf16 a[16:31], v[164:167], v[128:131], a[16:31]
	v_mfma_f32_32x32x16_bf16 a[0:15], v[164:167], v[168:171], a[0:15]
	s_waitcnt lgkmcnt(1)
	v_mfma_f32_32x32x16_bf16 a[80:95], v[100:103], v[104:107], a[80:95]
	v_mfma_f32_32x32x16_bf16 a[64:79], v[100:103], v[116:119], a[64:79]
	ds_read_b128 v[100:103], v59 offset:64544
	ds_read_b128 v[128:131], v59 offset:64576
	s_waitcnt lgkmcnt(1)
	v_mfma_f32_32x32x16_bf16 a[48:63], v[100:103], v[104:107], a[48:63]
	v_mfma_f32_32x32x16_bf16 a[32:47], v[100:103], v[116:119], a[32:47]
	ds_read_b128 v[100:103], v61 offset:55328
	ds_read_b128 v[136:139], v59 offset:64608
	s_waitcnt lgkmcnt(1)
	v_mfma_f32_32x32x16_bf16 a[16:31], v[100:103], v[104:107], a[16:31]
	v_mfma_f32_32x32x16_bf16 a[0:15], v[100:103], v[116:119], a[0:15]
	ds_read_b128 v[100:103], v69 offset:4672
	ds_read_b128 v[104:107], v69 offset:4704
	v_mfma_f32_32x32x16_bf16 a[112:127], v[112:115], v[108:111], a[112:127]
	s_waitcnt lgkmcnt(1)
	v_mfma_f32_32x32x16_bf16 a[96:111], v[112:115], v[100:103], a[96:111]
	ds_read_b128 v[112:115], v59 offset:59968
	ds_read_b128 v[116:119], v59 offset:60000
	s_waitcnt lgkmcnt(1)
	v_mfma_f32_32x32x16_bf16 a[80:95], v[112:115], v[108:111], a[80:95]
	v_mfma_f32_32x32x16_bf16 a[64:79], v[112:115], v[100:103], a[64:79]
	v_mfma_f32_32x32x16_bf16 a[48:63], v[128:131], v[108:111], a[48:63]
	v_mfma_f32_32x32x16_bf16 a[32:47], v[128:131], v[100:103], a[32:47]
	ds_read_b128 v[112:115], v61 offset:55360
	ds_read_b128 v[128:131], v61 offset:55392
	s_waitcnt lgkmcnt(1)
	v_mfma_f32_32x32x16_bf16 a[16:31], v[112:115], v[108:111], a[16:31]
	v_mfma_f32_32x32x16_bf16 a[0:15], v[112:115], v[100:103], a[0:15]
	v_mfma_f32_32x32x16_bf16 a[112:127], v[124:127], v[120:123], a[112:127]
	v_mfma_f32_32x32x16_bf16 a[96:111], v[124:127], v[104:107], a[96:111]
	v_mfma_f32_32x32x16_bf16 a[80:95], v[116:119], v[120:123], a[80:95]
	v_mfma_f32_32x32x16_bf16 a[64:79], v[116:119], v[104:107], a[64:79]
	global_load_dwordx4 v[100:103], v[4:5], off offset:1664
	global_load_dwordx4 v[108:111], v[0:1], off offset:1664
	global_load_dwordx4 v[112:115], v[18:19], off offset:1664
	global_load_dwordx4 v[116:119], v[6:7], off offset:1664
	v_mfma_f32_32x32x16_bf16 a[48:63], v[136:139], v[120:123], a[48:63]
	v_mfma_f32_32x32x16_bf16 a[32:47], v[136:139], v[104:107], a[32:47]
	global_load_dwordx4 v[124:127], v[20:21], off offset:1664
	global_load_dwordx4 v[136:139], v[22:23], off offset:1664
	global_load_dwordx4 v[140:143], v[26:27], off offset:1664
	global_load_dwordx4 v[144:147], v[24:25], off offset:1664
	global_load_dwordx4 v[148:151], v[28:29], off offset:1664
	global_load_dwordx4 v[152:155], v[2:3], off offset:1664
	global_load_dwordx4 v[156:159], v[30:31], off offset:1664
	s_waitcnt lgkmcnt(0)
	v_mfma_f32_32x32x16_bf16 a[16:31], v[128:131], v[120:123], a[16:31]
	global_load_dwordx4 v[120:123], v[32:33], off offset:1664
	s_barrier
	v_mfma_f32_32x32x16_bf16 a[0:15], v[128:131], v[104:107], a[0:15]
	ds_read_b128 v[104:107], v59
	ds_read_b128 v[128:131], v62 offset:36864
	ds_read_b128 v[160:163], v59 offset:4608
	ds_read_b128 v[164:167], v61
	ds_read_b128 v[168:171], v62 offset:41472
	s_waitcnt lgkmcnt(3)
	v_mfma_f32_32x32x16_bf16 a[112:127], v[104:107], v[128:131], a[112:127]
	s_waitcnt lgkmcnt(0)
	v_mfma_f32_32x32x16_bf16 a[96:111], v[104:107], v[168:171], a[96:111]
	ds_read_b128 v[104:107], v59 offset:9216
	s_waitcnt vmcnt(10)
	ds_write_b128 v60, v[108:111] offset:55296
	ds_write_b128 v60, v[100:103] offset:59904
	s_waitcnt vmcnt(8)
	ds_write_b128 v60, v[116:119] offset:64512
	ds_write_b128 v63, v[112:115] offset:55296
	s_waitcnt vmcnt(7)
	ds_write_b128 v64, v[124:127] offset:55296
	s_waitcnt vmcnt(6)
	ds_write_b128 v65, v[136:139] offset:55296
	s_waitcnt vmcnt(4)
	ds_write_b128 v66, v[144:147] offset:55296
	ds_write_b128 v67, v[140:143] offset:55296
	s_waitcnt vmcnt(2)
	ds_write_b128 v68, v[152:155]
	ds_write_b128 v68, v[148:151] offset:4608
	s_waitcnt vmcnt(1)
	ds_write_b128 v68, v[156:159] offset:9216
	s_waitcnt vmcnt(0)
	ds_write_b128 v68, v[120:123] offset:13824
	v_mfma_f32_32x32x16_bf16 a[80:95], v[160:163], v[128:131], a[80:95]
	v_mfma_f32_32x32x16_bf16 a[64:79], v[160:163], v[168:171], a[64:79]
	s_waitcnt lgkmcnt(12)
	v_mfma_f32_32x32x16_bf16 a[48:63], v[104:107], v[128:131], a[48:63]
	v_mfma_f32_32x32x16_bf16 a[32:47], v[104:107], v[168:171], a[32:47]
	ds_read_b128 v[100:103], v59 offset:32
	ds_read_b128 v[104:107], v62 offset:36896
	ds_read_b128 v[108:111], v62 offset:36928
	ds_read_b128 v[112:115], v59 offset:64
	ds_read_b128 v[116:119], v62 offset:41504
	ds_read_b128 v[120:123], v62 offset:36960
	s_waitcnt lgkmcnt(4)
	v_mfma_f32_32x32x16_bf16 a[112:127], v[100:103], v[104:107], a[112:127]
	s_waitcnt lgkmcnt(1)
	v_mfma_f32_32x32x16_bf16 a[96:111], v[100:103], v[116:119], a[96:111]
	ds_read_b128 v[100:103], v59 offset:4640
	ds_read_b128 v[124:127], v59 offset:96
	v_mfma_f32_32x32x16_bf16 a[16:31], v[164:167], v[128:131], a[16:31]
	v_mfma_f32_32x32x16_bf16 a[0:15], v[164:167], v[168:171], a[0:15]
	s_waitcnt lgkmcnt(1)
	v_mfma_f32_32x32x16_bf16 a[80:95], v[100:103], v[104:107], a[80:95]
	v_mfma_f32_32x32x16_bf16 a[64:79], v[100:103], v[116:119], a[64:79]
	ds_read_b128 v[100:103], v59 offset:9248
	ds_read_b128 v[128:131], v59 offset:9280
	s_waitcnt lgkmcnt(1)
	v_mfma_f32_32x32x16_bf16 a[48:63], v[100:103], v[104:107], a[48:63]
	v_mfma_f32_32x32x16_bf16 a[32:47], v[100:103], v[116:119], a[32:47]
	ds_read_b128 v[100:103], v61 offset:32
	ds_read_b128 v[136:139], v59 offset:9312
	s_waitcnt lgkmcnt(1)
	v_mfma_f32_32x32x16_bf16 a[16:31], v[100:103], v[104:107], a[16:31]
	v_mfma_f32_32x32x16_bf16 a[0:15], v[100:103], v[116:119], a[0:15]
	ds_read_b128 v[100:103], v62 offset:41536
	ds_read_b128 v[104:107], v62 offset:41568
	v_mfma_f32_32x32x16_bf16 a[112:127], v[112:115], v[108:111], a[112:127]
	s_waitcnt lgkmcnt(1)
	v_mfma_f32_32x32x16_bf16 a[96:111], v[112:115], v[100:103], a[96:111]
	ds_read_b128 v[112:115], v59 offset:4672
	ds_read_b128 v[116:119], v59 offset:4704
	s_waitcnt lgkmcnt(1)
	v_mfma_f32_32x32x16_bf16 a[80:95], v[112:115], v[108:111], a[80:95]
	v_mfma_f32_32x32x16_bf16 a[64:79], v[112:115], v[100:103], a[64:79]
	v_mfma_f32_32x32x16_bf16 a[48:63], v[128:131], v[108:111], a[48:63]
	v_mfma_f32_32x32x16_bf16 a[32:47], v[128:131], v[100:103], a[32:47]
	ds_read_b128 v[112:115], v61 offset:64
	ds_read_b128 v[128:131], v61 offset:96
	s_waitcnt lgkmcnt(1)
	v_mfma_f32_32x32x16_bf16 a[16:31], v[112:115], v[108:111], a[16:31]
	v_mfma_f32_32x32x16_bf16 a[0:15], v[112:115], v[100:103], a[0:15]
	global_load_dwordx4 v[100:103], v[32:33], off offset:1792
	v_mfma_f32_32x32x16_bf16 a[112:127], v[124:127], v[120:123], a[112:127]
	v_mfma_f32_32x32x16_bf16 a[96:111], v[124:127], v[104:107], a[96:111]
	v_mfma_f32_32x32x16_bf16 a[80:95], v[116:119], v[120:123], a[80:95]
	v_mfma_f32_32x32x16_bf16 a[64:79], v[116:119], v[104:107], a[64:79]
	v_mfma_f32_32x32x16_bf16 a[48:63], v[136:139], v[120:123], a[48:63]
	v_mfma_f32_32x32x16_bf16 a[32:47], v[136:139], v[104:107], a[32:47]
	global_load_dwordx4 v[108:111], v[30:31], off offset:1792
	global_load_dwordx4 v[112:115], v[18:19], off offset:1792
	global_load_dwordx4 v[116:119], v[6:7], off offset:1792
	global_load_dwordx4 v[124:127], v[4:5], off offset:1792
	global_load_dwordx4 v[136:139], v[0:1], off offset:1792
	global_load_dwordx4 v[140:143], v[22:23], off offset:1792
	global_load_dwordx4 v[144:147], v[20:21], off offset:1792
	s_waitcnt lgkmcnt(0)
	v_mfma_f32_32x32x16_bf16 a[16:31], v[128:131], v[120:123], a[16:31]
	global_load_dwordx4 v[120:123], v[26:27], off offset:1792
	global_load_dwordx4 v[148:151], v[24:25], off offset:1792
	global_load_dwordx4 v[152:155], v[28:29], off offset:1792
	global_load_dwordx4 v[156:159], v[2:3], off offset:1792
	s_barrier
	v_mfma_f32_32x32x16_bf16 a[0:15], v[128:131], v[104:107], a[0:15]
	ds_read_b128 v[104:107], v59 offset:55296
	ds_read_b128 v[128:131], v69
	ds_read_b128 v[160:163], v59 offset:59904
	ds_read_b128 v[164:167], v61 offset:55296
	ds_read_b128 v[168:171], v69 offset:4608
	s_waitcnt lgkmcnt(3)
	v_mfma_f32_32x32x16_bf16 a[112:127], v[104:107], v[128:131], a[112:127]
	s_waitcnt lgkmcnt(0)
	v_mfma_f32_32x32x16_bf16 a[96:111], v[104:107], v[168:171], a[96:111]
	ds_read_b128 v[104:107], v59 offset:64512
	s_waitcnt vmcnt(6)
	ds_write_b128 v60, v[136:139]
	ds_write_b128 v60, v[124:127] offset:4608
	ds_write_b128 v60, v[116:119] offset:9216
	ds_write_b128 v60, v[112:115] offset:13824
	s_waitcnt vmcnt(4)
	ds_write_b128 v60, v[144:147] offset:18432
	ds_write_b128 v60, v[140:143] offset:23040
	s_waitcnt vmcnt(2)
	ds_write_b128 v60, v[148:151] offset:27648
	ds_write_b128 v60, v[120:123] offset:32256
	s_waitcnt vmcnt(0)
	ds_write_b128 v60, v[156:159] offset:36864
	ds_write_b128 v60, v[152:155] offset:41472
	ds_write_b128 v60, v[108:111] offset:46080
	ds_write_b128 v60, v[100:103] offset:50688
	v_mfma_f32_32x32x16_bf16 a[80:95], v[160:163], v[128:131], a[80:95]
	v_mfma_f32_32x32x16_bf16 a[64:79], v[160:163], v[168:171], a[64:79]
	s_waitcnt lgkmcnt(12)
	v_mfma_f32_32x32x16_bf16 a[48:63], v[104:107], v[128:131], a[48:63]
	v_mfma_f32_32x32x16_bf16 a[32:47], v[104:107], v[168:171], a[32:47]
	ds_read_b128 v[100:103], v59 offset:55328
	ds_read_b128 v[104:107], v69 offset:32
	ds_read_b128 v[108:111], v69 offset:64
	ds_read_b128 v[112:115], v59 offset:55360
	ds_read_b128 v[116:119], v69 offset:4640
	ds_read_b128 v[120:123], v69 offset:96
	s_waitcnt lgkmcnt(4)
	v_mfma_f32_32x32x16_bf16 a[112:127], v[100:103], v[104:107], a[112:127]
	s_waitcnt lgkmcnt(1)
	v_mfma_f32_32x32x16_bf16 a[96:111], v[100:103], v[116:119], a[96:111]
	ds_read_b128 v[100:103], v59 offset:59936
	ds_read_b128 v[124:127], v59 offset:55392
	v_mfma_f32_32x32x16_bf16 a[16:31], v[164:167], v[128:131], a[16:31]
	v_mfma_f32_32x32x16_bf16 a[0:15], v[164:167], v[168:171], a[0:15]
	s_waitcnt lgkmcnt(1)
	v_mfma_f32_32x32x16_bf16 a[80:95], v[100:103], v[104:107], a[80:95]
	v_mfma_f32_32x32x16_bf16 a[64:79], v[100:103], v[116:119], a[64:79]
	ds_read_b128 v[100:103], v59 offset:64544
	ds_read_b128 v[128:131], v59 offset:64576
	s_waitcnt lgkmcnt(1)
	v_mfma_f32_32x32x16_bf16 a[48:63], v[100:103], v[104:107], a[48:63]
	v_mfma_f32_32x32x16_bf16 a[32:47], v[100:103], v[116:119], a[32:47]
	ds_read_b128 v[100:103], v61 offset:55328
	ds_read_b128 v[136:139], v59 offset:64608
	s_waitcnt lgkmcnt(1)
	v_mfma_f32_32x32x16_bf16 a[16:31], v[100:103], v[104:107], a[16:31]
	v_mfma_f32_32x32x16_bf16 a[0:15], v[100:103], v[116:119], a[0:15]
	ds_read_b128 v[100:103], v69 offset:4672
	ds_read_b128 v[104:107], v69 offset:4704
	v_mfma_f32_32x32x16_bf16 a[112:127], v[112:115], v[108:111], a[112:127]
	s_waitcnt lgkmcnt(1)
	v_mfma_f32_32x32x16_bf16 a[96:111], v[112:115], v[100:103], a[96:111]
	ds_read_b128 v[112:115], v59 offset:59968
	ds_read_b128 v[116:119], v59 offset:60000
	s_waitcnt lgkmcnt(1)
	v_mfma_f32_32x32x16_bf16 a[80:95], v[112:115], v[108:111], a[80:95]
	v_mfma_f32_32x32x16_bf16 a[64:79], v[112:115], v[100:103], a[64:79]
	v_mfma_f32_32x32x16_bf16 a[48:63], v[128:131], v[108:111], a[48:63]
	v_mfma_f32_32x32x16_bf16 a[32:47], v[128:131], v[100:103], a[32:47]
	ds_read_b128 v[112:115], v61 offset:55360
	ds_read_b128 v[128:131], v61 offset:55392
	s_waitcnt lgkmcnt(1)
	v_mfma_f32_32x32x16_bf16 a[16:31], v[112:115], v[108:111], a[16:31]
	v_mfma_f32_32x32x16_bf16 a[0:15], v[112:115], v[100:103], a[0:15]
	global_load_dwordx4 v[100:103], v[4:5], off offset:1920
	global_load_dwordx4 v[108:111], v[0:1], off offset:1920
	global_load_dwordx4 v[112:115], v[18:19], off offset:1920
	s_nop 0
	global_load_dwordx4 v[4:7], v[6:7], off offset:1920
	v_mfma_f32_32x32x16_bf16 a[112:127], v[124:127], v[120:123], a[112:127]
	v_mfma_f32_32x32x16_bf16 a[96:111], v[124:127], v[104:107], a[96:111]
	v_mfma_f32_32x32x16_bf16 a[80:95], v[116:119], v[120:123], a[80:95]
	v_mfma_f32_32x32x16_bf16 a[64:79], v[116:119], v[104:107], a[64:79]
	v_mfma_f32_32x32x16_bf16 a[48:63], v[136:139], v[120:123], a[48:63]
	v_mfma_f32_32x32x16_bf16 a[32:47], v[136:139], v[104:107], a[32:47]
	global_load_dwordx4 v[18:21], v[20:21], off offset:1920
	s_nop 0
	global_load_dwordx4 v[116:119], v[22:23], off offset:1920
	global_load_dwordx4 v[124:127], v[26:27], off offset:1920
	s_nop 0
	global_load_dwordx4 v[22:25], v[24:25], off offset:1920
	s_nop 0
	global_load_dwordx4 v[26:29], v[28:29], off offset:1920
	s_nop 0
	global_load_dwordx4 v[0:3], v[2:3], off offset:1920
	s_nop 0
	global_load_dwordx4 v[136:139], v[30:31], off offset:1920
	s_nop 0
	global_load_dwordx4 v[30:33], v[32:33], off offset:1920
	s_waitcnt lgkmcnt(0)
	s_barrier
	v_mfma_f32_32x32x16_bf16 a[16:31], v[128:131], v[120:123], a[16:31]
	v_mfma_f32_32x32x16_bf16 a[0:15], v[128:131], v[104:107], a[0:15]
	ds_read_b128 v[104:107], v59
	ds_read_b128 v[120:123], v62 offset:36864
	ds_read_b128 v[128:131], v59 offset:4608
	ds_read_b128 v[140:143], v62 offset:41472
	s_waitcnt lgkmcnt(2)
	v_mfma_f32_32x32x16_bf16 a[112:127], v[104:107], v[120:123], a[112:127]
	s_waitcnt lgkmcnt(0)
	v_mfma_f32_32x32x16_bf16 a[96:111], v[104:107], v[140:143], a[96:111]
	v_mfma_f32_32x32x16_bf16 a[80:95], v[128:131], v[120:123], a[80:95]
	v_mfma_f32_32x32x16_bf16 a[64:79], v[128:131], v[140:143], a[64:79]
	ds_read_b128 v[104:107], v59 offset:9216
	ds_read_b128 v[128:131], v61
	s_waitcnt vmcnt(10)
	ds_write_b128 v60, v[108:111] offset:55296
	ds_write_b128 v60, v[100:103] offset:59904
	s_waitcnt vmcnt(8)
	ds_write_b128 v60, v[4:7] offset:64512
	ds_write_b128 v63, v[112:115] offset:55296
	s_waitcnt vmcnt(7)
	ds_write_b128 v64, v[18:21] offset:55296
	s_waitcnt vmcnt(6)
	ds_write_b128 v65, v[116:119] offset:55296
	s_waitcnt vmcnt(4)
	ds_write_b128 v66, v[22:25] offset:55296
	ds_write_b128 v67, v[124:127] offset:55296
	s_waitcnt vmcnt(2)
	ds_write_b128 v68, v[0:3]
	ds_write_b128 v68, v[26:29] offset:4608
	s_waitcnt vmcnt(1)
	ds_write_b128 v68, v[136:139] offset:9216
	s_waitcnt lgkmcnt(12)
	v_mfma_f32_32x32x16_bf16 a[48:63], v[104:107], v[120:123], a[48:63]
	s_waitcnt vmcnt(0)
	ds_write_b128 v68, v[30:33] offset:13824
	ds_read_b128 v[0:3], v59 offset:32
	ds_read_b128 v[4:7], v62 offset:36896
	ds_read_b128 v[18:21], v62 offset:36928
	ds_read_b128 v[22:25], v59 offset:64
	ds_read_b128 v[26:29], v62 offset:41504
	ds_read_b128 v[30:33], v62 offset:36960
	v_accvgpr_read_b32 v112, a220
	v_accvgpr_read_b32 v113, a221
	v_accvgpr_read_b32 v114, a222
	v_accvgpr_read_b32 v115, a223
	v_mfma_f32_32x32x16_bf16 a[32:47], v[104:107], v[140:143], a[32:47]
	v_accvgpr_read_b32 v116, a224
	s_waitcnt lgkmcnt(4)
	v_mfma_f32_32x32x16_bf16 a[112:127], v[0:3], v[4:7], a[112:127]
	s_waitcnt lgkmcnt(1)
	v_mfma_f32_32x32x16_bf16 a[96:111], v[0:3], v[26:29], a[96:111]
	ds_read_b128 v[0:3], v59 offset:4640
	ds_read_b128 v[100:103], v59 offset:96
	v_mfma_f32_32x32x16_bf16 a[16:31], v[128:131], v[120:123], a[16:31]
	v_mfma_f32_32x32x16_bf16 a[0:15], v[128:131], v[140:143], a[0:15]
	s_waitcnt lgkmcnt(1)
	v_mfma_f32_32x32x16_bf16 a[80:95], v[0:3], v[4:7], a[80:95]
	v_mfma_f32_32x32x16_bf16 a[64:79], v[0:3], v[26:29], a[64:79]
	ds_read_b128 v[0:3], v59 offset:9248
	ds_read_b128 v[104:107], v59 offset:9280
	s_waitcnt lgkmcnt(1)
	v_mfma_f32_32x32x16_bf16 a[48:63], v[0:3], v[4:7], a[48:63]
	v_mfma_f32_32x32x16_bf16 a[32:47], v[0:3], v[26:29], a[32:47]
	ds_read_b128 v[0:3], v61 offset:32
	ds_read_b128 v[108:111], v59 offset:9312
	s_waitcnt lgkmcnt(1)
	v_mfma_f32_32x32x16_bf16 a[16:31], v[0:3], v[4:7], a[16:31]
	v_mfma_f32_32x32x16_bf16 a[0:15], v[0:3], v[26:29], a[0:15]
	ds_read_b128 v[0:3], v62 offset:41536
	ds_read_b128 v[4:7], v62 offset:41568
	v_mfma_f32_32x32x16_bf16 a[112:127], v[22:25], v[18:21], a[112:127]
	s_waitcnt lgkmcnt(1)
	v_mfma_f32_32x32x16_bf16 a[96:111], v[22:25], v[0:3], a[96:111]
	ds_read_b128 v[22:25], v59 offset:4672
	ds_read_b128 v[26:29], v59 offset:4704
	s_waitcnt lgkmcnt(1)
	v_mfma_f32_32x32x16_bf16 a[80:95], v[22:25], v[18:21], a[80:95]
	v_mfma_f32_32x32x16_bf16 a[64:79], v[22:25], v[0:3], a[64:79]
	v_mfma_f32_32x32x16_bf16 a[48:63], v[104:107], v[18:21], a[48:63]
	v_mfma_f32_32x32x16_bf16 a[32:47], v[104:107], v[0:3], a[32:47]
	ds_read_b128 v[22:25], v61 offset:64
	ds_read_b128 v[104:107], v61 offset:96
	s_waitcnt lgkmcnt(0)
	s_barrier
	v_mfma_f32_32x32x16_bf16 a[16:31], v[22:25], v[18:21], a[16:31]
	v_mfma_f32_32x32x16_bf16 a[0:15], v[22:25], v[0:3], a[0:15]
	v_mfma_f32_32x32x16_bf16 a[112:127], v[100:103], v[30:33], a[112:127]
	v_mfma_f32_32x32x16_bf16 a[96:111], v[100:103], v[4:7], a[96:111]
	v_mfma_f32_32x32x16_bf16 a[80:95], v[26:29], v[30:33], a[80:95]
	v_mfma_f32_32x32x16_bf16 a[64:79], v[26:29], v[4:7], a[64:79]
	v_mfma_f32_32x32x16_bf16 a[48:63], v[108:111], v[30:33], a[48:63]
	v_mfma_f32_32x32x16_bf16 a[32:47], v[108:111], v[4:7], a[32:47]
	v_mfma_f32_32x32x16_bf16 a[16:31], v[104:107], v[30:33], a[16:31]
	v_mfma_f32_32x32x16_bf16 a[0:15], v[104:107], v[4:7], a[0:15]
	ds_read_b128 v[0:3], v59 offset:55296
	ds_read_b128 v[4:7], v69
	ds_read_b128 v[18:21], v59 offset:55328
	ds_read_b128 v[22:25], v69 offset:32
	ds_read_b128 v[26:29], v69 offset:4608
	ds_read_b128 v[30:33], v69 offset:4640
	s_waitcnt lgkmcnt(4)
	v_mfma_f32_32x32x16_bf16 a[112:127], v[0:3], v[4:7], a[112:127]
	s_waitcnt lgkmcnt(1)
	v_mfma_f32_32x32x16_bf16 a[96:111], v[0:3], v[26:29], a[96:111]
	ds_read_b128 v[0:3], v59 offset:59904
	ds_read_b128 v[100:103], v59 offset:59936
	s_waitcnt lgkmcnt(1)
	v_mfma_f32_32x32x16_bf16 a[80:95], v[0:3], v[4:7], a[80:95]
	v_mfma_f32_32x32x16_bf16 a[64:79], v[0:3], v[26:29], a[64:79]
	ds_read_b128 v[0:3], v59 offset:64512
	ds_read_b128 v[104:107], v59 offset:64544
	s_waitcnt lgkmcnt(1)
	v_mfma_f32_32x32x16_bf16 a[48:63], v[0:3], v[4:7], a[48:63]
	v_mfma_f32_32x32x16_bf16 a[32:47], v[0:3], v[26:29], a[32:47]
	ds_read_b128 v[0:3], v61 offset:55296
	ds_read_b128 v[108:111], v61 offset:55328
	s_waitcnt lgkmcnt(1)
	v_mfma_f32_32x32x16_bf16 a[16:31], v[0:3], v[4:7], a[16:31]
	v_mfma_f32_32x32x16_bf16 a[0:15], v[0:3], v[26:29], a[0:15]
	v_mfma_f32_32x32x16_bf16 a[112:127], v[18:21], v[22:25], a[112:127]
	v_mfma_f32_32x32x16_bf16 a[96:111], v[18:21], v[30:33], a[96:111]
	v_mfma_f32_32x32x16_bf16 a[80:95], v[100:103], v[22:25], a[80:95]
	v_mfma_f32_32x32x16_bf16 a[64:79], v[100:103], v[30:33], a[64:79]
	v_mfma_f32_32x32x16_bf16 a[48:63], v[104:107], v[22:25], a[48:63]
	v_mfma_f32_32x32x16_bf16 a[32:47], v[104:107], v[30:33], a[32:47]
	s_waitcnt lgkmcnt(0)
	v_mfma_f32_32x32x16_bf16 a[16:31], v[108:111], v[22:25], a[16:31]
	ds_read_b128 v[0:3], v59 offset:55360
	ds_read_b128 v[4:7], v69 offset:64
	ds_read_b128 v[18:21], v59 offset:55392
	ds_read_b128 v[22:25], v69 offset:96
	v_mfma_f32_32x32x16_bf16 a[0:15], v[108:111], v[30:33], a[0:15]
	ds_read_b128 v[26:29], v69 offset:4672
	ds_read_b128 v[30:33], v69 offset:4704
	s_waitcnt lgkmcnt(4)
	v_mfma_f32_32x32x16_bf16 a[112:127], v[0:3], v[4:7], a[112:127]
	s_waitcnt lgkmcnt(1)
	v_mfma_f32_32x32x16_bf16 a[96:111], v[0:3], v[26:29], a[96:111]
	ds_read_b128 v[0:3], v59 offset:59968
	ds_read_b128 v[100:103], v59 offset:60000
	s_waitcnt lgkmcnt(1)
	v_mfma_f32_32x32x16_bf16 a[80:95], v[0:3], v[4:7], a[80:95]
	v_mfma_f32_32x32x16_bf16 a[64:79], v[0:3], v[26:29], a[64:79]
	ds_read_b128 v[0:3], v59 offset:64576
	ds_read_b128 v[104:107], v59 offset:64608
	s_waitcnt lgkmcnt(1)
	v_mfma_f32_32x32x16_bf16 a[48:63], v[0:3], v[4:7], a[48:63]
	v_mfma_f32_32x32x16_bf16 a[32:47], v[0:3], v[26:29], a[32:47]
	ds_read_b128 v[0:3], v61 offset:55360
	ds_read_b128 v[108:111], v61 offset:55392
	s_waitcnt lgkmcnt(0)
	s_barrier
	v_mfma_f32_32x32x16_bf16 a[16:31], v[0:3], v[4:7], a[16:31]
	v_mfma_f32_32x32x16_bf16 a[0:15], v[0:3], v[26:29], a[0:15]
	v_or_b32_e32 v0, s21, v132
	v_lshlrev_b32_e32 v8, 10, v0
	v_lshl_add_u64 v[0:1], s[22:23], 0, v[16:17]
	s_and_b64 s[22:23], s[6:7], exec
	s_cselect_b32 s22, s4, s14
	s_cselect_b32 s20, s5, s15
	s_add_u32 s22, s22, s8
	v_mfma_f32_32x32x16_bf16 a[112:127], v[18:21], v[22:25], a[112:127]
	s_addc_u32 s23, s20, 0
	v_lshlrev_b64 v[26:27], 2, v[8:9]
	v_add_co_u32_e32 v0, vcc, s19, v0
	v_or_b32_e32 v8, s21, v133
	s_nop 0
	v_addc_co_u32_e32 v1, vcc, 0, v1, vcc
	v_mfma_f32_32x32x16_bf16 a[96:111], v[18:21], v[30:33], a[96:111]
	v_lshl_add_u64 v[18:19], s[22:23], 0, v[16:17]
	v_lshl_add_u64 v[4:5], v[18:19], 0, v[26:27]
	v_lshlrev_b32_e32 v8, 10, v8
	v_lshl_add_u64 v[20:21], v[14:15], 0, s[8:9]
	s_or_b32 s20, s21, 0x80
	v_mfma_f32_32x32x16_bf16 a[80:95], v[100:103], v[22:25], a[80:95]
	v_mfma_f32_32x32x16_bf16 a[64:79], v[100:103], v[30:33], a[64:79]
	v_mfma_f32_32x32x16_bf16 a[48:63], v[104:107], v[22:25], a[48:63]
	v_mfma_f32_32x32x16_bf16 a[32:47], v[104:107], v[30:33], a[32:47]
	v_mfma_f32_32x32x16_bf16 a[16:31], v[108:111], v[22:25], a[16:31]
	v_lshlrev_b64 v[22:23], 2, v[8:9]
	v_lshl_add_u64 v[24:25], v[20:21], 0, v[26:27]
	v_lshl_add_u64 v[26:27], v[18:19], 0, v[22:23]
	v_or_b32_e32 v8, s21, v112
	v_lshlrev_b32_e32 v8, 10, v8
	v_lshl_add_u64 v[22:23], v[20:21], 0, v[22:23]
	v_mfma_f32_32x32x16_bf16 a[0:15], v[108:111], v[30:33], a[0:15]
	v_mov_b32_e32 v110, v8
	v_mov_b32_e32 v111, v9
	v_mov_b32_e32 v118, v22
	v_mov_b32_e32 v119, v23
	v_mov_b32_e32 v120, v24
	v_mov_b32_e32 v121, v25
	v_mov_b32_e32 v122, v26
	v_mov_b32_e32 v123, v27
	global_load_dwordx4 v[250:253], v[0:1], off
	global_load_dwordx4 v[246:249], v[4:5], off
	global_load_dwordx4 v[242:245], v[122:123], off
	v_lshlrev_b64 v[120:121], 2, v[110:111]
	v_lshl_add_u64 v[122:123], v[18:19], 0, v[120:121]
	v_or_b32_e32 v110, s21, v113
	v_lshlrev_b32_e32 v110, 10, v110
	global_load_dwordx4 v[238:241], v[122:123], off
	v_lshlrev_b64 v[118:119], 2, v[110:111]
	v_lshl_add_u64 v[122:123], v[18:19], 0, v[118:119]
	v_or_b32_e32 v110, s21, v114
	v_lshlrev_b32_e32 v110, 10, v110
	global_load_dwordx4 v[234:237], v[122:123], off
	v_lshlrev_b64 v[120:121], 2, v[110:111]
	v_lshl_add_u64 v[122:123], v[18:19], 0, v[120:121]
	v_or_b32_e32 v110, s21, v115
	v_lshlrev_b32_e32 v110, 10, v110
	global_load_dwordx4 v[212:215], v[122:123], off
	v_lshlrev_b64 v[118:119], 2, v[110:111]
	v_lshl_add_u64 v[122:123], v[18:19], 0, v[118:119]
	v_or_b32_e32 v110, s21, v116
	v_lshlrev_b32_e32 v110, 10, v110
	global_load_dwordx4 v[208:211], v[122:123], off
	v_lshlrev_b64 v[120:121], 2, v[110:111]
	v_lshl_add_u64 v[122:123], v[18:19], 0, v[120:121]
	v_or_b32_e32 v110, s21, v135
	v_lshlrev_b32_e32 v110, 10, v110
	global_load_dwordx4 v[204:207], v[122:123], off
	v_lshlrev_b64 v[118:119], 2, v[110:111]
	v_lshl_add_u64 v[122:123], v[18:19], 0, v[118:119]
	v_or_b32_e32 v110, s21, v200
	v_lshlrev_b32_e32 v110, 10, v110
	global_load_dwordx4 v[196:199], v[122:123], off
	v_lshlrev_b64 v[120:121], 2, v[110:111]
	v_lshl_add_u64 v[122:123], v[18:19], 0, v[120:121]
	v_or_b32_e32 v110, s21, v35
	v_lshlrev_b32_e32 v110, 10, v110
	global_load_dwordx4 v[192:195], v[122:123], off
	v_lshlrev_b64 v[120:121], 2, v[110:111]
	v_lshl_add_u64 v[122:123], v[18:19], 0, v[120:121]
	v_or_b32_e32 v110, s21, v36
	v_lshlrev_b32_e32 v110, 10, v110
	global_load_dwordx4 v[188:191], v[122:123], off
	v_lshlrev_b64 v[120:121], 2, v[110:111]
	v_lshl_add_u64 v[122:123], v[18:19], 0, v[120:121]
	v_or_b32_e32 v110, s21, v37
	v_lshlrev_b32_e32 v110, 10, v110
	global_load_dwordx4 v[184:187], v[122:123], off
	v_lshlrev_b64 v[120:121], 2, v[110:111]
	v_lshl_add_u64 v[122:123], v[18:19], 0, v[120:121]
	v_or_b32_e32 v110, s21, v38
	v_lshlrev_b32_e32 v110, 10, v110
	global_load_dwordx4 v[180:183], v[122:123], off
	v_lshlrev_b64 v[120:121], 2, v[110:111]
	v_lshl_add_u64 v[122:123], v[18:19], 0, v[120:121]
	v_or_b32_e32 v110, s21, v39
	v_lshlrev_b32_e32 v110, 10, v110
	global_load_dwordx4 v[176:179], v[122:123], off
	v_lshlrev_b64 v[120:121], 2, v[110:111]
	v_lshl_add_u64 v[122:123], v[18:19], 0, v[120:121]
	v_or_b32_e32 v110, s21, v40
	v_lshlrev_b32_e32 v110, 10, v110
	global_load_dwordx4 v[172:175], v[122:123], off
	v_lshlrev_b64 v[120:121], 2, v[110:111]
	v_lshl_add_u64 v[122:123], v[18:19], 0, v[120:121]
	v_or_b32_e32 v110, s21, v41
	v_lshlrev_b32_e32 v110, 10, v110
	global_load_dwordx4 v[168:171], v[122:123], off
	v_lshlrev_b64 v[120:121], 2, v[110:111]
	v_lshl_add_u64 v[122:123], v[18:19], 0, v[120:121]
	global_load_dwordx4 v[164:167], v[122:123], off
	ds_write_b32 v58, a112
	ds_write_b32 v58, a113 offset:516
	ds_write_b32 v58, a114 offset:1032
	ds_write_b32 v58, a115 offset:1548
	ds_write_b32 v58, a116 offset:4128
	ds_write_b32 v58, a117 offset:4644
	ds_write_b32 v58, a118 offset:5160
	ds_write_b32 v58, a119 offset:5676
	ds_write_b32 v58, a120 offset:8256
	ds_write_b32 v58, a121 offset:8772
	ds_write_b32 v58, a122 offset:9288
	ds_write_b32 v58, a123 offset:9804
	ds_write_b32 v58, a124 offset:12384
	ds_write_b32 v58, a125 offset:12900
	ds_write_b32 v58, a126 offset:13416
	ds_write_b32 v58, a127 offset:13932
	ds_write_b32 v58, a96 offset:128
	ds_write_b32 v58, a97 offset:644
	ds_write_b32 v58, a98 offset:1160
	ds_write_b32 v58, a99 offset:1676
	ds_write_b32 v58, a100 offset:4256
	ds_write_b32 v58, a101 offset:4772
	ds_write_b32 v58, a102 offset:5288
	ds_write_b32 v58, a103 offset:5804
	ds_write_b32 v58, a104 offset:8384
	ds_write_b32 v58, a105 offset:8900
	ds_write_b32 v58, a106 offset:9416
	ds_write_b32 v58, a107 offset:9932
	ds_write_b32 v58, a108 offset:12512
	ds_write_b32 v58, a109 offset:13028
	ds_write_b32 v58, a110 offset:13544
	ds_write_b32 v58, a111 offset:14060
	ds_write_b32 v58, a80 offset:16512
	ds_write_b32 v58, a81 offset:17028
	ds_write_b32 v58, a82 offset:17544
	ds_write_b32 v58, a83 offset:18060
	ds_write_b32 v58, a84 offset:20640
	ds_write_b32 v58, a85 offset:21156
	ds_write_b32 v58, a86 offset:21672
	ds_write_b32 v58, a87 offset:22188
	ds_write_b32 v58, a88 offset:24768
	ds_write_b32 v58, a89 offset:25284
	ds_write_b32 v58, a90 offset:25800
	ds_write_b32 v58, a91 offset:26316
	ds_write_b32 v58, a92 offset:28896
	ds_write_b32 v58, a93 offset:29412
	ds_write_b32 v58, a94 offset:29928
	ds_write_b32 v58, a95 offset:30444
	ds_write_b32 v58, a64 offset:16640
	ds_write_b32 v58, a65 offset:17156
	ds_write_b32 v58, a66 offset:17672
	ds_write_b32 v58, a67 offset:18188
	ds_write_b32 v58, a68 offset:20768
	ds_write_b32 v58, a69 offset:21284
	ds_write_b32 v58, a70 offset:21800
	ds_write_b32 v58, a71 offset:22316
	ds_write_b32 v58, a72 offset:24896
	ds_write_b32 v58, a73 offset:25412
	ds_write_b32 v58, a74 offset:25928
	ds_write_b32 v58, a75 offset:26444
	ds_write_b32 v58, a76 offset:29024
	ds_write_b32 v58, a77 offset:29540
	ds_write_b32 v58, a78 offset:30056
	ds_write_b32 v58, a79 offset:30572
	ds_write_b32 v58, a48 offset:33024
	ds_write_b32 v58, a49 offset:33540
	ds_write_b32 v58, a50 offset:34056
	ds_write_b32 v58, a51 offset:34572
	ds_write_b32 v58, a52 offset:37152
	ds_write_b32 v58, a53 offset:37668
	ds_write_b32 v58, a54 offset:38184
	ds_write_b32 v58, a55 offset:38700
	ds_write_b32 v58, a56 offset:41280
	ds_write_b32 v58, a57 offset:41796
	ds_write_b32 v58, a58 offset:42312
	ds_write_b32 v58, a59 offset:42828
	ds_write_b32 v58, a60 offset:45408
	ds_write_b32 v58, a61 offset:45924
	ds_write_b32 v58, a62 offset:46440
	ds_write_b32 v58, a63 offset:46956
	ds_write_b32 v58, a32 offset:33152
	ds_write_b32 v58, a33 offset:33668
	ds_write_b32 v58, a34 offset:34184
	ds_write_b32 v58, a35 offset:34700
	ds_write_b32 v58, a36 offset:37280
	ds_write_b32 v58, a37 offset:37796
	ds_write_b32 v58, a38 offset:38312
	ds_write_b32 v58, a39 offset:38828
	ds_write_b32 v58, a40 offset:41408
	ds_write_b32 v58, a41 offset:41924
	ds_write_b32 v58, a42 offset:42440
	ds_write_b32 v58, a43 offset:42956
	ds_write_b32 v58, a44 offset:45536
	ds_write_b32 v58, a45 offset:46052
	ds_write_b32 v58, a46 offset:46568
	ds_write_b32 v58, a47 offset:47084
	ds_write_b32 v58, a16 offset:49536
	ds_write_b32 v58, a17 offset:50052
	ds_write_b32 v58, a18 offset:50568
	ds_write_b32 v58, a19 offset:51084
	ds_write_b32 v58, a20 offset:53664
	ds_write_b32 v58, a21 offset:54180
	ds_write_b32 v58, a22 offset:54696
	ds_write_b32 v58, a23 offset:55212
	ds_write_b32 v58, a24 offset:57792
	ds_write_b32 v58, a25 offset:58308
	ds_write_b32 v58, a26 offset:58824
	ds_write_b32 v58, a27 offset:59340
	ds_write_b32 v58, a28 offset:61920
	ds_write_b32 v58, a29 offset:62436
	ds_write_b32 v58, a30 offset:62952
	ds_write_b32 v58, a31 offset:63468
	ds_write_b32 v58, a0 offset:49664
	ds_write_b32 v58, a1 offset:50180
	ds_write_b32 v58, a2 offset:50696
	ds_write_b32 v58, a3 offset:51212
	ds_write_b32 v58, a4 offset:53792
	ds_write_b32 v58, a5 offset:54308
	ds_write_b32 v58, a6 offset:54824
	ds_write_b32 v58, a7 offset:55340
	ds_write_b32 v58, a8 offset:57920
	ds_write_b32 v58, a9 offset:58436
	ds_write_b32 v58, a10 offset:58952
	ds_write_b32 v58, a11 offset:59468
	ds_write_b32 v58, a12 offset:62048
	ds_write_b32 v58, a13 offset:62564
	ds_write_b32 v58, a14 offset:63080
	ds_write_b32 v58, a15 offset:63596
	s_waitcnt lgkmcnt(0)
	s_barrier
	s_waitcnt vmcnt(16)
	s_nop 1
	v_mov_b64_e32 v[0:1], v[250:251]
	v_mov_b64_e32 v[2:3], v[252:253]
	s_nop 0
	s_waitcnt vmcnt(15)
	s_nop 1
	v_mov_b64_e32 v[4:5], v[246:247]
	v_mov_b64_e32 v[6:7], v[248:249]
	ds_read2_b32 v[28:29], v34 offset0:2 offset1:3
	ds_read2_b32 v[30:31], v42 offset1:1
	ds_read2_b32 v[32:33], v42 offset0:2 offset1:3
	ds_read2_b32 v[100:101], v34 offset1:1
	s_waitcnt lgkmcnt(3)
	v_pk_fma_f32 v[6:7], v[2:3], v[28:29], v[6:7]
	s_waitcnt lgkmcnt(0)
	v_pk_fma_f32 v[4:5], v[0:1], v[100:101], v[4:5]
	global_store_dwordx4 v[24:25], v[4:7], off
	s_waitcnt vmcnt(15)
	s_nop 1
	v_mov_b64_e32 v[4:5], v[242:243]
	v_mov_b64_e32 v[6:7], v[244:245]
	ds_read2_b32 v[28:29], v71 offset1:1
	ds_read2_b32 v[100:101], v72 offset1:1
	ds_read2_b32 v[102:103], v73 offset1:1
	ds_read2_b32 v[104:105], v70 offset1:1
	v_lshlrev_b64 v[24:25], 2, v[8:9]
	v_lshl_add_u64 v[26:27], v[18:19], 0, v[24:25]
	v_or_b32_e32 v8, s21, v113
	v_lshlrev_b32_e32 v8, 10, v8
	v_lshl_add_u64 v[24:25], v[20:21], 0, v[24:25]
	s_waitcnt lgkmcnt(3)
	v_pk_fma_f32 v[6:7], v[2:3], v[28:29], v[6:7]
	s_waitcnt lgkmcnt(0)
	v_pk_fma_f32 v[4:5], v[0:1], v[104:105], v[4:5]
	global_store_dwordx4 v[22:23], v[4:7], off
	s_waitcnt vmcnt(15)
	s_nop 1
	v_mov_b64_e32 v[4:5], v[238:239]
	v_mov_b64_e32 v[6:7], v[240:241]
	v_lshlrev_b64 v[22:23], 2, v[8:9]
	v_lshl_add_u64 v[26:27], v[18:19], 0, v[22:23]
	v_or_b32_e32 v8, s21, v114
	v_lshlrev_b32_e32 v8, 10, v8
	v_lshl_add_u64 v[22:23], v[20:21], 0, v[22:23]
	v_pk_fma_f32 v[6:7], v[2:3], v[102:103], v[6:7]
	v_pk_fma_f32 v[4:5], v[0:1], v[100:101], v[4:5]
	global_store_dwordx4 v[24:25], v[4:7], off
	s_waitcnt vmcnt(15)
	s_nop 1
	v_mov_b64_e32 v[4:5], v[234:235]
	v_mov_b64_e32 v[6:7], v[236:237]
	ds_read2_b32 v[28:29], v75 offset1:1
	ds_read2_b32 v[100:101], v76 offset1:1
	ds_read2_b32 v[102:103], v77 offset1:1
	ds_read2_b32 v[104:105], v74 offset1:1
	v_lshlrev_b64 v[24:25], 2, v[8:9]
	v_lshl_add_u64 v[26:27], v[18:19], 0, v[24:25]
	v_or_b32_e32 v8, s21, v115
	v_lshlrev_b32_e32 v8, 10, v8
	v_lshl_add_u64 v[24:25], v[20:21], 0, v[24:25]
	s_waitcnt lgkmcnt(3)
	v_pk_fma_f32 v[6:7], v[2:3], v[28:29], v[6:7]
	s_waitcnt lgkmcnt(0)
	v_pk_fma_f32 v[4:5], v[0:1], v[104:105], v[4:5]
	global_store_dwordx4 v[22:23], v[4:7], off
	s_waitcnt vmcnt(15)
	s_nop 1
	v_mov_b64_e32 v[4:5], v[212:213]
	v_mov_b64_e32 v[6:7], v[214:215]
	v_lshlrev_b64 v[22:23], 2, v[8:9]
	v_lshl_add_u64 v[26:27], v[18:19], 0, v[22:23]
	v_or_b32_e32 v8, s21, v116
	v_lshlrev_b32_e32 v8, 10, v8
	v_lshl_add_u64 v[22:23], v[20:21], 0, v[22:23]
	v_pk_fma_f32 v[6:7], v[2:3], v[102:103], v[6:7]
	v_pk_fma_f32 v[4:5], v[0:1], v[100:101], v[4:5]
	global_store_dwordx4 v[24:25], v[4:7], off
	s_waitcnt vmcnt(15)
	s_nop 1
	v_mov_b64_e32 v[4:5], v[208:209]
	v_mov_b64_e32 v[6:7], v[210:211]
	ds_read2_b32 v[28:29], v79 offset1:1
	ds_read2_b32 v[100:101], v80 offset1:1
	ds_read2_b32 v[102:103], v81 offset1:1
	ds_read2_b32 v[104:105], v78 offset1:1
	v_lshlrev_b64 v[24:25], 2, v[8:9]
	v_lshl_add_u64 v[26:27], v[18:19], 0, v[24:25]
	v_or_b32_e32 v8, s21, v135
	v_lshlrev_b32_e32 v8, 10, v8
	v_lshl_add_u64 v[24:25], v[20:21], 0, v[24:25]
	s_waitcnt lgkmcnt(3)
	v_pk_fma_f32 v[6:7], v[2:3], v[28:29], v[6:7]
	s_waitcnt lgkmcnt(0)
	v_pk_fma_f32 v[4:5], v[0:1], v[104:105], v[4:5]
	global_store_dwordx4 v[22:23], v[4:7], off
	s_waitcnt vmcnt(15)
	s_nop 1
	v_mov_b64_e32 v[4:5], v[204:205]
	v_mov_b64_e32 v[6:7], v[206:207]
	v_lshlrev_b64 v[22:23], 2, v[8:9]
	v_lshl_add_u64 v[26:27], v[18:19], 0, v[22:23]
	v_or_b32_e32 v8, s21, v200
	v_lshlrev_b32_e32 v8, 10, v8
	v_lshl_add_u64 v[22:23], v[20:21], 0, v[22:23]
	v_pk_fma_f32 v[6:7], v[2:3], v[102:103], v[6:7]
	v_pk_fma_f32 v[4:5], v[0:1], v[100:101], v[4:5]
	global_store_dwordx4 v[24:25], v[4:7], off
	s_waitcnt vmcnt(15)
	s_nop 1
	v_mov_b64_e32 v[4:5], v[196:197]
	v_mov_b64_e32 v[6:7], v[198:199]
	ds_read2_b32 v[28:29], v83 offset1:1
	ds_read2_b32 v[100:101], v84 offset1:1
	ds_read2_b32 v[102:103], v85 offset1:1
	ds_read2_b32 v[104:105], v82 offset1:1
	v_lshlrev_b64 v[24:25], 2, v[8:9]
	v_lshl_add_u64 v[26:27], v[18:19], 0, v[24:25]
	v_or_b32_e32 v8, s21, v35
	v_lshlrev_b32_e32 v8, 10, v8
	s_waitcnt lgkmcnt(3)
	v_pk_fma_f32 v[6:7], v[2:3], v[28:29], v[6:7]
	s_waitcnt lgkmcnt(0)
	v_pk_fma_f32 v[4:5], v[0:1], v[104:105], v[4:5]
	global_store_dwordx4 v[22:23], v[4:7], off
	s_waitcnt vmcnt(15)
	s_nop 1
	v_mov_b64_e32 v[4:5], v[192:193]
	v_mov_b64_e32 v[6:7], v[194:195]
	v_lshl_add_u64 v[22:23], v[20:21], 0, v[24:25]
	v_lshlrev_b64 v[24:25], 2, v[8:9]
	v_lshl_add_u64 v[26:27], v[18:19], 0, v[24:25]
	v_or_b32_e32 v8, s21, v36
	v_lshlrev_b32_e32 v8, 10, v8
	v_pk_fma_f32 v[6:7], v[2:3], v[102:103], v[6:7]
	v_pk_fma_f32 v[4:5], v[0:1], v[100:101], v[4:5]
	global_store_dwordx4 v[22:23], v[4:7], off
	s_waitcnt vmcnt(15)
	s_nop 1
	v_mov_b64_e32 v[4:5], v[188:189]
	v_mov_b64_e32 v[6:7], v[190:191]
	ds_read2_b32 v[28:29], v87 offset1:1
	ds_read2_b32 v[100:101], v88 offset1:1
	ds_read2_b32 v[102:103], v89 offset1:1
	ds_read2_b32 v[104:105], v86 offset1:1
	v_lshl_add_u64 v[22:23], v[20:21], 0, v[24:25]
	v_lshlrev_b64 v[24:25], 2, v[8:9]
	v_lshl_add_u64 v[26:27], v[18:19], 0, v[24:25]
	v_or_b32_e32 v8, s21, v37
	v_lshlrev_b32_e32 v8, 10, v8
	s_waitcnt lgkmcnt(3)
	v_pk_fma_f32 v[6:7], v[2:3], v[28:29], v[6:7]
	s_waitcnt lgkmcnt(0)
	v_pk_fma_f32 v[4:5], v[0:1], v[104:105], v[4:5]
	global_store_dwordx4 v[22:23], v[4:7], off
	s_waitcnt vmcnt(15)
	s_nop 1
	v_mov_b64_e32 v[4:5], v[184:185]
	v_mov_b64_e32 v[6:7], v[186:187]
	v_lshl_add_u64 v[22:23], v[20:21], 0, v[24:25]
	v_lshlrev_b64 v[24:25], 2, v[8:9]
	v_lshl_add_u64 v[26:27], v[18:19], 0, v[24:25]
	v_or_b32_e32 v8, s21, v38
	v_lshlrev_b32_e32 v8, 10, v8
	v_pk_fma_f32 v[6:7], v[2:3], v[102:103], v[6:7]
	v_pk_fma_f32 v[4:5], v[0:1], v[100:101], v[4:5]
	global_store_dwordx4 v[22:23], v[4:7], off
	s_waitcnt vmcnt(15)
	s_nop 1
	v_mov_b64_e32 v[4:5], v[180:181]
	v_mov_b64_e32 v[6:7], v[182:183]
	ds_read2_b32 v[28:29], v91 offset1:1
	ds_read2_b32 v[100:101], v92 offset1:1
	ds_read2_b32 v[102:103], v93 offset1:1
	ds_read2_b32 v[104:105], v90 offset1:1
	v_lshl_add_u64 v[22:23], v[20:21], 0, v[24:25]
	v_lshlrev_b64 v[24:25], 2, v[8:9]
	v_lshl_add_u64 v[26:27], v[18:19], 0, v[24:25]
	v_or_b32_e32 v8, s21, v39
	v_lshlrev_b32_e32 v8, 10, v8
	s_waitcnt lgkmcnt(3)
	v_pk_fma_f32 v[6:7], v[2:3], v[28:29], v[6:7]
	s_waitcnt lgkmcnt(0)
	v_pk_fma_f32 v[4:5], v[0:1], v[104:105], v[4:5]
	global_store_dwordx4 v[22:23], v[4:7], off
	s_waitcnt vmcnt(15)
	s_nop 1
	v_mov_b64_e32 v[4:5], v[176:177]
	v_mov_b64_e32 v[6:7], v[178:179]
	v_lshl_add_u64 v[22:23], v[20:21], 0, v[24:25]
	v_lshlrev_b64 v[24:25], 2, v[8:9]
	v_lshl_add_u64 v[26:27], v[18:19], 0, v[24:25]
	v_or_b32_e32 v8, s21, v40
	v_lshlrev_b32_e32 v8, 10, v8
	v_pk_fma_f32 v[6:7], v[2:3], v[102:103], v[6:7]
	v_pk_fma_f32 v[4:5], v[0:1], v[100:101], v[4:5]
	global_store_dwordx4 v[22:23], v[4:7], off
	s_waitcnt vmcnt(15)
	s_nop 1
	v_mov_b64_e32 v[4:5], v[172:173]
	v_mov_b64_e32 v[6:7], v[174:175]
	ds_read2_b32 v[28:29], v95 offset1:1
	ds_read2_b32 v[100:101], v96 offset1:1
	ds_read2_b32 v[102:103], v97 offset1:1
	ds_read2_b32 v[104:105], v94 offset1:1
	v_lshl_add_u64 v[22:23], v[20:21], 0, v[24:25]
	v_lshlrev_b64 v[24:25], 2, v[8:9]
	v_lshl_add_u64 v[26:27], v[18:19], 0, v[24:25]
	v_or_b32_e32 v8, s21, v41
	v_lshlrev_b32_e32 v8, 10, v8
	s_addk_i32 s21, 0xe080
	s_lshr_b32 s21, s21, 12
	s_add_i32 s21, s21, 1
	s_and_b64 s[6:7], s[6:7], exec
	s_cselect_b32 s6, 0, s21
	s_mul_hi_u32 s7, s6, 0x6000
	s_mulk_i32 s6, 0x6000
	s_add_u32 s6, s2, s6
	s_addc_u32 s7, s3, s7
	s_add_u32 s6, s6, s8
	s_addc_u32 s7, s7, 0
	s_add_i32 s10, s10, s79
	s_cmpk_lt_u32 s10, 0x60
	s_waitcnt lgkmcnt(3)
	v_pk_fma_f32 v[6:7], v[2:3], v[28:29], v[6:7]
	s_waitcnt lgkmcnt(0)
	v_pk_fma_f32 v[4:5], v[0:1], v[104:105], v[4:5]
	global_store_dwordx4 v[22:23], v[4:7], off
	s_waitcnt vmcnt(15)
	s_nop 1
	v_mov_b64_e32 v[4:5], v[168:169]
	v_mov_b64_e32 v[6:7], v[170:171]
	v_lshl_add_u64 v[22:23], v[20:21], 0, v[24:25]
	v_lshlrev_b64 v[24:25], 2, v[8:9]
	v_lshl_add_u64 v[26:27], v[18:19], 0, v[24:25]
	v_or_b32_e32 v8, s20, v132
	v_lshl_add_u64 v[28:29], s[6:7], 0, v[16:17]
	v_lshlrev_b32_e32 v8, 10, v8
	v_add_co_u32_e32 v28, vcc, s19, v28
	v_pk_fma_f32 v[6:7], v[2:3], v[102:103], v[6:7]
	v_pk_fma_f32 v[4:5], v[0:1], v[100:101], v[4:5]
	global_store_dwordx4 v[22:23], v[4:7], off
	s_waitcnt vmcnt(15)
	s_nop 1
	v_mov_b64_e32 v[4:5], v[164:165]
	v_mov_b64_e32 v[6:7], v[166:167]
	ds_read2_b32 v[100:101], v99 offset1:1
	ds_read2_b32 v[102:103], v98 offset1:1
	v_lshl_add_u64 v[22:23], v[20:21], 0, v[24:25]
	v_lshlrev_b64 v[24:25], 2, v[8:9]
	v_addc_co_u32_e32 v29, vcc, 0, v29, vcc
	v_lshl_add_u64 v[26:27], v[18:19], 0, v[24:25]
	v_or_b32_e32 v8, s20, v133
	v_lshlrev_b32_e32 v8, 10, v8
	s_waitcnt lgkmcnt(1)
	v_pk_fma_f32 v[2:3], v[2:3], v[100:101], v[6:7]
	s_waitcnt lgkmcnt(0)
	v_pk_fma_f32 v[0:1], v[0:1], v[102:103], v[4:5]
	global_store_dwordx4 v[22:23], v[0:3], off
	v_mov_b32_e32 v104, v8
	v_mov_b32_e32 v105, v9
	v_mov_b32_e32 v110, v18
	v_mov_b32_e32 v111, v19
	v_mov_b32_e32 v118, v24
	v_mov_b32_e32 v119, v25
	v_mov_b32_e32 v120, v26
	v_mov_b32_e32 v121, v27
	global_load_dwordx4 v[250:253], v[28:29], off
	global_load_dwordx4 v[246:249], v[120:121], off
	v_lshlrev_b64 v[118:119], 2, v[104:105]
	v_lshl_add_u64 v[120:121], v[110:111], 0, v[118:119]
	v_or_b32_e32 v104, s20, v112
	v_lshlrev_b32_e32 v104, 10, v104
	global_load_dwordx4 v[242:245], v[120:121], off
	v_lshlrev_b64 v[118:119], 2, v[104:105]
	v_lshl_add_u64 v[120:121], v[110:111], 0, v[118:119]
	v_or_b32_e32 v104, s20, v113
	v_lshlrev_b32_e32 v104, 10, v104
	global_load_dwordx4 v[238:241], v[120:121], off
	v_lshlrev_b64 v[118:119], 2, v[104:105]
	v_lshl_add_u64 v[120:121], v[110:111], 0, v[118:119]
	v_or_b32_e32 v104, s20, v114
	v_lshlrev_b32_e32 v104, 10, v104
	global_load_dwordx4 v[234:237], v[120:121], off
	v_lshlrev_b64 v[118:119], 2, v[104:105]
	v_lshl_add_u64 v[120:121], v[110:111], 0, v[118:119]
	v_or_b32_e32 v104, s20, v115
	v_lshlrev_b32_e32 v104, 10, v104
	global_load_dwordx4 v[212:215], v[120:121], off
	v_lshlrev_b64 v[118:119], 2, v[104:105]
	v_lshl_add_u64 v[120:121], v[110:111], 0, v[118:119]
	v_or_b32_e32 v104, s20, v116
	v_lshlrev_b32_e32 v104, 10, v104
	global_load_dwordx4 v[208:211], v[120:121], off
	v_lshlrev_b64 v[118:119], 2, v[104:105]
	v_lshl_add_u64 v[120:121], v[110:111], 0, v[118:119]
	v_or_b32_e32 v104, s20, v135
	v_lshlrev_b32_e32 v104, 10, v104
	global_load_dwordx4 v[204:207], v[120:121], off
	v_lshlrev_b64 v[118:119], 2, v[104:105]
	v_lshl_add_u64 v[120:121], v[110:111], 0, v[118:119]
	v_or_b32_e32 v104, s20, v200
	v_lshlrev_b32_e32 v104, 10, v104
	global_load_dwordx4 v[196:199], v[120:121], off
	v_lshlrev_b64 v[118:119], 2, v[104:105]
	v_lshl_add_u64 v[120:121], v[110:111], 0, v[118:119]
	v_or_b32_e32 v104, s20, v35
	v_lshlrev_b32_e32 v104, 10, v104
	global_load_dwordx4 v[192:195], v[120:121], off
	v_lshlrev_b64 v[118:119], 2, v[104:105]
	v_lshl_add_u64 v[120:121], v[110:111], 0, v[118:119]
	v_or_b32_e32 v104, s20, v36
	v_lshlrev_b32_e32 v104, 10, v104
	global_load_dwordx4 v[188:191], v[120:121], off
	v_lshlrev_b64 v[118:119], 2, v[104:105]
	v_lshl_add_u64 v[120:121], v[110:111], 0, v[118:119]
	v_or_b32_e32 v104, s20, v37
	v_lshlrev_b32_e32 v104, 10, v104
	global_load_dwordx4 v[184:187], v[120:121], off
	v_lshlrev_b64 v[118:119], 2, v[104:105]
	v_lshl_add_u64 v[120:121], v[110:111], 0, v[118:119]
	v_or_b32_e32 v104, s20, v38
	v_lshlrev_b32_e32 v104, 10, v104
	global_load_dwordx4 v[180:183], v[120:121], off
	v_lshlrev_b64 v[118:119], 2, v[104:105]
	v_lshl_add_u64 v[120:121], v[110:111], 0, v[118:119]
	v_add_lshl_u32 v104, s20, v39, 10
	global_load_dwordx4 v[176:179], v[120:121], off
	v_lshlrev_b64 v[118:119], 2, v[104:105]
	v_lshl_add_u64 v[120:121], v[110:111], 0, v[118:119]
	v_add_lshl_u32 v104, s20, v40, 10
	global_load_dwordx4 v[172:175], v[120:121], off
	v_lshlrev_b64 v[118:119], 2, v[104:105]
	v_lshl_add_u64 v[120:121], v[110:111], 0, v[118:119]
	v_add_lshl_u32 v104, s20, v41, 10
	global_load_dwordx4 v[168:171], v[120:121], off
	v_lshlrev_b64 v[118:119], 2, v[104:105]
	v_lshl_add_u64 v[110:111], v[110:111], 0, v[118:119]
	global_load_dwordx4 v[164:167], v[110:111], off
	s_waitcnt vmcnt(16)
	s_nop 1
	v_mov_b64_e32 v[0:1], v[250:251]
	v_mov_b64_e32 v[2:3], v[252:253]
	s_nop 0
	s_waitcnt vmcnt(15)
	s_nop 1
	v_mov_b64_e32 v[4:5], v[246:247]
	v_mov_b64_e32 v[6:7], v[248:249]
	v_lshl_add_u64 v[22:23], v[20:21], 0, v[24:25]
	v_lshlrev_b64 v[24:25], 2, v[8:9]
	v_lshl_add_u64 v[26:27], v[18:19], 0, v[24:25]
	v_or_b32_e32 v8, s20, v112
	v_lshlrev_b32_e32 v8, 10, v8
	v_pk_fma_f32 v[6:7], v[2:3], v[32:33], v[6:7]
	v_pk_fma_f32 v[4:5], v[0:1], v[30:31], v[4:5]
	global_store_dwordx4 v[22:23], v[4:7], off
	s_waitcnt vmcnt(15)
	s_nop 1
	v_mov_b64_e32 v[4:5], v[242:243]
	v_mov_b64_e32 v[6:7], v[244:245]
	ds_read2_b32 v[28:29], v43 offset0:2 offset1:3
	ds_read2_b32 v[30:31], v44 offset1:1
	ds_read2_b32 v[32:33], v44 offset0:2 offset1:3
	ds_read2_b32 v[100:101], v43 offset1:1
	v_lshl_add_u64 v[22:23], v[20:21], 0, v[24:25]
	v_lshlrev_b64 v[24:25], 2, v[8:9]
	v_lshl_add_u64 v[26:27], v[18:19], 0, v[24:25]
	v_or_b32_e32 v8, s20, v113
	v_lshlrev_b32_e32 v8, 10, v8
	s_waitcnt lgkmcnt(3)
	v_pk_fma_f32 v[6:7], v[2:3], v[28:29], v[6:7]
	s_waitcnt lgkmcnt(0)
	v_pk_fma_f32 v[4:5], v[0:1], v[100:101], v[4:5]
	global_store_dwordx4 v[22:23], v[4:7], off
	s_waitcnt vmcnt(15)
	s_nop 1
	v_mov_b64_e32 v[4:5], v[238:239]
	v_mov_b64_e32 v[6:7], v[240:241]
	v_lshl_add_u64 v[22:23], v[20:21], 0, v[24:25]
	v_lshlrev_b64 v[24:25], 2, v[8:9]
	v_lshl_add_u64 v[26:27], v[18:19], 0, v[24:25]
	v_or_b32_e32 v8, s20, v114
	v_lshlrev_b32_e32 v8, 10, v8
	v_pk_fma_f32 v[6:7], v[2:3], v[32:33], v[6:7]
	v_pk_fma_f32 v[4:5], v[0:1], v[30:31], v[4:5]
	global_store_dwordx4 v[22:23], v[4:7], off
	s_waitcnt vmcnt(15)
	s_nop 1
	v_mov_b64_e32 v[4:5], v[234:235]
	v_mov_b64_e32 v[6:7], v[236:237]
	ds_read2_b32 v[28:29], v45 offset0:2 offset1:3
	ds_read2_b32 v[30:31], v46 offset1:1
	ds_read2_b32 v[32:33], v46 offset0:2 offset1:3
	ds_read2_b32 v[100:101], v45 offset1:1
	v_lshl_add_u64 v[22:23], v[20:21], 0, v[24:25]
	v_lshlrev_b64 v[24:25], 2, v[8:9]
	v_lshl_add_u64 v[26:27], v[18:19], 0, v[24:25]
	v_or_b32_e32 v8, s20, v115
	v_lshlrev_b32_e32 v8, 10, v8
	s_waitcnt lgkmcnt(3)
	v_pk_fma_f32 v[6:7], v[2:3], v[28:29], v[6:7]
	s_waitcnt lgkmcnt(0)
	v_pk_fma_f32 v[4:5], v[0:1], v[100:101], v[4:5]
	global_store_dwordx4 v[22:23], v[4:7], off
	s_waitcnt vmcnt(15)
	s_nop 1
	v_mov_b64_e32 v[4:5], v[212:213]
	v_mov_b64_e32 v[6:7], v[214:215]
	v_lshl_add_u64 v[22:23], v[20:21], 0, v[24:25]
	v_lshlrev_b64 v[24:25], 2, v[8:9]
	v_lshl_add_u64 v[26:27], v[18:19], 0, v[24:25]
	v_or_b32_e32 v8, s20, v116
	v_lshlrev_b32_e32 v8, 10, v8
	v_pk_fma_f32 v[6:7], v[2:3], v[32:33], v[6:7]
	v_pk_fma_f32 v[4:5], v[0:1], v[30:31], v[4:5]
	global_store_dwordx4 v[22:23], v[4:7], off
	s_waitcnt vmcnt(15)
	s_nop 1
	v_mov_b64_e32 v[4:5], v[208:209]
	v_mov_b64_e32 v[6:7], v[210:211]
	ds_read2_b32 v[28:29], v47 offset0:2 offset1:3
	ds_read2_b32 v[30:31], v48 offset1:1
	ds_read2_b32 v[32:33], v48 offset0:2 offset1:3
	ds_read2_b32 v[100:101], v47 offset1:1
	v_lshl_add_u64 v[22:23], v[20:21], 0, v[24:25]
	v_lshlrev_b64 v[24:25], 2, v[8:9]
	v_lshl_add_u64 v[26:27], v[18:19], 0, v[24:25]
	v_or_b32_e32 v8, s20, v135
	v_lshlrev_b32_e32 v8, 10, v8
	s_waitcnt lgkmcnt(3)
	v_pk_fma_f32 v[6:7], v[2:3], v[28:29], v[6:7]
	s_waitcnt lgkmcnt(0)
	v_pk_fma_f32 v[4:5], v[0:1], v[100:101], v[4:5]
	global_store_dwordx4 v[22:23], v[4:7], off
	s_waitcnt vmcnt(15)
	s_nop 1
	v_mov_b64_e32 v[4:5], v[204:205]
	v_mov_b64_e32 v[6:7], v[206:207]
	v_lshl_add_u64 v[22:23], v[20:21], 0, v[24:25]
	v_lshlrev_b64 v[24:25], 2, v[8:9]
	v_lshl_add_u64 v[26:27], v[18:19], 0, v[24:25]
	v_or_b32_e32 v8, s20, v200
	v_lshlrev_b32_e32 v8, 10, v8
	v_pk_fma_f32 v[6:7], v[2:3], v[32:33], v[6:7]
	v_pk_fma_f32 v[4:5], v[0:1], v[30:31], v[4:5]
	global_store_dwordx4 v[22:23], v[4:7], off
	s_waitcnt vmcnt(15)
	s_nop 1
	v_mov_b64_e32 v[4:5], v[196:197]
	v_mov_b64_e32 v[6:7], v[198:199]
	ds_read2_b32 v[28:29], v49 offset0:2 offset1:3
	ds_read2_b32 v[30:31], v50 offset1:1
	ds_read2_b32 v[32:33], v50 offset0:2 offset1:3
	ds_read2_b32 v[100:101], v49 offset1:1
	v_lshl_add_u64 v[22:23], v[20:21], 0, v[24:25]
	v_lshlrev_b64 v[24:25], 2, v[8:9]
	v_lshl_add_u64 v[26:27], v[18:19], 0, v[24:25]
	v_or_b32_e32 v8, s20, v35
	v_lshlrev_b32_e32 v8, 10, v8
	s_waitcnt lgkmcnt(3)
	v_pk_fma_f32 v[6:7], v[2:3], v[28:29], v[6:7]
	s_waitcnt lgkmcnt(0)
	v_pk_fma_f32 v[4:5], v[0:1], v[100:101], v[4:5]
	global_store_dwordx4 v[22:23], v[4:7], off
	s_waitcnt vmcnt(15)
	s_nop 1
	v_mov_b64_e32 v[4:5], v[192:193]
	v_mov_b64_e32 v[6:7], v[194:195]
	v_lshl_add_u64 v[22:23], v[20:21], 0, v[24:25]
	v_lshlrev_b64 v[24:25], 2, v[8:9]
	v_lshl_add_u64 v[26:27], v[18:19], 0, v[24:25]
	v_or_b32_e32 v8, s20, v36
	v_lshlrev_b32_e32 v8, 10, v8
	v_pk_fma_f32 v[6:7], v[2:3], v[32:33], v[6:7]
	v_pk_fma_f32 v[4:5], v[0:1], v[30:31], v[4:5]
	global_store_dwordx4 v[22:23], v[4:7], off
	s_waitcnt vmcnt(15)
	s_nop 1
	v_mov_b64_e32 v[4:5], v[188:189]
	v_mov_b64_e32 v[6:7], v[190:191]
	ds_read2_b32 v[28:29], v51 offset0:2 offset1:3
	ds_read2_b32 v[30:31], v52 offset1:1
	ds_read2_b32 v[32:33], v52 offset0:2 offset1:3
	ds_read2_b32 v[100:101], v51 offset1:1
	v_lshl_add_u64 v[22:23], v[20:21], 0, v[24:25]
	v_lshlrev_b64 v[24:25], 2, v[8:9]
	v_lshl_add_u64 v[26:27], v[18:19], 0, v[24:25]
	v_or_b32_e32 v8, s20, v37
	v_lshlrev_b32_e32 v8, 10, v8
	s_waitcnt lgkmcnt(3)
	v_pk_fma_f32 v[6:7], v[2:3], v[28:29], v[6:7]
	s_waitcnt lgkmcnt(0)
	v_pk_fma_f32 v[4:5], v[0:1], v[100:101], v[4:5]
	global_store_dwordx4 v[22:23], v[4:7], off
	s_waitcnt vmcnt(15)
	s_nop 1
	v_mov_b64_e32 v[4:5], v[184:185]
	v_mov_b64_e32 v[6:7], v[186:187]
	v_lshl_add_u64 v[22:23], v[20:21], 0, v[24:25]
	v_lshlrev_b64 v[24:25], 2, v[8:9]
	v_lshl_add_u64 v[26:27], v[18:19], 0, v[24:25]
	v_or_b32_e32 v8, s20, v38
	v_lshlrev_b32_e32 v8, 10, v8
	v_pk_fma_f32 v[6:7], v[2:3], v[32:33], v[6:7]
	v_pk_fma_f32 v[4:5], v[0:1], v[30:31], v[4:5]
	global_store_dwordx4 v[22:23], v[4:7], off
	s_waitcnt vmcnt(15)
	s_nop 1
	v_mov_b64_e32 v[4:5], v[180:181]
	v_mov_b64_e32 v[6:7], v[182:183]
	ds_read2_b32 v[28:29], v53 offset0:2 offset1:3
	ds_read2_b32 v[30:31], v54 offset1:1
	ds_read2_b32 v[32:33], v54 offset0:2 offset1:3
	ds_read2_b32 v[100:101], v53 offset1:1
	v_lshl_add_u64 v[22:23], v[20:21], 0, v[24:25]
	v_lshlrev_b64 v[24:25], 2, v[8:9]
	v_lshl_add_u64 v[26:27], v[18:19], 0, v[24:25]
	v_add_lshl_u32 v8, s20, v39, 10
	s_waitcnt lgkmcnt(3)
	v_pk_fma_f32 v[6:7], v[2:3], v[28:29], v[6:7]
	s_waitcnt lgkmcnt(0)
	v_pk_fma_f32 v[4:5], v[0:1], v[100:101], v[4:5]
	global_store_dwordx4 v[22:23], v[4:7], off
	s_waitcnt vmcnt(15)
	s_nop 1
	v_mov_b64_e32 v[4:5], v[176:177]
	v_mov_b64_e32 v[6:7], v[178:179]
	v_lshl_add_u64 v[22:23], v[20:21], 0, v[24:25]
	v_lshlrev_b64 v[24:25], 2, v[8:9]
	v_lshl_add_u64 v[26:27], v[18:19], 0, v[24:25]
	v_add_lshl_u32 v8, s20, v40, 10
	v_pk_fma_f32 v[6:7], v[2:3], v[32:33], v[6:7]
	v_pk_fma_f32 v[4:5], v[0:1], v[30:31], v[4:5]
	global_store_dwordx4 v[22:23], v[4:7], off
	s_waitcnt vmcnt(15)
	s_nop 1
	v_mov_b64_e32 v[4:5], v[172:173]
	v_mov_b64_e32 v[6:7], v[174:175]
	ds_read2_b32 v[28:29], v55 offset0:2 offset1:3
	ds_read2_b32 v[30:31], v56 offset1:1
	ds_read2_b32 v[32:33], v56 offset0:2 offset1:3
	ds_read2_b32 v[100:101], v55 offset1:1
	v_lshl_add_u64 v[22:23], v[20:21], 0, v[24:25]
	v_lshlrev_b64 v[24:25], 2, v[8:9]
	v_lshl_add_u64 v[26:27], v[18:19], 0, v[24:25]
	v_add_lshl_u32 v8, s20, v41, 10
	s_waitcnt lgkmcnt(3)
	v_pk_fma_f32 v[6:7], v[2:3], v[28:29], v[6:7]
	s_waitcnt lgkmcnt(0)
	v_pk_fma_f32 v[4:5], v[0:1], v[100:101], v[4:5]
	global_store_dwordx4 v[22:23], v[4:7], off
	s_waitcnt vmcnt(15)
	s_nop 1
	v_mov_b64_e32 v[4:5], v[168:169]
	v_mov_b64_e32 v[6:7], v[170:171]
	v_lshl_add_u64 v[22:23], v[20:21], 0, v[24:25]
	v_lshlrev_b64 v[24:25], 2, v[8:9]
	v_lshl_add_u64 v[18:19], v[18:19], 0, v[24:25]
	v_pk_fma_f32 v[6:7], v[2:3], v[32:33], v[6:7]
	v_pk_fma_f32 v[4:5], v[0:1], v[30:31], v[4:5]
	global_store_dwordx4 v[22:23], v[4:7], off
	s_waitcnt vmcnt(15)
	s_nop 1
	v_mov_b64_e32 v[4:5], v[164:165]
	v_mov_b64_e32 v[6:7], v[166:167]
	v_lshl_add_u64 v[18:19], v[20:21], 0, v[24:25]
	ds_read2_b32 v[20:21], v57 offset0:2 offset1:3
	ds_read2_b32 v[22:23], v57 offset1:1
	s_waitcnt lgkmcnt(1)
	v_pk_fma_f32 v[2:3], v[2:3], v[20:21], v[6:7]
	s_waitcnt lgkmcnt(0)
	v_pk_fma_f32 v[0:1], v[0:1], v[22:23], v[4:5]
	global_store_dwordx4 v[18:19], v[0:3], off
	s_barrier
	s_cbranch_scc1 .LBB0_656
	s_load_dwordx2 s[2:3], s[0:1], 0x130
	v_accvgpr_read_b32 v104, a206
	v_mov_b32_e32 v20, v135

.LBB0_1145:
	s_lshr_b32 s13, s6, 3
	s_add_i32 s13, s13, s7
	s_lshl_b32 s4, s13, 19
	v_lshl_add_u64 v[0:1], v[18:19], 0, s[4:5]
	v_add_co_u32_e32 v4, vcc, 0x10000, v0
	s_and_b32 s12, s6, 7
	s_nop 0
	v_addc_co_u32_e32 v5, vcc, 0, v1, vcc
	v_add_co_u32_e32 v6, vcc, 0x20000, v0
	s_lshl_b32 s4, s12, 18
	s_nop 0
	v_addc_co_u32_e32 v7, vcc, 0, v1, vcc
	v_add_co_u32_e32 v8, vcc, 0x30000, v0
	v_lshl_add_u64 v[2:3], v[20:21], 0, s[4:5]
	s_nop 0
	v_addc_co_u32_e32 v9, vcc, 0, v1, vcc
	v_add_co_u32_e32 v10, vcc, 0x40000, v0
	global_load_dwordx4 v[100:103], v[0:1], off
	global_load_dwordx4 v[104:107], v[0:1], off offset:128
	v_addc_co_u32_e32 v11, vcc, 0, v1, vcc
	v_add_co_u32_e32 v12, vcc, 0x50000, v0
	global_load_dwordx4 v[108:111], v[2:3], off
	global_load_dwordx4 v[112:115], v[2:3], off offset:128
	v_addc_co_u32_e32 v13, vcc, 0, v1, vcc
	v_add_co_u32_e32 v14, vcc, 0x60000, v0
	global_load_dwordx4 v[116:119], v[4:5], off
	global_load_dwordx4 v[120:123], v[4:5], off offset:128
	v_addc_co_u32_e32 v15, vcc, 0, v1, vcc
	v_add_co_u32_e32 v26, vcc, 0x70000, v0
	global_load_dwordx4 v[124:127], v[6:7], off
	global_load_dwordx4 v[128:131], v[6:7], off offset:128
	v_addc_co_u32_e32 v27, vcc, 0, v1, vcc
	v_add_co_u32_e32 v28, vcc, s8, v2
	global_load_dwordx4 v[140:143], v[8:9], off
	global_load_dwordx4 v[144:147], v[8:9], off offset:128
	v_addc_co_u32_e32 v29, vcc, 0, v3, vcc
	v_add_co_u32_e32 v30, vcc, s9, v2
	global_load_dwordx4 v[148:151], v[10:11], off
	global_load_dwordx4 v[152:155], v[10:11], off offset:128
	v_addc_co_u32_e32 v31, vcc, 0, v3, vcc
	v_add_co_u32_e32 v32, vcc, s10, v2
	global_load_dwordx4 v[156:159], v[12:13], off
	global_load_dwordx4 v[160:163], v[12:13], off offset:128
	global_load_dwordx4 v[164:167], v[14:15], off
	global_load_dwordx4 v[168:171], v[14:15], off offset:128
	global_load_dwordx4 v[172:175], v[26:27], off
	global_load_dwordx4 v[176:179], v[26:27], off offset:128
	global_load_dwordx4 v[180:183], v[28:29], off
	global_load_dwordx4 v[184:187], v[28:29], off offset:128
	v_addc_co_u32_e32 v33, vcc, 0, v3, vcc
	global_load_dwordx4 v[188:191], v[30:31], off
	global_load_dwordx4 v[192:195], v[30:31], off offset:128
	global_load_dwordx4 v[196:199], v[32:33], off
	global_load_dwordx4 v[200:203], v[32:33], off offset:128
	s_lshl_b32 s14, s13, 8
	s_add_i32 s4, s14, 0xffffe000
	s_add_i32 s15, s14, 0xffffe080
	s_lshr_b32 s4, s4, 12
	s_lshr_b32 s15, s15, 12
	s_add_i32 s4, s4, 6
	s_add_i32 s15, s15, 6
	s_cmp_lt_u32 s13, 32
	s_cselect_b32 s4, 5, s4
	s_cselect_b32 s13, 5, s15
	s_mul_hi_u32 s15, s4, 0x6000
	s_mulk_i32 s4, 0x6000
	s_add_u32 s16, s2, s4
	s_addc_u32 s15, s3, s15
	s_lshl_b32 s4, s12, 9
	v_or_b32_e32 v16, s14, v135
	s_add_u32 s16, s16, s4
	v_lshlrev_b32_e32 v16, 10, v16
	s_addc_u32 s17, s15, 0
	s_mul_hi_u32 s12, s13, 0x6000
	s_mulk_i32 s13, 0x6000
	s_waitcnt vmcnt(23)
	ds_write_b128 v60, v[100:103]
	s_waitcnt vmcnt(21)
	ds_write_b128 v60, v[108:111] offset:36864
	s_waitcnt vmcnt(19)
	ds_write_b128 v60, v[116:119] offset:4608
	s_waitcnt vmcnt(17)
	ds_write_b128 v60, v[124:127] offset:9216
	s_waitcnt vmcnt(15)
	ds_write_b128 v60, v[140:143] offset:13824
	s_waitcnt vmcnt(13)
	ds_write_b128 v60, v[148:151] offset:18432
	s_waitcnt vmcnt(11)
	ds_write_b128 v60, v[156:159] offset:23040
	s_waitcnt vmcnt(9)
	ds_write_b128 v60, v[164:167] offset:27648
	s_waitcnt vmcnt(7)
	ds_write_b128 v60, v[172:175] offset:32256
	s_waitcnt vmcnt(5)
	ds_write_b128 v60, v[180:183] offset:41472
	s_waitcnt vmcnt(3)
	ds_write_b128 v60, v[188:191] offset:46080
	s_waitcnt vmcnt(1)
	ds_write_b128 v60, v[196:199] offset:50688
	s_waitcnt lgkmcnt(0)
	s_barrier
	ds_read_b128 v[100:103], v59
	ds_read_b128 v[108:111], v62 offset:36864
	ds_read_b128 v[116:119], v59 offset:4608
	ds_read_b128 v[124:127], v62 offset:41472
	s_waitcnt lgkmcnt(2)
	v_mfma_f32_32x32x16_bf16 a[112:127], v[100:103], v[108:111], 0
	s_waitcnt lgkmcnt(0)
	v_mfma_f32_32x32x16_bf16 a[96:111], v[100:103], v[124:127], 0
	ds_read_b128 v[100:103], v59 offset:9216
	s_waitcnt lgkmcnt(0)
	v_mfma_f32_32x32x16_bf16 a[48:63], v[100:103], v[108:111], 0
	v_mfma_f32_32x32x16_bf16 a[32:47], v[100:103], v[124:127], 0
	ds_read_b128 v[100:103], v61
	ds_write_b128 v60, v[104:107] offset:55296
	ds_write_b128 v60, v[120:123] offset:59904
	ds_write_b128 v60, v[128:131] offset:64512
	ds_write_b128 v63, v[144:147] offset:55296
	ds_write_b128 v64, v[152:155] offset:55296
	ds_write_b128 v65, v[160:163] offset:55296
	ds_write_b128 v66, v[168:171] offset:55296
	ds_write_b128 v67, v[176:179] offset:55296
	ds_write_b128 v68, v[112:115]
	ds_write_b128 v68, v[184:187] offset:4608
	ds_write_b128 v68, v[192:195] offset:9216
	s_waitcnt vmcnt(0)
	ds_write_b128 v68, v[200:203] offset:13824
	v_mfma_f32_32x32x16_bf16 a[80:95], v[116:119], v[108:111], 0
	v_mfma_f32_32x32x16_bf16 a[64:79], v[116:119], v[124:127], 0
	s_waitcnt lgkmcnt(12)
	v_mfma_f32_32x32x16_bf16 a[16:31], v[100:103], v[108:111], 0
	v_mfma_f32_32x32x16_bf16 a[0:15], v[100:103], v[124:127], 0
	ds_read_b128 v[100:103], v59 offset:32
	ds_read_b128 v[104:107], v62 offset:36896
	ds_read_b128 v[108:111], v62 offset:36928
	ds_read_b128 v[112:115], v59 offset:64
	ds_read_b128 v[116:119], v62 offset:41504
	ds_read_b128 v[120:123], v62 offset:36960
	s_waitcnt lgkmcnt(4)
	v_mfma_f32_32x32x16_bf16 a[112:127], v[100:103], v[104:107], a[112:127]
	s_waitcnt lgkmcnt(1)
	v_mfma_f32_32x32x16_bf16 a[96:111], v[100:103], v[116:119], a[96:111]
	ds_read_b128 v[100:103], v59 offset:4640
	ds_read_b128 v[124:127], v59 offset:96
	s_waitcnt lgkmcnt(1)
	v_mfma_f32_32x32x16_bf16 a[80:95], v[100:103], v[104:107], a[80:95]
	v_mfma_f32_32x32x16_bf16 a[64:79], v[100:103], v[116:119], a[64:79]
	ds_read_b128 v[100:103], v59 offset:9248
	ds_read_b128 v[128:131], v59 offset:9280
	s_waitcnt lgkmcnt(1)
	v_mfma_f32_32x32x16_bf16 a[48:63], v[100:103], v[104:107], a[48:63]
	v_mfma_f32_32x32x16_bf16 a[32:47], v[100:103], v[116:119], a[32:47]
	ds_read_b128 v[100:103], v61 offset:32
	ds_read_b128 v[140:143], v59 offset:9312
	s_waitcnt lgkmcnt(1)
	v_mfma_f32_32x32x16_bf16 a[16:31], v[100:103], v[104:107], a[16:31]
	v_mfma_f32_32x32x16_bf16 a[0:15], v[100:103], v[116:119], a[0:15]
	ds_read_b128 v[100:103], v62 offset:41536
	ds_read_b128 v[104:107], v62 offset:41568
	v_mfma_f32_32x32x16_bf16 a[112:127], v[112:115], v[108:111], a[112:127]
	s_waitcnt lgkmcnt(1)
	v_mfma_f32_32x32x16_bf16 a[96:111], v[112:115], v[100:103], a[96:111]
	ds_read_b128 v[112:115], v59 offset:4672
	ds_read_b128 v[116:119], v59 offset:4704
	s_waitcnt lgkmcnt(1)
	v_mfma_f32_32x32x16_bf16 a[80:95], v[112:115], v[108:111], a[80:95]
	v_mfma_f32_32x32x16_bf16 a[64:79], v[112:115], v[100:103], a[64:79]
	v_mfma_f32_32x32x16_bf16 a[48:63], v[128:131], v[108:111], a[48:63]
	v_mfma_f32_32x32x16_bf16 a[32:47], v[128:131], v[100:103], a[32:47]
	ds_read_b128 v[112:115], v61 offset:64
	ds_read_b128 v[128:131], v61 offset:96
	s_waitcnt lgkmcnt(1)
	v_mfma_f32_32x32x16_bf16 a[16:31], v[112:115], v[108:111], a[16:31]
	v_mfma_f32_32x32x16_bf16 a[0:15], v[112:115], v[100:103], a[0:15]
	global_load_dwordx4 v[100:103], v[32:33], off offset:256
	v_mfma_f32_32x32x16_bf16 a[112:127], v[124:127], v[120:123], a[112:127]
	v_mfma_f32_32x32x16_bf16 a[96:111], v[124:127], v[104:107], a[96:111]
	v_mfma_f32_32x32x16_bf16 a[80:95], v[116:119], v[120:123], a[80:95]
	v_mfma_f32_32x32x16_bf16 a[64:79], v[116:119], v[104:107], a[64:79]
	v_mfma_f32_32x32x16_bf16 a[48:63], v[140:143], v[120:123], a[48:63]
	v_mfma_f32_32x32x16_bf16 a[32:47], v[140:143], v[104:107], a[32:47]
	global_load_dwordx4 v[108:111], v[30:31], off offset:256
	global_load_dwordx4 v[112:115], v[28:29], off offset:256
	global_load_dwordx4 v[116:119], v[2:3], off offset:256
	global_load_dwordx4 v[124:127], v[8:9], off offset:256
	global_load_dwordx4 v[140:143], v[6:7], off offset:256
	global_load_dwordx4 v[144:147], v[4:5], off offset:256
	global_load_dwordx4 v[148:151], v[0:1], off offset:256
	s_waitcnt lgkmcnt(0)
	v_mfma_f32_32x32x16_bf16 a[16:31], v[128:131], v[120:123], a[16:31]
	global_load_dwordx4 v[120:123], v[12:13], off offset:256
	global_load_dwordx4 v[152:155], v[10:11], off offset:256
	global_load_dwordx4 v[156:159], v[26:27], off offset:256
	global_load_dwordx4 v[160:163], v[14:15], off offset:256
	s_barrier
	v_mfma_f32_32x32x16_bf16 a[0:15], v[128:131], v[104:107], a[0:15]
	ds_read_b128 v[104:107], v59 offset:55296
	ds_read_b128 v[128:131], v69
	ds_read_b128 v[164:167], v59 offset:59904
	ds_read_b128 v[168:171], v69 offset:4608
	s_waitcnt lgkmcnt(2)
	v_mfma_f32_32x32x16_bf16 a[112:127], v[104:107], v[128:131], a[112:127]
	s_waitcnt lgkmcnt(0)
	v_mfma_f32_32x32x16_bf16 a[96:111], v[104:107], v[168:171], a[96:111]
	ds_read_b128 v[104:107], v59 offset:64512
	s_waitcnt lgkmcnt(0)
	v_mfma_f32_32x32x16_bf16 a[48:63], v[104:107], v[128:131], a[48:63]
	v_mfma_f32_32x32x16_bf16 a[32:47], v[104:107], v[168:171], a[32:47]
	ds_read_b128 v[104:107], v61 offset:55296
	s_waitcnt vmcnt(4)
	ds_write_b128 v60, v[148:151]
	ds_write_b128 v60, v[144:147] offset:4608
	ds_write_b128 v60, v[140:143] offset:9216
	ds_write_b128 v60, v[124:127] offset:13824
	s_waitcnt vmcnt(2)
	ds_write_b128 v60, v[152:155] offset:18432
	ds_write_b128 v60, v[120:123] offset:23040
	s_waitcnt vmcnt(0)
	ds_write_b128 v60, v[160:163] offset:27648
	ds_write_b128 v60, v[156:159] offset:32256
	ds_write_b128 v60, v[116:119] offset:36864
	ds_write_b128 v60, v[112:115] offset:41472
	ds_write_b128 v60, v[108:111] offset:46080
	ds_write_b128 v60, v[100:103] offset:50688
	v_mfma_f32_32x32x16_bf16 a[80:95], v[164:167], v[128:131], a[80:95]
	v_mfma_f32_32x32x16_bf16 a[64:79], v[164:167], v[168:171], a[64:79]
	s_waitcnt lgkmcnt(12)
	v_mfma_f32_32x32x16_bf16 a[16:31], v[104:107], v[128:131], a[16:31]
	v_mfma_f32_32x32x16_bf16 a[0:15], v[104:107], v[168:171], a[0:15]
	ds_read_b128 v[100:103], v59 offset:55328
	ds_read_b128 v[104:107], v69 offset:32
	ds_read_b128 v[108:111], v69 offset:64
	ds_read_b128 v[112:115], v59 offset:55360
	ds_read_b128 v[116:119], v69 offset:4640
	ds_read_b128 v[120:123], v69 offset:96
	s_waitcnt lgkmcnt(4)
	v_mfma_f32_32x32x16_bf16 a[112:127], v[100:103], v[104:107], a[112:127]
	s_waitcnt lgkmcnt(1)
	v_mfma_f32_32x32x16_bf16 a[96:111], v[100:103], v[116:119], a[96:111]
	ds_read_b128 v[100:103], v59 offset:59936
	ds_read_b128 v[124:127], v59 offset:55392
	s_waitcnt lgkmcnt(1)
	v_mfma_f32_32x32x16_bf16 a[80:95], v[100:103], v[104:107], a[80:95]
	v_mfma_f32_32x32x16_bf16 a[64:79], v[100:103], v[116:119], a[64:79]
	ds_read_b128 v[100:103], v59 offset:64544
	ds_read_b128 v[128:131], v59 offset:64576
	s_waitcnt lgkmcnt(1)
	v_mfma_f32_32x32x16_bf16 a[48:63], v[100:103], v[104:107], a[48:63]
	v_mfma_f32_32x32x16_bf16 a[32:47], v[100:103], v[116:119], a[32:47]
	ds_read_b128 v[100:103], v61 offset:55328
	ds_read_b128 v[140:143], v59 offset:64608
	s_waitcnt lgkmcnt(1)
	v_mfma_f32_32x32x16_bf16 a[16:31], v[100:103], v[104:107], a[16:31]
	v_mfma_f32_32x32x16_bf16 a[0:15], v[100:103], v[116:119], a[0:15]
	ds_read_b128 v[100:103], v69 offset:4672
	ds_read_b128 v[104:107], v69 offset:4704
	v_mfma_f32_32x32x16_bf16 a[112:127], v[112:115], v[108:111], a[112:127]
	s_waitcnt lgkmcnt(1)
	v_mfma_f32_32x32x16_bf16 a[96:111], v[112:115], v[100:103], a[96:111]
	ds_read_b128 v[112:115], v59 offset:59968
	ds_read_b128 v[116:119], v59 offset:60000
	s_waitcnt lgkmcnt(1)
	v_mfma_f32_32x32x16_bf16 a[80:95], v[112:115], v[108:111], a[80:95]
	v_mfma_f32_32x32x16_bf16 a[64:79], v[112:115], v[100:103], a[64:79]
	v_mfma_f32_32x32x16_bf16 a[48:63], v[128:131], v[108:111], a[48:63]
	v_mfma_f32_32x32x16_bf16 a[32:47], v[128:131], v[100:103], a[32:47]
	ds_read_b128 v[112:115], v61 offset:55360
	ds_read_b128 v[128:131], v61 offset:55392
	s_waitcnt lgkmcnt(1)
	v_mfma_f32_32x32x16_bf16 a[16:31], v[112:115], v[108:111], a[16:31]
	v_mfma_f32_32x32x16_bf16 a[0:15], v[112:115], v[100:103], a[0:15]
	v_mfma_f32_32x32x16_bf16 a[112:127], v[124:127], v[120:123], a[112:127]
	v_mfma_f32_32x32x16_bf16 a[96:111], v[124:127], v[104:107], a[96:111]
	v_mfma_f32_32x32x16_bf16 a[80:95], v[116:119], v[120:123], a[80:95]
	v_mfma_f32_32x32x16_bf16 a[64:79], v[116:119], v[104:107], a[64:79]
	global_load_dwordx4 v[100:103], v[4:5], off offset:384
	global_load_dwordx4 v[108:111], v[0:1], off offset:384
	global_load_dwordx4 v[112:115], v[8:9], off offset:384
	global_load_dwordx4 v[116:119], v[6:7], off offset:384
	v_mfma_f32_32x32x16_bf16 a[48:63], v[140:143], v[120:123], a[48:63]
	v_mfma_f32_32x32x16_bf16 a[32:47], v[140:143], v[104:107], a[32:47]
	global_load_dwordx4 v[124:127], v[10:11], off offset:384
	global_load_dwordx4 v[140:143], v[12:13], off offset:384
	global_load_dwordx4 v[144:147], v[26:27], off offset:384
	global_load_dwordx4 v[148:151], v[14:15], off offset:384
	global_load_dwordx4 v[152:155], v[28:29], off offset:384
	global_load_dwordx4 v[156:159], v[2:3], off offset:384
	global_load_dwordx4 v[160:163], v[30:31], off offset:384
	s_waitcnt lgkmcnt(0)
	v_mfma_f32_32x32x16_bf16 a[16:31], v[128:131], v[120:123], a[16:31]
	global_load_dwordx4 v[120:123], v[32:33], off offset:384
	s_barrier
	v_mfma_f32_32x32x16_bf16 a[0:15], v[128:131], v[104:107], a[0:15]
	ds_read_b128 v[104:107], v59
	ds_read_b128 v[128:131], v62 offset:36864
	ds_read_b128 v[164:167], v59 offset:4608
	ds_read_b128 v[168:171], v62 offset:41472
	s_waitcnt lgkmcnt(2)
	v_mfma_f32_32x32x16_bf16 a[112:127], v[104:107], v[128:131], a[112:127]
	s_waitcnt lgkmcnt(0)
	v_mfma_f32_32x32x16_bf16 a[96:111], v[104:107], v[168:171], a[96:111]
	ds_read_b128 v[104:107], v59 offset:9216
	s_waitcnt lgkmcnt(0)
	v_mfma_f32_32x32x16_bf16 a[48:63], v[104:107], v[128:131], a[48:63]
	v_mfma_f32_32x32x16_bf16 a[32:47], v[104:107], v[168:171], a[32:47]
	ds_read_b128 v[104:107], v61
	s_waitcnt vmcnt(10)
	ds_write_b128 v60, v[108:111] offset:55296
	ds_write_b128 v60, v[100:103] offset:59904
	s_waitcnt vmcnt(8)
	ds_write_b128 v60, v[116:119] offset:64512
	ds_write_b128 v63, v[112:115] offset:55296
	s_waitcnt vmcnt(7)
	ds_write_b128 v64, v[124:127] offset:55296
	s_waitcnt vmcnt(6)
	ds_write_b128 v65, v[140:143] offset:55296
	s_waitcnt vmcnt(4)
	ds_write_b128 v66, v[148:151] offset:55296
	ds_write_b128 v67, v[144:147] offset:55296
	s_waitcnt vmcnt(2)
	ds_write_b128 v68, v[156:159]
	ds_write_b128 v68, v[152:155] offset:4608
	s_waitcnt vmcnt(1)
	ds_write_b128 v68, v[160:163] offset:9216
	s_waitcnt vmcnt(0)
	ds_write_b128 v68, v[120:123] offset:13824
	v_mfma_f32_32x32x16_bf16 a[80:95], v[164:167], v[128:131], a[80:95]
	v_mfma_f32_32x32x16_bf16 a[64:79], v[164:167], v[168:171], a[64:79]
	s_waitcnt lgkmcnt(12)
	v_mfma_f32_32x32x16_bf16 a[16:31], v[104:107], v[128:131], a[16:31]
	v_mfma_f32_32x32x16_bf16 a[0:15], v[104:107], v[168:171], a[0:15]
	ds_read_b128 v[100:103], v59 offset:32
	ds_read_b128 v[104:107], v62 offset:36896
	ds_read_b128 v[108:111], v62 offset:36928
	ds_read_b128 v[112:115], v59 offset:64
	ds_read_b128 v[116:119], v62 offset:41504
	ds_read_b128 v[120:123], v62 offset:36960
	s_waitcnt lgkmcnt(4)
	v_mfma_f32_32x32x16_bf16 a[112:127], v[100:103], v[104:107], a[112:127]
	s_waitcnt lgkmcnt(1)
	v_mfma_f32_32x32x16_bf16 a[96:111], v[100:103], v[116:119], a[96:111]
	ds_read_b128 v[100:103], v59 offset:4640
	ds_read_b128 v[124:127], v59 offset:96
	s_waitcnt lgkmcnt(1)
	v_mfma_f32_32x32x16_bf16 a[80:95], v[100:103], v[104:107], a[80:95]
	v_mfma_f32_32x32x16_bf16 a[64:79], v[100:103], v[116:119], a[64:79]
	ds_read_b128 v[100:103], v59 offset:9248
	ds_read_b128 v[128:131], v59 offset:9280
	s_waitcnt lgkmcnt(1)
	v_mfma_f32_32x32x16_bf16 a[48:63], v[100:103], v[104:107], a[48:63]
	v_mfma_f32_32x32x16_bf16 a[32:47], v[100:103], v[116:119], a[32:47]
	ds_read_b128 v[100:103], v61 offset:32
	ds_read_b128 v[140:143], v59 offset:9312
	s_waitcnt lgkmcnt(1)
	v_mfma_f32_32x32x16_bf16 a[16:31], v[100:103], v[104:107], a[16:31]
	v_mfma_f32_32x32x16_bf16 a[0:15], v[100:103], v[116:119], a[0:15]
	ds_read_b128 v[100:103], v62 offset:41536
	ds_read_b128 v[104:107], v62 offset:41568
	v_mfma_f32_32x32x16_bf16 a[112:127], v[112:115], v[108:111], a[112:127]
	s_waitcnt lgkmcnt(1)
	v_mfma_f32_32x32x16_bf16 a[96:111], v[112:115], v[100:103], a[96:111]
	ds_read_b128 v[112:115], v59 offset:4672
	ds_read_b128 v[116:119], v59 offset:4704
	s_waitcnt lgkmcnt(1)
	v_mfma_f32_32x32x16_bf16 a[80:95], v[112:115], v[108:111], a[80:95]
	v_mfma_f32_32x32x16_bf16 a[64:79], v[112:115], v[100:103], a[64:79]
	v_mfma_f32_32x32x16_bf16 a[48:63], v[128:131], v[108:111], a[48:63]
	v_mfma_f32_32x32x16_bf16 a[32:47], v[128:131], v[100:103], a[32:47]
	ds_read_b128 v[112:115], v61 offset:64
	ds_read_b128 v[128:131], v61 offset:96
	s_waitcnt lgkmcnt(1)
	v_mfma_f32_32x32x16_bf16 a[16:31], v[112:115], v[108:111], a[16:31]
	v_mfma_f32_32x32x16_bf16 a[0:15], v[112:115], v[100:103], a[0:15]
	global_load_dwordx4 v[100:103], v[32:33], off offset:512
	v_mfma_f32_32x32x16_bf16 a[112:127], v[124:127], v[120:123], a[112:127]
	v_mfma_f32_32x32x16_bf16 a[96:111], v[124:127], v[104:107], a[96:111]
	v_mfma_f32_32x32x16_bf16 a[80:95], v[116:119], v[120:123], a[80:95]
	v_mfma_f32_32x32x16_bf16 a[64:79], v[116:119], v[104:107], a[64:79]
	v_mfma_f32_32x32x16_bf16 a[48:63], v[140:143], v[120:123], a[48:63]
	v_mfma_f32_32x32x16_bf16 a[32:47], v[140:143], v[104:107], a[32:47]
	global_load_dwordx4 v[108:111], v[30:31], off offset:512
	global_load_dwordx4 v[112:115], v[28:29], off offset:512
	global_load_dwordx4 v[116:119], v[2:3], off offset:512
	global_load_dwordx4 v[124:127], v[8:9], off offset:512
	global_load_dwordx4 v[140:143], v[6:7], off offset:512
	global_load_dwordx4 v[144:147], v[4:5], off offset:512
	global_load_dwordx4 v[148:151], v[0:1], off offset:512
	s_waitcnt lgkmcnt(0)
	v_mfma_f32_32x32x16_bf16 a[16:31], v[128:131], v[120:123], a[16:31]
	global_load_dwordx4 v[120:123], v[12:13], off offset:512
	global_load_dwordx4 v[152:155], v[10:11], off offset:512
	global_load_dwordx4 v[156:159], v[26:27], off offset:512
	global_load_dwordx4 v[160:163], v[14:15], off offset:512
	s_barrier
	v_mfma_f32_32x32x16_bf16 a[0:15], v[128:131], v[104:107], a[0:15]
	ds_read_b128 v[104:107], v59 offset:55296
	ds_read_b128 v[128:131], v69
	ds_read_b128 v[164:167], v59 offset:59904
	ds_read_b128 v[168:171], v69 offset:4608
	s_waitcnt lgkmcnt(2)
	v_mfma_f32_32x32x16_bf16 a[112:127], v[104:107], v[128:131], a[112:127]
	s_waitcnt lgkmcnt(0)
	v_mfma_f32_32x32x16_bf16 a[96:111], v[104:107], v[168:171], a[96:111]
	ds_read_b128 v[104:107], v59 offset:64512
	s_waitcnt lgkmcnt(0)
	v_mfma_f32_32x32x16_bf16 a[48:63], v[104:107], v[128:131], a[48:63]
	v_mfma_f32_32x32x16_bf16 a[32:47], v[104:107], v[168:171], a[32:47]
	ds_read_b128 v[104:107], v61 offset:55296
	s_waitcnt vmcnt(4)
	ds_write_b128 v60, v[148:151]
	ds_write_b128 v60, v[144:147] offset:4608
	ds_write_b128 v60, v[140:143] offset:9216
	ds_write_b128 v60, v[124:127] offset:13824
	s_waitcnt vmcnt(2)
	ds_write_b128 v60, v[152:155] offset:18432
	ds_write_b128 v60, v[120:123] offset:23040
	s_waitcnt vmcnt(0)
	ds_write_b128 v60, v[160:163] offset:27648
	ds_write_b128 v60, v[156:159] offset:32256
	ds_write_b128 v60, v[116:119] offset:36864
	ds_write_b128 v60, v[112:115] offset:41472
	ds_write_b128 v60, v[108:111] offset:46080
	ds_write_b128 v60, v[100:103] offset:50688
	v_mfma_f32_32x32x16_bf16 a[80:95], v[164:167], v[128:131], a[80:95]
	v_mfma_f32_32x32x16_bf16 a[64:79], v[164:167], v[168:171], a[64:79]
	s_waitcnt lgkmcnt(12)
	v_mfma_f32_32x32x16_bf16 a[16:31], v[104:107], v[128:131], a[16:31]
	v_mfma_f32_32x32x16_bf16 a[0:15], v[104:107], v[168:171], a[0:15]
	ds_read_b128 v[100:103], v59 offset:55328
	ds_read_b128 v[104:107], v69 offset:32
	ds_read_b128 v[108:111], v69 offset:64
	ds_read_b128 v[112:115], v59 offset:55360
	ds_read_b128 v[116:119], v69 offset:4640
	ds_read_b128 v[120:123], v69 offset:96
	s_waitcnt lgkmcnt(4)
	v_mfma_f32_32x32x16_bf16 a[112:127], v[100:103], v[104:107], a[112:127]
	s_waitcnt lgkmcnt(1)
	v_mfma_f32_32x32x16_bf16 a[96:111], v[100:103], v[116:119], a[96:111]
	ds_read_b128 v[100:103], v59 offset:59936
	ds_read_b128 v[124:127], v59 offset:55392
	s_waitcnt lgkmcnt(1)
	v_mfma_f32_32x32x16_bf16 a[80:95], v[100:103], v[104:107], a[80:95]
	v_mfma_f32_32x32x16_bf16 a[64:79], v[100:103], v[116:119], a[64:79]
	ds_read_b128 v[100:103], v59 offset:64544
	ds_read_b128 v[128:131], v59 offset:64576
	s_waitcnt lgkmcnt(1)
	v_mfma_f32_32x32x16_bf16 a[48:63], v[100:103], v[104:107], a[48:63]
	v_mfma_f32_32x32x16_bf16 a[32:47], v[100:103], v[116:119], a[32:47]
	ds_read_b128 v[100:103], v61 offset:55328
	ds_read_b128 v[140:143], v59 offset:64608
	s_waitcnt lgkmcnt(1)
	v_mfma_f32_32x32x16_bf16 a[16:31], v[100:103], v[104:107], a[16:31]
	v_mfma_f32_32x32x16_bf16 a[0:15], v[100:103], v[116:119], a[0:15]
	ds_read_b128 v[100:103], v69 offset:4672
	ds_read_b128 v[104:107], v69 offset:4704
	v_mfma_f32_32x32x16_bf16 a[112:127], v[112:115], v[108:111], a[112:127]
	s_waitcnt lgkmcnt(1)
	v_mfma_f32_32x32x16_bf16 a[96:111], v[112:115], v[100:103], a[96:111]
	ds_read_b128 v[112:115], v59 offset:59968
	ds_read_b128 v[116:119], v59 offset:60000
	s_waitcnt lgkmcnt(1)
	v_mfma_f32_32x32x16_bf16 a[80:95], v[112:115], v[108:111], a[80:95]
	v_mfma_f32_32x32x16_bf16 a[64:79], v[112:115], v[100:103], a[64:79]
	v_mfma_f32_32x32x16_bf16 a[48:63], v[128:131], v[108:111], a[48:63]
	v_mfma_f32_32x32x16_bf16 a[32:47], v[128:131], v[100:103], a[32:47]
	ds_read_b128 v[112:115], v61 offset:55360
	ds_read_b128 v[128:131], v61 offset:55392
	s_waitcnt lgkmcnt(1)
	v_mfma_f32_32x32x16_bf16 a[16:31], v[112:115], v[108:111], a[16:31]
	v_mfma_f32_32x32x16_bf16 a[0:15], v[112:115], v[100:103], a[0:15]
	v_mfma_f32_32x32x16_bf16 a[112:127], v[124:127], v[120:123], a[112:127]
	v_mfma_f32_32x32x16_bf16 a[96:111], v[124:127], v[104:107], a[96:111]
	v_mfma_f32_32x32x16_bf16 a[80:95], v[116:119], v[120:123], a[80:95]
	v_mfma_f32_32x32x16_bf16 a[64:79], v[116:119], v[104:107], a[64:79]
	global_load_dwordx4 v[100:103], v[4:5], off offset:640
	global_load_dwordx4 v[108:111], v[0:1], off offset:640
	global_load_dwordx4 v[112:115], v[8:9], off offset:640
	global_load_dwordx4 v[116:119], v[6:7], off offset:640
	v_mfma_f32_32x32x16_bf16 a[48:63], v[140:143], v[120:123], a[48:63]
	v_mfma_f32_32x32x16_bf16 a[32:47], v[140:143], v[104:107], a[32:47]
	global_load_dwordx4 v[124:127], v[10:11], off offset:640
	global_load_dwordx4 v[140:143], v[12:13], off offset:640
	global_load_dwordx4 v[144:147], v[26:27], off offset:640
	global_load_dwordx4 v[148:151], v[14:15], off offset:640
	global_load_dwordx4 v[152:155], v[28:29], off offset:640
	global_load_dwordx4 v[156:159], v[2:3], off offset:640
	global_load_dwordx4 v[160:163], v[30:31], off offset:640
	s_waitcnt lgkmcnt(0)
	v_mfma_f32_32x32x16_bf16 a[16:31], v[128:131], v[120:123], a[16:31]
	global_load_dwordx4 v[120:123], v[32:33], off offset:640
	s_barrier
	v_mfma_f32_32x32x16_bf16 a[0:15], v[128:131], v[104:107], a[0:15]
	ds_read_b128 v[104:107], v59
	ds_read_b128 v[128:131], v62 offset:36864
	ds_read_b128 v[164:167], v59 offset:4608
	ds_read_b128 v[168:171], v62 offset:41472
	s_waitcnt lgkmcnt(2)
	v_mfma_f32_32x32x16_bf16 a[112:127], v[104:107], v[128:131], a[112:127]
	s_waitcnt lgkmcnt(0)
	v_mfma_f32_32x32x16_bf16 a[96:111], v[104:107], v[168:171], a[96:111]
	ds_read_b128 v[104:107], v59 offset:9216
	s_waitcnt lgkmcnt(0)
	v_mfma_f32_32x32x16_bf16 a[48:63], v[104:107], v[128:131], a[48:63]
	v_mfma_f32_32x32x16_bf16 a[32:47], v[104:107], v[168:171], a[32:47]
	ds_read_b128 v[104:107], v61
	s_waitcnt vmcnt(10)
	ds_write_b128 v60, v[108:111] offset:55296
	ds_write_b128 v60, v[100:103] offset:59904
	s_waitcnt vmcnt(8)
	ds_write_b128 v60, v[116:119] offset:64512
	ds_write_b128 v63, v[112:115] offset:55296
	s_waitcnt vmcnt(7)
	ds_write_b128 v64, v[124:127] offset:55296
	s_waitcnt vmcnt(6)
	ds_write_b128 v65, v[140:143] offset:55296
	s_waitcnt vmcnt(4)
	ds_write_b128 v66, v[148:151] offset:55296
	ds_write_b128 v67, v[144:147] offset:55296
	s_waitcnt vmcnt(2)
	ds_write_b128 v68, v[156:159]
	ds_write_b128 v68, v[152:155] offset:4608
	s_waitcnt vmcnt(1)
	ds_write_b128 v68, v[160:163] offset:9216
	s_waitcnt vmcnt(0)
	ds_write_b128 v68, v[120:123] offset:13824
	v_mfma_f32_32x32x16_bf16 a[80:95], v[164:167], v[128:131], a[80:95]
	v_mfma_f32_32x32x16_bf16 a[64:79], v[164:167], v[168:171], a[64:79]
	s_waitcnt lgkmcnt(12)
	v_mfma_f32_32x32x16_bf16 a[16:31], v[104:107], v[128:131], a[16:31]
	v_mfma_f32_32x32x16_bf16 a[0:15], v[104:107], v[168:171], a[0:15]
	ds_read_b128 v[100:103], v59 offset:32
	ds_read_b128 v[104:107], v62 offset:36896
	ds_read_b128 v[108:111], v62 offset:36928
	ds_read_b128 v[112:115], v59 offset:64
	ds_read_b128 v[116:119], v62 offset:41504
	ds_read_b128 v[120:123], v62 offset:36960
	s_waitcnt lgkmcnt(4)
	v_mfma_f32_32x32x16_bf16 a[112:127], v[100:103], v[104:107], a[112:127]
	s_waitcnt lgkmcnt(1)
	v_mfma_f32_32x32x16_bf16 a[96:111], v[100:103], v[116:119], a[96:111]
	ds_read_b128 v[100:103], v59 offset:4640
	ds_read_b128 v[124:127], v59 offset:96
	s_waitcnt lgkmcnt(1)
	v_mfma_f32_32x32x16_bf16 a[80:95], v[100:103], v[104:107], a[80:95]
	v_mfma_f32_32x32x16_bf16 a[64:79], v[100:103], v[116:119], a[64:79]
	ds_read_b128 v[100:103], v59 offset:9248
	ds_read_b128 v[128:131], v59 offset:9280
	s_waitcnt lgkmcnt(1)
	v_mfma_f32_32x32x16_bf16 a[48:63], v[100:103], v[104:107], a[48:63]
	v_mfma_f32_32x32x16_bf16 a[32:47], v[100:103], v[116:119], a[32:47]
	ds_read_b128 v[100:103], v61 offset:32
	ds_read_b128 v[140:143], v59 offset:9312
	s_waitcnt lgkmcnt(1)
	v_mfma_f32_32x32x16_bf16 a[16:31], v[100:103], v[104:107], a[16:31]
	v_mfma_f32_32x32x16_bf16 a[0:15], v[100:103], v[116:119], a[0:15]
	ds_read_b128 v[100:103], v62 offset:41536
	ds_read_b128 v[104:107], v62 offset:41568
	v_mfma_f32_32x32x16_bf16 a[112:127], v[112:115], v[108:111], a[112:127]
	s_waitcnt lgkmcnt(1)
	v_mfma_f32_32x32x16_bf16 a[96:111], v[112:115], v[100:103], a[96:111]
	ds_read_b128 v[112:115], v59 offset:4672
	ds_read_b128 v[116:119], v59 offset:4704
	s_waitcnt lgkmcnt(1)
	v_mfma_f32_32x32x16_bf16 a[80:95], v[112:115], v[108:111], a[80:95]
	v_mfma_f32_32x32x16_bf16 a[64:79], v[112:115], v[100:103], a[64:79]
	v_mfma_f32_32x32x16_bf16 a[48:63], v[128:131], v[108:111], a[48:63]
	v_mfma_f32_32x32x16_bf16 a[32:47], v[128:131], v[100:103], a[32:47]
	ds_read_b128 v[112:115], v61 offset:64
	ds_read_b128 v[128:131], v61 offset:96
	s_waitcnt lgkmcnt(1)
	v_mfma_f32_32x32x16_bf16 a[16:31], v[112:115], v[108:111], a[16:31]
	v_mfma_f32_32x32x16_bf16 a[0:15], v[112:115], v[100:103], a[0:15]
	global_load_dwordx4 v[100:103], v[32:33], off offset:768
	v_mfma_f32_32x32x16_bf16 a[112:127], v[124:127], v[120:123], a[112:127]
	v_mfma_f32_32x32x16_bf16 a[96:111], v[124:127], v[104:107], a[96:111]
	v_mfma_f32_32x32x16_bf16 a[80:95], v[116:119], v[120:123], a[80:95]
	v_mfma_f32_32x32x16_bf16 a[64:79], v[116:119], v[104:107], a[64:79]
	v_mfma_f32_32x32x16_bf16 a[48:63], v[140:143], v[120:123], a[48:63]
	v_mfma_f32_32x32x16_bf16 a[32:47], v[140:143], v[104:107], a[32:47]
	global_load_dwordx4 v[108:111], v[30:31], off offset:768
	global_load_dwordx4 v[112:115], v[28:29], off offset:768
	global_load_dwordx4 v[116:119], v[2:3], off offset:768
	global_load_dwordx4 v[124:127], v[8:9], off offset:768
	global_load_dwordx4 v[140:143], v[6:7], off offset:768
	global_load_dwordx4 v[144:147], v[4:5], off offset:768
	global_load_dwordx4 v[148:151], v[0:1], off offset:768
	s_waitcnt lgkmcnt(0)
	v_mfma_f32_32x32x16_bf16 a[16:31], v[128:131], v[120:123], a[16:31]
	global_load_dwordx4 v[120:123], v[12:13], off offset:768
	global_load_dwordx4 v[152:155], v[10:11], off offset:768
	global_load_dwordx4 v[156:159], v[26:27], off offset:768
	global_load_dwordx4 v[160:163], v[14:15], off offset:768
	s_barrier
	v_mfma_f32_32x32x16_bf16 a[0:15], v[128:131], v[104:107], a[0:15]
	ds_read_b128 v[104:107], v59 offset:55296
	ds_read_b128 v[128:131], v69
	ds_read_b128 v[164:167], v59 offset:59904
	ds_read_b128 v[168:171], v69 offset:4608
	s_waitcnt lgkmcnt(2)
	v_mfma_f32_32x32x16_bf16 a[112:127], v[104:107], v[128:131], a[112:127]
	s_waitcnt lgkmcnt(0)
	v_mfma_f32_32x32x16_bf16 a[96:111], v[104:107], v[168:171], a[96:111]
	ds_read_b128 v[104:107], v59 offset:64512
	s_waitcnt lgkmcnt(0)
	v_mfma_f32_32x32x16_bf16 a[48:63], v[104:107], v[128:131], a[48:63]
	v_mfma_f32_32x32x16_bf16 a[32:47], v[104:107], v[168:171], a[32:47]
	ds_read_b128 v[104:107], v61 offset:55296
	s_waitcnt vmcnt(4)
	ds_write_b128 v60, v[148:151]
	ds_write_b128 v60, v[144:147] offset:4608
	ds_write_b128 v60, v[140:143] offset:9216
	ds_write_b128 v60, v[124:127] offset:13824
	s_waitcnt vmcnt(2)
	ds_write_b128 v60, v[152:155] offset:18432
	ds_write_b128 v60, v[120:123] offset:23040
	s_waitcnt vmcnt(0)
	ds_write_b128 v60, v[160:163] offset:27648
	ds_write_b128 v60, v[156:159] offset:32256
	ds_write_b128 v60, v[116:119] offset:36864
	ds_write_b128 v60, v[112:115] offset:41472
	ds_write_b128 v60, v[108:111] offset:46080
	ds_write_b128 v60, v[100:103] offset:50688
	v_mfma_f32_32x32x16_bf16 a[80:95], v[164:167], v[128:131], a[80:95]
	v_mfma_f32_32x32x16_bf16 a[64:79], v[164:167], v[168:171], a[64:79]
	s_waitcnt lgkmcnt(12)
	v_mfma_f32_32x32x16_bf16 a[16:31], v[104:107], v[128:131], a[16:31]
	v_mfma_f32_32x32x16_bf16 a[0:15], v[104:107], v[168:171], a[0:15]
	ds_read_b128 v[100:103], v59 offset:55328
	ds_read_b128 v[104:107], v69 offset:32
	ds_read_b128 v[108:111], v69 offset:64
	ds_read_b128 v[112:115], v59 offset:55360
	ds_read_b128 v[116:119], v69 offset:4640
	ds_read_b128 v[120:123], v69 offset:96
	s_waitcnt lgkmcnt(4)
	v_mfma_f32_32x32x16_bf16 a[112:127], v[100:103], v[104:107], a[112:127]
	s_waitcnt lgkmcnt(1)
	v_mfma_f32_32x32x16_bf16 a[96:111], v[100:103], v[116:119], a[96:111]
	ds_read_b128 v[100:103], v59 offset:59936
	ds_read_b128 v[124:127], v59 offset:55392
	s_waitcnt lgkmcnt(1)
	v_mfma_f32_32x32x16_bf16 a[80:95], v[100:103], v[104:107], a[80:95]
	v_mfma_f32_32x32x16_bf16 a[64:79], v[100:103], v[116:119], a[64:79]
	ds_read_b128 v[100:103], v59 offset:64544
	ds_read_b128 v[128:131], v59 offset:64576
	s_waitcnt lgkmcnt(1)
	v_mfma_f32_32x32x16_bf16 a[48:63], v[100:103], v[104:107], a[48:63]
	v_mfma_f32_32x32x16_bf16 a[32:47], v[100:103], v[116:119], a[32:47]
	ds_read_b128 v[100:103], v61 offset:55328
	ds_read_b128 v[140:143], v59 offset:64608
	s_waitcnt lgkmcnt(1)
	v_mfma_f32_32x32x16_bf16 a[16:31], v[100:103], v[104:107], a[16:31]
	v_mfma_f32_32x32x16_bf16 a[0:15], v[100:103], v[116:119], a[0:15]
	ds_read_b128 v[100:103], v69 offset:4672
	ds_read_b128 v[104:107], v69 offset:4704
	v_mfma_f32_32x32x16_bf16 a[112:127], v[112:115], v[108:111], a[112:127]
	s_waitcnt lgkmcnt(1)
	v_mfma_f32_32x32x16_bf16 a[96:111], v[112:115], v[100:103], a[96:111]
	ds_read_b128 v[112:115], v59 offset:59968
	ds_read_b128 v[116:119], v59 offset:60000
	s_waitcnt lgkmcnt(1)
	v_mfma_f32_32x32x16_bf16 a[80:95], v[112:115], v[108:111], a[80:95]
	v_mfma_f32_32x32x16_bf16 a[64:79], v[112:115], v[100:103], a[64:79]
	v_mfma_f32_32x32x16_bf16 a[48:63], v[128:131], v[108:111], a[48:63]
	v_mfma_f32_32x32x16_bf16 a[32:47], v[128:131], v[100:103], a[32:47]
	ds_read_b128 v[112:115], v61 offset:55360
	ds_read_b128 v[128:131], v61 offset:55392
	s_waitcnt lgkmcnt(1)
	v_mfma_f32_32x32x16_bf16 a[16:31], v[112:115], v[108:111], a[16:31]
	v_mfma_f32_32x32x16_bf16 a[0:15], v[112:115], v[100:103], a[0:15]
	v_mfma_f32_32x32x16_bf16 a[112:127], v[124:127], v[120:123], a[112:127]
	v_mfma_f32_32x32x16_bf16 a[96:111], v[124:127], v[104:107], a[96:111]
	v_mfma_f32_32x32x16_bf16 a[80:95], v[116:119], v[120:123], a[80:95]
	v_mfma_f32_32x32x16_bf16 a[64:79], v[116:119], v[104:107], a[64:79]
	global_load_dwordx4 v[100:103], v[4:5], off offset:896
	global_load_dwordx4 v[108:111], v[0:1], off offset:896
	global_load_dwordx4 v[112:115], v[8:9], off offset:896
	global_load_dwordx4 v[116:119], v[6:7], off offset:896
	v_mfma_f32_32x32x16_bf16 a[48:63], v[140:143], v[120:123], a[48:63]
	v_mfma_f32_32x32x16_bf16 a[32:47], v[140:143], v[104:107], a[32:47]
	global_load_dwordx4 v[124:127], v[10:11], off offset:896
	global_load_dwordx4 v[140:143], v[12:13], off offset:896
	global_load_dwordx4 v[144:147], v[26:27], off offset:896
	global_load_dwordx4 v[148:151], v[14:15], off offset:896
	global_load_dwordx4 v[152:155], v[28:29], off offset:896
	global_load_dwordx4 v[156:159], v[2:3], off offset:896
	global_load_dwordx4 v[160:163], v[30:31], off offset:896
	s_waitcnt lgkmcnt(0)
	v_mfma_f32_32x32x16_bf16 a[16:31], v[128:131], v[120:123], a[16:31]
	global_load_dwordx4 v[120:123], v[32:33], off offset:896
	s_barrier
	v_mfma_f32_32x32x16_bf16 a[0:15], v[128:131], v[104:107], a[0:15]
	ds_read_b128 v[104:107], v59
	ds_read_b128 v[128:131], v62 offset:36864
	ds_read_b128 v[164:167], v59 offset:4608
	ds_read_b128 v[168:171], v62 offset:41472
	s_waitcnt lgkmcnt(2)
	v_mfma_f32_32x32x16_bf16 a[112:127], v[104:107], v[128:131], a[112:127]
	s_waitcnt lgkmcnt(0)
	v_mfma_f32_32x32x16_bf16 a[96:111], v[104:107], v[168:171], a[96:111]
	ds_read_b128 v[104:107], v59 offset:9216
	s_waitcnt lgkmcnt(0)
	v_mfma_f32_32x32x16_bf16 a[48:63], v[104:107], v[128:131], a[48:63]
	v_mfma_f32_32x32x16_bf16 a[32:47], v[104:107], v[168:171], a[32:47]
	ds_read_b128 v[104:107], v61
	s_waitcnt vmcnt(10)
	ds_write_b128 v60, v[108:111] offset:55296
	ds_write_b128 v60, v[100:103] offset:59904
	s_waitcnt vmcnt(8)
	ds_write_b128 v60, v[116:119] offset:64512
	ds_write_b128 v63, v[112:115] offset:55296
	s_waitcnt vmcnt(7)
	ds_write_b128 v64, v[124:127] offset:55296
	s_waitcnt vmcnt(6)
	ds_write_b128 v65, v[140:143] offset:55296
	s_waitcnt vmcnt(4)
	ds_write_b128 v66, v[148:151] offset:55296
	ds_write_b128 v67, v[144:147] offset:55296
	s_waitcnt vmcnt(2)
	ds_write_b128 v68, v[156:159]
	ds_write_b128 v68, v[152:155] offset:4608
	s_waitcnt vmcnt(1)
	ds_write_b128 v68, v[160:163] offset:9216
	s_waitcnt vmcnt(0)
	ds_write_b128 v68, v[120:123] offset:13824
	v_mfma_f32_32x32x16_bf16 a[80:95], v[164:167], v[128:131], a[80:95]
	v_mfma_f32_32x32x16_bf16 a[64:79], v[164:167], v[168:171], a[64:79]
	s_waitcnt lgkmcnt(12)
	v_mfma_f32_32x32x16_bf16 a[16:31], v[104:107], v[128:131], a[16:31]
	v_mfma_f32_32x32x16_bf16 a[0:15], v[104:107], v[168:171], a[0:15]
	ds_read_b128 v[100:103], v59 offset:32
	ds_read_b128 v[104:107], v62 offset:36896
	ds_read_b128 v[108:111], v62 offset:36928
	ds_read_b128 v[112:115], v59 offset:64
	ds_read_b128 v[116:119], v62 offset:41504
	ds_read_b128 v[120:123], v62 offset:36960
	s_waitcnt lgkmcnt(4)
	v_mfma_f32_32x32x16_bf16 a[112:127], v[100:103], v[104:107], a[112:127]
	s_waitcnt lgkmcnt(1)
	v_mfma_f32_32x32x16_bf16 a[96:111], v[100:103], v[116:119], a[96:111]
	ds_read_b128 v[100:103], v59 offset:4640
	ds_read_b128 v[124:127], v59 offset:96
	s_waitcnt lgkmcnt(1)
	v_mfma_f32_32x32x16_bf16 a[80:95], v[100:103], v[104:107], a[80:95]
	v_mfma_f32_32x32x16_bf16 a[64:79], v[100:103], v[116:119], a[64:79]
	ds_read_b128 v[100:103], v59 offset:9248
	ds_read_b128 v[128:131], v59 offset:9280
	s_waitcnt lgkmcnt(1)
	v_mfma_f32_32x32x16_bf16 a[48:63], v[100:103], v[104:107], a[48:63]
	v_mfma_f32_32x32x16_bf16 a[32:47], v[100:103], v[116:119], a[32:47]
	ds_read_b128 v[100:103], v61 offset:32
	ds_read_b128 v[140:143], v59 offset:9312
	s_waitcnt lgkmcnt(1)
	v_mfma_f32_32x32x16_bf16 a[16:31], v[100:103], v[104:107], a[16:31]
	v_mfma_f32_32x32x16_bf16 a[0:15], v[100:103], v[116:119], a[0:15]
	ds_read_b128 v[100:103], v62 offset:41536
	ds_read_b128 v[104:107], v62 offset:41568
	v_mfma_f32_32x32x16_bf16 a[112:127], v[112:115], v[108:111], a[112:127]
	s_waitcnt lgkmcnt(1)
	v_mfma_f32_32x32x16_bf16 a[96:111], v[112:115], v[100:103], a[96:111]
	ds_read_b128 v[112:115], v59 offset:4672
	ds_read_b128 v[116:119], v59 offset:4704
	s_waitcnt lgkmcnt(1)
	v_mfma_f32_32x32x16_bf16 a[80:95], v[112:115], v[108:111], a[80:95]
	v_mfma_f32_32x32x16_bf16 a[64:79], v[112:115], v[100:103], a[64:79]
	v_mfma_f32_32x32x16_bf16 a[48:63], v[128:131], v[108:111], a[48:63]
	v_mfma_f32_32x32x16_bf16 a[32:47], v[128:131], v[100:103], a[32:47]
	ds_read_b128 v[112:115], v61 offset:64
	ds_read_b128 v[128:131], v61 offset:96
	s_waitcnt lgkmcnt(1)
	v_mfma_f32_32x32x16_bf16 a[16:31], v[112:115], v[108:111], a[16:31]
	v_mfma_f32_32x32x16_bf16 a[0:15], v[112:115], v[100:103], a[0:15]
	global_load_dwordx4 v[100:103], v[32:33], off offset:1024
	v_mfma_f32_32x32x16_bf16 a[112:127], v[124:127], v[120:123], a[112:127]
	v_mfma_f32_32x32x16_bf16 a[96:111], v[124:127], v[104:107], a[96:111]
	v_mfma_f32_32x32x16_bf16 a[80:95], v[116:119], v[120:123], a[80:95]
	v_mfma_f32_32x32x16_bf16 a[64:79], v[116:119], v[104:107], a[64:79]
	v_mfma_f32_32x32x16_bf16 a[48:63], v[140:143], v[120:123], a[48:63]
	v_mfma_f32_32x32x16_bf16 a[32:47], v[140:143], v[104:107], a[32:47]
	global_load_dwordx4 v[108:111], v[30:31], off offset:1024
	global_load_dwordx4 v[112:115], v[28:29], off offset:1024
	global_load_dwordx4 v[116:119], v[2:3], off offset:1024
	global_load_dwordx4 v[124:127], v[8:9], off offset:1024
	global_load_dwordx4 v[140:143], v[6:7], off offset:1024
	global_load_dwordx4 v[144:147], v[4:5], off offset:1024
	global_load_dwordx4 v[148:151], v[0:1], off offset:1024
	s_waitcnt lgkmcnt(0)
	v_mfma_f32_32x32x16_bf16 a[16:31], v[128:131], v[120:123], a[16:31]
	global_load_dwordx4 v[120:123], v[12:13], off offset:1024
	global_load_dwordx4 v[152:155], v[10:11], off offset:1024
	global_load_dwordx4 v[156:159], v[26:27], off offset:1024
	global_load_dwordx4 v[160:163], v[14:15], off offset:1024
	s_barrier
	v_mfma_f32_32x32x16_bf16 a[0:15], v[128:131], v[104:107], a[0:15]
	ds_read_b128 v[104:107], v59 offset:55296
	ds_read_b128 v[128:131], v69
	ds_read_b128 v[164:167], v59 offset:59904
	ds_read_b128 v[168:171], v69 offset:4608
	s_waitcnt lgkmcnt(2)
	v_mfma_f32_32x32x16_bf16 a[112:127], v[104:107], v[128:131], a[112:127]
	s_waitcnt lgkmcnt(0)
	v_mfma_f32_32x32x16_bf16 a[96:111], v[104:107], v[168:171], a[96:111]
	ds_read_b128 v[104:107], v59 offset:64512
	s_waitcnt lgkmcnt(0)
	v_mfma_f32_32x32x16_bf16 a[48:63], v[104:107], v[128:131], a[48:63]
	v_mfma_f32_32x32x16_bf16 a[32:47], v[104:107], v[168:171], a[32:47]
	ds_read_b128 v[104:107], v61 offset:55296
	s_waitcnt vmcnt(4)
	ds_write_b128 v60, v[148:151]
	ds_write_b128 v60, v[144:147] offset:4608
	ds_write_b128 v60, v[140:143] offset:9216
	ds_write_b128 v60, v[124:127] offset:13824
	s_waitcnt vmcnt(2)
	ds_write_b128 v60, v[152:155] offset:18432
	ds_write_b128 v60, v[120:123] offset:23040
	s_waitcnt vmcnt(0)
	ds_write_b128 v60, v[160:163] offset:27648
	ds_write_b128 v60, v[156:159] offset:32256
	ds_write_b128 v60, v[116:119] offset:36864
	ds_write_b128 v60, v[112:115] offset:41472
	ds_write_b128 v60, v[108:111] offset:46080
	ds_write_b128 v60, v[100:103] offset:50688
	v_mfma_f32_32x32x16_bf16 a[80:95], v[164:167], v[128:131], a[80:95]
	v_mfma_f32_32x32x16_bf16 a[64:79], v[164:167], v[168:171], a[64:79]
	s_waitcnt lgkmcnt(12)
	v_mfma_f32_32x32x16_bf16 a[16:31], v[104:107], v[128:131], a[16:31]
	v_mfma_f32_32x32x16_bf16 a[0:15], v[104:107], v[168:171], a[0:15]
	ds_read_b128 v[100:103], v59 offset:55328
	ds_read_b128 v[104:107], v69 offset:32
	ds_read_b128 v[108:111], v69 offset:64
	ds_read_b128 v[112:115], v59 offset:55360
	ds_read_b128 v[116:119], v69 offset:4640
	ds_read_b128 v[120:123], v69 offset:96
	s_waitcnt lgkmcnt(4)
	v_mfma_f32_32x32x16_bf16 a[112:127], v[100:103], v[104:107], a[112:127]
	s_waitcnt lgkmcnt(1)
	v_mfma_f32_32x32x16_bf16 a[96:111], v[100:103], v[116:119], a[96:111]
	ds_read_b128 v[100:103], v59 offset:59936
	ds_read_b128 v[124:127], v59 offset:55392
	s_waitcnt lgkmcnt(1)
	v_mfma_f32_32x32x16_bf16 a[80:95], v[100:103], v[104:107], a[80:95]
	v_mfma_f32_32x32x16_bf16 a[64:79], v[100:103], v[116:119], a[64:79]
	ds_read_b128 v[100:103], v59 offset:64544
	ds_read_b128 v[128:131], v59 offset:64576
	s_waitcnt lgkmcnt(1)
	v_mfma_f32_32x32x16_bf16 a[48:63], v[100:103], v[104:107], a[48:63]
	v_mfma_f32_32x32x16_bf16 a[32:47], v[100:103], v[116:119], a[32:47]
	ds_read_b128 v[100:103], v61 offset:55328
	ds_read_b128 v[140:143], v59 offset:64608
	s_waitcnt lgkmcnt(1)
	v_mfma_f32_32x32x16_bf16 a[16:31], v[100:103], v[104:107], a[16:31]
	v_mfma_f32_32x32x16_bf16 a[0:15], v[100:103], v[116:119], a[0:15]
	ds_read_b128 v[100:103], v69 offset:4672
	ds_read_b128 v[104:107], v69 offset:4704
	v_mfma_f32_32x32x16_bf16 a[112:127], v[112:115], v[108:111], a[112:127]
	s_waitcnt lgkmcnt(1)
	v_mfma_f32_32x32x16_bf16 a[96:111], v[112:115], v[100:103], a[96:111]
	ds_read_b128 v[112:115], v59 offset:59968
	ds_read_b128 v[116:119], v59 offset:60000
	s_waitcnt lgkmcnt(1)
	v_mfma_f32_32x32x16_bf16 a[80:95], v[112:115], v[108:111], a[80:95]
	v_mfma_f32_32x32x16_bf16 a[64:79], v[112:115], v[100:103], a[64:79]
	v_mfma_f32_32x32x16_bf16 a[48:63], v[128:131], v[108:111], a[48:63]
	v_mfma_f32_32x32x16_bf16 a[32:47], v[128:131], v[100:103], a[32:47]
	ds_read_b128 v[112:115], v61 offset:55360
	ds_read_b128 v[128:131], v61 offset:55392
	s_waitcnt lgkmcnt(1)
	v_mfma_f32_32x32x16_bf16 a[16:31], v[112:115], v[108:111], a[16:31]
	v_mfma_f32_32x32x16_bf16 a[0:15], v[112:115], v[100:103], a[0:15]
	v_mfma_f32_32x32x16_bf16 a[112:127], v[124:127], v[120:123], a[112:127]
	v_mfma_f32_32x32x16_bf16 a[96:111], v[124:127], v[104:107], a[96:111]
	v_mfma_f32_32x32x16_bf16 a[80:95], v[116:119], v[120:123], a[80:95]
	v_mfma_f32_32x32x16_bf16 a[64:79], v[116:119], v[104:107], a[64:79]
	global_load_dwordx4 v[100:103], v[4:5], off offset:1152
	global_load_dwordx4 v[108:111], v[0:1], off offset:1152
	global_load_dwordx4 v[112:115], v[8:9], off offset:1152
	global_load_dwordx4 v[116:119], v[6:7], off offset:1152
	v_mfma_f32_32x32x16_bf16 a[48:63], v[140:143], v[120:123], a[48:63]
	v_mfma_f32_32x32x16_bf16 a[32:47], v[140:143], v[104:107], a[32:47]
	global_load_dwordx4 v[124:127], v[10:11], off offset:1152
	global_load_dwordx4 v[140:143], v[12:13], off offset:1152
	global_load_dwordx4 v[144:147], v[26:27], off offset:1152
	global_load_dwordx4 v[148:151], v[14:15], off offset:1152
	global_load_dwordx4 v[152:155], v[28:29], off offset:1152
	global_load_dwordx4 v[156:159], v[2:3], off offset:1152
	global_load_dwordx4 v[160:163], v[30:31], off offset:1152
	s_waitcnt lgkmcnt(0)
	v_mfma_f32_32x32x16_bf16 a[16:31], v[128:131], v[120:123], a[16:31]
	global_load_dwordx4 v[120:123], v[32:33], off offset:1152
	s_barrier
	v_mfma_f32_32x32x16_bf16 a[0:15], v[128:131], v[104:107], a[0:15]
	ds_read_b128 v[104:107], v59
	ds_read_b128 v[128:131], v62 offset:36864
	ds_read_b128 v[164:167], v59 offset:4608
	ds_read_b128 v[168:171], v62 offset:41472
	s_waitcnt lgkmcnt(2)
	v_mfma_f32_32x32x16_bf16 a[112:127], v[104:107], v[128:131], a[112:127]
	s_waitcnt lgkmcnt(0)
	v_mfma_f32_32x32x16_bf16 a[96:111], v[104:107], v[168:171], a[96:111]
	ds_read_b128 v[104:107], v59 offset:9216
	s_waitcnt lgkmcnt(0)
	v_mfma_f32_32x32x16_bf16 a[48:63], v[104:107], v[128:131], a[48:63]
	v_mfma_f32_32x32x16_bf16 a[32:47], v[104:107], v[168:171], a[32:47]
	ds_read_b128 v[104:107], v61
	s_waitcnt vmcnt(10)
	ds_write_b128 v60, v[108:111] offset:55296
	ds_write_b128 v60, v[100:103] offset:59904
	s_waitcnt vmcnt(8)
	ds_write_b128 v60, v[116:119] offset:64512
	ds_write_b128 v63, v[112:115] offset:55296
	s_waitcnt vmcnt(7)
	ds_write_b128 v64, v[124:127] offset:55296
	s_waitcnt vmcnt(6)
	ds_write_b128 v65, v[140:143] offset:55296
	s_waitcnt vmcnt(4)
	ds_write_b128 v66, v[148:151] offset:55296
	ds_write_b128 v67, v[144:147] offset:55296
	s_waitcnt vmcnt(2)
	ds_write_b128 v68, v[156:159]
	ds_write_b128 v68, v[152:155] offset:4608
	s_waitcnt vmcnt(1)
	ds_write_b128 v68, v[160:163] offset:9216
	s_waitcnt vmcnt(0)
	ds_write_b128 v68, v[120:123] offset:13824
	v_mfma_f32_32x32x16_bf16 a[80:95], v[164:167], v[128:131], a[80:95]
	v_mfma_f32_32x32x16_bf16 a[64:79], v[164:167], v[168:171], a[64:79]
	s_waitcnt lgkmcnt(12)
	v_mfma_f32_32x32x16_bf16 a[16:31], v[104:107], v[128:131], a[16:31]
	v_mfma_f32_32x32x16_bf16 a[0:15], v[104:107], v[168:171], a[0:15]
	ds_read_b128 v[100:103], v59 offset:32
	ds_read_b128 v[104:107], v62 offset:36896
	ds_read_b128 v[108:111], v62 offset:36928
	ds_read_b128 v[112:115], v59 offset:64
	ds_read_b128 v[116:119], v62 offset:41504
	ds_read_b128 v[120:123], v62 offset:36960
	s_waitcnt lgkmcnt(4)
	v_mfma_f32_32x32x16_bf16 a[112:127], v[100:103], v[104:107], a[112:127]
	s_waitcnt lgkmcnt(1)
	v_mfma_f32_32x32x16_bf16 a[96:111], v[100:103], v[116:119], a[96:111]
	ds_read_b128 v[100:103], v59 offset:4640
	ds_read_b128 v[124:127], v59 offset:96
	s_waitcnt lgkmcnt(1)
	v_mfma_f32_32x32x16_bf16 a[80:95], v[100:103], v[104:107], a[80:95]
	v_mfma_f32_32x32x16_bf16 a[64:79], v[100:103], v[116:119], a[64:79]
	ds_read_b128 v[100:103], v59 offset:9248
	ds_read_b128 v[128:131], v59 offset:9280
	s_waitcnt lgkmcnt(1)
	v_mfma_f32_32x32x16_bf16 a[48:63], v[100:103], v[104:107], a[48:63]
	v_mfma_f32_32x32x16_bf16 a[32:47], v[100:103], v[116:119], a[32:47]
	ds_read_b128 v[100:103], v61 offset:32
	ds_read_b128 v[140:143], v59 offset:9312
	s_waitcnt lgkmcnt(1)
	v_mfma_f32_32x32x16_bf16 a[16:31], v[100:103], v[104:107], a[16:31]
	v_mfma_f32_32x32x16_bf16 a[0:15], v[100:103], v[116:119], a[0:15]
	ds_read_b128 v[100:103], v62 offset:41536
	ds_read_b128 v[104:107], v62 offset:41568
	v_mfma_f32_32x32x16_bf16 a[112:127], v[112:115], v[108:111], a[112:127]
	s_waitcnt lgkmcnt(1)
	v_mfma_f32_32x32x16_bf16 a[96:111], v[112:115], v[100:103], a[96:111]
	ds_read_b128 v[112:115], v59 offset:4672
	ds_read_b128 v[116:119], v59 offset:4704
	s_waitcnt lgkmcnt(1)
	v_mfma_f32_32x32x16_bf16 a[80:95], v[112:115], v[108:111], a[80:95]
	v_mfma_f32_32x32x16_bf16 a[64:79], v[112:115], v[100:103], a[64:79]
	v_mfma_f32_32x32x16_bf16 a[48:63], v[128:131], v[108:111], a[48:63]
	v_mfma_f32_32x32x16_bf16 a[32:47], v[128:131], v[100:103], a[32:47]
	ds_read_b128 v[112:115], v61 offset:64
	ds_read_b128 v[128:131], v61 offset:96
	s_waitcnt lgkmcnt(1)
	v_mfma_f32_32x32x16_bf16 a[16:31], v[112:115], v[108:111], a[16:31]
	v_mfma_f32_32x32x16_bf16 a[0:15], v[112:115], v[100:103], a[0:15]
	global_load_dwordx4 v[100:103], v[32:33], off offset:1280
	v_mfma_f32_32x32x16_bf16 a[112:127], v[124:127], v[120:123], a[112:127]
	v_mfma_f32_32x32x16_bf16 a[96:111], v[124:127], v[104:107], a[96:111]
	v_mfma_f32_32x32x16_bf16 a[80:95], v[116:119], v[120:123], a[80:95]
	v_mfma_f32_32x32x16_bf16 a[64:79], v[116:119], v[104:107], a[64:79]
	v_mfma_f32_32x32x16_bf16 a[48:63], v[140:143], v[120:123], a[48:63]
	v_mfma_f32_32x32x16_bf16 a[32:47], v[140:143], v[104:107], a[32:47]
	global_load_dwordx4 v[108:111], v[30:31], off offset:1280
	global_load_dwordx4 v[112:115], v[28:29], off offset:1280
	global_load_dwordx4 v[116:119], v[2:3], off offset:1280
	global_load_dwordx4 v[124:127], v[8:9], off offset:1280
	global_load_dwordx4 v[140:143], v[6:7], off offset:1280
	global_load_dwordx4 v[144:147], v[4:5], off offset:1280
	global_load_dwordx4 v[148:151], v[0:1], off offset:1280
	s_waitcnt lgkmcnt(0)
	v_mfma_f32_32x32x16_bf16 a[16:31], v[128:131], v[120:123], a[16:31]
	global_load_dwordx4 v[120:123], v[12:13], off offset:1280
	global_load_dwordx4 v[152:155], v[10:11], off offset:1280
	global_load_dwordx4 v[156:159], v[26:27], off offset:1280
	global_load_dwordx4 v[160:163], v[14:15], off offset:1280
	s_barrier
	v_mfma_f32_32x32x16_bf16 a[0:15], v[128:131], v[104:107], a[0:15]
	ds_read_b128 v[104:107], v59 offset:55296
	ds_read_b128 v[128:131], v69
	ds_read_b128 v[164:167], v59 offset:59904
	ds_read_b128 v[168:171], v69 offset:4608
	s_waitcnt lgkmcnt(2)
	v_mfma_f32_32x32x16_bf16 a[112:127], v[104:107], v[128:131], a[112:127]
	s_waitcnt lgkmcnt(0)
	v_mfma_f32_32x32x16_bf16 a[96:111], v[104:107], v[168:171], a[96:111]
	ds_read_b128 v[104:107], v59 offset:64512
	s_waitcnt lgkmcnt(0)
	v_mfma_f32_32x32x16_bf16 a[48:63], v[104:107], v[128:131], a[48:63]
	v_mfma_f32_32x32x16_bf16 a[32:47], v[104:107], v[168:171], a[32:47]
	ds_read_b128 v[104:107], v61 offset:55296
	s_waitcnt vmcnt(4)
	ds_write_b128 v60, v[148:151]
	ds_write_b128 v60, v[144:147] offset:4608
	ds_write_b128 v60, v[140:143] offset:9216
	ds_write_b128 v60, v[124:127] offset:13824
	s_waitcnt vmcnt(2)
	ds_write_b128 v60, v[152:155] offset:18432
	ds_write_b128 v60, v[120:123] offset:23040
	s_waitcnt vmcnt(0)
	ds_write_b128 v60, v[160:163] offset:27648
	ds_write_b128 v60, v[156:159] offset:32256
	ds_write_b128 v60, v[116:119] offset:36864
	ds_write_b128 v60, v[112:115] offset:41472
	ds_write_b128 v60, v[108:111] offset:46080
	ds_write_b128 v60, v[100:103] offset:50688
	v_mfma_f32_32x32x16_bf16 a[80:95], v[164:167], v[128:131], a[80:95]
	v_mfma_f32_32x32x16_bf16 a[64:79], v[164:167], v[168:171], a[64:79]
	s_waitcnt lgkmcnt(12)
	v_mfma_f32_32x32x16_bf16 a[16:31], v[104:107], v[128:131], a[16:31]
	v_mfma_f32_32x32x16_bf16 a[0:15], v[104:107], v[168:171], a[0:15]
	ds_read_b128 v[100:103], v59 offset:55328
	ds_read_b128 v[104:107], v69 offset:32
	ds_read_b128 v[108:111], v69 offset:64
	ds_read_b128 v[112:115], v59 offset:55360
	ds_read_b128 v[116:119], v69 offset:4640
	ds_read_b128 v[120:123], v69 offset:96
	s_waitcnt lgkmcnt(4)
	v_mfma_f32_32x32x16_bf16 a[112:127], v[100:103], v[104:107], a[112:127]
	s_waitcnt lgkmcnt(1)
	v_mfma_f32_32x32x16_bf16 a[96:111], v[100:103], v[116:119], a[96:111]
	ds_read_b128 v[100:103], v59 offset:59936
	ds_read_b128 v[124:127], v59 offset:55392
	s_waitcnt lgkmcnt(1)
	v_mfma_f32_32x32x16_bf16 a[80:95], v[100:103], v[104:107], a[80:95]
	v_mfma_f32_32x32x16_bf16 a[64:79], v[100:103], v[116:119], a[64:79]
	ds_read_b128 v[100:103], v59 offset:64544
	ds_read_b128 v[128:131], v59 offset:64576
	s_waitcnt lgkmcnt(1)
	v_mfma_f32_32x32x16_bf16 a[48:63], v[100:103], v[104:107], a[48:63]
	v_mfma_f32_32x32x16_bf16 a[32:47], v[100:103], v[116:119], a[32:47]
	ds_read_b128 v[100:103], v61 offset:55328
	ds_read_b128 v[140:143], v59 offset:64608
	s_waitcnt lgkmcnt(1)
	v_mfma_f32_32x32x16_bf16 a[16:31], v[100:103], v[104:107], a[16:31]
	v_mfma_f32_32x32x16_bf16 a[0:15], v[100:103], v[116:119], a[0:15]
	ds_read_b128 v[100:103], v69 offset:4672
	ds_read_b128 v[104:107], v69 offset:4704
	v_mfma_f32_32x32x16_bf16 a[112:127], v[112:115], v[108:111], a[112:127]
	s_waitcnt lgkmcnt(1)
	v_mfma_f32_32x32x16_bf16 a[96:111], v[112:115], v[100:103], a[96:111]
	ds_read_b128 v[112:115], v59 offset:59968
	ds_read_b128 v[116:119], v59 offset:60000
	s_waitcnt lgkmcnt(1)
	v_mfma_f32_32x32x16_bf16 a[80:95], v[112:115], v[108:111], a[80:95]
	v_mfma_f32_32x32x16_bf16 a[64:79], v[112:115], v[100:103], a[64:79]
	v_mfma_f32_32x32x16_bf16 a[48:63], v[128:131], v[108:111], a[48:63]
	v_mfma_f32_32x32x16_bf16 a[32:47], v[128:131], v[100:103], a[32:47]
	ds_read_b128 v[112:115], v61 offset:55360
	ds_read_b128 v[128:131], v61 offset:55392
	s_waitcnt lgkmcnt(1)
	v_mfma_f32_32x32x16_bf16 a[16:31], v[112:115], v[108:111], a[16:31]
	v_mfma_f32_32x32x16_bf16 a[0:15], v[112:115], v[100:103], a[0:15]
	v_mfma_f32_32x32x16_bf16 a[112:127], v[124:127], v[120:123], a[112:127]
	v_mfma_f32_32x32x16_bf16 a[96:111], v[124:127], v[104:107], a[96:111]
	v_mfma_f32_32x32x16_bf16 a[80:95], v[116:119], v[120:123], a[80:95]
	v_mfma_f32_32x32x16_bf16 a[64:79], v[116:119], v[104:107], a[64:79]
	global_load_dwordx4 v[100:103], v[4:5], off offset:1408
	global_load_dwordx4 v[108:111], v[0:1], off offset:1408
	global_load_dwordx4 v[112:115], v[8:9], off offset:1408
	global_load_dwordx4 v[116:119], v[6:7], off offset:1408
	v_mfma_f32_32x32x16_bf16 a[48:63], v[140:143], v[120:123], a[48:63]
	v_mfma_f32_32x32x16_bf16 a[32:47], v[140:143], v[104:107], a[32:47]
	global_load_dwordx4 v[124:127], v[10:11], off offset:1408
	global_load_dwordx4 v[140:143], v[12:13], off offset:1408
	global_load_dwordx4 v[144:147], v[26:27], off offset:1408
	global_load_dwordx4 v[148:151], v[14:15], off offset:1408
	global_load_dwordx4 v[152:155], v[28:29], off offset:1408
	global_load_dwordx4 v[156:159], v[2:3], off offset:1408
	global_load_dwordx4 v[160:163], v[30:31], off offset:1408
	s_waitcnt lgkmcnt(0)
	v_mfma_f32_32x32x16_bf16 a[16:31], v[128:131], v[120:123], a[16:31]
	global_load_dwordx4 v[120:123], v[32:33], off offset:1408
	s_barrier
	v_mfma_f32_32x32x16_bf16 a[0:15], v[128:131], v[104:107], a[0:15]
	ds_read_b128 v[104:107], v59
	ds_read_b128 v[128:131], v62 offset:36864
	ds_read_b128 v[164:167], v59 offset:4608
	ds_read_b128 v[168:171], v62 offset:41472
	s_waitcnt lgkmcnt(2)
	v_mfma_f32_32x32x16_bf16 a[112:127], v[104:107], v[128:131], a[112:127]
	s_waitcnt lgkmcnt(0)
	v_mfma_f32_32x32x16_bf16 a[96:111], v[104:107], v[168:171], a[96:111]
	ds_read_b128 v[104:107], v59 offset:9216
	s_waitcnt lgkmcnt(0)
	v_mfma_f32_32x32x16_bf16 a[48:63], v[104:107], v[128:131], a[48:63]
	v_mfma_f32_32x32x16_bf16 a[32:47], v[104:107], v[168:171], a[32:47]
	ds_read_b128 v[104:107], v61
	s_waitcnt vmcnt(10)
	ds_write_b128 v60, v[108:111] offset:55296
	ds_write_b128 v60, v[100:103] offset:59904
	s_waitcnt vmcnt(8)
	ds_write_b128 v60, v[116:119] offset:64512
	ds_write_b128 v63, v[112:115] offset:55296
	s_waitcnt vmcnt(7)
	ds_write_b128 v64, v[124:127] offset:55296
	s_waitcnt vmcnt(6)
	ds_write_b128 v65, v[140:143] offset:55296
	s_waitcnt vmcnt(4)
	ds_write_b128 v66, v[148:151] offset:55296
	ds_write_b128 v67, v[144:147] offset:55296
	s_waitcnt vmcnt(2)
	ds_write_b128 v68, v[156:159]
	ds_write_b128 v68, v[152:155] offset:4608
	s_waitcnt vmcnt(1)
	ds_write_b128 v68, v[160:163] offset:9216
	s_waitcnt vmcnt(0)
	ds_write_b128 v68, v[120:123] offset:13824
	v_mfma_f32_32x32x16_bf16 a[80:95], v[164:167], v[128:131], a[80:95]
	v_mfma_f32_32x32x16_bf16 a[64:79], v[164:167], v[168:171], a[64:79]
	s_waitcnt lgkmcnt(12)
	v_mfma_f32_32x32x16_bf16 a[16:31], v[104:107], v[128:131], a[16:31]
	v_mfma_f32_32x32x16_bf16 a[0:15], v[104:107], v[168:171], a[0:15]
	ds_read_b128 v[100:103], v59 offset:32
	ds_read_b128 v[104:107], v62 offset:36896
	ds_read_b128 v[108:111], v62 offset:36928
	ds_read_b128 v[112:115], v59 offset:64
	ds_read_b128 v[116:119], v62 offset:41504
	ds_read_b128 v[120:123], v62 offset:36960
	s_waitcnt lgkmcnt(4)
	v_mfma_f32_32x32x16_bf16 a[112:127], v[100:103], v[104:107], a[112:127]
	s_waitcnt lgkmcnt(1)
	v_mfma_f32_32x32x16_bf16 a[96:111], v[100:103], v[116:119], a[96:111]
	ds_read_b128 v[100:103], v59 offset:4640
	ds_read_b128 v[124:127], v59 offset:96
	s_waitcnt lgkmcnt(1)
	v_mfma_f32_32x32x16_bf16 a[80:95], v[100:103], v[104:107], a[80:95]
	v_mfma_f32_32x32x16_bf16 a[64:79], v[100:103], v[116:119], a[64:79]
	ds_read_b128 v[100:103], v59 offset:9248
	ds_read_b128 v[128:131], v59 offset:9280
	s_waitcnt lgkmcnt(1)
	v_mfma_f32_32x32x16_bf16 a[48:63], v[100:103], v[104:107], a[48:63]
	v_mfma_f32_32x32x16_bf16 a[32:47], v[100:103], v[116:119], a[32:47]
	ds_read_b128 v[100:103], v61 offset:32
	ds_read_b128 v[140:143], v59 offset:9312
	s_waitcnt lgkmcnt(1)
	v_mfma_f32_32x32x16_bf16 a[16:31], v[100:103], v[104:107], a[16:31]
	v_mfma_f32_32x32x16_bf16 a[0:15], v[100:103], v[116:119], a[0:15]
	ds_read_b128 v[100:103], v62 offset:41536
	ds_read_b128 v[104:107], v62 offset:41568
	v_mfma_f32_32x32x16_bf16 a[112:127], v[112:115], v[108:111], a[112:127]
	s_waitcnt lgkmcnt(1)
	v_mfma_f32_32x32x16_bf16 a[96:111], v[112:115], v[100:103], a[96:111]
	ds_read_b128 v[112:115], v59 offset:4672
	ds_read_b128 v[116:119], v59 offset:4704
	s_waitcnt lgkmcnt(1)
	v_mfma_f32_32x32x16_bf16 a[80:95], v[112:115], v[108:111], a[80:95]
	v_mfma_f32_32x32x16_bf16 a[64:79], v[112:115], v[100:103], a[64:79]
	v_mfma_f32_32x32x16_bf16 a[48:63], v[128:131], v[108:111], a[48:63]
	v_mfma_f32_32x32x16_bf16 a[32:47], v[128:131], v[100:103], a[32:47]
	ds_read_b128 v[112:115], v61 offset:64
	ds_read_b128 v[128:131], v61 offset:96
	s_waitcnt lgkmcnt(1)
	v_mfma_f32_32x32x16_bf16 a[16:31], v[112:115], v[108:111], a[16:31]
	v_mfma_f32_32x32x16_bf16 a[0:15], v[112:115], v[100:103], a[0:15]
	global_load_dwordx4 v[100:103], v[32:33], off offset:1536
	v_mfma_f32_32x32x16_bf16 a[112:127], v[124:127], v[120:123], a[112:127]
	v_mfma_f32_32x32x16_bf16 a[96:111], v[124:127], v[104:107], a[96:111]
	v_mfma_f32_32x32x16_bf16 a[80:95], v[116:119], v[120:123], a[80:95]
	v_mfma_f32_32x32x16_bf16 a[64:79], v[116:119], v[104:107], a[64:79]
	v_mfma_f32_32x32x16_bf16 a[48:63], v[140:143], v[120:123], a[48:63]
	v_mfma_f32_32x32x16_bf16 a[32:47], v[140:143], v[104:107], a[32:47]
	global_load_dwordx4 v[108:111], v[30:31], off offset:1536
	global_load_dwordx4 v[112:115], v[28:29], off offset:1536
	global_load_dwordx4 v[116:119], v[2:3], off offset:1536
	global_load_dwordx4 v[124:127], v[8:9], off offset:1536
	global_load_dwordx4 v[140:143], v[6:7], off offset:1536
	global_load_dwordx4 v[144:147], v[4:5], off offset:1536
	global_load_dwordx4 v[148:151], v[0:1], off offset:1536
	s_waitcnt lgkmcnt(0)
	v_mfma_f32_32x32x16_bf16 a[16:31], v[128:131], v[120:123], a[16:31]
	global_load_dwordx4 v[120:123], v[12:13], off offset:1536
	global_load_dwordx4 v[152:155], v[10:11], off offset:1536
	global_load_dwordx4 v[156:159], v[26:27], off offset:1536
	global_load_dwordx4 v[160:163], v[14:15], off offset:1536
	s_barrier
	v_mfma_f32_32x32x16_bf16 a[0:15], v[128:131], v[104:107], a[0:15]
	ds_read_b128 v[104:107], v59 offset:55296
	ds_read_b128 v[128:131], v69
	ds_read_b128 v[164:167], v59 offset:59904
	ds_read_b128 v[168:171], v69 offset:4608
	s_waitcnt lgkmcnt(2)
	v_mfma_f32_32x32x16_bf16 a[112:127], v[104:107], v[128:131], a[112:127]
	s_waitcnt lgkmcnt(0)
	v_mfma_f32_32x32x16_bf16 a[96:111], v[104:107], v[168:171], a[96:111]
	ds_read_b128 v[104:107], v59 offset:64512
	s_waitcnt lgkmcnt(0)
	v_mfma_f32_32x32x16_bf16 a[48:63], v[104:107], v[128:131], a[48:63]
	v_mfma_f32_32x32x16_bf16 a[32:47], v[104:107], v[168:171], a[32:47]
	ds_read_b128 v[104:107], v61 offset:55296
	s_waitcnt vmcnt(4)
	ds_write_b128 v60, v[148:151]
	ds_write_b128 v60, v[144:147] offset:4608
	ds_write_b128 v60, v[140:143] offset:9216
	ds_write_b128 v60, v[124:127] offset:13824
	s_waitcnt vmcnt(2)
	ds_write_b128 v60, v[152:155] offset:18432
	ds_write_b128 v60, v[120:123] offset:23040
	s_waitcnt vmcnt(0)
	ds_write_b128 v60, v[160:163] offset:27648
	ds_write_b128 v60, v[156:159] offset:32256
	ds_write_b128 v60, v[116:119] offset:36864
	ds_write_b128 v60, v[112:115] offset:41472
	ds_write_b128 v60, v[108:111] offset:46080
	ds_write_b128 v60, v[100:103] offset:50688
	v_mfma_f32_32x32x16_bf16 a[80:95], v[164:167], v[128:131], a[80:95]
	v_mfma_f32_32x32x16_bf16 a[64:79], v[164:167], v[168:171], a[64:79]
	s_waitcnt lgkmcnt(12)
	v_mfma_f32_32x32x16_bf16 a[16:31], v[104:107], v[128:131], a[16:31]
	v_mfma_f32_32x32x16_bf16 a[0:15], v[104:107], v[168:171], a[0:15]
	ds_read_b128 v[100:103], v59 offset:55328
	ds_read_b128 v[104:107], v69 offset:32
	ds_read_b128 v[108:111], v69 offset:64
	ds_read_b128 v[112:115], v59 offset:55360
	ds_read_b128 v[116:119], v69 offset:4640
	ds_read_b128 v[120:123], v69 offset:96
	s_waitcnt lgkmcnt(4)
	v_mfma_f32_32x32x16_bf16 a[112:127], v[100:103], v[104:107], a[112:127]
	s_waitcnt lgkmcnt(1)
	v_mfma_f32_32x32x16_bf16 a[96:111], v[100:103], v[116:119], a[96:111]
	ds_read_b128 v[100:103], v59 offset:59936
	ds_read_b128 v[124:127], v59 offset:55392
	s_waitcnt lgkmcnt(1)
	v_mfma_f32_32x32x16_bf16 a[80:95], v[100:103], v[104:107], a[80:95]
	v_mfma_f32_32x32x16_bf16 a[64:79], v[100:103], v[116:119], a[64:79]
	ds_read_b128 v[100:103], v59 offset:64544
	ds_read_b128 v[128:131], v59 offset:64576
	s_waitcnt lgkmcnt(1)
	v_mfma_f32_32x32x16_bf16 a[48:63], v[100:103], v[104:107], a[48:63]
	v_mfma_f32_32x32x16_bf16 a[32:47], v[100:103], v[116:119], a[32:47]
	ds_read_b128 v[100:103], v61 offset:55328
	ds_read_b128 v[140:143], v59 offset:64608
	s_waitcnt lgkmcnt(1)
	v_mfma_f32_32x32x16_bf16 a[16:31], v[100:103], v[104:107], a[16:31]
	v_mfma_f32_32x32x16_bf16 a[0:15], v[100:103], v[116:119], a[0:15]
	ds_read_b128 v[100:103], v69 offset:4672
	ds_read_b128 v[104:107], v69 offset:4704
	v_mfma_f32_32x32x16_bf16 a[112:127], v[112:115], v[108:111], a[112:127]
	s_waitcnt lgkmcnt(1)
	v_mfma_f32_32x32x16_bf16 a[96:111], v[112:115], v[100:103], a[96:111]
	ds_read_b128 v[112:115], v59 offset:59968
	ds_read_b128 v[116:119], v59 offset:60000
	s_waitcnt lgkmcnt(1)
	v_mfma_f32_32x32x16_bf16 a[80:95], v[112:115], v[108:111], a[80:95]
	v_mfma_f32_32x32x16_bf16 a[64:79], v[112:115], v[100:103], a[64:79]
	v_mfma_f32_32x32x16_bf16 a[48:63], v[128:131], v[108:111], a[48:63]
	v_mfma_f32_32x32x16_bf16 a[32:47], v[128:131], v[100:103], a[32:47]
	ds_read_b128 v[112:115], v61 offset:55360
	ds_read_b128 v[128:131], v61 offset:55392
	s_waitcnt lgkmcnt(1)
	v_mfma_f32_32x32x16_bf16 a[16:31], v[112:115], v[108:111], a[16:31]
	v_mfma_f32_32x32x16_bf16 a[0:15], v[112:115], v[100:103], a[0:15]
	v_mfma_f32_32x32x16_bf16 a[112:127], v[124:127], v[120:123], a[112:127]
	v_mfma_f32_32x32x16_bf16 a[96:111], v[124:127], v[104:107], a[96:111]
	v_mfma_f32_32x32x16_bf16 a[80:95], v[116:119], v[120:123], a[80:95]
	v_mfma_f32_32x32x16_bf16 a[64:79], v[116:119], v[104:107], a[64:79]
	global_load_dwordx4 v[100:103], v[4:5], off offset:1664
	global_load_dwordx4 v[108:111], v[0:1], off offset:1664
	global_load_dwordx4 v[112:115], v[8:9], off offset:1664
	global_load_dwordx4 v[116:119], v[6:7], off offset:1664
	v_mfma_f32_32x32x16_bf16 a[48:63], v[140:143], v[120:123], a[48:63]
	v_mfma_f32_32x32x16_bf16 a[32:47], v[140:143], v[104:107], a[32:47]
	global_load_dwordx4 v[124:127], v[10:11], off offset:1664
	global_load_dwordx4 v[140:143], v[12:13], off offset:1664
	global_load_dwordx4 v[144:147], v[26:27], off offset:1664
	global_load_dwordx4 v[148:151], v[14:15], off offset:1664
	global_load_dwordx4 v[152:155], v[28:29], off offset:1664
	global_load_dwordx4 v[156:159], v[2:3], off offset:1664
	global_load_dwordx4 v[160:163], v[30:31], off offset:1664
	s_waitcnt lgkmcnt(0)
	v_mfma_f32_32x32x16_bf16 a[16:31], v[128:131], v[120:123], a[16:31]
	global_load_dwordx4 v[120:123], v[32:33], off offset:1664
	s_barrier
	v_mfma_f32_32x32x16_bf16 a[0:15], v[128:131], v[104:107], a[0:15]
	ds_read_b128 v[104:107], v59
	ds_read_b128 v[128:131], v62 offset:36864
	ds_read_b128 v[164:167], v59 offset:4608
	ds_read_b128 v[168:171], v62 offset:41472
	s_waitcnt lgkmcnt(2)
	v_mfma_f32_32x32x16_bf16 a[112:127], v[104:107], v[128:131], a[112:127]
	s_waitcnt lgkmcnt(0)
	v_mfma_f32_32x32x16_bf16 a[96:111], v[104:107], v[168:171], a[96:111]
	ds_read_b128 v[104:107], v59 offset:9216
	s_waitcnt lgkmcnt(0)
	v_mfma_f32_32x32x16_bf16 a[48:63], v[104:107], v[128:131], a[48:63]
	v_mfma_f32_32x32x16_bf16 a[32:47], v[104:107], v[168:171], a[32:47]
	ds_read_b128 v[104:107], v61
	s_waitcnt vmcnt(10)
	ds_write_b128 v60, v[108:111] offset:55296
	ds_write_b128 v60, v[100:103] offset:59904
	s_waitcnt vmcnt(8)
	ds_write_b128 v60, v[116:119] offset:64512
	ds_write_b128 v63, v[112:115] offset:55296
	s_waitcnt vmcnt(7)
	ds_write_b128 v64, v[124:127] offset:55296
	s_waitcnt vmcnt(6)
	ds_write_b128 v65, v[140:143] offset:55296
	s_waitcnt vmcnt(4)
	ds_write_b128 v66, v[148:151] offset:55296
	ds_write_b128 v67, v[144:147] offset:55296
	s_waitcnt vmcnt(2)
	ds_write_b128 v68, v[156:159]
	ds_write_b128 v68, v[152:155] offset:4608
	s_waitcnt vmcnt(1)
	ds_write_b128 v68, v[160:163] offset:9216
	s_waitcnt vmcnt(0)
	ds_write_b128 v68, v[120:123] offset:13824
	v_mfma_f32_32x32x16_bf16 a[80:95], v[164:167], v[128:131], a[80:95]
	v_mfma_f32_32x32x16_bf16 a[64:79], v[164:167], v[168:171], a[64:79]
	s_waitcnt lgkmcnt(12)
	v_mfma_f32_32x32x16_bf16 a[16:31], v[104:107], v[128:131], a[16:31]
	v_mfma_f32_32x32x16_bf16 a[0:15], v[104:107], v[168:171], a[0:15]
	ds_read_b128 v[100:103], v59 offset:32
	ds_read_b128 v[104:107], v62 offset:36896
	ds_read_b128 v[108:111], v62 offset:36928
	ds_read_b128 v[112:115], v59 offset:64
	ds_read_b128 v[116:119], v62 offset:41504
	ds_read_b128 v[120:123], v62 offset:36960
	s_waitcnt lgkmcnt(4)
	v_mfma_f32_32x32x16_bf16 a[112:127], v[100:103], v[104:107], a[112:127]
	s_waitcnt lgkmcnt(1)
	v_mfma_f32_32x32x16_bf16 a[96:111], v[100:103], v[116:119], a[96:111]
	ds_read_b128 v[100:103], v59 offset:4640
	ds_read_b128 v[124:127], v59 offset:96
	s_waitcnt lgkmcnt(1)
	v_mfma_f32_32x32x16_bf16 a[80:95], v[100:103], v[104:107], a[80:95]
	v_mfma_f32_32x32x16_bf16 a[64:79], v[100:103], v[116:119], a[64:79]
	ds_read_b128 v[100:103], v59 offset:9248
	ds_read_b128 v[128:131], v59 offset:9280
	s_waitcnt lgkmcnt(1)
	v_mfma_f32_32x32x16_bf16 a[48:63], v[100:103], v[104:107], a[48:63]
	v_mfma_f32_32x32x16_bf16 a[32:47], v[100:103], v[116:119], a[32:47]
	ds_read_b128 v[100:103], v61 offset:32
	ds_read_b128 v[140:143], v59 offset:9312
	s_waitcnt lgkmcnt(1)
	v_mfma_f32_32x32x16_bf16 a[16:31], v[100:103], v[104:107], a[16:31]
	v_mfma_f32_32x32x16_bf16 a[0:15], v[100:103], v[116:119], a[0:15]
	ds_read_b128 v[100:103], v62 offset:41536
	ds_read_b128 v[104:107], v62 offset:41568
	v_mfma_f32_32x32x16_bf16 a[112:127], v[112:115], v[108:111], a[112:127]
	s_waitcnt lgkmcnt(1)
	v_mfma_f32_32x32x16_bf16 a[96:111], v[112:115], v[100:103], a[96:111]
	ds_read_b128 v[112:115], v59 offset:4672
	ds_read_b128 v[116:119], v59 offset:4704
	s_waitcnt lgkmcnt(1)
	v_mfma_f32_32x32x16_bf16 a[80:95], v[112:115], v[108:111], a[80:95]
	v_mfma_f32_32x32x16_bf16 a[64:79], v[112:115], v[100:103], a[64:79]
	v_mfma_f32_32x32x16_bf16 a[48:63], v[128:131], v[108:111], a[48:63]
	v_mfma_f32_32x32x16_bf16 a[32:47], v[128:131], v[100:103], a[32:47]
	ds_read_b128 v[112:115], v61 offset:64
	ds_read_b128 v[128:131], v61 offset:96
	s_waitcnt lgkmcnt(1)
	v_mfma_f32_32x32x16_bf16 a[16:31], v[112:115], v[108:111], a[16:31]
	v_mfma_f32_32x32x16_bf16 a[0:15], v[112:115], v[100:103], a[0:15]
	global_load_dwordx4 v[100:103], v[32:33], off offset:1792
	v_mfma_f32_32x32x16_bf16 a[112:127], v[124:127], v[120:123], a[112:127]
	v_mfma_f32_32x32x16_bf16 a[96:111], v[124:127], v[104:107], a[96:111]
	v_mfma_f32_32x32x16_bf16 a[80:95], v[116:119], v[120:123], a[80:95]
	v_mfma_f32_32x32x16_bf16 a[64:79], v[116:119], v[104:107], a[64:79]
	v_mfma_f32_32x32x16_bf16 a[48:63], v[140:143], v[120:123], a[48:63]
	v_mfma_f32_32x32x16_bf16 a[32:47], v[140:143], v[104:107], a[32:47]
	global_load_dwordx4 v[108:111], v[30:31], off offset:1792
	global_load_dwordx4 v[112:115], v[28:29], off offset:1792
	global_load_dwordx4 v[116:119], v[2:3], off offset:1792
	global_load_dwordx4 v[124:127], v[8:9], off offset:1792
	global_load_dwordx4 v[140:143], v[6:7], off offset:1792
	global_load_dwordx4 v[144:147], v[4:5], off offset:1792
	global_load_dwordx4 v[148:151], v[0:1], off offset:1792
	s_waitcnt lgkmcnt(0)
	v_mfma_f32_32x32x16_bf16 a[16:31], v[128:131], v[120:123], a[16:31]
	global_load_dwordx4 v[120:123], v[12:13], off offset:1792
	global_load_dwordx4 v[152:155], v[10:11], off offset:1792
	global_load_dwordx4 v[156:159], v[26:27], off offset:1792
	global_load_dwordx4 v[160:163], v[14:15], off offset:1792
	s_barrier
	v_mfma_f32_32x32x16_bf16 a[0:15], v[128:131], v[104:107], a[0:15]
	ds_read_b128 v[104:107], v59 offset:55296
	ds_read_b128 v[128:131], v69
	ds_read_b128 v[164:167], v59 offset:59904
	ds_read_b128 v[168:171], v69 offset:4608
	s_waitcnt lgkmcnt(2)
	v_mfma_f32_32x32x16_bf16 a[112:127], v[104:107], v[128:131], a[112:127]
	s_waitcnt lgkmcnt(0)
	v_mfma_f32_32x32x16_bf16 a[96:111], v[104:107], v[168:171], a[96:111]
	ds_read_b128 v[104:107], v59 offset:64512
	s_waitcnt lgkmcnt(0)
	v_mfma_f32_32x32x16_bf16 a[48:63], v[104:107], v[128:131], a[48:63]
	v_mfma_f32_32x32x16_bf16 a[32:47], v[104:107], v[168:171], a[32:47]
	ds_read_b128 v[104:107], v61 offset:55296
	s_waitcnt vmcnt(4)
	ds_write_b128 v60, v[148:151]
	ds_write_b128 v60, v[144:147] offset:4608
	ds_write_b128 v60, v[140:143] offset:9216
	ds_write_b128 v60, v[124:127] offset:13824
	s_waitcnt vmcnt(2)
	ds_write_b128 v60, v[152:155] offset:18432
	ds_write_b128 v60, v[120:123] offset:23040
	s_waitcnt vmcnt(0)
	ds_write_b128 v60, v[160:163] offset:27648
	ds_write_b128 v60, v[156:159] offset:32256
	ds_write_b128 v60, v[116:119] offset:36864
	ds_write_b128 v60, v[112:115] offset:41472
	ds_write_b128 v60, v[108:111] offset:46080
	ds_write_b128 v60, v[100:103] offset:50688
	v_mfma_f32_32x32x16_bf16 a[80:95], v[164:167], v[128:131], a[80:95]
	v_mfma_f32_32x32x16_bf16 a[64:79], v[164:167], v[168:171], a[64:79]
	s_waitcnt lgkmcnt(12)
	v_mfma_f32_32x32x16_bf16 a[16:31], v[104:107], v[128:131], a[16:31]
	v_mfma_f32_32x32x16_bf16 a[0:15], v[104:107], v[168:171], a[0:15]
	ds_read_b128 v[100:103], v59 offset:55328
	ds_read_b128 v[104:107], v69 offset:32
	ds_read_b128 v[108:111], v69 offset:64
	ds_read_b128 v[112:115], v59 offset:55360
	ds_read_b128 v[116:119], v69 offset:4640
	ds_read_b128 v[120:123], v69 offset:96
	s_waitcnt lgkmcnt(4)
	v_mfma_f32_32x32x16_bf16 a[112:127], v[100:103], v[104:107], a[112:127]
	s_waitcnt lgkmcnt(1)
	v_mfma_f32_32x32x16_bf16 a[96:111], v[100:103], v[116:119], a[96:111]
	ds_read_b128 v[100:103], v59 offset:59936
	ds_read_b128 v[124:127], v59 offset:55392
	s_waitcnt lgkmcnt(1)
	v_mfma_f32_32x32x16_bf16 a[80:95], v[100:103], v[104:107], a[80:95]
	v_mfma_f32_32x32x16_bf16 a[64:79], v[100:103], v[116:119], a[64:79]
	ds_read_b128 v[100:103], v59 offset:64544
	ds_read_b128 v[128:131], v59 offset:64576
	s_waitcnt lgkmcnt(1)
	v_mfma_f32_32x32x16_bf16 a[48:63], v[100:103], v[104:107], a[48:63]
	v_mfma_f32_32x32x16_bf16 a[32:47], v[100:103], v[116:119], a[32:47]
	ds_read_b128 v[100:103], v61 offset:55328
	ds_read_b128 v[140:143], v59 offset:64608
	s_waitcnt lgkmcnt(1)
	v_mfma_f32_32x32x16_bf16 a[16:31], v[100:103], v[104:107], a[16:31]
	v_mfma_f32_32x32x16_bf16 a[0:15], v[100:103], v[116:119], a[0:15]
	ds_read_b128 v[100:103], v69 offset:4672
	ds_read_b128 v[104:107], v69 offset:4704
	v_mfma_f32_32x32x16_bf16 a[112:127], v[112:115], v[108:111], a[112:127]
	s_waitcnt lgkmcnt(1)
	v_mfma_f32_32x32x16_bf16 a[96:111], v[112:115], v[100:103], a[96:111]
	ds_read_b128 v[112:115], v59 offset:59968
	ds_read_b128 v[116:119], v59 offset:60000
	s_waitcnt lgkmcnt(1)
	v_mfma_f32_32x32x16_bf16 a[80:95], v[112:115], v[108:111], a[80:95]
	v_mfma_f32_32x32x16_bf16 a[64:79], v[112:115], v[100:103], a[64:79]
	v_mfma_f32_32x32x16_bf16 a[48:63], v[128:131], v[108:111], a[48:63]
	v_mfma_f32_32x32x16_bf16 a[32:47], v[128:131], v[100:103], a[32:47]
	ds_read_b128 v[112:115], v61 offset:55360
	ds_read_b128 v[128:131], v61 offset:55392
	s_waitcnt lgkmcnt(1)
	v_mfma_f32_32x32x16_bf16 a[16:31], v[112:115], v[108:111], a[16:31]
	v_mfma_f32_32x32x16_bf16 a[0:15], v[112:115], v[100:103], a[0:15]
	global_load_dwordx4 v[100:103], v[4:5], off offset:1920
	global_load_dwordx4 v[108:111], v[0:1], off offset:1920
	global_load_dwordx4 v[112:115], v[8:9], off offset:1920
	s_nop 0
	global_load_dwordx4 v[4:7], v[6:7], off offset:1920
	v_mfma_f32_32x32x16_bf16 a[112:127], v[124:127], v[120:123], a[112:127]
	v_mfma_f32_32x32x16_bf16 a[96:111], v[124:127], v[104:107], a[96:111]
	v_mfma_f32_32x32x16_bf16 a[80:95], v[116:119], v[120:123], a[80:95]
	v_mfma_f32_32x32x16_bf16 a[64:79], v[116:119], v[104:107], a[64:79]
	v_mfma_f32_32x32x16_bf16 a[48:63], v[140:143], v[120:123], a[48:63]
	v_mfma_f32_32x32x16_bf16 a[32:47], v[140:143], v[104:107], a[32:47]
	global_load_dwordx4 v[8:11], v[10:11], off offset:1920
	s_nop 0
	global_load_dwordx4 v[116:119], v[12:13], off offset:1920
	global_load_dwordx4 v[124:127], v[26:27], off offset:1920
	s_nop 0
	global_load_dwordx4 v[12:15], v[14:15], off offset:1920
	s_nop 0
	global_load_dwordx4 v[26:29], v[28:29], off offset:1920
	s_nop 0
	global_load_dwordx4 v[0:3], v[2:3], off offset:1920
	s_nop 0
	global_load_dwordx4 v[140:143], v[30:31], off offset:1920
	s_nop 0
	global_load_dwordx4 v[30:33], v[32:33], off offset:1920
	s_waitcnt lgkmcnt(0)
	s_barrier
	v_mfma_f32_32x32x16_bf16 a[16:31], v[128:131], v[120:123], a[16:31]
	v_mfma_f32_32x32x16_bf16 a[0:15], v[128:131], v[104:107], a[0:15]
	ds_read_b128 v[104:107], v59
	ds_read_b128 v[120:123], v62 offset:36864
	ds_read_b128 v[128:131], v59 offset:4608
	ds_read_b128 v[144:147], v62 offset:41472
	s_waitcnt lgkmcnt(2)
	v_mfma_f32_32x32x16_bf16 a[112:127], v[104:107], v[120:123], a[112:127]
	s_waitcnt lgkmcnt(0)
	v_mfma_f32_32x32x16_bf16 a[96:111], v[104:107], v[144:147], a[96:111]
	v_mfma_f32_32x32x16_bf16 a[80:95], v[128:131], v[120:123], a[80:95]
	v_mfma_f32_32x32x16_bf16 a[64:79], v[128:131], v[144:147], a[64:79]
	ds_read_b128 v[104:107], v59 offset:9216
	ds_read_b128 v[128:131], v61
	s_waitcnt vmcnt(10)
	ds_write_b128 v60, v[108:111] offset:55296
	ds_write_b128 v60, v[100:103] offset:59904
	s_waitcnt vmcnt(8)
	ds_write_b128 v60, v[4:7] offset:64512
	ds_write_b128 v63, v[112:115] offset:55296
	s_waitcnt vmcnt(7)
	ds_write_b128 v64, v[8:11] offset:55296
	s_waitcnt vmcnt(6)
	ds_write_b128 v65, v[116:119] offset:55296
	s_waitcnt vmcnt(4)
	ds_write_b128 v66, v[12:15] offset:55296
	ds_write_b128 v67, v[124:127] offset:55296
	s_waitcnt vmcnt(2)
	ds_write_b128 v68, v[0:3]
	ds_write_b128 v68, v[26:29] offset:4608
	s_waitcnt vmcnt(1)
	ds_write_b128 v68, v[140:143] offset:9216
	s_waitcnt vmcnt(0)
	ds_write_b128 v68, v[30:33] offset:13824
	ds_read_b128 v[0:3], v59 offset:32
	ds_read_b128 v[4:7], v62 offset:36896
	ds_read_b128 v[8:11], v62 offset:36928
	ds_read_b128 v[12:15], v59 offset:64
	ds_read_b128 v[26:29], v62 offset:41504
	ds_read_b128 v[30:33], v62 offset:36960
	s_waitcnt lgkmcnt(14)
	v_mfma_f32_32x32x16_bf16 a[48:63], v[104:107], v[120:123], a[48:63]
	v_mfma_f32_32x32x16_bf16 a[32:47], v[104:107], v[144:147], a[32:47]
	s_waitcnt lgkmcnt(4)
	v_mfma_f32_32x32x16_bf16 a[112:127], v[0:3], v[4:7], a[112:127]
	s_waitcnt lgkmcnt(1)
	v_mfma_f32_32x32x16_bf16 a[96:111], v[0:3], v[26:29], a[96:111]
	ds_read_b128 v[0:3], v59 offset:4640
	ds_read_b128 v[100:103], v59 offset:96
	v_mfma_f32_32x32x16_bf16 a[16:31], v[128:131], v[120:123], a[16:31]
	v_mfma_f32_32x32x16_bf16 a[0:15], v[128:131], v[144:147], a[0:15]
	s_waitcnt lgkmcnt(1)
	v_mfma_f32_32x32x16_bf16 a[80:95], v[0:3], v[4:7], a[80:95]
	v_mfma_f32_32x32x16_bf16 a[64:79], v[0:3], v[26:29], a[64:79]
	ds_read_b128 v[0:3], v59 offset:9248
	ds_read_b128 v[104:107], v59 offset:9280
	s_waitcnt lgkmcnt(1)
	v_mfma_f32_32x32x16_bf16 a[48:63], v[0:3], v[4:7], a[48:63]
	v_mfma_f32_32x32x16_bf16 a[32:47], v[0:3], v[26:29], a[32:47]
	ds_read_b128 v[0:3], v61 offset:32
	ds_read_b128 v[108:111], v59 offset:9312
	s_waitcnt lgkmcnt(1)
	v_mfma_f32_32x32x16_bf16 a[16:31], v[0:3], v[4:7], a[16:31]
	v_mfma_f32_32x32x16_bf16 a[0:15], v[0:3], v[26:29], a[0:15]
	ds_read_b128 v[0:3], v62 offset:41536
	ds_read_b128 v[4:7], v62 offset:41568
	v_mfma_f32_32x32x16_bf16 a[112:127], v[12:15], v[8:11], a[112:127]
	s_waitcnt lgkmcnt(1)
	v_mfma_f32_32x32x16_bf16 a[96:111], v[12:15], v[0:3], a[96:111]
	ds_read_b128 v[12:15], v59 offset:4672
	ds_read_b128 v[26:29], v59 offset:4704
	s_waitcnt lgkmcnt(1)
	v_mfma_f32_32x32x16_bf16 a[80:95], v[12:15], v[8:11], a[80:95]
	v_mfma_f32_32x32x16_bf16 a[64:79], v[12:15], v[0:3], a[64:79]
	v_mfma_f32_32x32x16_bf16 a[48:63], v[104:107], v[8:11], a[48:63]
	v_mfma_f32_32x32x16_bf16 a[32:47], v[104:107], v[0:3], a[32:47]
	ds_read_b128 v[12:15], v61 offset:64
	ds_read_b128 v[104:107], v61 offset:96
	s_waitcnt lgkmcnt(0)
	s_barrier
	v_mfma_f32_32x32x16_bf16 a[16:31], v[12:15], v[8:11], a[16:31]
	v_mfma_f32_32x32x16_bf16 a[0:15], v[12:15], v[0:3], a[0:15]
	v_mfma_f32_32x32x16_bf16 a[112:127], v[100:103], v[30:33], a[112:127]
	v_mfma_f32_32x32x16_bf16 a[96:111], v[100:103], v[4:7], a[96:111]
	v_mfma_f32_32x32x16_bf16 a[80:95], v[26:29], v[30:33], a[80:95]
	v_mfma_f32_32x32x16_bf16 a[64:79], v[26:29], v[4:7], a[64:79]
	v_mfma_f32_32x32x16_bf16 a[48:63], v[108:111], v[30:33], a[48:63]
	v_mfma_f32_32x32x16_bf16 a[32:47], v[108:111], v[4:7], a[32:47]
	v_mfma_f32_32x32x16_bf16 a[16:31], v[104:107], v[30:33], a[16:31]
	v_mfma_f32_32x32x16_bf16 a[0:15], v[104:107], v[4:7], a[0:15]
	ds_read_b128 v[0:3], v59 offset:55296
	ds_read_b128 v[4:7], v69
	ds_read_b128 v[8:11], v59 offset:55328
	ds_read_b128 v[12:15], v69 offset:32
	ds_read_b128 v[26:29], v69 offset:4608
	ds_read_b128 v[30:33], v69 offset:4640
	s_waitcnt lgkmcnt(4)
	v_mfma_f32_32x32x16_bf16 a[112:127], v[0:3], v[4:7], a[112:127]
	s_waitcnt lgkmcnt(1)
	v_mfma_f32_32x32x16_bf16 a[96:111], v[0:3], v[26:29], a[96:111]
	ds_read_b128 v[0:3], v59 offset:59904
	ds_read_b128 v[100:103], v59 offset:59936
	s_waitcnt lgkmcnt(1)
	v_mfma_f32_32x32x16_bf16 a[80:95], v[0:3], v[4:7], a[80:95]
	v_mfma_f32_32x32x16_bf16 a[64:79], v[0:3], v[26:29], a[64:79]
	ds_read_b128 v[0:3], v59 offset:64512
	ds_read_b128 v[104:107], v59 offset:64544
	s_waitcnt lgkmcnt(1)
	v_mfma_f32_32x32x16_bf16 a[48:63], v[0:3], v[4:7], a[48:63]
	v_mfma_f32_32x32x16_bf16 a[32:47], v[0:3], v[26:29], a[32:47]
	ds_read_b128 v[0:3], v61 offset:55296
	ds_read_b128 v[108:111], v61 offset:55328
	s_waitcnt lgkmcnt(1)
	v_mfma_f32_32x32x16_bf16 a[0:15], v[0:3], v[26:29], a[0:15]
	v_mfma_f32_32x32x16_bf16 a[112:127], v[8:11], v[12:15], a[112:127]
	v_mfma_f32_32x32x16_bf16 a[96:111], v[8:11], v[30:33], a[96:111]
	v_mfma_f32_32x32x16_bf16 a[16:31], v[0:3], v[4:7], a[16:31]
	v_mfma_f32_32x32x16_bf16 a[80:95], v[100:103], v[12:15], a[80:95]
	v_mfma_f32_32x32x16_bf16 a[64:79], v[100:103], v[30:33], a[64:79]
	v_mfma_f32_32x32x16_bf16 a[32:47], v[104:107], v[30:33], a[32:47]
	s_waitcnt lgkmcnt(0)
	v_mfma_f32_32x32x16_bf16 a[0:15], v[108:111], v[30:33], a[0:15]
	ds_read_b128 v[8:11], v59 offset:55360
	ds_read_b128 v[26:29], v69 offset:64
	ds_read_b128 v[30:33], v59 offset:55392
	ds_read_b128 v[4:7], v69 offset:96
	ds_read_b128 v[100:103], v69 offset:4672
	ds_read_b128 v[0:3], v69 offset:4704
	v_mfma_f32_32x32x16_bf16 a[48:63], v[104:107], v[12:15], a[48:63]
	s_waitcnt lgkmcnt(4)
	v_mfma_f32_32x32x16_bf16 a[112:127], v[8:11], v[26:29], a[112:127]
	s_waitcnt lgkmcnt(1)
	v_mfma_f32_32x32x16_bf16 a[96:111], v[8:11], v[100:103], a[96:111]
	ds_read_b128 v[8:11], v59 offset:59968
	ds_read_b128 v[104:107], v59 offset:60000
	v_mfma_f32_32x32x16_bf16 a[16:31], v[108:111], v[12:15], a[16:31]
	s_waitcnt lgkmcnt(1)
	v_mfma_f32_32x32x16_bf16 a[80:95], v[8:11], v[26:29], a[80:95]
	v_mfma_f32_32x32x16_bf16 a[64:79], v[8:11], v[100:103], a[64:79]
	ds_read_b128 v[8:11], v59 offset:64576
	ds_read_b128 v[12:15], v59 offset:64608
	s_waitcnt lgkmcnt(1)
	v_mfma_f32_32x32x16_bf16 a[48:63], v[8:11], v[26:29], a[48:63]
	v_mfma_f32_32x32x16_bf16 a[32:47], v[8:11], v[100:103], a[32:47]
	ds_read_b128 v[108:111], v61 offset:55360
	ds_read_b128 v[8:11], v61 offset:55392
	s_waitcnt lgkmcnt(0)
	s_barrier
	v_mfma_f32_32x32x16_bf16 a[16:31], v[108:111], v[26:29], a[16:31]
	v_or_b32_e32 v28, s14, v139
	v_lshl_add_u64 v[26:27], v[22:23], 0, s[4:5]
	v_or_b32_e32 v29, s14, v204
	v_mfma_f32_32x32x16_bf16 a[0:15], v[108:111], v[100:103], a[0:15]
	v_mfma_f32_32x32x16_bf16 a[112:127], v[30:33], v[4:7], a[112:127]
	v_mfma_f32_32x32x16_bf16 a[48:63], v[12:15], v[4:7], a[48:63]
	v_mfma_f32_32x32x16_bf16 a[32:47], v[12:15], v[0:3], a[32:47]
	v_lshl_add_u64 v[12:13], v[16:17], 2, v[26:27]
	v_lshlrev_b32_e32 v16, 10, v28
	v_lshl_add_u64 v[14:15], s[16:17], 0, v[24:25]
	v_add_co_u32_e32 v14, vcc, s11, v14
	s_nop 1
	v_addc_co_u32_e32 v15, vcc, 0, v15, vcc
	v_mfma_f32_32x32x16_bf16 a[96:111], v[30:33], v[0:3], a[96:111]
	v_or_b32_e32 v30, s14, v205
	v_lshl_add_u64 v[32:33], v[16:17], 2, v[26:27]
	v_lshlrev_b32_e32 v16, 10, v29
	v_mfma_f32_32x32x16_bf16 a[80:95], v[104:107], v[4:7], a[80:95]
	v_mfma_f32_32x32x16_bf16 a[64:79], v[104:107], v[0:3], a[64:79]
	v_lshl_add_u64 v[104:105], v[16:17], 2, v[26:27]
	v_lshlrev_b32_e32 v16, 10, v30
	v_lshl_add_u64 v[106:107], v[16:17], 2, v[26:27]
	v_mfma_f32_32x32x16_bf16 a[16:31], v[8:11], v[4:7], a[16:31]
	v_mfma_f32_32x32x16_bf16 a[0:15], v[8:11], v[0:3], a[0:15]
	v_mov_b32_e32 v144, v14
	v_mov_b32_e32 v145, v15
	v_mov_b32_e32 v146, v16
	v_mov_b32_e32 v147, v17
	v_mov_b32_e32 v148, v28
	v_mov_b32_e32 v149, v29
	v_mov_b32_e32 v150, v32
	v_mov_b32_e32 v151, v33
	v_mov_b32_e32 v152, v104
	v_mov_b32_e32 v153, v105
	v_mov_b32_e32 v154, v106
	v_mov_b32_e32 v155, v107
	v_mov_b32_e32 v156, v108
	v_mov_b32_e32 v157, v109
	v_mov_b32_e32 v158, v110
	v_mov_b32_e32 v159, v111
	global_load_dwordx4 v[250:253], v[144:145], off
	global_load_dwordx4 v[246:249], v[150:151], off
	global_load_dwordx4 v[242:245], v[152:153], off
	global_load_dwordx4 v[238:241], v[154:155], off
	global_load_dwordx4 v[234:237], v[12:13], off
	v_or_b32_e32 v144, s14, v206
	v_lshlrev_b32_e32 v146, 10, v144
	v_lshl_add_u64 v[144:145], v[146:147], 2, v[26:27]
	v_or_b32_e32 v146, s14, v207
	v_lshlrev_b32_e32 v146, 10, v146
	global_load_dwordx4 v[212:215], v[144:145], off
	v_or_b32_e32 v148, s14, v208
	v_or_b32_e32 v149, s14, v209
	v_lshl_add_u64 v[150:151], v[146:147], 2, v[26:27]
	v_lshlrev_b32_e32 v146, 10, v148
	v_lshl_add_u64 v[152:153], v[146:147], 2, v[26:27]
	v_lshlrev_b32_e32 v146, 10, v149
	v_lshl_add_u64 v[154:155], v[146:147], 2, v[26:27]
	global_load_dwordx4 v[200:203], v[150:151], off
	global_load_dwordx4 v[196:199], v[152:153], off
	global_load_dwordx4 v[192:195], v[154:155], off
	v_or_b32_e32 v144, s14, v210
	v_lshlrev_b32_e32 v146, 10, v144
	v_lshl_add_u64 v[144:145], v[146:147], 2, v[26:27]
	v_or_b32_e32 v146, s14, v35
	v_lshlrev_b32_e32 v146, 10, v146
	global_load_dwordx4 v[188:191], v[144:145], off
	v_or_b32_e32 v148, s14, v36
	v_or_b32_e32 v149, s14, v37
	v_lshl_add_u64 v[150:151], v[146:147], 2, v[26:27]
	v_lshlrev_b32_e32 v146, 10, v148
	v_lshl_add_u64 v[152:153], v[146:147], 2, v[26:27]
	v_lshlrev_b32_e32 v146, 10, v149
	v_lshl_add_u64 v[154:155], v[146:147], 2, v[26:27]
	global_load_dwordx4 v[184:187], v[150:151], off
	global_load_dwordx4 v[180:183], v[152:153], off
	global_load_dwordx4 v[176:179], v[154:155], off
	v_or_b32_e32 v144, s14, v38
	v_lshlrev_b32_e32 v146, 10, v144
	v_lshl_add_u64 v[144:145], v[146:147], 2, v[26:27]
	v_or_b32_e32 v146, s14, v39
	v_lshlrev_b32_e32 v146, 10, v146
	global_load_dwordx4 v[172:175], v[144:145], off
	v_or_b32_e32 v148, s14, v40
	v_or_b32_e32 v149, s14, v41
	v_lshl_add_u64 v[150:151], v[146:147], 2, v[26:27]
	v_lshlrev_b32_e32 v146, 10, v148
	v_lshl_add_u64 v[156:157], v[146:147], 2, v[26:27]
	v_lshlrev_b32_e32 v146, 10, v149
	v_lshl_add_u64 v[158:159], v[146:147], 2, v[26:27]
	global_load_dwordx4 v[168:171], v[150:151], off
	global_load_dwordx4 v[164:167], v[156:157], off
	global_load_dwordx4 v[160:163], v[158:159], off
	ds_write_b32 v58, a112
	ds_write_b32 v58, a113 offset:516
	ds_write_b32 v58, a114 offset:1032
	ds_write_b32 v58, a115 offset:1548
	ds_write_b32 v58, a116 offset:4128
	ds_write_b32 v58, a117 offset:4644
	ds_write_b32 v58, a118 offset:5160
	ds_write_b32 v58, a119 offset:5676
	ds_write_b32 v58, a120 offset:8256
	ds_write_b32 v58, a121 offset:8772
	ds_write_b32 v58, a122 offset:9288
	ds_write_b32 v58, a123 offset:9804
	ds_write_b32 v58, a124 offset:12384
	ds_write_b32 v58, a125 offset:12900
	ds_write_b32 v58, a126 offset:13416
	ds_write_b32 v58, a127 offset:13932
	ds_write_b32 v58, a96 offset:128
	ds_write_b32 v58, a97 offset:644
	ds_write_b32 v58, a98 offset:1160
	ds_write_b32 v58, a99 offset:1676
	ds_write_b32 v58, a100 offset:4256
	ds_write_b32 v58, a101 offset:4772
	ds_write_b32 v58, a102 offset:5288
	ds_write_b32 v58, a103 offset:5804
	ds_write_b32 v58, a104 offset:8384
	ds_write_b32 v58, a105 offset:8900
	ds_write_b32 v58, a106 offset:9416
	ds_write_b32 v58, a107 offset:9932
	ds_write_b32 v58, a108 offset:12512
	ds_write_b32 v58, a109 offset:13028
	ds_write_b32 v58, a110 offset:13544
	ds_write_b32 v58, a111 offset:14060
	ds_write_b32 v58, a80 offset:16512
	ds_write_b32 v58, a81 offset:17028
	ds_write_b32 v58, a82 offset:17544
	ds_write_b32 v58, a83 offset:18060
	ds_write_b32 v58, a84 offset:20640
	ds_write_b32 v58, a85 offset:21156
	ds_write_b32 v58, a86 offset:21672
	ds_write_b32 v58, a87 offset:22188
	ds_write_b32 v58, a88 offset:24768
	ds_write_b32 v58, a89 offset:25284
	ds_write_b32 v58, a90 offset:25800
	ds_write_b32 v58, a91 offset:26316
	ds_write_b32 v58, a92 offset:28896
	ds_write_b32 v58, a93 offset:29412
	ds_write_b32 v58, a94 offset:29928
	ds_write_b32 v58, a95 offset:30444
	ds_write_b32 v58, a64 offset:16640
	ds_write_b32 v58, a65 offset:17156
	ds_write_b32 v58, a66 offset:17672
	ds_write_b32 v58, a67 offset:18188
	ds_write_b32 v58, a68 offset:20768
	ds_write_b32 v58, a69 offset:21284
	ds_write_b32 v58, a70 offset:21800
	ds_write_b32 v58, a71 offset:22316
	ds_write_b32 v58, a72 offset:24896
	ds_write_b32 v58, a73 offset:25412
	ds_write_b32 v58, a74 offset:25928
	ds_write_b32 v58, a75 offset:26444
	ds_write_b32 v58, a76 offset:29024
	ds_write_b32 v58, a77 offset:29540
	ds_write_b32 v58, a78 offset:30056
	ds_write_b32 v58, a79 offset:30572
	ds_write_b32 v58, a48 offset:33024
	ds_write_b32 v58, a49 offset:33540
	ds_write_b32 v58, a50 offset:34056
	ds_write_b32 v58, a51 offset:34572
	ds_write_b32 v58, a52 offset:37152
	ds_write_b32 v58, a53 offset:37668
	ds_write_b32 v58, a54 offset:38184
	ds_write_b32 v58, a55 offset:38700
	ds_write_b32 v58, a56 offset:41280
	ds_write_b32 v58, a57 offset:41796
	ds_write_b32 v58, a58 offset:42312
	ds_write_b32 v58, a59 offset:42828
	ds_write_b32 v58, a60 offset:45408
	ds_write_b32 v58, a61 offset:45924
	ds_write_b32 v58, a62 offset:46440
	ds_write_b32 v58, a63 offset:46956
	ds_write_b32 v58, a32 offset:33152
	ds_write_b32 v58, a33 offset:33668
	ds_write_b32 v58, a34 offset:34184
	ds_write_b32 v58, a35 offset:34700
	ds_write_b32 v58, a36 offset:37280
	ds_write_b32 v58, a37 offset:37796
	ds_write_b32 v58, a38 offset:38312
	ds_write_b32 v58, a39 offset:38828
	ds_write_b32 v58, a40 offset:41408
	ds_write_b32 v58, a41 offset:41924
	ds_write_b32 v58, a42 offset:42440
	ds_write_b32 v58, a43 offset:42956
	ds_write_b32 v58, a44 offset:45536
	ds_write_b32 v58, a45 offset:46052
	ds_write_b32 v58, a46 offset:46568
	ds_write_b32 v58, a47 offset:47084
	ds_write_b32 v58, a16 offset:49536
	ds_write_b32 v58, a17 offset:50052
	ds_write_b32 v58, a18 offset:50568
	ds_write_b32 v58, a19 offset:51084
	ds_write_b32 v58, a20 offset:53664
	ds_write_b32 v58, a21 offset:54180
	ds_write_b32 v58, a22 offset:54696
	ds_write_b32 v58, a23 offset:55212
	ds_write_b32 v58, a24 offset:57792
	ds_write_b32 v58, a25 offset:58308
	ds_write_b32 v58, a26 offset:58824
	ds_write_b32 v58, a27 offset:59340
	ds_write_b32 v58, a28 offset:61920
	ds_write_b32 v58, a29 offset:62436
	ds_write_b32 v58, a30 offset:62952
	ds_write_b32 v58, a31 offset:63468
	ds_write_b32 v58, a0 offset:49664
	ds_write_b32 v58, a1 offset:50180
	ds_write_b32 v58, a2 offset:50696
	ds_write_b32 v58, a3 offset:51212
	ds_write_b32 v58, a4 offset:53792
	ds_write_b32 v58, a5 offset:54308
	ds_write_b32 v58, a6 offset:54824
	ds_write_b32 v58, a7 offset:55340
	ds_write_b32 v58, a8 offset:57920
	ds_write_b32 v58, a9 offset:58436
	ds_write_b32 v58, a10 offset:58952
	ds_write_b32 v58, a11 offset:59468
	ds_write_b32 v58, a12 offset:62048
	ds_write_b32 v58, a13 offset:62564
	ds_write_b32 v58, a14 offset:63080
	ds_write_b32 v58, a15 offset:63596
	s_waitcnt lgkmcnt(0)
	s_barrier
	s_waitcnt vmcnt(16)
	s_nop 1
	v_mov_b64_e32 v[0:1], v[250:251]
	v_mov_b64_e32 v[2:3], v[252:253]
	s_waitcnt vmcnt(15)
	s_nop 1
	v_mov_b64_e32 v[8:9], v[246:247]
	v_mov_b64_e32 v[10:11], v[248:249]
	s_waitcnt vmcnt(14)
	s_nop 1
	v_mov_b64_e32 v[28:29], v[242:243]
	v_mov_b64_e32 v[30:31], v[244:245]
	s_waitcnt vmcnt(13)
	s_nop 1
	v_mov_b64_e32 v[100:101], v[238:239]
	v_mov_b64_e32 v[102:103], v[240:241]
	s_waitcnt vmcnt(12)
	s_nop 1
	v_mov_b64_e32 v[4:5], v[234:235]
	v_mov_b64_e32 v[6:7], v[236:237]
	ds_read2_b32 v[108:109], v70 offset1:1
	ds_read2_b32 v[110:111], v71 offset1:1
	ds_read2_b32 v[112:113], v72 offset1:1
	ds_read2_b32 v[114:115], v73 offset1:1
	ds_read2_b32 v[116:117], v74 offset1:1
	ds_read2_b32 v[118:119], v75 offset1:1
	ds_read2_b32 v[120:121], v76 offset1:1
	ds_read2_b32 v[122:123], v77 offset1:1
	v_or_b32_e32 v14, s14, v206
	v_lshlrev_b32_e32 v16, 10, v14
	v_lshl_add_u64 v[14:15], v[16:17], 2, v[26:27]
	v_or_b32_e32 v16, s14, v207
	v_lshlrev_b32_e32 v16, 10, v16
	s_waitcnt lgkmcnt(6)
	v_pk_fma_f32 v[10:11], v[2:3], v[110:111], v[10:11]
	v_pk_fma_f32 v[8:9], v[0:1], v[108:109], v[8:9]
	s_waitcnt lgkmcnt(4)
	v_pk_fma_f32 v[30:31], v[2:3], v[114:115], v[30:31]
	v_pk_fma_f32 v[28:29], v[0:1], v[112:113], v[28:29]
	s_waitcnt lgkmcnt(2)
	v_pk_fma_f32 v[102:103], v[2:3], v[118:119], v[102:103]
	v_pk_fma_f32 v[100:101], v[0:1], v[116:117], v[100:101]
	global_store_dwordx4 v[32:33], v[8:11], off
	global_store_dwordx4 v[104:105], v[28:31], off
	global_store_dwordx4 v[106:107], v[100:103], off
	s_waitcnt vmcnt(14)
	s_nop 1
	v_mov_b64_e32 v[8:9], v[212:213]
	v_mov_b64_e32 v[10:11], v[214:215]
	v_or_b32_e32 v28, s14, v208
	v_or_b32_e32 v29, s14, v209
	v_lshl_add_u64 v[32:33], v[16:17], 2, v[26:27]
	v_lshlrev_b32_e32 v16, 10, v28
	v_lshl_add_u64 v[104:105], v[16:17], 2, v[26:27]
	v_lshlrev_b32_e32 v16, 10, v29
	v_lshl_add_u64 v[106:107], v[16:17], 2, v[26:27]
	s_waitcnt lgkmcnt(0)
	v_pk_fma_f32 v[10:11], v[2:3], v[122:123], v[10:11]
	v_pk_fma_f32 v[8:9], v[0:1], v[120:121], v[8:9]
	global_store_dwordx4 v[14:15], v[8:11], off
	s_waitcnt vmcnt(14)
	s_nop 1
	v_mov_b64_e32 v[8:9], v[200:201]
	v_mov_b64_e32 v[10:11], v[202:203]
	s_nop 0
	s_waitcnt vmcnt(13)
	s_nop 1
	v_mov_b64_e32 v[28:29], v[196:197]
	v_mov_b64_e32 v[30:31], v[198:199]
	s_waitcnt vmcnt(12)
	s_nop 1
	v_mov_b64_e32 v[100:101], v[192:193]
	v_mov_b64_e32 v[102:103], v[194:195]
	ds_read2_b32 v[108:109], v78 offset1:1
	ds_read2_b32 v[110:111], v79 offset1:1
	ds_read2_b32 v[112:113], v80 offset1:1
	ds_read2_b32 v[114:115], v81 offset1:1
	ds_read2_b32 v[116:117], v82 offset1:1
	ds_read2_b32 v[118:119], v83 offset1:1
	ds_read2_b32 v[120:121], v84 offset1:1
	ds_read2_b32 v[122:123], v85 offset1:1
	v_or_b32_e32 v14, s14, v210
	v_lshlrev_b32_e32 v16, 10, v14
	v_lshl_add_u64 v[14:15], v[16:17], 2, v[26:27]
	v_or_b32_e32 v16, s14, v35
	v_lshlrev_b32_e32 v16, 10, v16
	s_waitcnt lgkmcnt(6)
	v_pk_fma_f32 v[10:11], v[2:3], v[110:111], v[10:11]
	v_pk_fma_f32 v[8:9], v[0:1], v[108:109], v[8:9]
	s_waitcnt lgkmcnt(4)
	v_pk_fma_f32 v[30:31], v[2:3], v[114:115], v[30:31]
	v_pk_fma_f32 v[28:29], v[0:1], v[112:113], v[28:29]
	s_waitcnt lgkmcnt(2)
	v_pk_fma_f32 v[102:103], v[2:3], v[118:119], v[102:103]
	v_pk_fma_f32 v[100:101], v[0:1], v[116:117], v[100:101]
	global_store_dwordx4 v[32:33], v[8:11], off
	global_store_dwordx4 v[104:105], v[28:31], off
	global_store_dwordx4 v[106:107], v[100:103], off
	s_waitcnt vmcnt(14)
	s_nop 1
	v_mov_b64_e32 v[8:9], v[188:189]
	v_mov_b64_e32 v[10:11], v[190:191]
	v_or_b32_e32 v28, s14, v36
	v_or_b32_e32 v29, s14, v37
	v_lshl_add_u64 v[32:33], v[16:17], 2, v[26:27]
	v_lshlrev_b32_e32 v16, 10, v28
	v_lshl_add_u64 v[104:105], v[16:17], 2, v[26:27]
	v_lshlrev_b32_e32 v16, 10, v29
	v_lshl_add_u64 v[106:107], v[16:17], 2, v[26:27]
	s_waitcnt lgkmcnt(0)
	v_pk_fma_f32 v[10:11], v[2:3], v[122:123], v[10:11]
	v_pk_fma_f32 v[8:9], v[0:1], v[120:121], v[8:9]
	global_store_dwordx4 v[14:15], v[8:11], off
	s_waitcnt vmcnt(14)
	s_nop 1
	v_mov_b64_e32 v[8:9], v[184:185]
	v_mov_b64_e32 v[10:11], v[186:187]
	s_nop 0
	s_waitcnt vmcnt(13)
	s_nop 1
	v_mov_b64_e32 v[28:29], v[180:181]
	v_mov_b64_e32 v[30:31], v[182:183]
	s_waitcnt vmcnt(12)
	s_nop 1
	v_mov_b64_e32 v[100:101], v[176:177]
	v_mov_b64_e32 v[102:103], v[178:179]
	ds_read2_b32 v[108:109], v86 offset1:1
	ds_read2_b32 v[110:111], v87 offset1:1
	ds_read2_b32 v[112:113], v88 offset1:1
	ds_read2_b32 v[114:115], v89 offset1:1
	ds_read2_b32 v[116:117], v90 offset1:1
	ds_read2_b32 v[118:119], v91 offset1:1
	ds_read2_b32 v[120:121], v92 offset1:1
	ds_read2_b32 v[122:123], v93 offset1:1
	v_or_b32_e32 v14, s14, v38
	v_lshlrev_b32_e32 v16, 10, v14
	v_lshl_add_u64 v[14:15], v[16:17], 2, v[26:27]
	v_or_b32_e32 v16, s14, v39
	v_lshlrev_b32_e32 v16, 10, v16
	s_waitcnt lgkmcnt(6)
	v_pk_fma_f32 v[10:11], v[2:3], v[110:111], v[10:11]
	v_pk_fma_f32 v[8:9], v[0:1], v[108:109], v[8:9]
	s_waitcnt lgkmcnt(4)
	v_pk_fma_f32 v[30:31], v[2:3], v[114:115], v[30:31]
	v_pk_fma_f32 v[28:29], v[0:1], v[112:113], v[28:29]
	s_waitcnt lgkmcnt(2)
	v_pk_fma_f32 v[102:103], v[2:3], v[118:119], v[102:103]
	v_pk_fma_f32 v[100:101], v[0:1], v[116:117], v[100:101]
	global_store_dwordx4 v[32:33], v[8:11], off
	global_store_dwordx4 v[104:105], v[28:31], off
	global_store_dwordx4 v[106:107], v[100:103], off
	s_waitcnt vmcnt(14)
	s_nop 1
	v_mov_b64_e32 v[8:9], v[172:173]
	v_mov_b64_e32 v[10:11], v[174:175]
	v_or_b32_e32 v28, s14, v40
	v_or_b32_e32 v29, s14, v41
	v_lshl_add_u64 v[32:33], v[16:17], 2, v[26:27]
	v_lshlrev_b32_e32 v16, 10, v28
	v_lshl_add_u64 v[108:109], v[16:17], 2, v[26:27]
	v_lshlrev_b32_e32 v16, 10, v29
	v_lshl_add_u64 v[110:111], v[16:17], 2, v[26:27]
	s_bitset1_b32 s14, 7
	s_add_u32 s13, s2, s13
	s_addc_u32 s15, s3, s12
	s_add_u32 s12, s13, s4
	s_addc_u32 s13, s15, 0
	s_add_i32 s6, s6, s77
	s_cmpk_lt_u32 s6, 0x60
	s_waitcnt lgkmcnt(0)
	v_pk_fma_f32 v[10:11], v[2:3], v[122:123], v[10:11]
	v_pk_fma_f32 v[8:9], v[0:1], v[120:121], v[8:9]
	global_store_dwordx4 v[14:15], v[8:11], off
	s_waitcnt vmcnt(14)
	s_nop 1
	v_mov_b64_e32 v[28:29], v[168:169]
	v_mov_b64_e32 v[30:31], v[170:171]
	s_waitcnt vmcnt(13)
	s_nop 1
	v_mov_b64_e32 v[100:101], v[164:165]
	v_mov_b64_e32 v[102:103], v[166:167]
	s_waitcnt vmcnt(12)
	s_nop 1
	v_mov_b64_e32 v[104:105], v[160:161]
	v_mov_b64_e32 v[106:107], v[162:163]
	v_or_b32_e32 v10, s14, v135
	v_lshl_add_u64 v[8:9], s[12:13], 0, v[24:25]
	v_or_b32_e32 v11, s14, v139
	v_add_co_u32_e32 v112, vcc, s11, v8
	v_lshlrev_b32_e32 v16, 10, v10
	v_or_b32_e32 v14, s14, v204
	v_addc_co_u32_e32 v113, vcc, 0, v9, vcc
	v_lshl_add_u64 v[8:9], v[16:17], 2, v[26:27]
	v_lshlrev_b32_e32 v16, 10, v11
	v_or_b32_e32 v15, s14, v205
	v_lshl_add_u64 v[114:115], v[16:17], 2, v[26:27]
	v_lshlrev_b32_e32 v16, 10, v14
	v_lshl_add_u64 v[116:117], v[16:17], 2, v[26:27]
	v_lshlrev_b32_e32 v16, 10, v15
	ds_read2_b32 v[120:121], v34 offset1:1
	ds_read2_b32 v[122:123], v34 offset0:2 offset1:3
	ds_read2_b32 v[124:125], v94 offset1:1
	ds_read2_b32 v[126:127], v95 offset1:1
	ds_read2_b32 v[128:129], v96 offset1:1
	ds_read2_b32 v[130:131], v97 offset1:1
	ds_read2_b32 v[132:133], v98 offset1:1
	ds_read2_b32 v[136:137], v99 offset1:1
	ds_read2_b32 v[10:11], v42 offset1:1
	ds_read2_b32 v[14:15], v42 offset0:2 offset1:3
	s_waitcnt lgkmcnt(8)
	v_pk_fma_f32 v[6:7], v[2:3], v[122:123], v[6:7]
	v_pk_fma_f32 v[4:5], v[0:1], v[120:121], v[4:5]
	global_store_dwordx4 v[12:13], v[4:7], off
	v_lshl_add_u64 v[118:119], v[16:17], 2, v[26:27]
	v_or_b32_e32 v12, s14, v206
	v_lshlrev_b32_e32 v16, 10, v12
	v_lshl_add_u64 v[12:13], v[16:17], 2, v[26:27]
	v_or_b32_e32 v16, s14, v207
	v_lshlrev_b32_e32 v16, 10, v16
	s_waitcnt lgkmcnt(6)
	v_pk_fma_f32 v[6:7], v[2:3], v[126:127], v[30:31]
	v_pk_fma_f32 v[4:5], v[0:1], v[124:125], v[28:29]
	s_waitcnt lgkmcnt(4)
	v_pk_fma_f32 v[30:31], v[2:3], v[130:131], v[102:103]
	v_pk_fma_f32 v[28:29], v[0:1], v[128:129], v[100:101]
	s_waitcnt lgkmcnt(2)
	v_pk_fma_f32 v[2:3], v[2:3], v[136:137], v[106:107]
	v_pk_fma_f32 v[0:1], v[0:1], v[132:133], v[104:105]
	global_store_dwordx4 v[32:33], v[4:7], off
	global_store_dwordx4 v[108:109], v[28:31], off
	global_store_dwordx4 v[110:111], v[0:3], off
	v_mov_b32_e32 v128, v12
	v_mov_b32_e32 v129, v13
	v_mov_b32_e32 v130, v16
	v_mov_b32_e32 v131, v17
	v_mov_b32_e32 v132, v26
	v_mov_b32_e32 v133, v27
	v_mov_b32_e32 v136, v32
	v_mov_b32_e32 v137, v33
	v_mov_b32_e32 v144, v100
	v_mov_b32_e32 v145, v101
	v_mov_b32_e32 v146, v108
	v_mov_b32_e32 v147, v109
	v_mov_b32_e32 v148, v110
	v_mov_b32_e32 v149, v111
	global_load_dwordx4 v[250:253], v[112:113], off
	global_load_dwordx4 v[246:249], v[114:115], off
	global_load_dwordx4 v[242:245], v[116:117], off
	global_load_dwordx4 v[238:241], v[118:119], off
	global_load_dwordx4 v[234:237], v[8:9], off
	global_load_dwordx4 v[212:215], v[128:129], off
	v_or_b32_e32 v144, s14, v208
	v_or_b32_e32 v145, s14, v209
	v_lshl_add_u64 v[136:137], v[130:131], 2, v[132:133]
	v_lshlrev_b32_e32 v130, 10, v144
	v_lshl_add_u64 v[146:147], v[130:131], 2, v[132:133]
	v_lshlrev_b32_e32 v130, 10, v145
	v_lshl_add_u64 v[148:149], v[130:131], 2, v[132:133]
	global_load_dwordx4 v[200:203], v[136:137], off
	global_load_dwordx4 v[196:199], v[146:147], off
	global_load_dwordx4 v[192:195], v[148:149], off
	v_or_b32_e32 v128, s14, v210
	v_lshlrev_b32_e32 v130, 10, v128
	v_lshl_add_u64 v[128:129], v[130:131], 2, v[132:133]
	v_or_b32_e32 v130, s14, v35
	v_lshlrev_b32_e32 v130, 10, v130
	global_load_dwordx4 v[188:191], v[128:129], off
	v_or_b32_e32 v144, s14, v36
	v_or_b32_e32 v145, s14, v37
	v_lshl_add_u64 v[136:137], v[130:131], 2, v[132:133]
	v_lshlrev_b32_e32 v130, 10, v144
	v_lshl_add_u64 v[146:147], v[130:131], 2, v[132:133]
	v_lshlrev_b32_e32 v130, 10, v145
	v_lshl_add_u64 v[148:149], v[130:131], 2, v[132:133]
	global_load_dwordx4 v[184:187], v[136:137], off
	global_load_dwordx4 v[180:183], v[146:147], off
	global_load_dwordx4 v[176:179], v[148:149], off
	v_or_b32_e32 v128, s14, v38
	v_lshlrev_b32_e32 v130, 10, v128
	v_lshl_add_u64 v[128:129], v[130:131], 2, v[132:133]
	v_add_lshl_u32 v130, s14, v39, 10
	global_load_dwordx4 v[172:175], v[128:129], off
	v_lshl_add_u64 v[136:137], v[130:131], 2, v[132:133]
	v_add_lshl_u32 v130, s14, v40, 10
	v_lshl_add_u64 v[144:145], v[130:131], 2, v[132:133]
	v_add_lshl_u32 v130, s14, v41, 10
	v_lshl_add_u64 v[132:133], v[130:131], 2, v[132:133]
	global_load_dwordx4 v[168:171], v[136:137], off
	global_load_dwordx4 v[164:167], v[144:145], off
	global_load_dwordx4 v[160:163], v[132:133], off
	s_waitcnt vmcnt(16)
	s_nop 1
	v_mov_b64_e32 v[0:1], v[250:251]
	v_mov_b64_e32 v[2:3], v[252:253]
	s_nop 0
	s_waitcnt vmcnt(15)
	s_nop 1
	v_mov_b64_e32 v[28:29], v[246:247]
	v_mov_b64_e32 v[30:31], v[248:249]
	s_waitcnt vmcnt(14)
	s_nop 1
	v_mov_b64_e32 v[100:101], v[242:243]
	v_mov_b64_e32 v[102:103], v[244:245]
	s_waitcnt vmcnt(13)
	s_nop 1
	v_mov_b64_e32 v[104:105], v[238:239]
	v_mov_b64_e32 v[106:107], v[240:241]
	s_waitcnt vmcnt(12)
	s_nop 1
	v_mov_b64_e32 v[4:5], v[234:235]
	v_mov_b64_e32 v[6:7], v[236:237]
	ds_read2_b32 v[32:33], v43 offset1:1
	ds_read2_b32 v[108:109], v43 offset0:2 offset1:3
	ds_read2_b32 v[110:111], v44 offset1:1
	ds_read2_b32 v[112:113], v44 offset0:2 offset1:3
	ds_read2_b32 v[120:121], v45 offset1:1
	ds_read2_b32 v[122:123], v45 offset0:2 offset1:3
	ds_read2_b32 v[124:125], v46 offset1:1
	ds_read2_b32 v[126:127], v46 offset0:2 offset1:3
	s_waitcnt lgkmcnt(6)
	v_pk_fma_f32 v[30:31], v[2:3], v[108:109], v[30:31]
	v_pk_fma_f32 v[28:29], v[0:1], v[32:33], v[28:29]
	s_waitcnt lgkmcnt(4)
	v_pk_fma_f32 v[102:103], v[2:3], v[112:113], v[102:103]
	v_pk_fma_f32 v[100:101], v[0:1], v[110:111], v[100:101]
	s_waitcnt lgkmcnt(2)
	v_pk_fma_f32 v[106:107], v[2:3], v[122:123], v[106:107]
	v_pk_fma_f32 v[104:105], v[0:1], v[120:121], v[104:105]
	global_store_dwordx4 v[114:115], v[28:31], off
	global_store_dwordx4 v[116:117], v[100:103], off
	global_store_dwordx4 v[118:119], v[104:107], off
	s_waitcnt vmcnt(14)
	s_nop 1
	v_mov_b64_e32 v[28:29], v[212:213]
	v_mov_b64_e32 v[30:31], v[214:215]
	v_or_b32_e32 v100, s14, v208
	v_or_b32_e32 v101, s14, v209
	v_lshl_add_u64 v[32:33], v[16:17], 2, v[26:27]
	v_lshlrev_b32_e32 v16, 10, v100
	v_lshl_add_u64 v[108:109], v[16:17], 2, v[26:27]
	v_lshlrev_b32_e32 v16, 10, v101
	v_lshl_add_u64 v[110:111], v[16:17], 2, v[26:27]
	v_pk_fma_f32 v[6:7], v[2:3], v[14:15], v[6:7]
	v_pk_fma_f32 v[4:5], v[0:1], v[10:11], v[4:5]
	s_waitcnt lgkmcnt(0)
	v_pk_fma_f32 v[30:31], v[2:3], v[126:127], v[30:31]
	v_pk_fma_f32 v[28:29], v[0:1], v[124:125], v[28:29]
	global_store_dwordx4 v[12:13], v[28:31], off
	s_waitcnt vmcnt(14)
	s_nop 1
	v_mov_b64_e32 v[28:29], v[200:201]
	v_mov_b64_e32 v[30:31], v[202:203]
	s_nop 0
	s_waitcnt vmcnt(13)
	s_nop 1
	v_mov_b64_e32 v[100:101], v[196:197]
	v_mov_b64_e32 v[102:103], v[198:199]
	s_waitcnt vmcnt(12)
	s_nop 1
	v_mov_b64_e32 v[104:105], v[192:193]
	v_mov_b64_e32 v[106:107], v[194:195]
	ds_read2_b32 v[112:113], v47 offset1:1
	ds_read2_b32 v[114:115], v47 offset0:2 offset1:3
	ds_read2_b32 v[116:117], v48 offset1:1
	ds_read2_b32 v[118:119], v48 offset0:2 offset1:3
	ds_read2_b32 v[120:121], v49 offset1:1
	ds_read2_b32 v[122:123], v49 offset0:2 offset1:3
	ds_read2_b32 v[124:125], v50 offset1:1
	ds_read2_b32 v[126:127], v50 offset0:2 offset1:3
	v_or_b32_e32 v12, s14, v210
	v_lshlrev_b32_e32 v16, 10, v12
	v_lshl_add_u64 v[12:13], v[16:17], 2, v[26:27]
	v_or_b32_e32 v16, s14, v35
	v_lshlrev_b32_e32 v16, 10, v16
	s_waitcnt lgkmcnt(6)
	v_pk_fma_f32 v[30:31], v[2:3], v[114:115], v[30:31]
	v_pk_fma_f32 v[28:29], v[0:1], v[112:113], v[28:29]
	s_waitcnt lgkmcnt(4)
	v_pk_fma_f32 v[102:103], v[2:3], v[118:119], v[102:103]
	v_pk_fma_f32 v[100:101], v[0:1], v[116:117], v[100:101]
	s_waitcnt lgkmcnt(2)
	v_pk_fma_f32 v[106:107], v[2:3], v[122:123], v[106:107]
	v_pk_fma_f32 v[104:105], v[0:1], v[120:121], v[104:105]
	global_store_dwordx4 v[32:33], v[28:31], off
	global_store_dwordx4 v[108:109], v[100:103], off
	global_store_dwordx4 v[110:111], v[104:107], off
	s_waitcnt vmcnt(14)
	s_nop 1
	v_mov_b64_e32 v[28:29], v[188:189]
	v_mov_b64_e32 v[30:31], v[190:191]
	v_or_b32_e32 v100, s14, v36
	v_or_b32_e32 v101, s14, v37
	v_lshl_add_u64 v[32:33], v[16:17], 2, v[26:27]
	v_lshlrev_b32_e32 v16, 10, v100
	v_lshl_add_u64 v[108:109], v[16:17], 2, v[26:27]
	v_lshlrev_b32_e32 v16, 10, v101
	v_lshl_add_u64 v[110:111], v[16:17], 2, v[26:27]
	s_waitcnt lgkmcnt(0)
	v_pk_fma_f32 v[30:31], v[2:3], v[126:127], v[30:31]
	v_pk_fma_f32 v[28:29], v[0:1], v[124:125], v[28:29]
	global_store_dwordx4 v[12:13], v[28:31], off
	s_waitcnt vmcnt(14)
	s_nop 1
	v_mov_b64_e32 v[28:29], v[184:185]
	v_mov_b64_e32 v[30:31], v[186:187]
	s_nop 0
	s_waitcnt vmcnt(13)
	s_nop 1
	v_mov_b64_e32 v[100:101], v[180:181]
	v_mov_b64_e32 v[102:103], v[182:183]
	s_waitcnt vmcnt(12)
	s_nop 1
	v_mov_b64_e32 v[104:105], v[176:177]
	v_mov_b64_e32 v[106:107], v[178:179]
	ds_read2_b32 v[112:113], v51 offset1:1
	ds_read2_b32 v[114:115], v51 offset0:2 offset1:3
	ds_read2_b32 v[116:117], v52 offset1:1
	ds_read2_b32 v[118:119], v52 offset0:2 offset1:3
	ds_read2_b32 v[120:121], v53 offset1:1
	ds_read2_b32 v[122:123], v53 offset0:2 offset1:3
	ds_read2_b32 v[124:125], v54 offset1:1
	ds_read2_b32 v[126:127], v54 offset0:2 offset1:3
	v_or_b32_e32 v12, s14, v38
	v_lshlrev_b32_e32 v16, 10, v12
	v_lshl_add_u64 v[12:13], v[16:17], 2, v[26:27]
	v_add_lshl_u32 v16, s14, v39, 10
	s_waitcnt lgkmcnt(6)
	v_pk_fma_f32 v[30:31], v[2:3], v[114:115], v[30:31]
	v_pk_fma_f32 v[28:29], v[0:1], v[112:113], v[28:29]
	s_waitcnt lgkmcnt(4)
	v_pk_fma_f32 v[102:103], v[2:3], v[118:119], v[102:103]
	v_pk_fma_f32 v[100:101], v[0:1], v[116:117], v[100:101]
	s_waitcnt lgkmcnt(2)
	v_pk_fma_f32 v[106:107], v[2:3], v[122:123], v[106:107]
	v_pk_fma_f32 v[104:105], v[0:1], v[120:121], v[104:105]
	global_store_dwordx4 v[32:33], v[28:31], off
	global_store_dwordx4 v[108:109], v[100:103], off
	global_store_dwordx4 v[110:111], v[104:107], off
	s_waitcnt vmcnt(14)
	s_nop 1
	v_mov_b64_e32 v[28:29], v[172:173]
	v_mov_b64_e32 v[30:31], v[174:175]
	v_lshl_add_u64 v[32:33], v[16:17], 2, v[26:27]
	v_add_lshl_u32 v16, s14, v40, 10
	global_store_dwordx4 v[8:9], v[4:7], off
	v_lshl_add_u64 v[100:101], v[16:17], 2, v[26:27]
	v_add_lshl_u32 v16, s14, v41, 10
	v_lshl_add_u64 v[26:27], v[16:17], 2, v[26:27]
	s_waitcnt lgkmcnt(0)
	v_pk_fma_f32 v[6:7], v[2:3], v[126:127], v[30:31]
	v_pk_fma_f32 v[4:5], v[0:1], v[124:125], v[28:29]
	global_store_dwordx4 v[12:13], v[4:7], off
	s_waitcnt vmcnt(15)
	s_nop 1
	v_mov_b64_e32 v[4:5], v[168:169]
	v_mov_b64_e32 v[6:7], v[170:171]
	s_nop 0
	s_waitcnt vmcnt(14)
	s_nop 1
	v_mov_b64_e32 v[8:9], v[164:165]
	v_mov_b64_e32 v[10:11], v[166:167]
	s_waitcnt vmcnt(13)
	s_nop 1
	v_mov_b64_e32 v[12:13], v[160:161]
	v_mov_b64_e32 v[14:15], v[162:163]
	ds_read2_b32 v[28:29], v55 offset1:1
	ds_read2_b32 v[30:31], v55 offset0:2 offset1:3
	ds_read2_b32 v[102:103], v56 offset1:1
	ds_read2_b32 v[104:105], v56 offset0:2 offset1:3
	ds_read2_b32 v[106:107], v57 offset1:1
	ds_read2_b32 v[108:109], v57 offset0:2 offset1:3
	s_waitcnt lgkmcnt(4)
	v_pk_fma_f32 v[6:7], v[2:3], v[30:31], v[6:7]
	v_pk_fma_f32 v[4:5], v[0:1], v[28:29], v[4:5]
	s_waitcnt lgkmcnt(2)
	v_pk_fma_f32 v[10:11], v[2:3], v[104:105], v[10:11]
	v_pk_fma_f32 v[8:9], v[0:1], v[102:103], v[8:9]
	s_waitcnt lgkmcnt(0)
	v_pk_fma_f32 v[2:3], v[2:3], v[108:109], v[14:15]
	v_pk_fma_f32 v[0:1], v[0:1], v[106:107], v[12:13]
	global_store_dwordx4 v[32:33], v[4:7], off
	global_store_dwordx4 v[100:101], v[8:11], off
	global_store_dwordx4 v[26:27], v[0:3], off
	s_barrier
	s_cbranch_scc1 .LBB0_1145
	s_load_dwordx2 s[2:3], s[0:1], 0x130

.LBB0_1844:
	s_lshr_b32 s13, s6, 3
	s_add_i32 s13, s13, s7
	s_lshl_b32 s4, s13, 19
	v_lshl_add_u64 v[0:1], v[18:19], 0, s[4:5]
	v_add_co_u32_e32 v4, vcc, 0x10000, v0
	s_and_b32 s12, s6, 7
	s_nop 0
	v_addc_co_u32_e32 v5, vcc, 0, v1, vcc
	v_add_co_u32_e32 v6, vcc, 0x20000, v0
	s_lshl_b32 s4, s12, 18
	s_nop 0
	v_addc_co_u32_e32 v7, vcc, 0, v1, vcc
	v_add_co_u32_e32 v8, vcc, 0x30000, v0
	v_lshl_add_u64 v[2:3], v[20:21], 0, s[4:5]
	s_nop 0
	v_addc_co_u32_e32 v9, vcc, 0, v1, vcc
	v_add_co_u32_e32 v10, vcc, 0x40000, v0
	global_load_dwordx4 v[100:103], v[0:1], off
	global_load_dwordx4 v[104:107], v[0:1], off offset:128
	v_addc_co_u32_e32 v11, vcc, 0, v1, vcc
	v_add_co_u32_e32 v12, vcc, 0x50000, v0
	global_load_dwordx4 v[108:111], v[2:3], off
	global_load_dwordx4 v[112:115], v[2:3], off offset:128
	v_addc_co_u32_e32 v13, vcc, 0, v1, vcc
	v_add_co_u32_e32 v14, vcc, 0x60000, v0
	global_load_dwordx4 v[116:119], v[4:5], off
	global_load_dwordx4 v[120:123], v[4:5], off offset:128
	v_addc_co_u32_e32 v15, vcc, 0, v1, vcc
	v_add_co_u32_e32 v26, vcc, 0x70000, v0
	global_load_dwordx4 v[124:127], v[6:7], off
	global_load_dwordx4 v[128:131], v[6:7], off offset:128
	v_addc_co_u32_e32 v27, vcc, 0, v1, vcc
	v_add_co_u32_e32 v28, vcc, s8, v2
	global_load_dwordx4 v[140:143], v[8:9], off
	global_load_dwordx4 v[144:147], v[8:9], off offset:128
	v_addc_co_u32_e32 v29, vcc, 0, v3, vcc
	s_waitcnt vmcnt(14)
	v_add_co_u32_e32 v30, vcc, s9, v2
	global_load_dwordx4 v[148:151], v[10:11], off
	global_load_dwordx4 v[152:155], v[10:11], off offset:128
	v_addc_co_u32_e32 v31, vcc, 0, v3, vcc
	v_add_co_u32_e32 v32, vcc, s10, v2
	global_load_dwordx4 v[156:159], v[12:13], off
	global_load_dwordx4 v[160:163], v[12:13], off offset:128
	global_load_dwordx4 v[164:167], v[14:15], off
	global_load_dwordx4 v[168:171], v[14:15], off offset:128
	global_load_dwordx4 v[172:175], v[26:27], off
	global_load_dwordx4 v[176:179], v[26:27], off offset:128
	global_load_dwordx4 v[180:183], v[28:29], off
	global_load_dwordx4 v[184:187], v[28:29], off offset:128
	v_addc_co_u32_e32 v33, vcc, 0, v3, vcc
	global_load_dwordx4 v[188:191], v[30:31], off
	global_load_dwordx4 v[192:195], v[30:31], off offset:128
	global_load_dwordx4 v[196:199], v[32:33], off
	global_load_dwordx4 v[200:203], v[32:33], off offset:128
	s_lshl_b32 s14, s13, 8
	s_add_i32 s4, s14, 0xffffe000
	s_add_i32 s15, s14, 0xffffe080
	s_lshr_b32 s4, s4, 12
	s_lshr_b32 s15, s15, 12
	s_add_i32 s4, s4, 11
	s_add_i32 s15, s15, 11
	s_cmp_lt_u32 s13, 32
	s_cselect_b32 s4, 10, s4
	s_cselect_b32 s13, 10, s15
	s_mul_hi_u32 s15, s4, 0x6000
	s_mulk_i32 s4, 0x6000
	s_add_u32 s16, s2, s4
	s_addc_u32 s15, s3, s15
	s_lshl_b32 s4, s12, 9
	v_or_b32_e32 v16, s14, v135
	s_add_u32 s16, s16, s4
	v_lshlrev_b32_e32 v16, 10, v16
	s_addc_u32 s17, s15, 0
	s_mul_hi_u32 s12, s13, 0x6000
	s_mulk_i32 s13, 0x6000
	s_waitcnt vmcnt(23)
	ds_write_b128 v60, v[100:103]
	s_waitcnt vmcnt(21)
	ds_write_b128 v60, v[108:111] offset:36864
	s_waitcnt vmcnt(19)
	ds_write_b128 v60, v[116:119] offset:4608
	s_waitcnt vmcnt(17)
	ds_write_b128 v60, v[124:127] offset:9216
	s_waitcnt vmcnt(15)
	ds_write_b128 v60, v[140:143] offset:13824
	s_waitcnt vmcnt(13)
	ds_write_b128 v60, v[148:151] offset:18432
	s_waitcnt vmcnt(11)
	ds_write_b128 v60, v[156:159] offset:23040
	s_waitcnt vmcnt(9)
	ds_write_b128 v60, v[164:167] offset:27648
	s_waitcnt vmcnt(7)
	ds_write_b128 v60, v[172:175] offset:32256
	s_waitcnt vmcnt(5)
	ds_write_b128 v60, v[180:183] offset:41472
	s_waitcnt vmcnt(3)
	ds_write_b128 v60, v[188:191] offset:46080
	s_waitcnt vmcnt(1)
	ds_write_b128 v60, v[196:199] offset:50688
	s_waitcnt lgkmcnt(0)
	s_barrier
	ds_read_b128 v[100:103], v59
	ds_read_b128 v[108:111], v62 offset:36864
	ds_read_b128 v[116:119], v59 offset:4608
	ds_read_b128 v[124:127], v62 offset:41472
	s_waitcnt lgkmcnt(2)
	v_mfma_f32_32x32x16_bf16 a[112:127], v[100:103], v[108:111], 0
	s_waitcnt lgkmcnt(0)
	v_mfma_f32_32x32x16_bf16 a[96:111], v[100:103], v[124:127], 0
	ds_read_b128 v[100:103], v59 offset:9216
	s_waitcnt lgkmcnt(0)
	v_mfma_f32_32x32x16_bf16 a[48:63], v[100:103], v[108:111], 0
	v_mfma_f32_32x32x16_bf16 a[32:47], v[100:103], v[124:127], 0
	ds_read_b128 v[100:103], v61
	ds_write_b128 v60, v[104:107] offset:55296
	ds_write_b128 v60, v[120:123] offset:59904
	ds_write_b128 v60, v[128:131] offset:64512
	ds_write_b128 v63, v[144:147] offset:55296
	ds_write_b128 v64, v[152:155] offset:55296
	ds_write_b128 v65, v[160:163] offset:55296
	ds_write_b128 v66, v[168:171] offset:55296
	ds_write_b128 v67, v[176:179] offset:55296
	ds_write_b128 v68, v[112:115]
	ds_write_b128 v68, v[184:187] offset:4608
	ds_write_b128 v68, v[192:195] offset:9216
	s_waitcnt vmcnt(0)
	ds_write_b128 v68, v[200:203] offset:13824
	v_mfma_f32_32x32x16_bf16 a[80:95], v[116:119], v[108:111], 0
	v_mfma_f32_32x32x16_bf16 a[64:79], v[116:119], v[124:127], 0
	s_waitcnt lgkmcnt(12)
	v_mfma_f32_32x32x16_bf16 a[16:31], v[100:103], v[108:111], 0
	v_mfma_f32_32x32x16_bf16 a[0:15], v[100:103], v[124:127], 0
	ds_read_b128 v[100:103], v59 offset:32
	ds_read_b128 v[104:107], v62 offset:36896
	ds_read_b128 v[108:111], v62 offset:36928
	ds_read_b128 v[112:115], v59 offset:64
	ds_read_b128 v[116:119], v62 offset:41504
	ds_read_b128 v[120:123], v62 offset:36960
	s_waitcnt lgkmcnt(4)
	v_mfma_f32_32x32x16_bf16 a[112:127], v[100:103], v[104:107], a[112:127]
	s_waitcnt lgkmcnt(1)
	v_mfma_f32_32x32x16_bf16 a[96:111], v[100:103], v[116:119], a[96:111]
	ds_read_b128 v[100:103], v59 offset:4640
	ds_read_b128 v[124:127], v59 offset:96
	s_waitcnt lgkmcnt(1)
	v_mfma_f32_32x32x16_bf16 a[80:95], v[100:103], v[104:107], a[80:95]
	v_mfma_f32_32x32x16_bf16 a[64:79], v[100:103], v[116:119], a[64:79]
	ds_read_b128 v[100:103], v59 offset:9248
	ds_read_b128 v[128:131], v59 offset:9280
	s_waitcnt lgkmcnt(1)
	v_mfma_f32_32x32x16_bf16 a[48:63], v[100:103], v[104:107], a[48:63]
	v_mfma_f32_32x32x16_bf16 a[32:47], v[100:103], v[116:119], a[32:47]
	ds_read_b128 v[100:103], v61 offset:32
	ds_read_b128 v[140:143], v59 offset:9312
	s_waitcnt lgkmcnt(1)
	v_mfma_f32_32x32x16_bf16 a[16:31], v[100:103], v[104:107], a[16:31]
	v_mfma_f32_32x32x16_bf16 a[0:15], v[100:103], v[116:119], a[0:15]
	ds_read_b128 v[100:103], v62 offset:41536
	ds_read_b128 v[104:107], v62 offset:41568
	v_mfma_f32_32x32x16_bf16 a[112:127], v[112:115], v[108:111], a[112:127]
	s_waitcnt lgkmcnt(1)
	v_mfma_f32_32x32x16_bf16 a[96:111], v[112:115], v[100:103], a[96:111]
	ds_read_b128 v[112:115], v59 offset:4672
	ds_read_b128 v[116:119], v59 offset:4704
	s_waitcnt lgkmcnt(1)
	v_mfma_f32_32x32x16_bf16 a[80:95], v[112:115], v[108:111], a[80:95]
	v_mfma_f32_32x32x16_bf16 a[64:79], v[112:115], v[100:103], a[64:79]
	v_mfma_f32_32x32x16_bf16 a[48:63], v[128:131], v[108:111], a[48:63]
	v_mfma_f32_32x32x16_bf16 a[32:47], v[128:131], v[100:103], a[32:47]
	ds_read_b128 v[112:115], v61 offset:64
	ds_read_b128 v[128:131], v61 offset:96
	s_waitcnt lgkmcnt(1)
	v_mfma_f32_32x32x16_bf16 a[16:31], v[112:115], v[108:111], a[16:31]
	v_mfma_f32_32x32x16_bf16 a[0:15], v[112:115], v[100:103], a[0:15]
	global_load_dwordx4 v[100:103], v[32:33], off offset:256
	v_mfma_f32_32x32x16_bf16 a[112:127], v[124:127], v[120:123], a[112:127]
	v_mfma_f32_32x32x16_bf16 a[96:111], v[124:127], v[104:107], a[96:111]
	v_mfma_f32_32x32x16_bf16 a[80:95], v[116:119], v[120:123], a[80:95]
	v_mfma_f32_32x32x16_bf16 a[64:79], v[116:119], v[104:107], a[64:79]
	v_mfma_f32_32x32x16_bf16 a[48:63], v[140:143], v[120:123], a[48:63]
	v_mfma_f32_32x32x16_bf16 a[32:47], v[140:143], v[104:107], a[32:47]
	global_load_dwordx4 v[108:111], v[30:31], off offset:256
	global_load_dwordx4 v[112:115], v[28:29], off offset:256
	global_load_dwordx4 v[116:119], v[2:3], off offset:256
	global_load_dwordx4 v[124:127], v[8:9], off offset:256
	global_load_dwordx4 v[140:143], v[6:7], off offset:256
	global_load_dwordx4 v[144:147], v[4:5], off offset:256
	global_load_dwordx4 v[148:151], v[0:1], off offset:256
	s_waitcnt lgkmcnt(0)
	v_mfma_f32_32x32x16_bf16 a[16:31], v[128:131], v[120:123], a[16:31]
	global_load_dwordx4 v[120:123], v[12:13], off offset:256
	global_load_dwordx4 v[152:155], v[10:11], off offset:256
	global_load_dwordx4 v[156:159], v[26:27], off offset:256
	global_load_dwordx4 v[160:163], v[14:15], off offset:256
	s_barrier
	v_mfma_f32_32x32x16_bf16 a[0:15], v[128:131], v[104:107], a[0:15]
	ds_read_b128 v[104:107], v59 offset:55296
	ds_read_b128 v[128:131], v69
	ds_read_b128 v[164:167], v59 offset:59904
	ds_read_b128 v[168:171], v69 offset:4608
	s_waitcnt lgkmcnt(2)
	v_mfma_f32_32x32x16_bf16 a[112:127], v[104:107], v[128:131], a[112:127]
	s_waitcnt lgkmcnt(0)
	v_mfma_f32_32x32x16_bf16 a[96:111], v[104:107], v[168:171], a[96:111]
	ds_read_b128 v[104:107], v59 offset:64512
	s_waitcnt lgkmcnt(0)
	v_mfma_f32_32x32x16_bf16 a[48:63], v[104:107], v[128:131], a[48:63]
	v_mfma_f32_32x32x16_bf16 a[32:47], v[104:107], v[168:171], a[32:47]
	ds_read_b128 v[104:107], v61 offset:55296
	s_waitcnt vmcnt(4)
	ds_write_b128 v60, v[148:151]
	ds_write_b128 v60, v[144:147] offset:4608
	ds_write_b128 v60, v[140:143] offset:9216
	ds_write_b128 v60, v[124:127] offset:13824
	s_waitcnt vmcnt(2)
	ds_write_b128 v60, v[152:155] offset:18432
	ds_write_b128 v60, v[120:123] offset:23040
	s_waitcnt vmcnt(0)
	ds_write_b128 v60, v[160:163] offset:27648
	ds_write_b128 v60, v[156:159] offset:32256
	ds_write_b128 v60, v[116:119] offset:36864
	ds_write_b128 v60, v[112:115] offset:41472
	ds_write_b128 v60, v[108:111] offset:46080
	ds_write_b128 v60, v[100:103] offset:50688
	v_mfma_f32_32x32x16_bf16 a[80:95], v[164:167], v[128:131], a[80:95]
	v_mfma_f32_32x32x16_bf16 a[64:79], v[164:167], v[168:171], a[64:79]
	s_waitcnt lgkmcnt(12)
	v_mfma_f32_32x32x16_bf16 a[16:31], v[104:107], v[128:131], a[16:31]
	v_mfma_f32_32x32x16_bf16 a[0:15], v[104:107], v[168:171], a[0:15]
	ds_read_b128 v[100:103], v59 offset:55328
	ds_read_b128 v[104:107], v69 offset:32
	ds_read_b128 v[108:111], v69 offset:64
	ds_read_b128 v[112:115], v59 offset:55360
	ds_read_b128 v[116:119], v69 offset:4640
	ds_read_b128 v[120:123], v69 offset:96
	s_waitcnt lgkmcnt(4)
	v_mfma_f32_32x32x16_bf16 a[112:127], v[100:103], v[104:107], a[112:127]
	s_waitcnt lgkmcnt(1)
	v_mfma_f32_32x32x16_bf16 a[96:111], v[100:103], v[116:119], a[96:111]
	ds_read_b128 v[100:103], v59 offset:59936
	ds_read_b128 v[124:127], v59 offset:55392
	s_waitcnt lgkmcnt(1)
	v_mfma_f32_32x32x16_bf16 a[80:95], v[100:103], v[104:107], a[80:95]
	v_mfma_f32_32x32x16_bf16 a[64:79], v[100:103], v[116:119], a[64:79]
	ds_read_b128 v[100:103], v59 offset:64544
	ds_read_b128 v[128:131], v59 offset:64576
	s_waitcnt lgkmcnt(1)
	v_mfma_f32_32x32x16_bf16 a[48:63], v[100:103], v[104:107], a[48:63]
	v_mfma_f32_32x32x16_bf16 a[32:47], v[100:103], v[116:119], a[32:47]
	ds_read_b128 v[100:103], v61 offset:55328
	ds_read_b128 v[140:143], v59 offset:64608
	s_waitcnt lgkmcnt(1)
	v_mfma_f32_32x32x16_bf16 a[16:31], v[100:103], v[104:107], a[16:31]
	v_mfma_f32_32x32x16_bf16 a[0:15], v[100:103], v[116:119], a[0:15]
	ds_read_b128 v[100:103], v69 offset:4672
	ds_read_b128 v[104:107], v69 offset:4704
	v_mfma_f32_32x32x16_bf16 a[112:127], v[112:115], v[108:111], a[112:127]
	s_waitcnt lgkmcnt(1)
	v_mfma_f32_32x32x16_bf16 a[96:111], v[112:115], v[100:103], a[96:111]
	ds_read_b128 v[112:115], v59 offset:59968
	ds_read_b128 v[116:119], v59 offset:60000
	s_waitcnt lgkmcnt(1)
	v_mfma_f32_32x32x16_bf16 a[80:95], v[112:115], v[108:111], a[80:95]
	v_mfma_f32_32x32x16_bf16 a[64:79], v[112:115], v[100:103], a[64:79]
	v_mfma_f32_32x32x16_bf16 a[48:63], v[128:131], v[108:111], a[48:63]
	v_mfma_f32_32x32x16_bf16 a[32:47], v[128:131], v[100:103], a[32:47]
	ds_read_b128 v[112:115], v61 offset:55360
	ds_read_b128 v[128:131], v61 offset:55392
	s_waitcnt lgkmcnt(1)
	v_mfma_f32_32x32x16_bf16 a[16:31], v[112:115], v[108:111], a[16:31]
	v_mfma_f32_32x32x16_bf16 a[0:15], v[112:115], v[100:103], a[0:15]
	v_mfma_f32_32x32x16_bf16 a[112:127], v[124:127], v[120:123], a[112:127]
	v_mfma_f32_32x32x16_bf16 a[96:111], v[124:127], v[104:107], a[96:111]
	v_mfma_f32_32x32x16_bf16 a[80:95], v[116:119], v[120:123], a[80:95]
	v_mfma_f32_32x32x16_bf16 a[64:79], v[116:119], v[104:107], a[64:79]
	global_load_dwordx4 v[100:103], v[4:5], off offset:384
	global_load_dwordx4 v[108:111], v[0:1], off offset:384
	global_load_dwordx4 v[112:115], v[8:9], off offset:384
	global_load_dwordx4 v[116:119], v[6:7], off offset:384
	v_mfma_f32_32x32x16_bf16 a[48:63], v[140:143], v[120:123], a[48:63]
	v_mfma_f32_32x32x16_bf16 a[32:47], v[140:143], v[104:107], a[32:47]
	global_load_dwordx4 v[124:127], v[10:11], off offset:384
	global_load_dwordx4 v[140:143], v[12:13], off offset:384
	global_load_dwordx4 v[144:147], v[26:27], off offset:384
	global_load_dwordx4 v[148:151], v[14:15], off offset:384
	global_load_dwordx4 v[152:155], v[28:29], off offset:384
	global_load_dwordx4 v[156:159], v[2:3], off offset:384
	global_load_dwordx4 v[160:163], v[30:31], off offset:384
	s_waitcnt lgkmcnt(0)
	v_mfma_f32_32x32x16_bf16 a[16:31], v[128:131], v[120:123], a[16:31]
	global_load_dwordx4 v[120:123], v[32:33], off offset:384
	s_barrier
	v_mfma_f32_32x32x16_bf16 a[0:15], v[128:131], v[104:107], a[0:15]
	ds_read_b128 v[104:107], v59
	ds_read_b128 v[128:131], v62 offset:36864
	ds_read_b128 v[164:167], v59 offset:4608
	ds_read_b128 v[168:171], v62 offset:41472
	s_waitcnt lgkmcnt(2)
	v_mfma_f32_32x32x16_bf16 a[112:127], v[104:107], v[128:131], a[112:127]
	s_waitcnt lgkmcnt(0)
	v_mfma_f32_32x32x16_bf16 a[96:111], v[104:107], v[168:171], a[96:111]
	ds_read_b128 v[104:107], v59 offset:9216
	s_waitcnt lgkmcnt(0)
	v_mfma_f32_32x32x16_bf16 a[48:63], v[104:107], v[128:131], a[48:63]
	v_mfma_f32_32x32x16_bf16 a[32:47], v[104:107], v[168:171], a[32:47]
	ds_read_b128 v[104:107], v61
	s_waitcnt vmcnt(10)
	ds_write_b128 v60, v[108:111] offset:55296
	ds_write_b128 v60, v[100:103] offset:59904
	s_waitcnt vmcnt(8)
	ds_write_b128 v60, v[116:119] offset:64512
	ds_write_b128 v63, v[112:115] offset:55296
	s_waitcnt vmcnt(7)
	ds_write_b128 v64, v[124:127] offset:55296
	s_waitcnt vmcnt(6)
	ds_write_b128 v65, v[140:143] offset:55296
	s_waitcnt vmcnt(4)
	ds_write_b128 v66, v[148:151] offset:55296
	ds_write_b128 v67, v[144:147] offset:55296
	s_waitcnt vmcnt(2)
	ds_write_b128 v68, v[156:159]
	ds_write_b128 v68, v[152:155] offset:4608
	s_waitcnt vmcnt(1)
	ds_write_b128 v68, v[160:163] offset:9216
	s_waitcnt vmcnt(0)
	ds_write_b128 v68, v[120:123] offset:13824
	v_mfma_f32_32x32x16_bf16 a[80:95], v[164:167], v[128:131], a[80:95]
	v_mfma_f32_32x32x16_bf16 a[64:79], v[164:167], v[168:171], a[64:79]
	s_waitcnt lgkmcnt(12)
	v_mfma_f32_32x32x16_bf16 a[16:31], v[104:107], v[128:131], a[16:31]
	v_mfma_f32_32x32x16_bf16 a[0:15], v[104:107], v[168:171], a[0:15]
	ds_read_b128 v[100:103], v59 offset:32
	ds_read_b128 v[104:107], v62 offset:36896
	ds_read_b128 v[108:111], v62 offset:36928
	ds_read_b128 v[112:115], v59 offset:64
	ds_read_b128 v[116:119], v62 offset:41504
	ds_read_b128 v[120:123], v62 offset:36960
	s_waitcnt lgkmcnt(4)
	v_mfma_f32_32x32x16_bf16 a[112:127], v[100:103], v[104:107], a[112:127]
	s_waitcnt lgkmcnt(1)
	v_mfma_f32_32x32x16_bf16 a[96:111], v[100:103], v[116:119], a[96:111]
	ds_read_b128 v[100:103], v59 offset:4640
	ds_read_b128 v[124:127], v59 offset:96
	s_waitcnt lgkmcnt(1)
	v_mfma_f32_32x32x16_bf16 a[80:95], v[100:103], v[104:107], a[80:95]
	v_mfma_f32_32x32x16_bf16 a[64:79], v[100:103], v[116:119], a[64:79]
	ds_read_b128 v[100:103], v59 offset:9248
	ds_read_b128 v[128:131], v59 offset:9280
	s_waitcnt lgkmcnt(1)
	v_mfma_f32_32x32x16_bf16 a[48:63], v[100:103], v[104:107], a[48:63]
	v_mfma_f32_32x32x16_bf16 a[32:47], v[100:103], v[116:119], a[32:47]
	ds_read_b128 v[100:103], v61 offset:32
	ds_read_b128 v[140:143], v59 offset:9312
	s_waitcnt lgkmcnt(1)
	v_mfma_f32_32x32x16_bf16 a[16:31], v[100:103], v[104:107], a[16:31]
	v_mfma_f32_32x32x16_bf16 a[0:15], v[100:103], v[116:119], a[0:15]
	ds_read_b128 v[100:103], v62 offset:41536
	ds_read_b128 v[104:107], v62 offset:41568
	v_mfma_f32_32x32x16_bf16 a[112:127], v[112:115], v[108:111], a[112:127]
	s_waitcnt lgkmcnt(1)
	v_mfma_f32_32x32x16_bf16 a[96:111], v[112:115], v[100:103], a[96:111]
	ds_read_b128 v[112:115], v59 offset:4672
	ds_read_b128 v[116:119], v59 offset:4704
	s_waitcnt lgkmcnt(1)
	v_mfma_f32_32x32x16_bf16 a[80:95], v[112:115], v[108:111], a[80:95]
	v_mfma_f32_32x32x16_bf16 a[64:79], v[112:115], v[100:103], a[64:79]
	v_mfma_f32_32x32x16_bf16 a[48:63], v[128:131], v[108:111], a[48:63]
	v_mfma_f32_32x32x16_bf16 a[32:47], v[128:131], v[100:103], a[32:47]
	ds_read_b128 v[112:115], v61 offset:64
	ds_read_b128 v[128:131], v61 offset:96
	s_waitcnt lgkmcnt(1)
	v_mfma_f32_32x32x16_bf16 a[16:31], v[112:115], v[108:111], a[16:31]
	v_mfma_f32_32x32x16_bf16 a[0:15], v[112:115], v[100:103], a[0:15]
	global_load_dwordx4 v[100:103], v[32:33], off offset:512
	v_mfma_f32_32x32x16_bf16 a[112:127], v[124:127], v[120:123], a[112:127]
	v_mfma_f32_32x32x16_bf16 a[96:111], v[124:127], v[104:107], a[96:111]
	v_mfma_f32_32x32x16_bf16 a[80:95], v[116:119], v[120:123], a[80:95]
	v_mfma_f32_32x32x16_bf16 a[64:79], v[116:119], v[104:107], a[64:79]
	v_mfma_f32_32x32x16_bf16 a[48:63], v[140:143], v[120:123], a[48:63]
	v_mfma_f32_32x32x16_bf16 a[32:47], v[140:143], v[104:107], a[32:47]
	global_load_dwordx4 v[108:111], v[30:31], off offset:512
	global_load_dwordx4 v[112:115], v[28:29], off offset:512
	global_load_dwordx4 v[116:119], v[2:3], off offset:512
	global_load_dwordx4 v[124:127], v[8:9], off offset:512
	global_load_dwordx4 v[140:143], v[6:7], off offset:512
	global_load_dwordx4 v[144:147], v[4:5], off offset:512
	global_load_dwordx4 v[148:151], v[0:1], off offset:512
	s_waitcnt lgkmcnt(0)
	v_mfma_f32_32x32x16_bf16 a[16:31], v[128:131], v[120:123], a[16:31]
	global_load_dwordx4 v[120:123], v[12:13], off offset:512
	global_load_dwordx4 v[152:155], v[10:11], off offset:512
	global_load_dwordx4 v[156:159], v[26:27], off offset:512
	global_load_dwordx4 v[160:163], v[14:15], off offset:512
	s_barrier
	v_mfma_f32_32x32x16_bf16 a[0:15], v[128:131], v[104:107], a[0:15]
	ds_read_b128 v[104:107], v59 offset:55296
	ds_read_b128 v[128:131], v69
	ds_read_b128 v[164:167], v59 offset:59904
	ds_read_b128 v[168:171], v69 offset:4608
	s_waitcnt lgkmcnt(2)
	v_mfma_f32_32x32x16_bf16 a[112:127], v[104:107], v[128:131], a[112:127]
	s_waitcnt lgkmcnt(0)
	v_mfma_f32_32x32x16_bf16 a[96:111], v[104:107], v[168:171], a[96:111]
	ds_read_b128 v[104:107], v59 offset:64512
	s_waitcnt lgkmcnt(0)
	v_mfma_f32_32x32x16_bf16 a[48:63], v[104:107], v[128:131], a[48:63]
	v_mfma_f32_32x32x16_bf16 a[32:47], v[104:107], v[168:171], a[32:47]
	ds_read_b128 v[104:107], v61 offset:55296
	s_waitcnt vmcnt(4)
	ds_write_b128 v60, v[148:151]
	ds_write_b128 v60, v[144:147] offset:4608
	ds_write_b128 v60, v[140:143] offset:9216
	ds_write_b128 v60, v[124:127] offset:13824
	s_waitcnt vmcnt(2)
	ds_write_b128 v60, v[152:155] offset:18432
	ds_write_b128 v60, v[120:123] offset:23040
	s_waitcnt vmcnt(0)
	ds_write_b128 v60, v[160:163] offset:27648
	ds_write_b128 v60, v[156:159] offset:32256
	ds_write_b128 v60, v[116:119] offset:36864
	ds_write_b128 v60, v[112:115] offset:41472
	ds_write_b128 v60, v[108:111] offset:46080
	ds_write_b128 v60, v[100:103] offset:50688
	v_mfma_f32_32x32x16_bf16 a[80:95], v[164:167], v[128:131], a[80:95]
	v_mfma_f32_32x32x16_bf16 a[64:79], v[164:167], v[168:171], a[64:79]
	s_waitcnt lgkmcnt(12)
	v_mfma_f32_32x32x16_bf16 a[16:31], v[104:107], v[128:131], a[16:31]
	v_mfma_f32_32x32x16_bf16 a[0:15], v[104:107], v[168:171], a[0:15]
	ds_read_b128 v[100:103], v59 offset:55328
	ds_read_b128 v[104:107], v69 offset:32
	ds_read_b128 v[108:111], v69 offset:64
	ds_read_b128 v[112:115], v59 offset:55360
	ds_read_b128 v[116:119], v69 offset:4640
	ds_read_b128 v[120:123], v69 offset:96
	s_waitcnt lgkmcnt(4)
	v_mfma_f32_32x32x16_bf16 a[112:127], v[100:103], v[104:107], a[112:127]
	s_waitcnt lgkmcnt(1)
	v_mfma_f32_32x32x16_bf16 a[96:111], v[100:103], v[116:119], a[96:111]
	ds_read_b128 v[100:103], v59 offset:59936
	ds_read_b128 v[124:127], v59 offset:55392
	s_waitcnt lgkmcnt(1)
	v_mfma_f32_32x32x16_bf16 a[80:95], v[100:103], v[104:107], a[80:95]
	v_mfma_f32_32x32x16_bf16 a[64:79], v[100:103], v[116:119], a[64:79]
	ds_read_b128 v[100:103], v59 offset:64544
	ds_read_b128 v[128:131], v59 offset:64576
	s_waitcnt lgkmcnt(1)
	v_mfma_f32_32x32x16_bf16 a[48:63], v[100:103], v[104:107], a[48:63]
	v_mfma_f32_32x32x16_bf16 a[32:47], v[100:103], v[116:119], a[32:47]
	ds_read_b128 v[100:103], v61 offset:55328
	ds_read_b128 v[140:143], v59 offset:64608
	s_waitcnt lgkmcnt(1)
	v_mfma_f32_32x32x16_bf16 a[16:31], v[100:103], v[104:107], a[16:31]
	v_mfma_f32_32x32x16_bf16 a[0:15], v[100:103], v[116:119], a[0:15]
	ds_read_b128 v[100:103], v69 offset:4672
	ds_read_b128 v[104:107], v69 offset:4704
	v_mfma_f32_32x32x16_bf16 a[112:127], v[112:115], v[108:111], a[112:127]
	s_waitcnt lgkmcnt(1)
	v_mfma_f32_32x32x16_bf16 a[96:111], v[112:115], v[100:103], a[96:111]
	ds_read_b128 v[112:115], v59 offset:59968
	ds_read_b128 v[116:119], v59 offset:60000
	s_waitcnt lgkmcnt(1)
	v_mfma_f32_32x32x16_bf16 a[80:95], v[112:115], v[108:111], a[80:95]
	v_mfma_f32_32x32x16_bf16 a[64:79], v[112:115], v[100:103], a[64:79]
	v_mfma_f32_32x32x16_bf16 a[48:63], v[128:131], v[108:111], a[48:63]
	v_mfma_f32_32x32x16_bf16 a[32:47], v[128:131], v[100:103], a[32:47]
	ds_read_b128 v[112:115], v61 offset:55360
	ds_read_b128 v[128:131], v61 offset:55392
	s_waitcnt lgkmcnt(1)
	v_mfma_f32_32x32x16_bf16 a[16:31], v[112:115], v[108:111], a[16:31]
	v_mfma_f32_32x32x16_bf16 a[0:15], v[112:115], v[100:103], a[0:15]
	v_mfma_f32_32x32x16_bf16 a[112:127], v[124:127], v[120:123], a[112:127]
	v_mfma_f32_32x32x16_bf16 a[96:111], v[124:127], v[104:107], a[96:111]
	v_mfma_f32_32x32x16_bf16 a[80:95], v[116:119], v[120:123], a[80:95]
	v_mfma_f32_32x32x16_bf16 a[64:79], v[116:119], v[104:107], a[64:79]
	global_load_dwordx4 v[100:103], v[4:5], off offset:640
	global_load_dwordx4 v[108:111], v[0:1], off offset:640
	global_load_dwordx4 v[112:115], v[8:9], off offset:640
	global_load_dwordx4 v[116:119], v[6:7], off offset:640
	v_mfma_f32_32x32x16_bf16 a[48:63], v[140:143], v[120:123], a[48:63]
	v_mfma_f32_32x32x16_bf16 a[32:47], v[140:143], v[104:107], a[32:47]
	global_load_dwordx4 v[124:127], v[10:11], off offset:640
	global_load_dwordx4 v[140:143], v[12:13], off offset:640
	global_load_dwordx4 v[144:147], v[26:27], off offset:640
	global_load_dwordx4 v[148:151], v[14:15], off offset:640
	global_load_dwordx4 v[152:155], v[28:29], off offset:640
	global_load_dwordx4 v[156:159], v[2:3], off offset:640
	global_load_dwordx4 v[160:163], v[30:31], off offset:640
	s_waitcnt lgkmcnt(0)
	v_mfma_f32_32x32x16_bf16 a[16:31], v[128:131], v[120:123], a[16:31]
	global_load_dwordx4 v[120:123], v[32:33], off offset:640
	s_barrier
	v_mfma_f32_32x32x16_bf16 a[0:15], v[128:131], v[104:107], a[0:15]
	ds_read_b128 v[104:107], v59
	ds_read_b128 v[128:131], v62 offset:36864
	ds_read_b128 v[164:167], v59 offset:4608
	ds_read_b128 v[168:171], v62 offset:41472
	s_waitcnt lgkmcnt(2)
	v_mfma_f32_32x32x16_bf16 a[112:127], v[104:107], v[128:131], a[112:127]
	s_waitcnt lgkmcnt(0)
	v_mfma_f32_32x32x16_bf16 a[96:111], v[104:107], v[168:171], a[96:111]
	ds_read_b128 v[104:107], v59 offset:9216
	s_waitcnt lgkmcnt(0)
	v_mfma_f32_32x32x16_bf16 a[48:63], v[104:107], v[128:131], a[48:63]
	v_mfma_f32_32x32x16_bf16 a[32:47], v[104:107], v[168:171], a[32:47]
	ds_read_b128 v[104:107], v61
	s_waitcnt vmcnt(10)
	ds_write_b128 v60, v[108:111] offset:55296
	ds_write_b128 v60, v[100:103] offset:59904
	s_waitcnt vmcnt(8)
	ds_write_b128 v60, v[116:119] offset:64512
	ds_write_b128 v63, v[112:115] offset:55296
	s_waitcnt vmcnt(7)
	ds_write_b128 v64, v[124:127] offset:55296
	s_waitcnt vmcnt(6)
	ds_write_b128 v65, v[140:143] offset:55296
	s_waitcnt vmcnt(4)
	ds_write_b128 v66, v[148:151] offset:55296
	ds_write_b128 v67, v[144:147] offset:55296
	s_waitcnt vmcnt(2)
	ds_write_b128 v68, v[156:159]
	ds_write_b128 v68, v[152:155] offset:4608
	s_waitcnt vmcnt(1)
	ds_write_b128 v68, v[160:163] offset:9216
	s_waitcnt vmcnt(0)
	ds_write_b128 v68, v[120:123] offset:13824
	v_mfma_f32_32x32x16_bf16 a[80:95], v[164:167], v[128:131], a[80:95]
	v_mfma_f32_32x32x16_bf16 a[64:79], v[164:167], v[168:171], a[64:79]
	s_waitcnt lgkmcnt(12)
	v_mfma_f32_32x32x16_bf16 a[16:31], v[104:107], v[128:131], a[16:31]
	v_mfma_f32_32x32x16_bf16 a[0:15], v[104:107], v[168:171], a[0:15]
	ds_read_b128 v[100:103], v59 offset:32
	ds_read_b128 v[104:107], v62 offset:36896
	ds_read_b128 v[108:111], v62 offset:36928
	ds_read_b128 v[112:115], v59 offset:64
	ds_read_b128 v[116:119], v62 offset:41504
	ds_read_b128 v[120:123], v62 offset:36960
	s_waitcnt lgkmcnt(4)
	v_mfma_f32_32x32x16_bf16 a[112:127], v[100:103], v[104:107], a[112:127]
	s_waitcnt lgkmcnt(1)
	v_mfma_f32_32x32x16_bf16 a[96:111], v[100:103], v[116:119], a[96:111]
	ds_read_b128 v[100:103], v59 offset:4640
	ds_read_b128 v[124:127], v59 offset:96
	s_waitcnt lgkmcnt(1)
	v_mfma_f32_32x32x16_bf16 a[80:95], v[100:103], v[104:107], a[80:95]
	v_mfma_f32_32x32x16_bf16 a[64:79], v[100:103], v[116:119], a[64:79]
	ds_read_b128 v[100:103], v59 offset:9248
	ds_read_b128 v[128:131], v59 offset:9280
	s_waitcnt lgkmcnt(1)
	v_mfma_f32_32x32x16_bf16 a[48:63], v[100:103], v[104:107], a[48:63]
	v_mfma_f32_32x32x16_bf16 a[32:47], v[100:103], v[116:119], a[32:47]
	ds_read_b128 v[100:103], v61 offset:32
	ds_read_b128 v[140:143], v59 offset:9312
	s_waitcnt lgkmcnt(1)
	v_mfma_f32_32x32x16_bf16 a[16:31], v[100:103], v[104:107], a[16:31]
	v_mfma_f32_32x32x16_bf16 a[0:15], v[100:103], v[116:119], a[0:15]
	ds_read_b128 v[100:103], v62 offset:41536
	ds_read_b128 v[104:107], v62 offset:41568
	v_mfma_f32_32x32x16_bf16 a[112:127], v[112:115], v[108:111], a[112:127]
	s_waitcnt lgkmcnt(1)
	v_mfma_f32_32x32x16_bf16 a[96:111], v[112:115], v[100:103], a[96:111]
	ds_read_b128 v[112:115], v59 offset:4672
	ds_read_b128 v[116:119], v59 offset:4704
	s_waitcnt lgkmcnt(1)
	v_mfma_f32_32x32x16_bf16 a[80:95], v[112:115], v[108:111], a[80:95]
	v_mfma_f32_32x32x16_bf16 a[64:79], v[112:115], v[100:103], a[64:79]
	v_mfma_f32_32x32x16_bf16 a[48:63], v[128:131], v[108:111], a[48:63]
	v_mfma_f32_32x32x16_bf16 a[32:47], v[128:131], v[100:103], a[32:47]
	ds_read_b128 v[112:115], v61 offset:64
	ds_read_b128 v[128:131], v61 offset:96
	s_waitcnt lgkmcnt(1)
	v_mfma_f32_32x32x16_bf16 a[16:31], v[112:115], v[108:111], a[16:31]
	v_mfma_f32_32x32x16_bf16 a[0:15], v[112:115], v[100:103], a[0:15]
	global_load_dwordx4 v[100:103], v[32:33], off offset:768
	v_mfma_f32_32x32x16_bf16 a[112:127], v[124:127], v[120:123], a[112:127]
	v_mfma_f32_32x32x16_bf16 a[96:111], v[124:127], v[104:107], a[96:111]
	v_mfma_f32_32x32x16_bf16 a[80:95], v[116:119], v[120:123], a[80:95]
	v_mfma_f32_32x32x16_bf16 a[64:79], v[116:119], v[104:107], a[64:79]
	v_mfma_f32_32x32x16_bf16 a[48:63], v[140:143], v[120:123], a[48:63]
	v_mfma_f32_32x32x16_bf16 a[32:47], v[140:143], v[104:107], a[32:47]
	global_load_dwordx4 v[108:111], v[30:31], off offset:768
	global_load_dwordx4 v[112:115], v[28:29], off offset:768
	global_load_dwordx4 v[116:119], v[2:3], off offset:768
	global_load_dwordx4 v[124:127], v[8:9], off offset:768
	global_load_dwordx4 v[140:143], v[6:7], off offset:768
	global_load_dwordx4 v[144:147], v[4:5], off offset:768
	global_load_dwordx4 v[148:151], v[0:1], off offset:768
	s_waitcnt lgkmcnt(0)
	v_mfma_f32_32x32x16_bf16 a[16:31], v[128:131], v[120:123], a[16:31]
	global_load_dwordx4 v[120:123], v[12:13], off offset:768
	global_load_dwordx4 v[152:155], v[10:11], off offset:768
	global_load_dwordx4 v[156:159], v[26:27], off offset:768
	global_load_dwordx4 v[160:163], v[14:15], off offset:768
	s_barrier
	v_mfma_f32_32x32x16_bf16 a[0:15], v[128:131], v[104:107], a[0:15]
	ds_read_b128 v[104:107], v59 offset:55296
	ds_read_b128 v[128:131], v69
	ds_read_b128 v[164:167], v59 offset:59904
	ds_read_b128 v[168:171], v69 offset:4608
	s_waitcnt lgkmcnt(2)
	v_mfma_f32_32x32x16_bf16 a[112:127], v[104:107], v[128:131], a[112:127]
	s_waitcnt lgkmcnt(0)
	v_mfma_f32_32x32x16_bf16 a[96:111], v[104:107], v[168:171], a[96:111]
	ds_read_b128 v[104:107], v59 offset:64512
	s_waitcnt lgkmcnt(0)
	v_mfma_f32_32x32x16_bf16 a[48:63], v[104:107], v[128:131], a[48:63]
	v_mfma_f32_32x32x16_bf16 a[32:47], v[104:107], v[168:171], a[32:47]
	ds_read_b128 v[104:107], v61 offset:55296
	s_waitcnt vmcnt(4)
	ds_write_b128 v60, v[148:151]
	ds_write_b128 v60, v[144:147] offset:4608
	ds_write_b128 v60, v[140:143] offset:9216
	ds_write_b128 v60, v[124:127] offset:13824
	s_waitcnt vmcnt(2)
	ds_write_b128 v60, v[152:155] offset:18432
	ds_write_b128 v60, v[120:123] offset:23040
	s_waitcnt vmcnt(0)
	ds_write_b128 v60, v[160:163] offset:27648
	ds_write_b128 v60, v[156:159] offset:32256
	ds_write_b128 v60, v[116:119] offset:36864
	ds_write_b128 v60, v[112:115] offset:41472
	ds_write_b128 v60, v[108:111] offset:46080
	ds_write_b128 v60, v[100:103] offset:50688
	v_mfma_f32_32x32x16_bf16 a[80:95], v[164:167], v[128:131], a[80:95]
	v_mfma_f32_32x32x16_bf16 a[64:79], v[164:167], v[168:171], a[64:79]
	s_waitcnt lgkmcnt(12)
	v_mfma_f32_32x32x16_bf16 a[16:31], v[104:107], v[128:131], a[16:31]
	v_mfma_f32_32x32x16_bf16 a[0:15], v[104:107], v[168:171], a[0:15]
	ds_read_b128 v[100:103], v59 offset:55328
	ds_read_b128 v[104:107], v69 offset:32
	ds_read_b128 v[108:111], v69 offset:64
	ds_read_b128 v[112:115], v59 offset:55360
	ds_read_b128 v[116:119], v69 offset:4640
	ds_read_b128 v[120:123], v69 offset:96
	s_waitcnt lgkmcnt(4)
	v_mfma_f32_32x32x16_bf16 a[112:127], v[100:103], v[104:107], a[112:127]
	s_waitcnt lgkmcnt(1)
	v_mfma_f32_32x32x16_bf16 a[96:111], v[100:103], v[116:119], a[96:111]
	ds_read_b128 v[100:103], v59 offset:59936
	ds_read_b128 v[124:127], v59 offset:55392
	s_waitcnt lgkmcnt(1)
	v_mfma_f32_32x32x16_bf16 a[80:95], v[100:103], v[104:107], a[80:95]
	v_mfma_f32_32x32x16_bf16 a[64:79], v[100:103], v[116:119], a[64:79]
	ds_read_b128 v[100:103], v59 offset:64544
	ds_read_b128 v[128:131], v59 offset:64576
	s_waitcnt lgkmcnt(1)
	v_mfma_f32_32x32x16_bf16 a[48:63], v[100:103], v[104:107], a[48:63]
	v_mfma_f32_32x32x16_bf16 a[32:47], v[100:103], v[116:119], a[32:47]
	ds_read_b128 v[100:103], v61 offset:55328
	ds_read_b128 v[140:143], v59 offset:64608
	s_waitcnt lgkmcnt(1)
	v_mfma_f32_32x32x16_bf16 a[16:31], v[100:103], v[104:107], a[16:31]
	v_mfma_f32_32x32x16_bf16 a[0:15], v[100:103], v[116:119], a[0:15]
	ds_read_b128 v[100:103], v69 offset:4672
	ds_read_b128 v[104:107], v69 offset:4704
	v_mfma_f32_32x32x16_bf16 a[112:127], v[112:115], v[108:111], a[112:127]
	s_waitcnt lgkmcnt(1)
	v_mfma_f32_32x32x16_bf16 a[96:111], v[112:115], v[100:103], a[96:111]
	ds_read_b128 v[112:115], v59 offset:59968
	ds_read_b128 v[116:119], v59 offset:60000
	s_waitcnt lgkmcnt(1)
	v_mfma_f32_32x32x16_bf16 a[80:95], v[112:115], v[108:111], a[80:95]
	v_mfma_f32_32x32x16_bf16 a[64:79], v[112:115], v[100:103], a[64:79]
	v_mfma_f32_32x32x16_bf16 a[48:63], v[128:131], v[108:111], a[48:63]
	v_mfma_f32_32x32x16_bf16 a[32:47], v[128:131], v[100:103], a[32:47]
	ds_read_b128 v[112:115], v61 offset:55360
	ds_read_b128 v[128:131], v61 offset:55392
	s_waitcnt lgkmcnt(1)
	v_mfma_f32_32x32x16_bf16 a[16:31], v[112:115], v[108:111], a[16:31]
	v_mfma_f32_32x32x16_bf16 a[0:15], v[112:115], v[100:103], a[0:15]
	v_mfma_f32_32x32x16_bf16 a[112:127], v[124:127], v[120:123], a[112:127]
	v_mfma_f32_32x32x16_bf16 a[96:111], v[124:127], v[104:107], a[96:111]
	v_mfma_f32_32x32x16_bf16 a[80:95], v[116:119], v[120:123], a[80:95]
	v_mfma_f32_32x32x16_bf16 a[64:79], v[116:119], v[104:107], a[64:79]
	global_load_dwordx4 v[100:103], v[4:5], off offset:896
	global_load_dwordx4 v[108:111], v[0:1], off offset:896
	global_load_dwordx4 v[112:115], v[8:9], off offset:896
	global_load_dwordx4 v[116:119], v[6:7], off offset:896
	v_mfma_f32_32x32x16_bf16 a[48:63], v[140:143], v[120:123], a[48:63]
	v_mfma_f32_32x32x16_bf16 a[32:47], v[140:143], v[104:107], a[32:47]
	global_load_dwordx4 v[124:127], v[10:11], off offset:896
	global_load_dwordx4 v[140:143], v[12:13], off offset:896
	global_load_dwordx4 v[144:147], v[26:27], off offset:896
	global_load_dwordx4 v[148:151], v[14:15], off offset:896
	global_load_dwordx4 v[152:155], v[28:29], off offset:896
	global_load_dwordx4 v[156:159], v[2:3], off offset:896
	global_load_dwordx4 v[160:163], v[30:31], off offset:896
	s_waitcnt lgkmcnt(0)
	v_mfma_f32_32x32x16_bf16 a[16:31], v[128:131], v[120:123], a[16:31]
	global_load_dwordx4 v[120:123], v[32:33], off offset:896
	s_barrier
	v_mfma_f32_32x32x16_bf16 a[0:15], v[128:131], v[104:107], a[0:15]
	ds_read_b128 v[104:107], v59
	ds_read_b128 v[128:131], v62 offset:36864
	ds_read_b128 v[164:167], v59 offset:4608
	ds_read_b128 v[168:171], v62 offset:41472
	s_waitcnt lgkmcnt(2)
	v_mfma_f32_32x32x16_bf16 a[112:127], v[104:107], v[128:131], a[112:127]
	s_waitcnt lgkmcnt(0)
	v_mfma_f32_32x32x16_bf16 a[96:111], v[104:107], v[168:171], a[96:111]
	ds_read_b128 v[104:107], v59 offset:9216
	s_waitcnt lgkmcnt(0)
	v_mfma_f32_32x32x16_bf16 a[48:63], v[104:107], v[128:131], a[48:63]
	v_mfma_f32_32x32x16_bf16 a[32:47], v[104:107], v[168:171], a[32:47]
	ds_read_b128 v[104:107], v61
	s_waitcnt vmcnt(10)
	ds_write_b128 v60, v[108:111] offset:55296
	ds_write_b128 v60, v[100:103] offset:59904
	s_waitcnt vmcnt(8)
	ds_write_b128 v60, v[116:119] offset:64512
	ds_write_b128 v63, v[112:115] offset:55296
	s_waitcnt vmcnt(7)
	ds_write_b128 v64, v[124:127] offset:55296
	s_waitcnt vmcnt(6)
	ds_write_b128 v65, v[140:143] offset:55296
	s_waitcnt vmcnt(4)
	ds_write_b128 v66, v[148:151] offset:55296
	ds_write_b128 v67, v[144:147] offset:55296
	s_waitcnt vmcnt(2)
	ds_write_b128 v68, v[156:159]
	ds_write_b128 v68, v[152:155] offset:4608
	s_waitcnt vmcnt(1)
	ds_write_b128 v68, v[160:163] offset:9216
	s_waitcnt vmcnt(0)
	ds_write_b128 v68, v[120:123] offset:13824
	v_mfma_f32_32x32x16_bf16 a[80:95], v[164:167], v[128:131], a[80:95]
	v_mfma_f32_32x32x16_bf16 a[64:79], v[164:167], v[168:171], a[64:79]
	s_waitcnt lgkmcnt(12)
	v_mfma_f32_32x32x16_bf16 a[16:31], v[104:107], v[128:131], a[16:31]
	v_mfma_f32_32x32x16_bf16 a[0:15], v[104:107], v[168:171], a[0:15]
	ds_read_b128 v[100:103], v59 offset:32
	ds_read_b128 v[104:107], v62 offset:36896
	ds_read_b128 v[108:111], v62 offset:36928
	ds_read_b128 v[112:115], v59 offset:64
	ds_read_b128 v[116:119], v62 offset:41504
	ds_read_b128 v[120:123], v62 offset:36960
	s_waitcnt lgkmcnt(4)
	v_mfma_f32_32x32x16_bf16 a[112:127], v[100:103], v[104:107], a[112:127]
	s_waitcnt lgkmcnt(1)
	v_mfma_f32_32x32x16_bf16 a[96:111], v[100:103], v[116:119], a[96:111]
	ds_read_b128 v[100:103], v59 offset:4640
	ds_read_b128 v[124:127], v59 offset:96
	s_waitcnt lgkmcnt(1)
	v_mfma_f32_32x32x16_bf16 a[80:95], v[100:103], v[104:107], a[80:95]
	v_mfma_f32_32x32x16_bf16 a[64:79], v[100:103], v[116:119], a[64:79]
	ds_read_b128 v[100:103], v59 offset:9248
	ds_read_b128 v[128:131], v59 offset:9280
	s_waitcnt lgkmcnt(1)
	v_mfma_f32_32x32x16_bf16 a[48:63], v[100:103], v[104:107], a[48:63]
	v_mfma_f32_32x32x16_bf16 a[32:47], v[100:103], v[116:119], a[32:47]
	ds_read_b128 v[100:103], v61 offset:32
	ds_read_b128 v[140:143], v59 offset:9312
	s_waitcnt lgkmcnt(1)
	v_mfma_f32_32x32x16_bf16 a[16:31], v[100:103], v[104:107], a[16:31]
	v_mfma_f32_32x32x16_bf16 a[0:15], v[100:103], v[116:119], a[0:15]
	ds_read_b128 v[100:103], v62 offset:41536
	ds_read_b128 v[104:107], v62 offset:41568
	v_mfma_f32_32x32x16_bf16 a[112:127], v[112:115], v[108:111], a[112:127]
	s_waitcnt lgkmcnt(1)
	v_mfma_f32_32x32x16_bf16 a[96:111], v[112:115], v[100:103], a[96:111]
	ds_read_b128 v[112:115], v59 offset:4672
	ds_read_b128 v[116:119], v59 offset:4704
	s_waitcnt lgkmcnt(1)
	v_mfma_f32_32x32x16_bf16 a[80:95], v[112:115], v[108:111], a[80:95]
	v_mfma_f32_32x32x16_bf16 a[64:79], v[112:115], v[100:103], a[64:79]
	v_mfma_f32_32x32x16_bf16 a[48:63], v[128:131], v[108:111], a[48:63]
	v_mfma_f32_32x32x16_bf16 a[32:47], v[128:131], v[100:103], a[32:47]
	ds_read_b128 v[112:115], v61 offset:64
	ds_read_b128 v[128:131], v61 offset:96
	s_waitcnt lgkmcnt(1)
	v_mfma_f32_32x32x16_bf16 a[16:31], v[112:115], v[108:111], a[16:31]
	v_mfma_f32_32x32x16_bf16 a[0:15], v[112:115], v[100:103], a[0:15]
	global_load_dwordx4 v[100:103], v[32:33], off offset:1024
	v_mfma_f32_32x32x16_bf16 a[112:127], v[124:127], v[120:123], a[112:127]
	v_mfma_f32_32x32x16_bf16 a[96:111], v[124:127], v[104:107], a[96:111]
	v_mfma_f32_32x32x16_bf16 a[80:95], v[116:119], v[120:123], a[80:95]
	v_mfma_f32_32x32x16_bf16 a[64:79], v[116:119], v[104:107], a[64:79]
	v_mfma_f32_32x32x16_bf16 a[48:63], v[140:143], v[120:123], a[48:63]
	v_mfma_f32_32x32x16_bf16 a[32:47], v[140:143], v[104:107], a[32:47]
	global_load_dwordx4 v[108:111], v[30:31], off offset:1024
	global_load_dwordx4 v[112:115], v[28:29], off offset:1024
	global_load_dwordx4 v[116:119], v[2:3], off offset:1024
	global_load_dwordx4 v[124:127], v[8:9], off offset:1024
	global_load_dwordx4 v[140:143], v[6:7], off offset:1024
	global_load_dwordx4 v[144:147], v[4:5], off offset:1024
	global_load_dwordx4 v[148:151], v[0:1], off offset:1024
	s_waitcnt lgkmcnt(0)
	v_mfma_f32_32x32x16_bf16 a[16:31], v[128:131], v[120:123], a[16:31]
	global_load_dwordx4 v[120:123], v[12:13], off offset:1024
	global_load_dwordx4 v[152:155], v[10:11], off offset:1024
	global_load_dwordx4 v[156:159], v[26:27], off offset:1024
	global_load_dwordx4 v[160:163], v[14:15], off offset:1024
	s_barrier
	v_mfma_f32_32x32x16_bf16 a[0:15], v[128:131], v[104:107], a[0:15]
	ds_read_b128 v[104:107], v59 offset:55296
	ds_read_b128 v[128:131], v69
	ds_read_b128 v[164:167], v59 offset:59904
	ds_read_b128 v[168:171], v69 offset:4608
	s_waitcnt lgkmcnt(2)
	v_mfma_f32_32x32x16_bf16 a[112:127], v[104:107], v[128:131], a[112:127]
	s_waitcnt lgkmcnt(0)
	v_mfma_f32_32x32x16_bf16 a[96:111], v[104:107], v[168:171], a[96:111]
	ds_read_b128 v[104:107], v59 offset:64512
	s_waitcnt lgkmcnt(0)
	v_mfma_f32_32x32x16_bf16 a[48:63], v[104:107], v[128:131], a[48:63]
	v_mfma_f32_32x32x16_bf16 a[32:47], v[104:107], v[168:171], a[32:47]
	ds_read_b128 v[104:107], v61 offset:55296
	s_waitcnt vmcnt(4)
	ds_write_b128 v60, v[148:151]
	ds_write_b128 v60, v[144:147] offset:4608
	ds_write_b128 v60, v[140:143] offset:9216
	ds_write_b128 v60, v[124:127] offset:13824
	s_waitcnt vmcnt(2)
	ds_write_b128 v60, v[152:155] offset:18432
	ds_write_b128 v60, v[120:123] offset:23040
	s_waitcnt vmcnt(0)
	ds_write_b128 v60, v[160:163] offset:27648
	ds_write_b128 v60, v[156:159] offset:32256
	ds_write_b128 v60, v[116:119] offset:36864
	ds_write_b128 v60, v[112:115] offset:41472
	ds_write_b128 v60, v[108:111] offset:46080
	ds_write_b128 v60, v[100:103] offset:50688
	v_mfma_f32_32x32x16_bf16 a[80:95], v[164:167], v[128:131], a[80:95]
	v_mfma_f32_32x32x16_bf16 a[64:79], v[164:167], v[168:171], a[64:79]
	s_waitcnt lgkmcnt(12)
	v_mfma_f32_32x32x16_bf16 a[16:31], v[104:107], v[128:131], a[16:31]
	v_mfma_f32_32x32x16_bf16 a[0:15], v[104:107], v[168:171], a[0:15]
	ds_read_b128 v[100:103], v59 offset:55328
	ds_read_b128 v[104:107], v69 offset:32
	ds_read_b128 v[108:111], v69 offset:64
	ds_read_b128 v[112:115], v59 offset:55360
	ds_read_b128 v[116:119], v69 offset:4640
	ds_read_b128 v[120:123], v69 offset:96
	s_waitcnt lgkmcnt(4)
	v_mfma_f32_32x32x16_bf16 a[112:127], v[100:103], v[104:107], a[112:127]
	s_waitcnt lgkmcnt(1)
	v_mfma_f32_32x32x16_bf16 a[96:111], v[100:103], v[116:119], a[96:111]
	ds_read_b128 v[100:103], v59 offset:59936
	ds_read_b128 v[124:127], v59 offset:55392
	s_waitcnt lgkmcnt(1)
	v_mfma_f32_32x32x16_bf16 a[80:95], v[100:103], v[104:107], a[80:95]
	v_mfma_f32_32x32x16_bf16 a[64:79], v[100:103], v[116:119], a[64:79]
	ds_read_b128 v[100:103], v59 offset:64544
	ds_read_b128 v[128:131], v59 offset:64576
	s_waitcnt lgkmcnt(1)
	v_mfma_f32_32x32x16_bf16 a[48:63], v[100:103], v[104:107], a[48:63]
	v_mfma_f32_32x32x16_bf16 a[32:47], v[100:103], v[116:119], a[32:47]
	ds_read_b128 v[100:103], v61 offset:55328
	ds_read_b128 v[140:143], v59 offset:64608
	s_waitcnt lgkmcnt(1)
	v_mfma_f32_32x32x16_bf16 a[16:31], v[100:103], v[104:107], a[16:31]
	v_mfma_f32_32x32x16_bf16 a[0:15], v[100:103], v[116:119], a[0:15]
	ds_read_b128 v[100:103], v69 offset:4672
	ds_read_b128 v[104:107], v69 offset:4704
	v_mfma_f32_32x32x16_bf16 a[112:127], v[112:115], v[108:111], a[112:127]
	s_waitcnt lgkmcnt(1)
	v_mfma_f32_32x32x16_bf16 a[96:111], v[112:115], v[100:103], a[96:111]
	ds_read_b128 v[112:115], v59 offset:59968
	ds_read_b128 v[116:119], v59 offset:60000
	s_waitcnt lgkmcnt(1)
	v_mfma_f32_32x32x16_bf16 a[80:95], v[112:115], v[108:111], a[80:95]
	v_mfma_f32_32x32x16_bf16 a[64:79], v[112:115], v[100:103], a[64:79]
	v_mfma_f32_32x32x16_bf16 a[48:63], v[128:131], v[108:111], a[48:63]
	v_mfma_f32_32x32x16_bf16 a[32:47], v[128:131], v[100:103], a[32:47]
	ds_read_b128 v[112:115], v61 offset:55360
	ds_read_b128 v[128:131], v61 offset:55392
	s_waitcnt lgkmcnt(1)
	v_mfma_f32_32x32x16_bf16 a[16:31], v[112:115], v[108:111], a[16:31]
	v_mfma_f32_32x32x16_bf16 a[0:15], v[112:115], v[100:103], a[0:15]
	v_mfma_f32_32x32x16_bf16 a[112:127], v[124:127], v[120:123], a[112:127]
	v_mfma_f32_32x32x16_bf16 a[96:111], v[124:127], v[104:107], a[96:111]
	v_mfma_f32_32x32x16_bf16 a[80:95], v[116:119], v[120:123], a[80:95]
	v_mfma_f32_32x32x16_bf16 a[64:79], v[116:119], v[104:107], a[64:79]
	global_load_dwordx4 v[100:103], v[4:5], off offset:1152
	global_load_dwordx4 v[108:111], v[0:1], off offset:1152
	global_load_dwordx4 v[112:115], v[8:9], off offset:1152
	global_load_dwordx4 v[116:119], v[6:7], off offset:1152
	v_mfma_f32_32x32x16_bf16 a[48:63], v[140:143], v[120:123], a[48:63]
	v_mfma_f32_32x32x16_bf16 a[32:47], v[140:143], v[104:107], a[32:47]
	global_load_dwordx4 v[124:127], v[10:11], off offset:1152
	global_load_dwordx4 v[140:143], v[12:13], off offset:1152
	global_load_dwordx4 v[144:147], v[26:27], off offset:1152
	global_load_dwordx4 v[148:151], v[14:15], off offset:1152
	global_load_dwordx4 v[152:155], v[28:29], off offset:1152
	global_load_dwordx4 v[156:159], v[2:3], off offset:1152
	global_load_dwordx4 v[160:163], v[30:31], off offset:1152
	s_waitcnt lgkmcnt(0)
	v_mfma_f32_32x32x16_bf16 a[16:31], v[128:131], v[120:123], a[16:31]
	global_load_dwordx4 v[120:123], v[32:33], off offset:1152
	s_barrier
	v_mfma_f32_32x32x16_bf16 a[0:15], v[128:131], v[104:107], a[0:15]
	ds_read_b128 v[104:107], v59
	ds_read_b128 v[128:131], v62 offset:36864
	ds_read_b128 v[164:167], v59 offset:4608
	ds_read_b128 v[168:171], v62 offset:41472
	s_waitcnt lgkmcnt(2)
	v_mfma_f32_32x32x16_bf16 a[112:127], v[104:107], v[128:131], a[112:127]
	s_waitcnt lgkmcnt(0)
	v_mfma_f32_32x32x16_bf16 a[96:111], v[104:107], v[168:171], a[96:111]
	ds_read_b128 v[104:107], v59 offset:9216
	s_waitcnt lgkmcnt(0)
	v_mfma_f32_32x32x16_bf16 a[48:63], v[104:107], v[128:131], a[48:63]
	v_mfma_f32_32x32x16_bf16 a[32:47], v[104:107], v[168:171], a[32:47]
	ds_read_b128 v[104:107], v61
	s_waitcnt vmcnt(10)
	ds_write_b128 v60, v[108:111] offset:55296
	ds_write_b128 v60, v[100:103] offset:59904
	s_waitcnt vmcnt(8)
	ds_write_b128 v60, v[116:119] offset:64512
	ds_write_b128 v63, v[112:115] offset:55296
	s_waitcnt vmcnt(7)
	ds_write_b128 v64, v[124:127] offset:55296
	s_waitcnt vmcnt(6)
	ds_write_b128 v65, v[140:143] offset:55296
	s_waitcnt vmcnt(4)
	ds_write_b128 v66, v[148:151] offset:55296
	ds_write_b128 v67, v[144:147] offset:55296
	s_waitcnt vmcnt(2)
	ds_write_b128 v68, v[156:159]
	ds_write_b128 v68, v[152:155] offset:4608
	s_waitcnt vmcnt(1)
	ds_write_b128 v68, v[160:163] offset:9216
	s_waitcnt vmcnt(0)
	ds_write_b128 v68, v[120:123] offset:13824
	v_mfma_f32_32x32x16_bf16 a[80:95], v[164:167], v[128:131], a[80:95]
	v_mfma_f32_32x32x16_bf16 a[64:79], v[164:167], v[168:171], a[64:79]
	s_waitcnt lgkmcnt(12)
	v_mfma_f32_32x32x16_bf16 a[16:31], v[104:107], v[128:131], a[16:31]
	v_mfma_f32_32x32x16_bf16 a[0:15], v[104:107], v[168:171], a[0:15]
	ds_read_b128 v[100:103], v59 offset:32
	ds_read_b128 v[104:107], v62 offset:36896
	ds_read_b128 v[108:111], v62 offset:36928
	ds_read_b128 v[112:115], v59 offset:64
	ds_read_b128 v[116:119], v62 offset:41504
	ds_read_b128 v[120:123], v62 offset:36960
	s_waitcnt lgkmcnt(4)
	v_mfma_f32_32x32x16_bf16 a[112:127], v[100:103], v[104:107], a[112:127]
	s_waitcnt lgkmcnt(1)
	v_mfma_f32_32x32x16_bf16 a[96:111], v[100:103], v[116:119], a[96:111]
	ds_read_b128 v[100:103], v59 offset:4640
	ds_read_b128 v[124:127], v59 offset:96
	s_waitcnt lgkmcnt(1)
	v_mfma_f32_32x32x16_bf16 a[80:95], v[100:103], v[104:107], a[80:95]
	v_mfma_f32_32x32x16_bf16 a[64:79], v[100:103], v[116:119], a[64:79]
	ds_read_b128 v[100:103], v59 offset:9248
	ds_read_b128 v[128:131], v59 offset:9280
	s_waitcnt lgkmcnt(1)
	v_mfma_f32_32x32x16_bf16 a[48:63], v[100:103], v[104:107], a[48:63]
	v_mfma_f32_32x32x16_bf16 a[32:47], v[100:103], v[116:119], a[32:47]
	ds_read_b128 v[100:103], v61 offset:32
	ds_read_b128 v[140:143], v59 offset:9312
	s_waitcnt lgkmcnt(1)
	v_mfma_f32_32x32x16_bf16 a[16:31], v[100:103], v[104:107], a[16:31]
	v_mfma_f32_32x32x16_bf16 a[0:15], v[100:103], v[116:119], a[0:15]
	ds_read_b128 v[100:103], v62 offset:41536
	ds_read_b128 v[104:107], v62 offset:41568
	v_mfma_f32_32x32x16_bf16 a[112:127], v[112:115], v[108:111], a[112:127]
	s_waitcnt lgkmcnt(1)
	v_mfma_f32_32x32x16_bf16 a[96:111], v[112:115], v[100:103], a[96:111]
	ds_read_b128 v[112:115], v59 offset:4672
	ds_read_b128 v[116:119], v59 offset:4704
	s_waitcnt lgkmcnt(1)
	v_mfma_f32_32x32x16_bf16 a[80:95], v[112:115], v[108:111], a[80:95]
	v_mfma_f32_32x32x16_bf16 a[64:79], v[112:115], v[100:103], a[64:79]
	v_mfma_f32_32x32x16_bf16 a[48:63], v[128:131], v[108:111], a[48:63]
	v_mfma_f32_32x32x16_bf16 a[32:47], v[128:131], v[100:103], a[32:47]
	ds_read_b128 v[112:115], v61 offset:64
	ds_read_b128 v[128:131], v61 offset:96
	s_waitcnt lgkmcnt(1)
	v_mfma_f32_32x32x16_bf16 a[16:31], v[112:115], v[108:111], a[16:31]
	v_mfma_f32_32x32x16_bf16 a[0:15], v[112:115], v[100:103], a[0:15]
	global_load_dwordx4 v[100:103], v[32:33], off offset:1280
	v_mfma_f32_32x32x16_bf16 a[112:127], v[124:127], v[120:123], a[112:127]
	v_mfma_f32_32x32x16_bf16 a[96:111], v[124:127], v[104:107], a[96:111]
	v_mfma_f32_32x32x16_bf16 a[80:95], v[116:119], v[120:123], a[80:95]
	v_mfma_f32_32x32x16_bf16 a[64:79], v[116:119], v[104:107], a[64:79]
	v_mfma_f32_32x32x16_bf16 a[48:63], v[140:143], v[120:123], a[48:63]
	v_mfma_f32_32x32x16_bf16 a[32:47], v[140:143], v[104:107], a[32:47]
	global_load_dwordx4 v[108:111], v[30:31], off offset:1280
	global_load_dwordx4 v[112:115], v[28:29], off offset:1280
	global_load_dwordx4 v[116:119], v[2:3], off offset:1280
	global_load_dwordx4 v[124:127], v[8:9], off offset:1280
	global_load_dwordx4 v[140:143], v[6:7], off offset:1280
	global_load_dwordx4 v[144:147], v[4:5], off offset:1280
	global_load_dwordx4 v[148:151], v[0:1], off offset:1280
	s_waitcnt lgkmcnt(0)
	v_mfma_f32_32x32x16_bf16 a[16:31], v[128:131], v[120:123], a[16:31]
	global_load_dwordx4 v[120:123], v[12:13], off offset:1280
	global_load_dwordx4 v[152:155], v[10:11], off offset:1280
	global_load_dwordx4 v[156:159], v[26:27], off offset:1280
	global_load_dwordx4 v[160:163], v[14:15], off offset:1280
	s_barrier
	v_mfma_f32_32x32x16_bf16 a[0:15], v[128:131], v[104:107], a[0:15]
	ds_read_b128 v[104:107], v59 offset:55296
	ds_read_b128 v[128:131], v69
	ds_read_b128 v[164:167], v59 offset:59904
	ds_read_b128 v[168:171], v69 offset:4608
	s_waitcnt lgkmcnt(2)
	v_mfma_f32_32x32x16_bf16 a[112:127], v[104:107], v[128:131], a[112:127]
	s_waitcnt lgkmcnt(0)
	v_mfma_f32_32x32x16_bf16 a[96:111], v[104:107], v[168:171], a[96:111]
	ds_read_b128 v[104:107], v59 offset:64512
	s_waitcnt lgkmcnt(0)
	v_mfma_f32_32x32x16_bf16 a[48:63], v[104:107], v[128:131], a[48:63]
	v_mfma_f32_32x32x16_bf16 a[32:47], v[104:107], v[168:171], a[32:47]
	ds_read_b128 v[104:107], v61 offset:55296
	s_waitcnt vmcnt(4)
	ds_write_b128 v60, v[148:151]
	ds_write_b128 v60, v[144:147] offset:4608
	ds_write_b128 v60, v[140:143] offset:9216
	ds_write_b128 v60, v[124:127] offset:13824
	s_waitcnt vmcnt(2)
	ds_write_b128 v60, v[152:155] offset:18432
	ds_write_b128 v60, v[120:123] offset:23040
	s_waitcnt vmcnt(0)
	ds_write_b128 v60, v[160:163] offset:27648
	ds_write_b128 v60, v[156:159] offset:32256
	ds_write_b128 v60, v[116:119] offset:36864
	ds_write_b128 v60, v[112:115] offset:41472
	ds_write_b128 v60, v[108:111] offset:46080
	ds_write_b128 v60, v[100:103] offset:50688
	v_mfma_f32_32x32x16_bf16 a[80:95], v[164:167], v[128:131], a[80:95]
	v_mfma_f32_32x32x16_bf16 a[64:79], v[164:167], v[168:171], a[64:79]
	s_waitcnt lgkmcnt(12)
	v_mfma_f32_32x32x16_bf16 a[16:31], v[104:107], v[128:131], a[16:31]
	v_mfma_f32_32x32x16_bf16 a[0:15], v[104:107], v[168:171], a[0:15]
	ds_read_b128 v[100:103], v59 offset:55328
	ds_read_b128 v[104:107], v69 offset:32
	ds_read_b128 v[108:111], v69 offset:64
	ds_read_b128 v[112:115], v59 offset:55360
	ds_read_b128 v[116:119], v69 offset:4640
	ds_read_b128 v[120:123], v69 offset:96
	s_waitcnt lgkmcnt(4)
	v_mfma_f32_32x32x16_bf16 a[112:127], v[100:103], v[104:107], a[112:127]
	s_waitcnt lgkmcnt(1)
	v_mfma_f32_32x32x16_bf16 a[96:111], v[100:103], v[116:119], a[96:111]
	ds_read_b128 v[100:103], v59 offset:59936
	ds_read_b128 v[124:127], v59 offset:55392
	s_waitcnt lgkmcnt(1)
	v_mfma_f32_32x32x16_bf16 a[80:95], v[100:103], v[104:107], a[80:95]
	v_mfma_f32_32x32x16_bf16 a[64:79], v[100:103], v[116:119], a[64:79]
	ds_read_b128 v[100:103], v59 offset:64544
	ds_read_b128 v[128:131], v59 offset:64576
	s_waitcnt lgkmcnt(1)
	v_mfma_f32_32x32x16_bf16 a[48:63], v[100:103], v[104:107], a[48:63]
	v_mfma_f32_32x32x16_bf16 a[32:47], v[100:103], v[116:119], a[32:47]
	ds_read_b128 v[100:103], v61 offset:55328
	ds_read_b128 v[140:143], v59 offset:64608
	s_waitcnt lgkmcnt(1)
	v_mfma_f32_32x32x16_bf16 a[16:31], v[100:103], v[104:107], a[16:31]
	v_mfma_f32_32x32x16_bf16 a[0:15], v[100:103], v[116:119], a[0:15]
	ds_read_b128 v[100:103], v69 offset:4672
	ds_read_b128 v[104:107], v69 offset:4704
	v_mfma_f32_32x32x16_bf16 a[112:127], v[112:115], v[108:111], a[112:127]
	s_waitcnt lgkmcnt(1)
	v_mfma_f32_32x32x16_bf16 a[96:111], v[112:115], v[100:103], a[96:111]
	ds_read_b128 v[112:115], v59 offset:59968
	ds_read_b128 v[116:119], v59 offset:60000
	s_waitcnt lgkmcnt(1)
	v_mfma_f32_32x32x16_bf16 a[80:95], v[112:115], v[108:111], a[80:95]
	v_mfma_f32_32x32x16_bf16 a[64:79], v[112:115], v[100:103], a[64:79]
	v_mfma_f32_32x32x16_bf16 a[48:63], v[128:131], v[108:111], a[48:63]
	v_mfma_f32_32x32x16_bf16 a[32:47], v[128:131], v[100:103], a[32:47]
	ds_read_b128 v[112:115], v61 offset:55360
	ds_read_b128 v[128:131], v61 offset:55392
	s_waitcnt lgkmcnt(1)
	v_mfma_f32_32x32x16_bf16 a[16:31], v[112:115], v[108:111], a[16:31]
	v_mfma_f32_32x32x16_bf16 a[0:15], v[112:115], v[100:103], a[0:15]
	v_mfma_f32_32x32x16_bf16 a[112:127], v[124:127], v[120:123], a[112:127]
	v_mfma_f32_32x32x16_bf16 a[96:111], v[124:127], v[104:107], a[96:111]
	v_mfma_f32_32x32x16_bf16 a[80:95], v[116:119], v[120:123], a[80:95]
	v_mfma_f32_32x32x16_bf16 a[64:79], v[116:119], v[104:107], a[64:79]
	global_load_dwordx4 v[100:103], v[4:5], off offset:1408
	global_load_dwordx4 v[108:111], v[0:1], off offset:1408
	global_load_dwordx4 v[112:115], v[8:9], off offset:1408
	global_load_dwordx4 v[116:119], v[6:7], off offset:1408
	v_mfma_f32_32x32x16_bf16 a[48:63], v[140:143], v[120:123], a[48:63]
	v_mfma_f32_32x32x16_bf16 a[32:47], v[140:143], v[104:107], a[32:47]
	global_load_dwordx4 v[124:127], v[10:11], off offset:1408
	global_load_dwordx4 v[140:143], v[12:13], off offset:1408
	global_load_dwordx4 v[144:147], v[26:27], off offset:1408
	global_load_dwordx4 v[148:151], v[14:15], off offset:1408
	global_load_dwordx4 v[152:155], v[28:29], off offset:1408
	global_load_dwordx4 v[156:159], v[2:3], off offset:1408
	global_load_dwordx4 v[160:163], v[30:31], off offset:1408
	s_waitcnt lgkmcnt(0)
	v_mfma_f32_32x32x16_bf16 a[16:31], v[128:131], v[120:123], a[16:31]
	global_load_dwordx4 v[120:123], v[32:33], off offset:1408
	s_barrier
	v_mfma_f32_32x32x16_bf16 a[0:15], v[128:131], v[104:107], a[0:15]
	ds_read_b128 v[104:107], v59
	ds_read_b128 v[128:131], v62 offset:36864
	ds_read_b128 v[164:167], v59 offset:4608
	ds_read_b128 v[168:171], v62 offset:41472
	s_waitcnt lgkmcnt(2)
	v_mfma_f32_32x32x16_bf16 a[112:127], v[104:107], v[128:131], a[112:127]
	s_waitcnt lgkmcnt(0)
	v_mfma_f32_32x32x16_bf16 a[96:111], v[104:107], v[168:171], a[96:111]
	ds_read_b128 v[104:107], v59 offset:9216
	s_waitcnt lgkmcnt(0)
	v_mfma_f32_32x32x16_bf16 a[48:63], v[104:107], v[128:131], a[48:63]
	v_mfma_f32_32x32x16_bf16 a[32:47], v[104:107], v[168:171], a[32:47]
	ds_read_b128 v[104:107], v61
	s_waitcnt vmcnt(10)
	ds_write_b128 v60, v[108:111] offset:55296
	ds_write_b128 v60, v[100:103] offset:59904
	s_waitcnt vmcnt(8)
	ds_write_b128 v60, v[116:119] offset:64512
	ds_write_b128 v63, v[112:115] offset:55296
	s_waitcnt vmcnt(7)
	ds_write_b128 v64, v[124:127] offset:55296
	s_waitcnt vmcnt(6)
	ds_write_b128 v65, v[140:143] offset:55296
	s_waitcnt vmcnt(4)
	ds_write_b128 v66, v[148:151] offset:55296
	ds_write_b128 v67, v[144:147] offset:55296
	s_waitcnt vmcnt(2)
	ds_write_b128 v68, v[156:159]
	ds_write_b128 v68, v[152:155] offset:4608
	s_waitcnt vmcnt(1)
	ds_write_b128 v68, v[160:163] offset:9216
	s_waitcnt vmcnt(0)
	ds_write_b128 v68, v[120:123] offset:13824
	v_mfma_f32_32x32x16_bf16 a[80:95], v[164:167], v[128:131], a[80:95]
	v_mfma_f32_32x32x16_bf16 a[64:79], v[164:167], v[168:171], a[64:79]
	s_waitcnt lgkmcnt(12)
	v_mfma_f32_32x32x16_bf16 a[16:31], v[104:107], v[128:131], a[16:31]
	v_mfma_f32_32x32x16_bf16 a[0:15], v[104:107], v[168:171], a[0:15]
	ds_read_b128 v[100:103], v59 offset:32
	ds_read_b128 v[104:107], v62 offset:36896
	ds_read_b128 v[108:111], v62 offset:36928
	ds_read_b128 v[112:115], v59 offset:64
	ds_read_b128 v[116:119], v62 offset:41504
	ds_read_b128 v[120:123], v62 offset:36960
	s_waitcnt lgkmcnt(4)
	v_mfma_f32_32x32x16_bf16 a[112:127], v[100:103], v[104:107], a[112:127]
	s_waitcnt lgkmcnt(1)
	v_mfma_f32_32x32x16_bf16 a[96:111], v[100:103], v[116:119], a[96:111]
	ds_read_b128 v[100:103], v59 offset:4640
	ds_read_b128 v[124:127], v59 offset:96
	s_waitcnt lgkmcnt(1)
	v_mfma_f32_32x32x16_bf16 a[80:95], v[100:103], v[104:107], a[80:95]
	v_mfma_f32_32x32x16_bf16 a[64:79], v[100:103], v[116:119], a[64:79]
	ds_read_b128 v[100:103], v59 offset:9248
	ds_read_b128 v[128:131], v59 offset:9280
	s_waitcnt lgkmcnt(1)
	v_mfma_f32_32x32x16_bf16 a[48:63], v[100:103], v[104:107], a[48:63]
	v_mfma_f32_32x32x16_bf16 a[32:47], v[100:103], v[116:119], a[32:47]
	ds_read_b128 v[100:103], v61 offset:32
	ds_read_b128 v[140:143], v59 offset:9312
	s_waitcnt lgkmcnt(1)
	v_mfma_f32_32x32x16_bf16 a[16:31], v[100:103], v[104:107], a[16:31]
	v_mfma_f32_32x32x16_bf16 a[0:15], v[100:103], v[116:119], a[0:15]
	ds_read_b128 v[100:103], v62 offset:41536
	ds_read_b128 v[104:107], v62 offset:41568
	v_mfma_f32_32x32x16_bf16 a[112:127], v[112:115], v[108:111], a[112:127]
	s_waitcnt lgkmcnt(1)
	v_mfma_f32_32x32x16_bf16 a[96:111], v[112:115], v[100:103], a[96:111]
	ds_read_b128 v[112:115], v59 offset:4672
	ds_read_b128 v[116:119], v59 offset:4704
	s_waitcnt lgkmcnt(1)
	v_mfma_f32_32x32x16_bf16 a[80:95], v[112:115], v[108:111], a[80:95]
	v_mfma_f32_32x32x16_bf16 a[64:79], v[112:115], v[100:103], a[64:79]
	v_mfma_f32_32x32x16_bf16 a[48:63], v[128:131], v[108:111], a[48:63]
	v_mfma_f32_32x32x16_bf16 a[32:47], v[128:131], v[100:103], a[32:47]
	ds_read_b128 v[112:115], v61 offset:64
	ds_read_b128 v[128:131], v61 offset:96
	s_waitcnt lgkmcnt(1)
	v_mfma_f32_32x32x16_bf16 a[16:31], v[112:115], v[108:111], a[16:31]
	v_mfma_f32_32x32x16_bf16 a[0:15], v[112:115], v[100:103], a[0:15]
	global_load_dwordx4 v[100:103], v[32:33], off offset:1536
	v_mfma_f32_32x32x16_bf16 a[112:127], v[124:127], v[120:123], a[112:127]
	v_mfma_f32_32x32x16_bf16 a[96:111], v[124:127], v[104:107], a[96:111]
	v_mfma_f32_32x32x16_bf16 a[80:95], v[116:119], v[120:123], a[80:95]
	v_mfma_f32_32x32x16_bf16 a[64:79], v[116:119], v[104:107], a[64:79]
	v_mfma_f32_32x32x16_bf16 a[48:63], v[140:143], v[120:123], a[48:63]
	v_mfma_f32_32x32x16_bf16 a[32:47], v[140:143], v[104:107], a[32:47]
	global_load_dwordx4 v[108:111], v[30:31], off offset:1536
	global_load_dwordx4 v[112:115], v[28:29], off offset:1536
	global_load_dwordx4 v[116:119], v[2:3], off offset:1536
	global_load_dwordx4 v[124:127], v[8:9], off offset:1536
	global_load_dwordx4 v[140:143], v[6:7], off offset:1536
	global_load_dwordx4 v[144:147], v[4:5], off offset:1536
	global_load_dwordx4 v[148:151], v[0:1], off offset:1536
	s_waitcnt lgkmcnt(0)
	v_mfma_f32_32x32x16_bf16 a[16:31], v[128:131], v[120:123], a[16:31]
	global_load_dwordx4 v[120:123], v[12:13], off offset:1536
	global_load_dwordx4 v[152:155], v[10:11], off offset:1536
	global_load_dwordx4 v[156:159], v[26:27], off offset:1536
	global_load_dwordx4 v[160:163], v[14:15], off offset:1536
	s_barrier
	v_mfma_f32_32x32x16_bf16 a[0:15], v[128:131], v[104:107], a[0:15]
	ds_read_b128 v[104:107], v59 offset:55296
	ds_read_b128 v[128:131], v69
	ds_read_b128 v[164:167], v59 offset:59904
	ds_read_b128 v[168:171], v69 offset:4608
	s_waitcnt lgkmcnt(2)
	v_mfma_f32_32x32x16_bf16 a[112:127], v[104:107], v[128:131], a[112:127]
	s_waitcnt lgkmcnt(0)
	v_mfma_f32_32x32x16_bf16 a[96:111], v[104:107], v[168:171], a[96:111]
	ds_read_b128 v[104:107], v59 offset:64512
	s_waitcnt lgkmcnt(0)
	v_mfma_f32_32x32x16_bf16 a[48:63], v[104:107], v[128:131], a[48:63]
	v_mfma_f32_32x32x16_bf16 a[32:47], v[104:107], v[168:171], a[32:47]
	ds_read_b128 v[104:107], v61 offset:55296
	s_waitcnt vmcnt(4)
	ds_write_b128 v60, v[148:151]
	ds_write_b128 v60, v[144:147] offset:4608
	ds_write_b128 v60, v[140:143] offset:9216
	ds_write_b128 v60, v[124:127] offset:13824
	s_waitcnt vmcnt(2)
	ds_write_b128 v60, v[152:155] offset:18432
	ds_write_b128 v60, v[120:123] offset:23040
	s_waitcnt vmcnt(0)
	ds_write_b128 v60, v[160:163] offset:27648
	ds_write_b128 v60, v[156:159] offset:32256
	ds_write_b128 v60, v[116:119] offset:36864
	ds_write_b128 v60, v[112:115] offset:41472
	ds_write_b128 v60, v[108:111] offset:46080
	ds_write_b128 v60, v[100:103] offset:50688
	v_mfma_f32_32x32x16_bf16 a[80:95], v[164:167], v[128:131], a[80:95]
	v_mfma_f32_32x32x16_bf16 a[64:79], v[164:167], v[168:171], a[64:79]
	s_waitcnt lgkmcnt(12)
	v_mfma_f32_32x32x16_bf16 a[16:31], v[104:107], v[128:131], a[16:31]
	v_mfma_f32_32x32x16_bf16 a[0:15], v[104:107], v[168:171], a[0:15]
	ds_read_b128 v[100:103], v59 offset:55328
	ds_read_b128 v[104:107], v69 offset:32
	ds_read_b128 v[108:111], v69 offset:64
	ds_read_b128 v[112:115], v59 offset:55360
	ds_read_b128 v[116:119], v69 offset:4640
	ds_read_b128 v[120:123], v69 offset:96
	s_waitcnt lgkmcnt(4)
	v_mfma_f32_32x32x16_bf16 a[112:127], v[100:103], v[104:107], a[112:127]
	s_waitcnt lgkmcnt(1)
	v_mfma_f32_32x32x16_bf16 a[96:111], v[100:103], v[116:119], a[96:111]
	ds_read_b128 v[100:103], v59 offset:59936
	ds_read_b128 v[124:127], v59 offset:55392
	s_waitcnt lgkmcnt(1)
	v_mfma_f32_32x32x16_bf16 a[80:95], v[100:103], v[104:107], a[80:95]
	v_mfma_f32_32x32x16_bf16 a[64:79], v[100:103], v[116:119], a[64:79]
	ds_read_b128 v[100:103], v59 offset:64544
	ds_read_b128 v[128:131], v59 offset:64576
	s_waitcnt lgkmcnt(1)
	v_mfma_f32_32x32x16_bf16 a[48:63], v[100:103], v[104:107], a[48:63]
	v_mfma_f32_32x32x16_bf16 a[32:47], v[100:103], v[116:119], a[32:47]
	ds_read_b128 v[100:103], v61 offset:55328
	ds_read_b128 v[140:143], v59 offset:64608
	s_waitcnt lgkmcnt(1)
	v_mfma_f32_32x32x16_bf16 a[16:31], v[100:103], v[104:107], a[16:31]
	v_mfma_f32_32x32x16_bf16 a[0:15], v[100:103], v[116:119], a[0:15]
	ds_read_b128 v[100:103], v69 offset:4672
	ds_read_b128 v[104:107], v69 offset:4704
	v_mfma_f32_32x32x16_bf16 a[112:127], v[112:115], v[108:111], a[112:127]
	s_waitcnt lgkmcnt(1)
	v_mfma_f32_32x32x16_bf16 a[96:111], v[112:115], v[100:103], a[96:111]
	ds_read_b128 v[112:115], v59 offset:59968
	ds_read_b128 v[116:119], v59 offset:60000
	s_waitcnt lgkmcnt(1)
	v_mfma_f32_32x32x16_bf16 a[80:95], v[112:115], v[108:111], a[80:95]
	v_mfma_f32_32x32x16_bf16 a[64:79], v[112:115], v[100:103], a[64:79]
	v_mfma_f32_32x32x16_bf16 a[48:63], v[128:131], v[108:111], a[48:63]
	v_mfma_f32_32x32x16_bf16 a[32:47], v[128:131], v[100:103], a[32:47]
	ds_read_b128 v[112:115], v61 offset:55360
	ds_read_b128 v[128:131], v61 offset:55392
	s_waitcnt lgkmcnt(1)
	v_mfma_f32_32x32x16_bf16 a[16:31], v[112:115], v[108:111], a[16:31]
	v_mfma_f32_32x32x16_bf16 a[0:15], v[112:115], v[100:103], a[0:15]
	v_mfma_f32_32x32x16_bf16 a[112:127], v[124:127], v[120:123], a[112:127]
	v_mfma_f32_32x32x16_bf16 a[96:111], v[124:127], v[104:107], a[96:111]
	v_mfma_f32_32x32x16_bf16 a[80:95], v[116:119], v[120:123], a[80:95]
	v_mfma_f32_32x32x16_bf16 a[64:79], v[116:119], v[104:107], a[64:79]
	global_load_dwordx4 v[100:103], v[4:5], off offset:1664
	global_load_dwordx4 v[108:111], v[0:1], off offset:1664
	global_load_dwordx4 v[112:115], v[8:9], off offset:1664
	global_load_dwordx4 v[116:119], v[6:7], off offset:1664
	v_mfma_f32_32x32x16_bf16 a[48:63], v[140:143], v[120:123], a[48:63]
	v_mfma_f32_32x32x16_bf16 a[32:47], v[140:143], v[104:107], a[32:47]
	global_load_dwordx4 v[124:127], v[10:11], off offset:1664
	global_load_dwordx4 v[140:143], v[12:13], off offset:1664
	global_load_dwordx4 v[144:147], v[26:27], off offset:1664
	global_load_dwordx4 v[148:151], v[14:15], off offset:1664
	global_load_dwordx4 v[152:155], v[28:29], off offset:1664
	global_load_dwordx4 v[156:159], v[2:3], off offset:1664
	global_load_dwordx4 v[160:163], v[30:31], off offset:1664
	s_waitcnt lgkmcnt(0)
	v_mfma_f32_32x32x16_bf16 a[16:31], v[128:131], v[120:123], a[16:31]
	global_load_dwordx4 v[120:123], v[32:33], off offset:1664
	s_barrier
	v_mfma_f32_32x32x16_bf16 a[0:15], v[128:131], v[104:107], a[0:15]
	ds_read_b128 v[104:107], v59
	ds_read_b128 v[128:131], v62 offset:36864
	ds_read_b128 v[164:167], v59 offset:4608
	ds_read_b128 v[168:171], v62 offset:41472
	s_waitcnt lgkmcnt(2)
	v_mfma_f32_32x32x16_bf16 a[112:127], v[104:107], v[128:131], a[112:127]
	s_waitcnt lgkmcnt(0)
	v_mfma_f32_32x32x16_bf16 a[96:111], v[104:107], v[168:171], a[96:111]
	ds_read_b128 v[104:107], v59 offset:9216
	s_waitcnt lgkmcnt(0)
	v_mfma_f32_32x32x16_bf16 a[48:63], v[104:107], v[128:131], a[48:63]
	v_mfma_f32_32x32x16_bf16 a[32:47], v[104:107], v[168:171], a[32:47]
	ds_read_b128 v[104:107], v61
	s_waitcnt vmcnt(10)
	ds_write_b128 v60, v[108:111] offset:55296
	ds_write_b128 v60, v[100:103] offset:59904
	s_waitcnt vmcnt(8)
	ds_write_b128 v60, v[116:119] offset:64512
	ds_write_b128 v63, v[112:115] offset:55296
	s_waitcnt vmcnt(7)
	ds_write_b128 v64, v[124:127] offset:55296
	s_waitcnt vmcnt(6)
	ds_write_b128 v65, v[140:143] offset:55296
	s_waitcnt vmcnt(4)
	ds_write_b128 v66, v[148:151] offset:55296
	ds_write_b128 v67, v[144:147] offset:55296
	s_waitcnt vmcnt(2)
	ds_write_b128 v68, v[156:159]
	ds_write_b128 v68, v[152:155] offset:4608
	s_waitcnt vmcnt(1)
	ds_write_b128 v68, v[160:163] offset:9216
	s_waitcnt vmcnt(0)
	ds_write_b128 v68, v[120:123] offset:13824
	v_mfma_f32_32x32x16_bf16 a[80:95], v[164:167], v[128:131], a[80:95]
	v_mfma_f32_32x32x16_bf16 a[64:79], v[164:167], v[168:171], a[64:79]
	s_waitcnt lgkmcnt(12)
	v_mfma_f32_32x32x16_bf16 a[16:31], v[104:107], v[128:131], a[16:31]
	v_mfma_f32_32x32x16_bf16 a[0:15], v[104:107], v[168:171], a[0:15]
	ds_read_b128 v[100:103], v59 offset:32
	ds_read_b128 v[104:107], v62 offset:36896
	ds_read_b128 v[108:111], v62 offset:36928
	ds_read_b128 v[112:115], v59 offset:64
	ds_read_b128 v[116:119], v62 offset:41504
	ds_read_b128 v[120:123], v62 offset:36960
	s_waitcnt lgkmcnt(4)
	v_mfma_f32_32x32x16_bf16 a[112:127], v[100:103], v[104:107], a[112:127]
	s_waitcnt lgkmcnt(1)
	v_mfma_f32_32x32x16_bf16 a[96:111], v[100:103], v[116:119], a[96:111]
	ds_read_b128 v[100:103], v59 offset:4640
	ds_read_b128 v[124:127], v59 offset:96
	s_waitcnt lgkmcnt(1)
	v_mfma_f32_32x32x16_bf16 a[80:95], v[100:103], v[104:107], a[80:95]
	v_mfma_f32_32x32x16_bf16 a[64:79], v[100:103], v[116:119], a[64:79]
	ds_read_b128 v[100:103], v59 offset:9248
	ds_read_b128 v[128:131], v59 offset:9280
	s_waitcnt lgkmcnt(1)
	v_mfma_f32_32x32x16_bf16 a[48:63], v[100:103], v[104:107], a[48:63]
	v_mfma_f32_32x32x16_bf16 a[32:47], v[100:103], v[116:119], a[32:47]
	ds_read_b128 v[100:103], v61 offset:32
	ds_read_b128 v[140:143], v59 offset:9312
	s_waitcnt lgkmcnt(1)
	v_mfma_f32_32x32x16_bf16 a[16:31], v[100:103], v[104:107], a[16:31]
	v_mfma_f32_32x32x16_bf16 a[0:15], v[100:103], v[116:119], a[0:15]
	ds_read_b128 v[100:103], v62 offset:41536
	ds_read_b128 v[104:107], v62 offset:41568
	v_mfma_f32_32x32x16_bf16 a[112:127], v[112:115], v[108:111], a[112:127]
	s_waitcnt lgkmcnt(1)
	v_mfma_f32_32x32x16_bf16 a[96:111], v[112:115], v[100:103], a[96:111]
	ds_read_b128 v[112:115], v59 offset:4672
	ds_read_b128 v[116:119], v59 offset:4704
	s_waitcnt lgkmcnt(1)
	v_mfma_f32_32x32x16_bf16 a[80:95], v[112:115], v[108:111], a[80:95]
	v_mfma_f32_32x32x16_bf16 a[64:79], v[112:115], v[100:103], a[64:79]
	v_mfma_f32_32x32x16_bf16 a[48:63], v[128:131], v[108:111], a[48:63]
	v_mfma_f32_32x32x16_bf16 a[32:47], v[128:131], v[100:103], a[32:47]
	ds_read_b128 v[112:115], v61 offset:64
	ds_read_b128 v[128:131], v61 offset:96
	s_waitcnt lgkmcnt(1)
	v_mfma_f32_32x32x16_bf16 a[16:31], v[112:115], v[108:111], a[16:31]
	v_mfma_f32_32x32x16_bf16 a[0:15], v[112:115], v[100:103], a[0:15]
	global_load_dwordx4 v[100:103], v[32:33], off offset:1792
	v_mfma_f32_32x32x16_bf16 a[112:127], v[124:127], v[120:123], a[112:127]
	v_mfma_f32_32x32x16_bf16 a[96:111], v[124:127], v[104:107], a[96:111]
	v_mfma_f32_32x32x16_bf16 a[80:95], v[116:119], v[120:123], a[80:95]
	v_mfma_f32_32x32x16_bf16 a[64:79], v[116:119], v[104:107], a[64:79]
	v_mfma_f32_32x32x16_bf16 a[48:63], v[140:143], v[120:123], a[48:63]
	v_mfma_f32_32x32x16_bf16 a[32:47], v[140:143], v[104:107], a[32:47]
	global_load_dwordx4 v[108:111], v[30:31], off offset:1792
	global_load_dwordx4 v[112:115], v[28:29], off offset:1792
	global_load_dwordx4 v[116:119], v[2:3], off offset:1792
	global_load_dwordx4 v[124:127], v[8:9], off offset:1792
	global_load_dwordx4 v[140:143], v[6:7], off offset:1792
	global_load_dwordx4 v[144:147], v[4:5], off offset:1792
	global_load_dwordx4 v[148:151], v[0:1], off offset:1792
	s_waitcnt lgkmcnt(0)
	v_mfma_f32_32x32x16_bf16 a[16:31], v[128:131], v[120:123], a[16:31]
	global_load_dwordx4 v[120:123], v[12:13], off offset:1792
	global_load_dwordx4 v[152:155], v[10:11], off offset:1792
	global_load_dwordx4 v[156:159], v[26:27], off offset:1792
	global_load_dwordx4 v[160:163], v[14:15], off offset:1792
	s_barrier
	v_mfma_f32_32x32x16_bf16 a[0:15], v[128:131], v[104:107], a[0:15]
	ds_read_b128 v[104:107], v59 offset:55296
	ds_read_b128 v[128:131], v69
	ds_read_b128 v[164:167], v59 offset:59904
	ds_read_b128 v[168:171], v69 offset:4608
	s_waitcnt lgkmcnt(2)
	v_mfma_f32_32x32x16_bf16 a[112:127], v[104:107], v[128:131], a[112:127]
	s_waitcnt lgkmcnt(0)
	v_mfma_f32_32x32x16_bf16 a[96:111], v[104:107], v[168:171], a[96:111]
	ds_read_b128 v[104:107], v59 offset:64512
	s_waitcnt lgkmcnt(0)
	v_mfma_f32_32x32x16_bf16 a[48:63], v[104:107], v[128:131], a[48:63]
	v_mfma_f32_32x32x16_bf16 a[32:47], v[104:107], v[168:171], a[32:47]
	ds_read_b128 v[104:107], v61 offset:55296
	s_waitcnt vmcnt(4)
	ds_write_b128 v60, v[148:151]
	ds_write_b128 v60, v[144:147] offset:4608
	ds_write_b128 v60, v[140:143] offset:9216
	ds_write_b128 v60, v[124:127] offset:13824
	s_waitcnt vmcnt(2)
	ds_write_b128 v60, v[152:155] offset:18432
	ds_write_b128 v60, v[120:123] offset:23040
	s_waitcnt vmcnt(0)
	ds_write_b128 v60, v[160:163] offset:27648
	ds_write_b128 v60, v[156:159] offset:32256
	ds_write_b128 v60, v[116:119] offset:36864
	ds_write_b128 v60, v[112:115] offset:41472
	ds_write_b128 v60, v[108:111] offset:46080
	ds_write_b128 v60, v[100:103] offset:50688
	v_mfma_f32_32x32x16_bf16 a[80:95], v[164:167], v[128:131], a[80:95]
	v_mfma_f32_32x32x16_bf16 a[64:79], v[164:167], v[168:171], a[64:79]
	s_waitcnt lgkmcnt(12)
	v_mfma_f32_32x32x16_bf16 a[16:31], v[104:107], v[128:131], a[16:31]
	v_mfma_f32_32x32x16_bf16 a[0:15], v[104:107], v[168:171], a[0:15]
	ds_read_b128 v[100:103], v59 offset:55328
	ds_read_b128 v[104:107], v69 offset:32
	ds_read_b128 v[108:111], v69 offset:64
	ds_read_b128 v[112:115], v59 offset:55360
	ds_read_b128 v[116:119], v69 offset:4640
	ds_read_b128 v[120:123], v69 offset:96
	s_waitcnt lgkmcnt(4)
	v_mfma_f32_32x32x16_bf16 a[112:127], v[100:103], v[104:107], a[112:127]
	s_waitcnt lgkmcnt(1)
	v_mfma_f32_32x32x16_bf16 a[96:111], v[100:103], v[116:119], a[96:111]
	ds_read_b128 v[100:103], v59 offset:59936
	ds_read_b128 v[124:127], v59 offset:55392
	s_waitcnt lgkmcnt(1)
	v_mfma_f32_32x32x16_bf16 a[80:95], v[100:103], v[104:107], a[80:95]
	v_mfma_f32_32x32x16_bf16 a[64:79], v[100:103], v[116:119], a[64:79]
	ds_read_b128 v[100:103], v59 offset:64544
	ds_read_b128 v[128:131], v59 offset:64576
	s_waitcnt lgkmcnt(1)
	v_mfma_f32_32x32x16_bf16 a[48:63], v[100:103], v[104:107], a[48:63]
	v_mfma_f32_32x32x16_bf16 a[32:47], v[100:103], v[116:119], a[32:47]
	ds_read_b128 v[100:103], v61 offset:55328
	ds_read_b128 v[140:143], v59 offset:64608
	s_waitcnt lgkmcnt(1)
	v_mfma_f32_32x32x16_bf16 a[16:31], v[100:103], v[104:107], a[16:31]
	v_mfma_f32_32x32x16_bf16 a[0:15], v[100:103], v[116:119], a[0:15]
	ds_read_b128 v[100:103], v69 offset:4672
	ds_read_b128 v[104:107], v69 offset:4704
	v_mfma_f32_32x32x16_bf16 a[112:127], v[112:115], v[108:111], a[112:127]
	s_waitcnt lgkmcnt(1)
	v_mfma_f32_32x32x16_bf16 a[96:111], v[112:115], v[100:103], a[96:111]
	ds_read_b128 v[112:115], v59 offset:59968
	ds_read_b128 v[116:119], v59 offset:60000
	s_waitcnt lgkmcnt(1)
	v_mfma_f32_32x32x16_bf16 a[80:95], v[112:115], v[108:111], a[80:95]
	v_mfma_f32_32x32x16_bf16 a[64:79], v[112:115], v[100:103], a[64:79]
	v_mfma_f32_32x32x16_bf16 a[48:63], v[128:131], v[108:111], a[48:63]
	v_mfma_f32_32x32x16_bf16 a[32:47], v[128:131], v[100:103], a[32:47]
	ds_read_b128 v[112:115], v61 offset:55360
	ds_read_b128 v[128:131], v61 offset:55392
	s_waitcnt lgkmcnt(1)
	v_mfma_f32_32x32x16_bf16 a[16:31], v[112:115], v[108:111], a[16:31]
	v_mfma_f32_32x32x16_bf16 a[0:15], v[112:115], v[100:103], a[0:15]
	global_load_dwordx4 v[100:103], v[4:5], off offset:1920
	global_load_dwordx4 v[108:111], v[0:1], off offset:1920
	global_load_dwordx4 v[112:115], v[8:9], off offset:1920
	s_nop 0
	global_load_dwordx4 v[4:7], v[6:7], off offset:1920
	v_mfma_f32_32x32x16_bf16 a[112:127], v[124:127], v[120:123], a[112:127]
	v_mfma_f32_32x32x16_bf16 a[96:111], v[124:127], v[104:107], a[96:111]
	v_mfma_f32_32x32x16_bf16 a[80:95], v[116:119], v[120:123], a[80:95]
	v_mfma_f32_32x32x16_bf16 a[64:79], v[116:119], v[104:107], a[64:79]
	v_mfma_f32_32x32x16_bf16 a[48:63], v[140:143], v[120:123], a[48:63]
	v_mfma_f32_32x32x16_bf16 a[32:47], v[140:143], v[104:107], a[32:47]
	global_load_dwordx4 v[8:11], v[10:11], off offset:1920
	s_nop 0
	global_load_dwordx4 v[116:119], v[12:13], off offset:1920
	global_load_dwordx4 v[124:127], v[26:27], off offset:1920
	s_nop 0
	global_load_dwordx4 v[12:15], v[14:15], off offset:1920
	s_nop 0
	global_load_dwordx4 v[26:29], v[28:29], off offset:1920
	s_nop 0
	global_load_dwordx4 v[0:3], v[2:3], off offset:1920
	s_nop 0
	global_load_dwordx4 v[140:143], v[30:31], off offset:1920
	s_nop 0
	global_load_dwordx4 v[30:33], v[32:33], off offset:1920
	s_waitcnt lgkmcnt(0)
	s_barrier
	v_mfma_f32_32x32x16_bf16 a[16:31], v[128:131], v[120:123], a[16:31]
	v_mfma_f32_32x32x16_bf16 a[0:15], v[128:131], v[104:107], a[0:15]
	ds_read_b128 v[104:107], v59
	ds_read_b128 v[120:123], v62 offset:36864
	ds_read_b128 v[128:131], v59 offset:4608
	ds_read_b128 v[144:147], v62 offset:41472
	s_waitcnt lgkmcnt(2)
	v_mfma_f32_32x32x16_bf16 a[112:127], v[104:107], v[120:123], a[112:127]
	s_waitcnt lgkmcnt(0)
	v_mfma_f32_32x32x16_bf16 a[96:111], v[104:107], v[144:147], a[96:111]
	v_mfma_f32_32x32x16_bf16 a[80:95], v[128:131], v[120:123], a[80:95]
	v_mfma_f32_32x32x16_bf16 a[64:79], v[128:131], v[144:147], a[64:79]
	ds_read_b128 v[104:107], v59 offset:9216
	ds_read_b128 v[128:131], v61
	s_waitcnt vmcnt(10)
	ds_write_b128 v60, v[108:111] offset:55296
	ds_write_b128 v60, v[100:103] offset:59904
	s_waitcnt vmcnt(8)
	ds_write_b128 v60, v[4:7] offset:64512
	ds_write_b128 v63, v[112:115] offset:55296
	s_waitcnt vmcnt(7)
	ds_write_b128 v64, v[8:11] offset:55296
	s_waitcnt vmcnt(6)
	ds_write_b128 v65, v[116:119] offset:55296
	s_waitcnt vmcnt(4)
	ds_write_b128 v66, v[12:15] offset:55296
	ds_write_b128 v67, v[124:127] offset:55296
	s_waitcnt vmcnt(2)
	ds_write_b128 v68, v[0:3]
	ds_write_b128 v68, v[26:29] offset:4608
	s_waitcnt vmcnt(1)
	ds_write_b128 v68, v[140:143] offset:9216
	s_waitcnt vmcnt(0)
	ds_write_b128 v68, v[30:33] offset:13824
	ds_read_b128 v[0:3], v59 offset:32
	ds_read_b128 v[4:7], v62 offset:36896
	ds_read_b128 v[8:11], v62 offset:36928
	ds_read_b128 v[12:15], v59 offset:64
	ds_read_b128 v[26:29], v62 offset:41504
	ds_read_b128 v[30:33], v62 offset:36960
	s_waitcnt lgkmcnt(14)
	v_mfma_f32_32x32x16_bf16 a[48:63], v[104:107], v[120:123], a[48:63]
	v_mfma_f32_32x32x16_bf16 a[32:47], v[104:107], v[144:147], a[32:47]
	s_waitcnt lgkmcnt(4)
	v_mfma_f32_32x32x16_bf16 a[112:127], v[0:3], v[4:7], a[112:127]
	s_waitcnt lgkmcnt(1)
	v_mfma_f32_32x32x16_bf16 a[96:111], v[0:3], v[26:29], a[96:111]
	ds_read_b128 v[0:3], v59 offset:4640
	ds_read_b128 v[100:103], v59 offset:96
	v_mfma_f32_32x32x16_bf16 a[16:31], v[128:131], v[120:123], a[16:31]
	v_mfma_f32_32x32x16_bf16 a[0:15], v[128:131], v[144:147], a[0:15]
	s_waitcnt lgkmcnt(1)
	v_mfma_f32_32x32x16_bf16 a[80:95], v[0:3], v[4:7], a[80:95]
	v_mfma_f32_32x32x16_bf16 a[64:79], v[0:3], v[26:29], a[64:79]
	ds_read_b128 v[0:3], v59 offset:9248
	ds_read_b128 v[104:107], v59 offset:9280
	s_waitcnt lgkmcnt(1)
	v_mfma_f32_32x32x16_bf16 a[48:63], v[0:3], v[4:7], a[48:63]
	v_mfma_f32_32x32x16_bf16 a[32:47], v[0:3], v[26:29], a[32:47]
	ds_read_b128 v[0:3], v61 offset:32
	ds_read_b128 v[108:111], v59 offset:9312
	s_waitcnt lgkmcnt(1)
	v_mfma_f32_32x32x16_bf16 a[16:31], v[0:3], v[4:7], a[16:31]
	v_mfma_f32_32x32x16_bf16 a[0:15], v[0:3], v[26:29], a[0:15]
	ds_read_b128 v[0:3], v62 offset:41536
	ds_read_b128 v[4:7], v62 offset:41568
	v_mfma_f32_32x32x16_bf16 a[112:127], v[12:15], v[8:11], a[112:127]
	s_waitcnt lgkmcnt(1)
	v_mfma_f32_32x32x16_bf16 a[96:111], v[12:15], v[0:3], a[96:111]
	ds_read_b128 v[12:15], v59 offset:4672
	ds_read_b128 v[26:29], v59 offset:4704
	s_waitcnt lgkmcnt(1)
	v_mfma_f32_32x32x16_bf16 a[80:95], v[12:15], v[8:11], a[80:95]
	v_mfma_f32_32x32x16_bf16 a[64:79], v[12:15], v[0:3], a[64:79]
	v_mfma_f32_32x32x16_bf16 a[48:63], v[104:107], v[8:11], a[48:63]
	v_mfma_f32_32x32x16_bf16 a[32:47], v[104:107], v[0:3], a[32:47]
	ds_read_b128 v[12:15], v61 offset:64
	ds_read_b128 v[104:107], v61 offset:96
	s_waitcnt lgkmcnt(0)
	s_barrier
	v_mfma_f32_32x32x16_bf16 a[16:31], v[12:15], v[8:11], a[16:31]
	v_mfma_f32_32x32x16_bf16 a[0:15], v[12:15], v[0:3], a[0:15]
	v_mfma_f32_32x32x16_bf16 a[112:127], v[100:103], v[30:33], a[112:127]
	v_mfma_f32_32x32x16_bf16 a[96:111], v[100:103], v[4:7], a[96:111]
	v_mfma_f32_32x32x16_bf16 a[80:95], v[26:29], v[30:33], a[80:95]
	v_mfma_f32_32x32x16_bf16 a[64:79], v[26:29], v[4:7], a[64:79]
	v_mfma_f32_32x32x16_bf16 a[48:63], v[108:111], v[30:33], a[48:63]
	v_mfma_f32_32x32x16_bf16 a[32:47], v[108:111], v[4:7], a[32:47]
	v_mfma_f32_32x32x16_bf16 a[16:31], v[104:107], v[30:33], a[16:31]
	v_mfma_f32_32x32x16_bf16 a[0:15], v[104:107], v[4:7], a[0:15]
	ds_read_b128 v[0:3], v59 offset:55296
	ds_read_b128 v[4:7], v69
	ds_read_b128 v[8:11], v59 offset:55328
	ds_read_b128 v[12:15], v69 offset:32
	ds_read_b128 v[26:29], v69 offset:4608
	ds_read_b128 v[30:33], v69 offset:4640
	s_waitcnt lgkmcnt(4)
	v_mfma_f32_32x32x16_bf16 a[112:127], v[0:3], v[4:7], a[112:127]
	s_waitcnt lgkmcnt(1)
	v_mfma_f32_32x32x16_bf16 a[96:111], v[0:3], v[26:29], a[96:111]
	ds_read_b128 v[0:3], v59 offset:59904
	ds_read_b128 v[100:103], v59 offset:59936
	s_waitcnt lgkmcnt(1)
	v_mfma_f32_32x32x16_bf16 a[80:95], v[0:3], v[4:7], a[80:95]
	v_mfma_f32_32x32x16_bf16 a[64:79], v[0:3], v[26:29], a[64:79]
	ds_read_b128 v[0:3], v59 offset:64512
	ds_read_b128 v[104:107], v59 offset:64544
	s_waitcnt lgkmcnt(1)
	v_mfma_f32_32x32x16_bf16 a[48:63], v[0:3], v[4:7], a[48:63]
	v_mfma_f32_32x32x16_bf16 a[32:47], v[0:3], v[26:29], a[32:47]
	ds_read_b128 v[0:3], v61 offset:55296
	ds_read_b128 v[108:111], v61 offset:55328
	s_waitcnt lgkmcnt(1)
	v_mfma_f32_32x32x16_bf16 a[0:15], v[0:3], v[26:29], a[0:15]
	v_mfma_f32_32x32x16_bf16 a[112:127], v[8:11], v[12:15], a[112:127]
	v_mfma_f32_32x32x16_bf16 a[96:111], v[8:11], v[30:33], a[96:111]
	v_mfma_f32_32x32x16_bf16 a[16:31], v[0:3], v[4:7], a[16:31]
	v_mfma_f32_32x32x16_bf16 a[80:95], v[100:103], v[12:15], a[80:95]
	v_mfma_f32_32x32x16_bf16 a[64:79], v[100:103], v[30:33], a[64:79]
	v_mfma_f32_32x32x16_bf16 a[32:47], v[104:107], v[30:33], a[32:47]
	s_waitcnt lgkmcnt(0)
	v_mfma_f32_32x32x16_bf16 a[0:15], v[108:111], v[30:33], a[0:15]
	ds_read_b128 v[8:11], v59 offset:55360
	ds_read_b128 v[26:29], v69 offset:64
	ds_read_b128 v[30:33], v59 offset:55392
	ds_read_b128 v[4:7], v69 offset:96
	ds_read_b128 v[100:103], v69 offset:4672
	ds_read_b128 v[0:3], v69 offset:4704
	v_mfma_f32_32x32x16_bf16 a[48:63], v[104:107], v[12:15], a[48:63]
	s_waitcnt lgkmcnt(4)
	v_mfma_f32_32x32x16_bf16 a[112:127], v[8:11], v[26:29], a[112:127]
	s_waitcnt lgkmcnt(1)
	v_mfma_f32_32x32x16_bf16 a[96:111], v[8:11], v[100:103], a[96:111]
	ds_read_b128 v[8:11], v59 offset:59968
	ds_read_b128 v[104:107], v59 offset:60000
	v_mfma_f32_32x32x16_bf16 a[16:31], v[108:111], v[12:15], a[16:31]
	s_waitcnt lgkmcnt(1)
	v_mfma_f32_32x32x16_bf16 a[80:95], v[8:11], v[26:29], a[80:95]
	v_mfma_f32_32x32x16_bf16 a[64:79], v[8:11], v[100:103], a[64:79]
	ds_read_b128 v[8:11], v59 offset:64576
	ds_read_b128 v[12:15], v59 offset:64608
	s_waitcnt lgkmcnt(1)
	v_mfma_f32_32x32x16_bf16 a[48:63], v[8:11], v[26:29], a[48:63]
	v_mfma_f32_32x32x16_bf16 a[32:47], v[8:11], v[100:103], a[32:47]
	ds_read_b128 v[108:111], v61 offset:55360
	ds_read_b128 v[8:11], v61 offset:55392
	s_waitcnt lgkmcnt(0)
	s_barrier
	v_mfma_f32_32x32x16_bf16 a[16:31], v[108:111], v[26:29], a[16:31]
	v_or_b32_e32 v28, s14, v139
	v_lshl_add_u64 v[26:27], v[22:23], 0, s[4:5]
	v_or_b32_e32 v29, s14, v204
	v_mfma_f32_32x32x16_bf16 a[0:15], v[108:111], v[100:103], a[0:15]
	v_mfma_f32_32x32x16_bf16 a[112:127], v[30:33], v[4:7], a[112:127]
	v_mfma_f32_32x32x16_bf16 a[48:63], v[12:15], v[4:7], a[48:63]
	v_mfma_f32_32x32x16_bf16 a[32:47], v[12:15], v[0:3], a[32:47]
	v_lshl_add_u64 v[12:13], v[16:17], 2, v[26:27]
	v_lshlrev_b32_e32 v16, 10, v28
	v_lshl_add_u64 v[14:15], s[16:17], 0, v[24:25]
	v_add_co_u32_e32 v14, vcc, s11, v14
	s_nop 1
	v_addc_co_u32_e32 v15, vcc, 0, v15, vcc
	v_mfma_f32_32x32x16_bf16 a[96:111], v[30:33], v[0:3], a[96:111]
	v_or_b32_e32 v30, s14, v205
	v_lshl_add_u64 v[32:33], v[16:17], 2, v[26:27]
	v_lshlrev_b32_e32 v16, 10, v29
	v_mfma_f32_32x32x16_bf16 a[80:95], v[104:107], v[4:7], a[80:95]
	v_mfma_f32_32x32x16_bf16 a[64:79], v[104:107], v[0:3], a[64:79]
	v_lshl_add_u64 v[104:105], v[16:17], 2, v[26:27]
	v_lshlrev_b32_e32 v16, 10, v30
	v_lshl_add_u64 v[106:107], v[16:17], 2, v[26:27]
	v_mfma_f32_32x32x16_bf16 a[16:31], v[8:11], v[4:7], a[16:31]
	v_mfma_f32_32x32x16_bf16 a[0:15], v[8:11], v[0:3], a[0:15]
	v_mov_b32_e32 v144, v14
	v_mov_b32_e32 v145, v15
	v_mov_b32_e32 v146, v16
	v_mov_b32_e32 v147, v17
	v_mov_b32_e32 v148, v28
	v_mov_b32_e32 v149, v29
	v_mov_b32_e32 v150, v32
	v_mov_b32_e32 v151, v33
	v_mov_b32_e32 v152, v104
	v_mov_b32_e32 v153, v105
	v_mov_b32_e32 v154, v106
	v_mov_b32_e32 v155, v107
	v_mov_b32_e32 v156, v108
	v_mov_b32_e32 v157, v109
	v_mov_b32_e32 v158, v110
	v_mov_b32_e32 v159, v111
	global_load_dwordx4 v[250:253], v[144:145], off
	global_load_dwordx4 v[246:249], v[150:151], off
	global_load_dwordx4 v[242:245], v[152:153], off
	global_load_dwordx4 v[238:241], v[154:155], off
	global_load_dwordx4 v[234:237], v[12:13], off
	v_or_b32_e32 v144, s14, v206
	v_lshlrev_b32_e32 v146, 10, v144
	v_lshl_add_u64 v[144:145], v[146:147], 2, v[26:27]
	v_or_b32_e32 v146, s14, v207
	v_lshlrev_b32_e32 v146, 10, v146
	global_load_dwordx4 v[212:215], v[144:145], off
	v_or_b32_e32 v148, s14, v208
	v_or_b32_e32 v149, s14, v209
	v_lshl_add_u64 v[150:151], v[146:147], 2, v[26:27]
	v_lshlrev_b32_e32 v146, 10, v148
	v_lshl_add_u64 v[152:153], v[146:147], 2, v[26:27]
	v_lshlrev_b32_e32 v146, 10, v149
	v_lshl_add_u64 v[154:155], v[146:147], 2, v[26:27]
	global_load_dwordx4 v[200:203], v[150:151], off
	global_load_dwordx4 v[196:199], v[152:153], off
	global_load_dwordx4 v[192:195], v[154:155], off
	v_or_b32_e32 v144, s14, v210
	v_lshlrev_b32_e32 v146, 10, v144
	v_lshl_add_u64 v[144:145], v[146:147], 2, v[26:27]
	v_or_b32_e32 v146, s14, v35
	v_lshlrev_b32_e32 v146, 10, v146
	global_load_dwordx4 v[188:191], v[144:145], off
	v_or_b32_e32 v148, s14, v36
	v_or_b32_e32 v149, s14, v37
	v_lshl_add_u64 v[150:151], v[146:147], 2, v[26:27]
	v_lshlrev_b32_e32 v146, 10, v148
	v_lshl_add_u64 v[152:153], v[146:147], 2, v[26:27]
	v_lshlrev_b32_e32 v146, 10, v149
	v_lshl_add_u64 v[154:155], v[146:147], 2, v[26:27]
	global_load_dwordx4 v[184:187], v[150:151], off
	global_load_dwordx4 v[180:183], v[152:153], off
	global_load_dwordx4 v[176:179], v[154:155], off
	v_or_b32_e32 v144, s14, v38
	v_lshlrev_b32_e32 v146, 10, v144
	v_lshl_add_u64 v[144:145], v[146:147], 2, v[26:27]
	v_or_b32_e32 v146, s14, v39
	v_lshlrev_b32_e32 v146, 10, v146
	global_load_dwordx4 v[172:175], v[144:145], off
	v_or_b32_e32 v148, s14, v40
	v_or_b32_e32 v149, s14, v41
	v_lshl_add_u64 v[150:151], v[146:147], 2, v[26:27]
	v_lshlrev_b32_e32 v146, 10, v148
	v_lshl_add_u64 v[156:157], v[146:147], 2, v[26:27]
	v_lshlrev_b32_e32 v146, 10, v149
	v_lshl_add_u64 v[158:159], v[146:147], 2, v[26:27]
	global_load_dwordx4 v[168:171], v[150:151], off
	global_load_dwordx4 v[164:167], v[156:157], off
	global_load_dwordx4 v[160:163], v[158:159], off
	ds_write_b32 v58, a112
	ds_write_b32 v58, a113 offset:516
	ds_write_b32 v58, a114 offset:1032
	ds_write_b32 v58, a115 offset:1548
	ds_write_b32 v58, a116 offset:4128
	ds_write_b32 v58, a117 offset:4644
	ds_write_b32 v58, a118 offset:5160
	ds_write_b32 v58, a119 offset:5676
	ds_write_b32 v58, a120 offset:8256
	ds_write_b32 v58, a121 offset:8772
	ds_write_b32 v58, a122 offset:9288
	ds_write_b32 v58, a123 offset:9804
	ds_write_b32 v58, a124 offset:12384
	ds_write_b32 v58, a125 offset:12900
	ds_write_b32 v58, a126 offset:13416
	ds_write_b32 v58, a127 offset:13932
	ds_write_b32 v58, a96 offset:128
	ds_write_b32 v58, a97 offset:644
	ds_write_b32 v58, a98 offset:1160
	ds_write_b32 v58, a99 offset:1676
	ds_write_b32 v58, a100 offset:4256
	ds_write_b32 v58, a101 offset:4772
	ds_write_b32 v58, a102 offset:5288
	ds_write_b32 v58, a103 offset:5804
	ds_write_b32 v58, a104 offset:8384
	ds_write_b32 v58, a105 offset:8900
	ds_write_b32 v58, a106 offset:9416
	ds_write_b32 v58, a107 offset:9932
	ds_write_b32 v58, a108 offset:12512
	ds_write_b32 v58, a109 offset:13028
	ds_write_b32 v58, a110 offset:13544
	ds_write_b32 v58, a111 offset:14060
	ds_write_b32 v58, a80 offset:16512
	ds_write_b32 v58, a81 offset:17028
	ds_write_b32 v58, a82 offset:17544
	ds_write_b32 v58, a83 offset:18060
	ds_write_b32 v58, a84 offset:20640
	ds_write_b32 v58, a85 offset:21156
	ds_write_b32 v58, a86 offset:21672
	ds_write_b32 v58, a87 offset:22188
	ds_write_b32 v58, a88 offset:24768
	ds_write_b32 v58, a89 offset:25284
	ds_write_b32 v58, a90 offset:25800
	ds_write_b32 v58, a91 offset:26316
	ds_write_b32 v58, a92 offset:28896
	ds_write_b32 v58, a93 offset:29412
	ds_write_b32 v58, a94 offset:29928
	ds_write_b32 v58, a95 offset:30444
	ds_write_b32 v58, a64 offset:16640
	ds_write_b32 v58, a65 offset:17156
	ds_write_b32 v58, a66 offset:17672
	ds_write_b32 v58, a67 offset:18188
	ds_write_b32 v58, a68 offset:20768
	ds_write_b32 v58, a69 offset:21284
	ds_write_b32 v58, a70 offset:21800
	ds_write_b32 v58, a71 offset:22316
	ds_write_b32 v58, a72 offset:24896
	ds_write_b32 v58, a73 offset:25412
	ds_write_b32 v58, a74 offset:25928
	ds_write_b32 v58, a75 offset:26444
	ds_write_b32 v58, a76 offset:29024
	ds_write_b32 v58, a77 offset:29540
	ds_write_b32 v58, a78 offset:30056
	ds_write_b32 v58, a79 offset:30572
	ds_write_b32 v58, a48 offset:33024
	ds_write_b32 v58, a49 offset:33540
	ds_write_b32 v58, a50 offset:34056
	ds_write_b32 v58, a51 offset:34572
	ds_write_b32 v58, a52 offset:37152
	ds_write_b32 v58, a53 offset:37668
	ds_write_b32 v58, a54 offset:38184
	ds_write_b32 v58, a55 offset:38700
	ds_write_b32 v58, a56 offset:41280
	ds_write_b32 v58, a57 offset:41796
	ds_write_b32 v58, a58 offset:42312
	ds_write_b32 v58, a59 offset:42828
	ds_write_b32 v58, a60 offset:45408
	ds_write_b32 v58, a61 offset:45924
	ds_write_b32 v58, a62 offset:46440
	ds_write_b32 v58, a63 offset:46956
	ds_write_b32 v58, a32 offset:33152
	ds_write_b32 v58, a33 offset:33668
	ds_write_b32 v58, a34 offset:34184
	ds_write_b32 v58, a35 offset:34700
	ds_write_b32 v58, a36 offset:37280
	ds_write_b32 v58, a37 offset:37796
	ds_write_b32 v58, a38 offset:38312
	ds_write_b32 v58, a39 offset:38828
	ds_write_b32 v58, a40 offset:41408
	ds_write_b32 v58, a41 offset:41924
	ds_write_b32 v58, a42 offset:42440
	ds_write_b32 v58, a43 offset:42956
	ds_write_b32 v58, a44 offset:45536
	ds_write_b32 v58, a45 offset:46052
	ds_write_b32 v58, a46 offset:46568
	ds_write_b32 v58, a47 offset:47084
	ds_write_b32 v58, a16 offset:49536
	ds_write_b32 v58, a17 offset:50052
	ds_write_b32 v58, a18 offset:50568
	ds_write_b32 v58, a19 offset:51084
	ds_write_b32 v58, a20 offset:53664
	ds_write_b32 v58, a21 offset:54180
	ds_write_b32 v58, a22 offset:54696
	ds_write_b32 v58, a23 offset:55212
	ds_write_b32 v58, a24 offset:57792
	ds_write_b32 v58, a25 offset:58308
	ds_write_b32 v58, a26 offset:58824
	ds_write_b32 v58, a27 offset:59340
	ds_write_b32 v58, a28 offset:61920
	ds_write_b32 v58, a29 offset:62436
	ds_write_b32 v58, a30 offset:62952
	ds_write_b32 v58, a31 offset:63468
	ds_write_b32 v58, a0 offset:49664
	ds_write_b32 v58, a1 offset:50180
	ds_write_b32 v58, a2 offset:50696
	ds_write_b32 v58, a3 offset:51212
	ds_write_b32 v58, a4 offset:53792
	ds_write_b32 v58, a5 offset:54308
	ds_write_b32 v58, a6 offset:54824
	ds_write_b32 v58, a7 offset:55340
	ds_write_b32 v58, a8 offset:57920
	ds_write_b32 v58, a9 offset:58436
	ds_write_b32 v58, a10 offset:58952
	ds_write_b32 v58, a11 offset:59468
	ds_write_b32 v58, a12 offset:62048
	ds_write_b32 v58, a13 offset:62564
	ds_write_b32 v58, a14 offset:63080
	ds_write_b32 v58, a15 offset:63596
	s_waitcnt lgkmcnt(0)
	s_barrier
	s_waitcnt vmcnt(16)
	s_nop 1
	v_mov_b64_e32 v[0:1], v[250:251]
	v_mov_b64_e32 v[2:3], v[252:253]
	s_waitcnt vmcnt(15)
	s_nop 1
	v_mov_b64_e32 v[8:9], v[246:247]
	v_mov_b64_e32 v[10:11], v[248:249]
	s_waitcnt vmcnt(14)
	s_nop 1
	v_mov_b64_e32 v[28:29], v[242:243]
	v_mov_b64_e32 v[30:31], v[244:245]
	s_waitcnt vmcnt(13)
	s_nop 1
	v_mov_b64_e32 v[100:101], v[238:239]
	v_mov_b64_e32 v[102:103], v[240:241]
	s_waitcnt vmcnt(12)
	s_nop 1
	v_mov_b64_e32 v[4:5], v[234:235]
	v_mov_b64_e32 v[6:7], v[236:237]
	ds_read2_b32 v[108:109], v70 offset1:1
	ds_read2_b32 v[110:111], v71 offset1:1
	ds_read2_b32 v[112:113], v72 offset1:1
	ds_read2_b32 v[114:115], v73 offset1:1
	ds_read2_b32 v[116:117], v74 offset1:1
	ds_read2_b32 v[118:119], v75 offset1:1
	ds_read2_b32 v[120:121], v76 offset1:1
	ds_read2_b32 v[122:123], v77 offset1:1
	v_or_b32_e32 v14, s14, v206
	v_lshlrev_b32_e32 v16, 10, v14
	v_lshl_add_u64 v[14:15], v[16:17], 2, v[26:27]
	v_or_b32_e32 v16, s14, v207
	v_lshlrev_b32_e32 v16, 10, v16
	s_waitcnt lgkmcnt(6)
	v_pk_fma_f32 v[10:11], v[2:3], v[110:111], v[10:11]
	v_pk_fma_f32 v[8:9], v[0:1], v[108:109], v[8:9]
	s_waitcnt lgkmcnt(4)
	v_pk_fma_f32 v[30:31], v[2:3], v[114:115], v[30:31]
	v_pk_fma_f32 v[28:29], v[0:1], v[112:113], v[28:29]
	s_waitcnt lgkmcnt(2)
	v_pk_fma_f32 v[102:103], v[2:3], v[118:119], v[102:103]
	v_pk_fma_f32 v[100:101], v[0:1], v[116:117], v[100:101]
	global_store_dwordx4 v[32:33], v[8:11], off
	global_store_dwordx4 v[104:105], v[28:31], off
	global_store_dwordx4 v[106:107], v[100:103], off
	s_waitcnt vmcnt(14)
	s_nop 1
	v_mov_b64_e32 v[8:9], v[212:213]
	v_mov_b64_e32 v[10:11], v[214:215]
	v_or_b32_e32 v28, s14, v208
	v_or_b32_e32 v29, s14, v209
	v_lshl_add_u64 v[32:33], v[16:17], 2, v[26:27]
	v_lshlrev_b32_e32 v16, 10, v28
	v_lshl_add_u64 v[104:105], v[16:17], 2, v[26:27]
	v_lshlrev_b32_e32 v16, 10, v29
	v_lshl_add_u64 v[106:107], v[16:17], 2, v[26:27]
	s_waitcnt lgkmcnt(0)
	v_pk_fma_f32 v[10:11], v[2:3], v[122:123], v[10:11]
	v_pk_fma_f32 v[8:9], v[0:1], v[120:121], v[8:9]
	global_store_dwordx4 v[14:15], v[8:11], off
	s_waitcnt vmcnt(14)
	s_nop 1
	v_mov_b64_e32 v[8:9], v[200:201]
	v_mov_b64_e32 v[10:11], v[202:203]
	s_nop 0
	s_waitcnt vmcnt(13)
	s_nop 1
	v_mov_b64_e32 v[28:29], v[196:197]
	v_mov_b64_e32 v[30:31], v[198:199]
	s_waitcnt vmcnt(12)
	s_nop 1
	v_mov_b64_e32 v[100:101], v[192:193]
	v_mov_b64_e32 v[102:103], v[194:195]
	ds_read2_b32 v[108:109], v78 offset1:1
	ds_read2_b32 v[110:111], v79 offset1:1
	ds_read2_b32 v[112:113], v80 offset1:1
	ds_read2_b32 v[114:115], v81 offset1:1
	ds_read2_b32 v[116:117], v82 offset1:1
	ds_read2_b32 v[118:119], v83 offset1:1
	ds_read2_b32 v[120:121], v84 offset1:1
	ds_read2_b32 v[122:123], v85 offset1:1
	v_or_b32_e32 v14, s14, v210
	v_lshlrev_b32_e32 v16, 10, v14
	v_lshl_add_u64 v[14:15], v[16:17], 2, v[26:27]
	v_or_b32_e32 v16, s14, v35
	v_lshlrev_b32_e32 v16, 10, v16
	s_waitcnt lgkmcnt(6)
	v_pk_fma_f32 v[10:11], v[2:3], v[110:111], v[10:11]
	v_pk_fma_f32 v[8:9], v[0:1], v[108:109], v[8:9]
	s_waitcnt lgkmcnt(4)
	v_pk_fma_f32 v[30:31], v[2:3], v[114:115], v[30:31]
	v_pk_fma_f32 v[28:29], v[0:1], v[112:113], v[28:29]
	s_waitcnt lgkmcnt(2)
	v_pk_fma_f32 v[102:103], v[2:3], v[118:119], v[102:103]
	v_pk_fma_f32 v[100:101], v[0:1], v[116:117], v[100:101]
	global_store_dwordx4 v[32:33], v[8:11], off
	global_store_dwordx4 v[104:105], v[28:31], off
	global_store_dwordx4 v[106:107], v[100:103], off
	s_waitcnt vmcnt(14)
	s_nop 1
	v_mov_b64_e32 v[8:9], v[188:189]
	v_mov_b64_e32 v[10:11], v[190:191]
	v_or_b32_e32 v28, s14, v36
	v_or_b32_e32 v29, s14, v37
	v_lshl_add_u64 v[32:33], v[16:17], 2, v[26:27]
	v_lshlrev_b32_e32 v16, 10, v28
	v_lshl_add_u64 v[104:105], v[16:17], 2, v[26:27]
	v_lshlrev_b32_e32 v16, 10, v29
	v_lshl_add_u64 v[106:107], v[16:17], 2, v[26:27]
	s_waitcnt lgkmcnt(0)
	v_pk_fma_f32 v[10:11], v[2:3], v[122:123], v[10:11]
	v_pk_fma_f32 v[8:9], v[0:1], v[120:121], v[8:9]
	global_store_dwordx4 v[14:15], v[8:11], off
	s_waitcnt vmcnt(14)
	s_nop 1
	v_mov_b64_e32 v[8:9], v[184:185]
	v_mov_b64_e32 v[10:11], v[186:187]
	s_nop 0
	s_waitcnt vmcnt(13)
	s_nop 1
	v_mov_b64_e32 v[28:29], v[180:181]
	v_mov_b64_e32 v[30:31], v[182:183]
	s_waitcnt vmcnt(12)
	s_nop 1
	v_mov_b64_e32 v[100:101], v[176:177]
	v_mov_b64_e32 v[102:103], v[178:179]
	ds_read2_b32 v[108:109], v86 offset1:1
	ds_read2_b32 v[110:111], v87 offset1:1
	ds_read2_b32 v[112:113], v88 offset1:1
	ds_read2_b32 v[114:115], v89 offset1:1
	ds_read2_b32 v[116:117], v90 offset1:1
	ds_read2_b32 v[118:119], v91 offset1:1
	ds_read2_b32 v[120:121], v92 offset1:1
	ds_read2_b32 v[122:123], v93 offset1:1
	v_or_b32_e32 v14, s14, v38
	v_lshlrev_b32_e32 v16, 10, v14
	v_lshl_add_u64 v[14:15], v[16:17], 2, v[26:27]
	v_or_b32_e32 v16, s14, v39
	v_lshlrev_b32_e32 v16, 10, v16
	s_waitcnt lgkmcnt(6)
	v_pk_fma_f32 v[10:11], v[2:3], v[110:111], v[10:11]
	v_pk_fma_f32 v[8:9], v[0:1], v[108:109], v[8:9]
	s_waitcnt lgkmcnt(4)
	v_pk_fma_f32 v[30:31], v[2:3], v[114:115], v[30:31]
	v_pk_fma_f32 v[28:29], v[0:1], v[112:113], v[28:29]
	s_waitcnt lgkmcnt(2)
	v_pk_fma_f32 v[102:103], v[2:3], v[118:119], v[102:103]
	v_pk_fma_f32 v[100:101], v[0:1], v[116:117], v[100:101]
	global_store_dwordx4 v[32:33], v[8:11], off
	global_store_dwordx4 v[104:105], v[28:31], off
	global_store_dwordx4 v[106:107], v[100:103], off
	s_waitcnt vmcnt(14)
	s_nop 1
	v_mov_b64_e32 v[8:9], v[172:173]
	v_mov_b64_e32 v[10:11], v[174:175]
	v_or_b32_e32 v28, s14, v40
	v_or_b32_e32 v29, s14, v41
	v_lshl_add_u64 v[32:33], v[16:17], 2, v[26:27]
	v_lshlrev_b32_e32 v16, 10, v28
	v_lshl_add_u64 v[108:109], v[16:17], 2, v[26:27]
	v_lshlrev_b32_e32 v16, 10, v29
	v_lshl_add_u64 v[110:111], v[16:17], 2, v[26:27]
	s_bitset1_b32 s14, 7
	s_add_u32 s13, s2, s13
	s_addc_u32 s15, s3, s12
	s_add_u32 s12, s13, s4
	s_addc_u32 s13, s15, 0
	s_add_i32 s6, s6, s77
	s_cmpk_lt_u32 s6, 0x60
	s_waitcnt lgkmcnt(0)
	v_pk_fma_f32 v[10:11], v[2:3], v[122:123], v[10:11]
	v_pk_fma_f32 v[8:9], v[0:1], v[120:121], v[8:9]
	global_store_dwordx4 v[14:15], v[8:11], off
	s_waitcnt vmcnt(14)
	s_nop 1
	v_mov_b64_e32 v[28:29], v[168:169]
	v_mov_b64_e32 v[30:31], v[170:171]
	s_waitcnt vmcnt(13)
	s_nop 1
	v_mov_b64_e32 v[100:101], v[164:165]
	v_mov_b64_e32 v[102:103], v[166:167]
	s_waitcnt vmcnt(12)
	s_nop 1
	v_mov_b64_e32 v[104:105], v[160:161]
	v_mov_b64_e32 v[106:107], v[162:163]
	v_or_b32_e32 v10, s14, v135
	v_lshl_add_u64 v[8:9], s[12:13], 0, v[24:25]
	v_or_b32_e32 v11, s14, v139
	v_add_co_u32_e32 v112, vcc, s11, v8
	v_lshlrev_b32_e32 v16, 10, v10
	v_or_b32_e32 v14, s14, v204
	v_addc_co_u32_e32 v113, vcc, 0, v9, vcc
	v_lshl_add_u64 v[8:9], v[16:17], 2, v[26:27]
	v_lshlrev_b32_e32 v16, 10, v11
	v_or_b32_e32 v15, s14, v205
	v_lshl_add_u64 v[114:115], v[16:17], 2, v[26:27]
	v_lshlrev_b32_e32 v16, 10, v14
	v_lshl_add_u64 v[116:117], v[16:17], 2, v[26:27]
	v_lshlrev_b32_e32 v16, 10, v15
	ds_read2_b32 v[120:121], v34 offset1:1
	ds_read2_b32 v[122:123], v34 offset0:2 offset1:3
	ds_read2_b32 v[124:125], v94 offset1:1
	ds_read2_b32 v[126:127], v95 offset1:1
	ds_read2_b32 v[128:129], v96 offset1:1
	ds_read2_b32 v[130:131], v97 offset1:1
	ds_read2_b32 v[132:133], v98 offset1:1
	ds_read2_b32 v[136:137], v99 offset1:1
	ds_read2_b32 v[10:11], v42 offset1:1
	ds_read2_b32 v[14:15], v42 offset0:2 offset1:3
	s_waitcnt lgkmcnt(8)
	v_pk_fma_f32 v[6:7], v[2:3], v[122:123], v[6:7]
	v_pk_fma_f32 v[4:5], v[0:1], v[120:121], v[4:5]
	global_store_dwordx4 v[12:13], v[4:7], off
	v_lshl_add_u64 v[118:119], v[16:17], 2, v[26:27]
	v_or_b32_e32 v12, s14, v206
	v_lshlrev_b32_e32 v16, 10, v12
	v_lshl_add_u64 v[12:13], v[16:17], 2, v[26:27]
	v_or_b32_e32 v16, s14, v207
	v_lshlrev_b32_e32 v16, 10, v16
	s_waitcnt lgkmcnt(6)
	v_pk_fma_f32 v[6:7], v[2:3], v[126:127], v[30:31]
	v_pk_fma_f32 v[4:5], v[0:1], v[124:125], v[28:29]
	s_waitcnt lgkmcnt(4)
	v_pk_fma_f32 v[30:31], v[2:3], v[130:131], v[102:103]
	v_pk_fma_f32 v[28:29], v[0:1], v[128:129], v[100:101]
	s_waitcnt lgkmcnt(2)
	v_pk_fma_f32 v[2:3], v[2:3], v[136:137], v[106:107]
	v_pk_fma_f32 v[0:1], v[0:1], v[132:133], v[104:105]
	global_store_dwordx4 v[32:33], v[4:7], off
	global_store_dwordx4 v[108:109], v[28:31], off
	global_store_dwordx4 v[110:111], v[0:3], off
	v_mov_b32_e32 v128, v12
	v_mov_b32_e32 v129, v13
	v_mov_b32_e32 v130, v16
	v_mov_b32_e32 v131, v17
	v_mov_b32_e32 v132, v26
	v_mov_b32_e32 v133, v27
	v_mov_b32_e32 v136, v32
	v_mov_b32_e32 v137, v33
	v_mov_b32_e32 v144, v100
	v_mov_b32_e32 v145, v101
	v_mov_b32_e32 v146, v108
	v_mov_b32_e32 v147, v109
	v_mov_b32_e32 v148, v110
	v_mov_b32_e32 v149, v111
	global_load_dwordx4 v[250:253], v[112:113], off
	global_load_dwordx4 v[246:249], v[114:115], off
	global_load_dwordx4 v[242:245], v[116:117], off
	global_load_dwordx4 v[238:241], v[118:119], off
	global_load_dwordx4 v[234:237], v[8:9], off
	global_load_dwordx4 v[212:215], v[128:129], off
	v_or_b32_e32 v144, s14, v208
	v_or_b32_e32 v145, s14, v209
	v_lshl_add_u64 v[136:137], v[130:131], 2, v[132:133]
	v_lshlrev_b32_e32 v130, 10, v144
	v_lshl_add_u64 v[146:147], v[130:131], 2, v[132:133]
	v_lshlrev_b32_e32 v130, 10, v145
	v_lshl_add_u64 v[148:149], v[130:131], 2, v[132:133]
	global_load_dwordx4 v[200:203], v[136:137], off
	global_load_dwordx4 v[196:199], v[146:147], off
	global_load_dwordx4 v[192:195], v[148:149], off
	v_or_b32_e32 v128, s14, v210
	v_lshlrev_b32_e32 v130, 10, v128
	v_lshl_add_u64 v[128:129], v[130:131], 2, v[132:133]
	v_or_b32_e32 v130, s14, v35
	v_lshlrev_b32_e32 v130, 10, v130
	global_load_dwordx4 v[188:191], v[128:129], off
	v_or_b32_e32 v144, s14, v36
	v_or_b32_e32 v145, s14, v37
	v_lshl_add_u64 v[136:137], v[130:131], 2, v[132:133]
	v_lshlrev_b32_e32 v130, 10, v144
	v_lshl_add_u64 v[146:147], v[130:131], 2, v[132:133]
	v_lshlrev_b32_e32 v130, 10, v145
	v_lshl_add_u64 v[148:149], v[130:131], 2, v[132:133]
	global_load_dwordx4 v[184:187], v[136:137], off
	global_load_dwordx4 v[180:183], v[146:147], off
	global_load_dwordx4 v[176:179], v[148:149], off
	v_or_b32_e32 v128, s14, v38
	v_lshlrev_b32_e32 v130, 10, v128
	v_lshl_add_u64 v[128:129], v[130:131], 2, v[132:133]
	v_add_lshl_u32 v130, s14, v39, 10
	global_load_dwordx4 v[172:175], v[128:129], off
	v_lshl_add_u64 v[136:137], v[130:131], 2, v[132:133]
	v_add_lshl_u32 v130, s14, v40, 10
	v_lshl_add_u64 v[144:145], v[130:131], 2, v[132:133]
	v_add_lshl_u32 v130, s14, v41, 10
	v_lshl_add_u64 v[132:133], v[130:131], 2, v[132:133]
	global_load_dwordx4 v[168:171], v[136:137], off
	global_load_dwordx4 v[164:167], v[144:145], off
	global_load_dwordx4 v[160:163], v[132:133], off
	s_waitcnt vmcnt(16)
	s_nop 1
	v_mov_b64_e32 v[0:1], v[250:251]
	v_mov_b64_e32 v[2:3], v[252:253]
	s_nop 0
	s_waitcnt vmcnt(15)
	s_nop 1
	v_mov_b64_e32 v[28:29], v[246:247]
	v_mov_b64_e32 v[30:31], v[248:249]
	s_waitcnt vmcnt(14)
	s_nop 1
	v_mov_b64_e32 v[100:101], v[242:243]
	v_mov_b64_e32 v[102:103], v[244:245]
	s_waitcnt vmcnt(13)
	s_nop 1
	v_mov_b64_e32 v[104:105], v[238:239]
	v_mov_b64_e32 v[106:107], v[240:241]
	s_waitcnt vmcnt(12)
	s_nop 1
	v_mov_b64_e32 v[4:5], v[234:235]
	v_mov_b64_e32 v[6:7], v[236:237]
	ds_read2_b32 v[32:33], v43 offset1:1
	ds_read2_b32 v[108:109], v43 offset0:2 offset1:3
	ds_read2_b32 v[110:111], v44 offset1:1
	ds_read2_b32 v[112:113], v44 offset0:2 offset1:3
	ds_read2_b32 v[120:121], v45 offset1:1
	ds_read2_b32 v[122:123], v45 offset0:2 offset1:3
	ds_read2_b32 v[124:125], v46 offset1:1
	ds_read2_b32 v[126:127], v46 offset0:2 offset1:3
	s_waitcnt lgkmcnt(6)
	v_pk_fma_f32 v[30:31], v[2:3], v[108:109], v[30:31]
	v_pk_fma_f32 v[28:29], v[0:1], v[32:33], v[28:29]
	s_waitcnt lgkmcnt(4)
	v_pk_fma_f32 v[102:103], v[2:3], v[112:113], v[102:103]
	v_pk_fma_f32 v[100:101], v[0:1], v[110:111], v[100:101]
	s_waitcnt lgkmcnt(2)
	v_pk_fma_f32 v[106:107], v[2:3], v[122:123], v[106:107]
	v_pk_fma_f32 v[104:105], v[0:1], v[120:121], v[104:105]
	global_store_dwordx4 v[114:115], v[28:31], off
	global_store_dwordx4 v[116:117], v[100:103], off
	global_store_dwordx4 v[118:119], v[104:107], off
	s_waitcnt vmcnt(14)
	s_nop 1
	v_mov_b64_e32 v[28:29], v[212:213]
	v_mov_b64_e32 v[30:31], v[214:215]
	v_or_b32_e32 v100, s14, v208
	v_or_b32_e32 v101, s14, v209
	v_lshl_add_u64 v[32:33], v[16:17], 2, v[26:27]
	v_lshlrev_b32_e32 v16, 10, v100
	v_lshl_add_u64 v[108:109], v[16:17], 2, v[26:27]
	v_lshlrev_b32_e32 v16, 10, v101
	v_lshl_add_u64 v[110:111], v[16:17], 2, v[26:27]
	v_pk_fma_f32 v[6:7], v[2:3], v[14:15], v[6:7]
	v_pk_fma_f32 v[4:5], v[0:1], v[10:11], v[4:5]
	s_waitcnt lgkmcnt(0)
	v_pk_fma_f32 v[30:31], v[2:3], v[126:127], v[30:31]
	v_pk_fma_f32 v[28:29], v[0:1], v[124:125], v[28:29]
	global_store_dwordx4 v[12:13], v[28:31], off
	s_waitcnt vmcnt(14)
	s_nop 1
	v_mov_b64_e32 v[28:29], v[200:201]
	v_mov_b64_e32 v[30:31], v[202:203]
	s_nop 0
	s_waitcnt vmcnt(13)
	s_nop 1
	v_mov_b64_e32 v[100:101], v[196:197]
	v_mov_b64_e32 v[102:103], v[198:199]
	s_waitcnt vmcnt(12)
	s_nop 1
	v_mov_b64_e32 v[104:105], v[192:193]
	v_mov_b64_e32 v[106:107], v[194:195]
	ds_read2_b32 v[112:113], v47 offset1:1
	ds_read2_b32 v[114:115], v47 offset0:2 offset1:3
	ds_read2_b32 v[116:117], v48 offset1:1
	ds_read2_b32 v[118:119], v48 offset0:2 offset1:3
	ds_read2_b32 v[120:121], v49 offset1:1
	ds_read2_b32 v[122:123], v49 offset0:2 offset1:3
	ds_read2_b32 v[124:125], v50 offset1:1
	ds_read2_b32 v[126:127], v50 offset0:2 offset1:3
	v_or_b32_e32 v12, s14, v210
	v_lshlrev_b32_e32 v16, 10, v12
	v_lshl_add_u64 v[12:13], v[16:17], 2, v[26:27]
	v_or_b32_e32 v16, s14, v35
	v_lshlrev_b32_e32 v16, 10, v16
	s_waitcnt lgkmcnt(6)
	v_pk_fma_f32 v[30:31], v[2:3], v[114:115], v[30:31]
	v_pk_fma_f32 v[28:29], v[0:1], v[112:113], v[28:29]
	s_waitcnt lgkmcnt(4)
	v_pk_fma_f32 v[102:103], v[2:3], v[118:119], v[102:103]
	v_pk_fma_f32 v[100:101], v[0:1], v[116:117], v[100:101]
	s_waitcnt lgkmcnt(2)
	v_pk_fma_f32 v[106:107], v[2:3], v[122:123], v[106:107]
	v_pk_fma_f32 v[104:105], v[0:1], v[120:121], v[104:105]
	global_store_dwordx4 v[32:33], v[28:31], off
	global_store_dwordx4 v[108:109], v[100:103], off
	global_store_dwordx4 v[110:111], v[104:107], off
	s_waitcnt vmcnt(14)
	s_nop 1
	v_mov_b64_e32 v[28:29], v[188:189]
	v_mov_b64_e32 v[30:31], v[190:191]
	v_or_b32_e32 v100, s14, v36
	v_or_b32_e32 v101, s14, v37
	v_lshl_add_u64 v[32:33], v[16:17], 2, v[26:27]
	v_lshlrev_b32_e32 v16, 10, v100
	v_lshl_add_u64 v[108:109], v[16:17], 2, v[26:27]
	v_lshlrev_b32_e32 v16, 10, v101
	v_lshl_add_u64 v[110:111], v[16:17], 2, v[26:27]
	s_waitcnt lgkmcnt(0)
	v_pk_fma_f32 v[30:31], v[2:3], v[126:127], v[30:31]
	v_pk_fma_f32 v[28:29], v[0:1], v[124:125], v[28:29]
	global_store_dwordx4 v[12:13], v[28:31], off
	s_waitcnt vmcnt(14)
	s_nop 1
	v_mov_b64_e32 v[28:29], v[184:185]
	v_mov_b64_e32 v[30:31], v[186:187]
	s_nop 0
	s_waitcnt vmcnt(13)
	s_nop 1
	v_mov_b64_e32 v[100:101], v[180:181]
	v_mov_b64_e32 v[102:103], v[182:183]
	s_waitcnt vmcnt(12)
	s_nop 1
	v_mov_b64_e32 v[104:105], v[176:177]
	v_mov_b64_e32 v[106:107], v[178:179]
	ds_read2_b32 v[112:113], v51 offset1:1
	ds_read2_b32 v[114:115], v51 offset0:2 offset1:3
	ds_read2_b32 v[116:117], v52 offset1:1
	ds_read2_b32 v[118:119], v52 offset0:2 offset1:3
	ds_read2_b32 v[120:121], v53 offset1:1
	ds_read2_b32 v[122:123], v53 offset0:2 offset1:3
	ds_read2_b32 v[124:125], v54 offset1:1
	ds_read2_b32 v[126:127], v54 offset0:2 offset1:3
	v_or_b32_e32 v12, s14, v38
	v_lshlrev_b32_e32 v16, 10, v12
	v_lshl_add_u64 v[12:13], v[16:17], 2, v[26:27]
	v_add_lshl_u32 v16, s14, v39, 10
	s_waitcnt lgkmcnt(6)
	v_pk_fma_f32 v[30:31], v[2:3], v[114:115], v[30:31]
	v_pk_fma_f32 v[28:29], v[0:1], v[112:113], v[28:29]
	s_waitcnt lgkmcnt(4)
	v_pk_fma_f32 v[102:103], v[2:3], v[118:119], v[102:103]
	v_pk_fma_f32 v[100:101], v[0:1], v[116:117], v[100:101]
	s_waitcnt lgkmcnt(2)
	v_pk_fma_f32 v[106:107], v[2:3], v[122:123], v[106:107]
	v_pk_fma_f32 v[104:105], v[0:1], v[120:121], v[104:105]
	global_store_dwordx4 v[32:33], v[28:31], off
	global_store_dwordx4 v[108:109], v[100:103], off
	global_store_dwordx4 v[110:111], v[104:107], off
	s_waitcnt vmcnt(14)
	s_nop 1
	v_mov_b64_e32 v[28:29], v[172:173]
	v_mov_b64_e32 v[30:31], v[174:175]
	v_lshl_add_u64 v[32:33], v[16:17], 2, v[26:27]
	v_add_lshl_u32 v16, s14, v40, 10
	global_store_dwordx4 v[8:9], v[4:7], off
	v_lshl_add_u64 v[100:101], v[16:17], 2, v[26:27]
	v_add_lshl_u32 v16, s14, v41, 10
	v_lshl_add_u64 v[26:27], v[16:17], 2, v[26:27]
	s_waitcnt lgkmcnt(0)
	v_pk_fma_f32 v[6:7], v[2:3], v[126:127], v[30:31]
	v_pk_fma_f32 v[4:5], v[0:1], v[124:125], v[28:29]
	global_store_dwordx4 v[12:13], v[4:7], off
	s_waitcnt vmcnt(15)
	s_nop 1
	v_mov_b64_e32 v[4:5], v[168:169]
	v_mov_b64_e32 v[6:7], v[170:171]
	s_nop 0
	s_waitcnt vmcnt(14)
	s_nop 1
	v_mov_b64_e32 v[8:9], v[164:165]
	v_mov_b64_e32 v[10:11], v[166:167]
	s_waitcnt vmcnt(13)
	s_nop 1
	v_mov_b64_e32 v[12:13], v[160:161]
	v_mov_b64_e32 v[14:15], v[162:163]
	ds_read2_b32 v[28:29], v55 offset1:1
	ds_read2_b32 v[30:31], v55 offset0:2 offset1:3
	ds_read2_b32 v[102:103], v56 offset1:1
	ds_read2_b32 v[104:105], v56 offset0:2 offset1:3
	ds_read2_b32 v[106:107], v57 offset1:1
	ds_read2_b32 v[108:109], v57 offset0:2 offset1:3
	s_waitcnt lgkmcnt(4)
	v_pk_fma_f32 v[6:7], v[2:3], v[30:31], v[6:7]
	v_pk_fma_f32 v[4:5], v[0:1], v[28:29], v[4:5]
	s_waitcnt lgkmcnt(2)
	v_pk_fma_f32 v[10:11], v[2:3], v[104:105], v[10:11]
	v_pk_fma_f32 v[8:9], v[0:1], v[102:103], v[8:9]
	s_waitcnt lgkmcnt(0)
	v_pk_fma_f32 v[2:3], v[2:3], v[108:109], v[14:15]
	v_pk_fma_f32 v[0:1], v[0:1], v[106:107], v[12:13]
	global_store_dwordx4 v[32:33], v[4:7], off
	global_store_dwordx4 v[100:101], v[8:11], off
	global_store_dwordx4 v[26:27], v[0:3], off
	s_barrier
	s_cbranch_scc1 .LBB0_1844
	s_load_dwordx2 s[2:3], s[0:1], 0x130
	v_accvgpr_read_b32 v110, a206

.LBB0_2329:
	s_lshr_b32 s13, s6, 3
	s_add_i32 s13, s13, s7
	s_lshl_b32 s4, s13, 19
	v_lshl_add_u64 v[0:1], v[18:19], 0, s[4:5]
	v_add_co_u32_e32 v4, vcc, 0x10000, v0
	s_and_b32 s12, s6, 7
	s_nop 0
	v_addc_co_u32_e32 v5, vcc, 0, v1, vcc
	v_add_co_u32_e32 v6, vcc, 0x20000, v0
	s_lshl_b32 s4, s12, 18
	s_nop 0
	v_addc_co_u32_e32 v7, vcc, 0, v1, vcc
	v_add_co_u32_e32 v8, vcc, 0x30000, v0
	v_lshl_add_u64 v[2:3], v[20:21], 0, s[4:5]
	s_nop 0
	v_addc_co_u32_e32 v9, vcc, 0, v1, vcc
	v_add_co_u32_e32 v10, vcc, 0x40000, v0
	global_load_dwordx4 v[100:103], v[0:1], off
	global_load_dwordx4 v[104:107], v[0:1], off offset:128
	v_addc_co_u32_e32 v11, vcc, 0, v1, vcc
	v_add_co_u32_e32 v12, vcc, 0x50000, v0
	global_load_dwordx4 v[108:111], v[2:3], off
	global_load_dwordx4 v[112:115], v[2:3], off offset:128
	v_addc_co_u32_e32 v13, vcc, 0, v1, vcc
	v_add_co_u32_e32 v14, vcc, 0x60000, v0
	global_load_dwordx4 v[116:119], v[4:5], off
	global_load_dwordx4 v[120:123], v[4:5], off offset:128
	v_addc_co_u32_e32 v15, vcc, 0, v1, vcc
	v_add_co_u32_e32 v26, vcc, 0x70000, v0
	global_load_dwordx4 v[124:127], v[6:7], off
	global_load_dwordx4 v[128:131], v[6:7], off offset:128
	v_addc_co_u32_e32 v27, vcc, 0, v1, vcc
	v_add_co_u32_e32 v28, vcc, s8, v2
	global_load_dwordx4 v[140:143], v[8:9], off
	global_load_dwordx4 v[144:147], v[8:9], off offset:128
	v_addc_co_u32_e32 v29, vcc, 0, v3, vcc
	v_add_co_u32_e32 v30, vcc, s9, v2
	global_load_dwordx4 v[148:151], v[10:11], off
	global_load_dwordx4 v[152:155], v[10:11], off offset:128
	v_addc_co_u32_e32 v31, vcc, 0, v3, vcc
	v_add_co_u32_e32 v32, vcc, s10, v2
	global_load_dwordx4 v[156:159], v[12:13], off
	global_load_dwordx4 v[160:163], v[12:13], off offset:128
	global_load_dwordx4 v[164:167], v[14:15], off
	global_load_dwordx4 v[168:171], v[14:15], off offset:128
	global_load_dwordx4 v[172:175], v[26:27], off
	global_load_dwordx4 v[176:179], v[26:27], off offset:128
	global_load_dwordx4 v[180:183], v[28:29], off
	global_load_dwordx4 v[184:187], v[28:29], off offset:128
	v_addc_co_u32_e32 v33, vcc, 0, v3, vcc
	global_load_dwordx4 v[188:191], v[30:31], off
	global_load_dwordx4 v[192:195], v[30:31], off offset:128
	global_load_dwordx4 v[196:199], v[32:33], off
	global_load_dwordx4 v[200:203], v[32:33], off offset:128
	s_lshl_b32 s14, s13, 8
	s_add_i32 s4, s14, 0xffffe000
	s_add_i32 s15, s14, 0xffffe080
	s_lshr_b32 s4, s4, 12
	s_lshr_b32 s15, s15, 12
	s_add_i32 s4, s4, 16
	s_add_i32 s15, s15, 16
	s_cmp_lt_u32 s13, 32
	s_cselect_b32 s4, 15, s4
	s_cselect_b32 s13, 15, s15
	s_mul_hi_u32 s15, s4, 0x6000
	s_mulk_i32 s4, 0x6000
	s_add_u32 s16, s2, s4
	s_addc_u32 s15, s3, s15
	s_lshl_b32 s4, s12, 9
	v_or_b32_e32 v16, s14, v135
	s_add_u32 s16, s16, s4
	v_lshlrev_b32_e32 v16, 10, v16
	s_addc_u32 s17, s15, 0
	s_mul_hi_u32 s12, s13, 0x6000
	s_mulk_i32 s13, 0x6000
	s_waitcnt vmcnt(23)
	ds_write_b128 v60, v[100:103]
	s_waitcnt vmcnt(21)
	ds_write_b128 v60, v[108:111] offset:36864
	s_waitcnt vmcnt(19)
	ds_write_b128 v60, v[116:119] offset:4608
	s_waitcnt vmcnt(17)
	ds_write_b128 v60, v[124:127] offset:9216
	s_waitcnt vmcnt(15)
	ds_write_b128 v60, v[140:143] offset:13824
	s_waitcnt vmcnt(13)
	ds_write_b128 v60, v[148:151] offset:18432
	s_waitcnt vmcnt(11)
	ds_write_b128 v60, v[156:159] offset:23040
	s_waitcnt vmcnt(9)
	ds_write_b128 v60, v[164:167] offset:27648
	s_waitcnt vmcnt(7)
	ds_write_b128 v60, v[172:175] offset:32256
	s_waitcnt vmcnt(5)
	ds_write_b128 v60, v[180:183] offset:41472
	s_waitcnt vmcnt(3)
	ds_write_b128 v60, v[188:191] offset:46080
	s_waitcnt vmcnt(1)
	ds_write_b128 v60, v[196:199] offset:50688
	s_waitcnt lgkmcnt(0)
	s_barrier
	ds_read_b128 v[100:103], v59
	ds_read_b128 v[108:111], v62 offset:36864
	ds_read_b128 v[116:119], v59 offset:4608
	ds_read_b128 v[124:127], v62 offset:41472
	s_waitcnt lgkmcnt(2)
	v_mfma_f32_32x32x16_bf16 a[112:127], v[100:103], v[108:111], 0
	s_waitcnt lgkmcnt(0)
	v_mfma_f32_32x32x16_bf16 a[96:111], v[100:103], v[124:127], 0
	ds_read_b128 v[100:103], v59 offset:9216
	s_waitcnt lgkmcnt(0)
	v_mfma_f32_32x32x16_bf16 a[48:63], v[100:103], v[108:111], 0
	v_mfma_f32_32x32x16_bf16 a[32:47], v[100:103], v[124:127], 0
	ds_read_b128 v[100:103], v61
	ds_write_b128 v60, v[104:107] offset:55296
	ds_write_b128 v60, v[120:123] offset:59904
	ds_write_b128 v60, v[128:131] offset:64512
	ds_write_b128 v63, v[144:147] offset:55296
	ds_write_b128 v64, v[152:155] offset:55296
	ds_write_b128 v65, v[160:163] offset:55296
	ds_write_b128 v66, v[168:171] offset:55296
	ds_write_b128 v67, v[176:179] offset:55296
	ds_write_b128 v68, v[112:115]
	ds_write_b128 v68, v[184:187] offset:4608
	ds_write_b128 v68, v[192:195] offset:9216
	s_waitcnt vmcnt(0)
	ds_write_b128 v68, v[200:203] offset:13824
	v_mfma_f32_32x32x16_bf16 a[80:95], v[116:119], v[108:111], 0
	v_mfma_f32_32x32x16_bf16 a[64:79], v[116:119], v[124:127], 0
	s_waitcnt lgkmcnt(12)
	v_mfma_f32_32x32x16_bf16 a[16:31], v[100:103], v[108:111], 0
	v_mfma_f32_32x32x16_bf16 a[0:15], v[100:103], v[124:127], 0
	ds_read_b128 v[100:103], v59 offset:32
	ds_read_b128 v[104:107], v62 offset:36896
	ds_read_b128 v[108:111], v62 offset:36928
	ds_read_b128 v[112:115], v59 offset:64
	ds_read_b128 v[116:119], v62 offset:41504
	ds_read_b128 v[120:123], v62 offset:36960
	s_waitcnt lgkmcnt(4)
	v_mfma_f32_32x32x16_bf16 a[112:127], v[100:103], v[104:107], a[112:127]
	s_waitcnt lgkmcnt(1)
	v_mfma_f32_32x32x16_bf16 a[96:111], v[100:103], v[116:119], a[96:111]
	ds_read_b128 v[100:103], v59 offset:4640
	ds_read_b128 v[124:127], v59 offset:96
	s_waitcnt lgkmcnt(1)
	v_mfma_f32_32x32x16_bf16 a[80:95], v[100:103], v[104:107], a[80:95]
	v_mfma_f32_32x32x16_bf16 a[64:79], v[100:103], v[116:119], a[64:79]
	ds_read_b128 v[100:103], v59 offset:9248
	ds_read_b128 v[128:131], v59 offset:9280
	s_waitcnt lgkmcnt(1)
	v_mfma_f32_32x32x16_bf16 a[48:63], v[100:103], v[104:107], a[48:63]
	v_mfma_f32_32x32x16_bf16 a[32:47], v[100:103], v[116:119], a[32:47]
	ds_read_b128 v[100:103], v61 offset:32
	ds_read_b128 v[140:143], v59 offset:9312
	s_waitcnt lgkmcnt(1)
	v_mfma_f32_32x32x16_bf16 a[16:31], v[100:103], v[104:107], a[16:31]
	v_mfma_f32_32x32x16_bf16 a[0:15], v[100:103], v[116:119], a[0:15]
	ds_read_b128 v[100:103], v62 offset:41536
	ds_read_b128 v[104:107], v62 offset:41568
	v_mfma_f32_32x32x16_bf16 a[112:127], v[112:115], v[108:111], a[112:127]
	s_waitcnt lgkmcnt(1)
	v_mfma_f32_32x32x16_bf16 a[96:111], v[112:115], v[100:103], a[96:111]
	ds_read_b128 v[112:115], v59 offset:4672
	ds_read_b128 v[116:119], v59 offset:4704
	s_waitcnt lgkmcnt(1)
	v_mfma_f32_32x32x16_bf16 a[80:95], v[112:115], v[108:111], a[80:95]
	v_mfma_f32_32x32x16_bf16 a[64:79], v[112:115], v[100:103], a[64:79]
	v_mfma_f32_32x32x16_bf16 a[48:63], v[128:131], v[108:111], a[48:63]
	v_mfma_f32_32x32x16_bf16 a[32:47], v[128:131], v[100:103], a[32:47]
	ds_read_b128 v[112:115], v61 offset:64
	ds_read_b128 v[128:131], v61 offset:96
	s_waitcnt lgkmcnt(1)
	v_mfma_f32_32x32x16_bf16 a[16:31], v[112:115], v[108:111], a[16:31]
	v_mfma_f32_32x32x16_bf16 a[0:15], v[112:115], v[100:103], a[0:15]
	global_load_dwordx4 v[100:103], v[32:33], off offset:256
	v_mfma_f32_32x32x16_bf16 a[112:127], v[124:127], v[120:123], a[112:127]
	v_mfma_f32_32x32x16_bf16 a[96:111], v[124:127], v[104:107], a[96:111]
	v_mfma_f32_32x32x16_bf16 a[80:95], v[116:119], v[120:123], a[80:95]
	v_mfma_f32_32x32x16_bf16 a[64:79], v[116:119], v[104:107], a[64:79]
	v_mfma_f32_32x32x16_bf16 a[48:63], v[140:143], v[120:123], a[48:63]
	v_mfma_f32_32x32x16_bf16 a[32:47], v[140:143], v[104:107], a[32:47]
	global_load_dwordx4 v[108:111], v[30:31], off offset:256
	global_load_dwordx4 v[112:115], v[28:29], off offset:256
	global_load_dwordx4 v[116:119], v[2:3], off offset:256
	global_load_dwordx4 v[124:127], v[8:9], off offset:256
	global_load_dwordx4 v[140:143], v[6:7], off offset:256
	global_load_dwordx4 v[144:147], v[4:5], off offset:256
	global_load_dwordx4 v[148:151], v[0:1], off offset:256
	s_waitcnt lgkmcnt(0)
	v_mfma_f32_32x32x16_bf16 a[16:31], v[128:131], v[120:123], a[16:31]
	global_load_dwordx4 v[120:123], v[12:13], off offset:256
	global_load_dwordx4 v[152:155], v[10:11], off offset:256
	global_load_dwordx4 v[156:159], v[26:27], off offset:256
	global_load_dwordx4 v[160:163], v[14:15], off offset:256
	s_barrier
	v_mfma_f32_32x32x16_bf16 a[0:15], v[128:131], v[104:107], a[0:15]
	ds_read_b128 v[104:107], v59 offset:55296
	ds_read_b128 v[128:131], v69
	ds_read_b128 v[164:167], v59 offset:59904
	ds_read_b128 v[168:171], v69 offset:4608
	s_waitcnt lgkmcnt(2)
	v_mfma_f32_32x32x16_bf16 a[112:127], v[104:107], v[128:131], a[112:127]
	s_waitcnt lgkmcnt(0)
	v_mfma_f32_32x32x16_bf16 a[96:111], v[104:107], v[168:171], a[96:111]
	ds_read_b128 v[104:107], v59 offset:64512
	s_waitcnt lgkmcnt(0)
	v_mfma_f32_32x32x16_bf16 a[48:63], v[104:107], v[128:131], a[48:63]
	v_mfma_f32_32x32x16_bf16 a[32:47], v[104:107], v[168:171], a[32:47]
	ds_read_b128 v[104:107], v61 offset:55296
	s_waitcnt vmcnt(4)
	ds_write_b128 v60, v[148:151]
	ds_write_b128 v60, v[144:147] offset:4608
	ds_write_b128 v60, v[140:143] offset:9216
	ds_write_b128 v60, v[124:127] offset:13824
	s_waitcnt vmcnt(2)
	ds_write_b128 v60, v[152:155] offset:18432
	ds_write_b128 v60, v[120:123] offset:23040
	s_waitcnt vmcnt(0)
	ds_write_b128 v60, v[160:163] offset:27648
	ds_write_b128 v60, v[156:159] offset:32256
	ds_write_b128 v60, v[116:119] offset:36864
	ds_write_b128 v60, v[112:115] offset:41472
	ds_write_b128 v60, v[108:111] offset:46080
	ds_write_b128 v60, v[100:103] offset:50688
	v_mfma_f32_32x32x16_bf16 a[80:95], v[164:167], v[128:131], a[80:95]
	v_mfma_f32_32x32x16_bf16 a[64:79], v[164:167], v[168:171], a[64:79]
	s_waitcnt lgkmcnt(12)
	v_mfma_f32_32x32x16_bf16 a[16:31], v[104:107], v[128:131], a[16:31]
	v_mfma_f32_32x32x16_bf16 a[0:15], v[104:107], v[168:171], a[0:15]
	ds_read_b128 v[100:103], v59 offset:55328
	ds_read_b128 v[104:107], v69 offset:32
	ds_read_b128 v[108:111], v69 offset:64
	ds_read_b128 v[112:115], v59 offset:55360
	ds_read_b128 v[116:119], v69 offset:4640
	ds_read_b128 v[120:123], v69 offset:96
	s_waitcnt lgkmcnt(4)
	v_mfma_f32_32x32x16_bf16 a[112:127], v[100:103], v[104:107], a[112:127]
	s_waitcnt lgkmcnt(1)
	v_mfma_f32_32x32x16_bf16 a[96:111], v[100:103], v[116:119], a[96:111]
	ds_read_b128 v[100:103], v59 offset:59936
	ds_read_b128 v[124:127], v59 offset:55392
	s_waitcnt lgkmcnt(1)
	v_mfma_f32_32x32x16_bf16 a[80:95], v[100:103], v[104:107], a[80:95]
	v_mfma_f32_32x32x16_bf16 a[64:79], v[100:103], v[116:119], a[64:79]
	ds_read_b128 v[100:103], v59 offset:64544
	ds_read_b128 v[128:131], v59 offset:64576
	s_waitcnt lgkmcnt(1)
	v_mfma_f32_32x32x16_bf16 a[48:63], v[100:103], v[104:107], a[48:63]
	v_mfma_f32_32x32x16_bf16 a[32:47], v[100:103], v[116:119], a[32:47]
	ds_read_b128 v[100:103], v61 offset:55328
	ds_read_b128 v[140:143], v59 offset:64608
	s_waitcnt lgkmcnt(1)
	v_mfma_f32_32x32x16_bf16 a[16:31], v[100:103], v[104:107], a[16:31]
	v_mfma_f32_32x32x16_bf16 a[0:15], v[100:103], v[116:119], a[0:15]
	ds_read_b128 v[100:103], v69 offset:4672
	ds_read_b128 v[104:107], v69 offset:4704
	v_mfma_f32_32x32x16_bf16 a[112:127], v[112:115], v[108:111], a[112:127]
	s_waitcnt lgkmcnt(1)
	v_mfma_f32_32x32x16_bf16 a[96:111], v[112:115], v[100:103], a[96:111]
	ds_read_b128 v[112:115], v59 offset:59968
	ds_read_b128 v[116:119], v59 offset:60000
	s_waitcnt lgkmcnt(1)
	v_mfma_f32_32x32x16_bf16 a[80:95], v[112:115], v[108:111], a[80:95]
	v_mfma_f32_32x32x16_bf16 a[64:79], v[112:115], v[100:103], a[64:79]
	v_mfma_f32_32x32x16_bf16 a[48:63], v[128:131], v[108:111], a[48:63]
	v_mfma_f32_32x32x16_bf16 a[32:47], v[128:131], v[100:103], a[32:47]
	ds_read_b128 v[112:115], v61 offset:55360
	ds_read_b128 v[128:131], v61 offset:55392
	s_waitcnt lgkmcnt(1)
	v_mfma_f32_32x32x16_bf16 a[16:31], v[112:115], v[108:111], a[16:31]
	v_mfma_f32_32x32x16_bf16 a[0:15], v[112:115], v[100:103], a[0:15]
	v_mfma_f32_32x32x16_bf16 a[112:127], v[124:127], v[120:123], a[112:127]
	v_mfma_f32_32x32x16_bf16 a[96:111], v[124:127], v[104:107], a[96:111]
	v_mfma_f32_32x32x16_bf16 a[80:95], v[116:119], v[120:123], a[80:95]
	v_mfma_f32_32x32x16_bf16 a[64:79], v[116:119], v[104:107], a[64:79]
	global_load_dwordx4 v[100:103], v[4:5], off offset:384
	global_load_dwordx4 v[108:111], v[0:1], off offset:384
	global_load_dwordx4 v[112:115], v[8:9], off offset:384
	global_load_dwordx4 v[116:119], v[6:7], off offset:384
	v_mfma_f32_32x32x16_bf16 a[48:63], v[140:143], v[120:123], a[48:63]
	v_mfma_f32_32x32x16_bf16 a[32:47], v[140:143], v[104:107], a[32:47]
	global_load_dwordx4 v[124:127], v[10:11], off offset:384
	global_load_dwordx4 v[140:143], v[12:13], off offset:384
	global_load_dwordx4 v[144:147], v[26:27], off offset:384
	global_load_dwordx4 v[148:151], v[14:15], off offset:384
	global_load_dwordx4 v[152:155], v[28:29], off offset:384
	global_load_dwordx4 v[156:159], v[2:3], off offset:384
	global_load_dwordx4 v[160:163], v[30:31], off offset:384
	s_waitcnt lgkmcnt(0)
	v_mfma_f32_32x32x16_bf16 a[16:31], v[128:131], v[120:123], a[16:31]
	global_load_dwordx4 v[120:123], v[32:33], off offset:384
	s_barrier
	v_mfma_f32_32x32x16_bf16 a[0:15], v[128:131], v[104:107], a[0:15]
	ds_read_b128 v[104:107], v59
	ds_read_b128 v[128:131], v62 offset:36864
	ds_read_b128 v[164:167], v59 offset:4608
	ds_read_b128 v[168:171], v62 offset:41472
	s_waitcnt lgkmcnt(2)
	v_mfma_f32_32x32x16_bf16 a[112:127], v[104:107], v[128:131], a[112:127]
	s_waitcnt lgkmcnt(0)
	v_mfma_f32_32x32x16_bf16 a[96:111], v[104:107], v[168:171], a[96:111]
	ds_read_b128 v[104:107], v59 offset:9216
	s_waitcnt lgkmcnt(0)
	v_mfma_f32_32x32x16_bf16 a[48:63], v[104:107], v[128:131], a[48:63]
	v_mfma_f32_32x32x16_bf16 a[32:47], v[104:107], v[168:171], a[32:47]
	ds_read_b128 v[104:107], v61
	s_waitcnt vmcnt(10)
	ds_write_b128 v60, v[108:111] offset:55296
	ds_write_b128 v60, v[100:103] offset:59904
	s_waitcnt vmcnt(8)
	ds_write_b128 v60, v[116:119] offset:64512
	ds_write_b128 v63, v[112:115] offset:55296
	s_waitcnt vmcnt(7)
	ds_write_b128 v64, v[124:127] offset:55296
	s_waitcnt vmcnt(6)
	ds_write_b128 v65, v[140:143] offset:55296
	s_waitcnt vmcnt(4)
	ds_write_b128 v66, v[148:151] offset:55296
	ds_write_b128 v67, v[144:147] offset:55296
	s_waitcnt vmcnt(2)
	ds_write_b128 v68, v[156:159]
	ds_write_b128 v68, v[152:155] offset:4608
	s_waitcnt vmcnt(1)
	ds_write_b128 v68, v[160:163] offset:9216
	s_waitcnt vmcnt(0)
	ds_write_b128 v68, v[120:123] offset:13824
	v_mfma_f32_32x32x16_bf16 a[80:95], v[164:167], v[128:131], a[80:95]
	v_mfma_f32_32x32x16_bf16 a[64:79], v[164:167], v[168:171], a[64:79]
	s_waitcnt lgkmcnt(12)
	v_mfma_f32_32x32x16_bf16 a[16:31], v[104:107], v[128:131], a[16:31]
	v_mfma_f32_32x32x16_bf16 a[0:15], v[104:107], v[168:171], a[0:15]
	ds_read_b128 v[100:103], v59 offset:32
	ds_read_b128 v[104:107], v62 offset:36896
	ds_read_b128 v[108:111], v62 offset:36928
	ds_read_b128 v[112:115], v59 offset:64
	ds_read_b128 v[116:119], v62 offset:41504
	ds_read_b128 v[120:123], v62 offset:36960
	s_waitcnt lgkmcnt(4)
	v_mfma_f32_32x32x16_bf16 a[112:127], v[100:103], v[104:107], a[112:127]
	s_waitcnt lgkmcnt(1)
	v_mfma_f32_32x32x16_bf16 a[96:111], v[100:103], v[116:119], a[96:111]
	ds_read_b128 v[100:103], v59 offset:4640
	ds_read_b128 v[124:127], v59 offset:96
	s_waitcnt lgkmcnt(1)
	v_mfma_f32_32x32x16_bf16 a[80:95], v[100:103], v[104:107], a[80:95]
	v_mfma_f32_32x32x16_bf16 a[64:79], v[100:103], v[116:119], a[64:79]
	ds_read_b128 v[100:103], v59 offset:9248
	ds_read_b128 v[128:131], v59 offset:9280
	s_waitcnt lgkmcnt(1)
	v_mfma_f32_32x32x16_bf16 a[48:63], v[100:103], v[104:107], a[48:63]
	v_mfma_f32_32x32x16_bf16 a[32:47], v[100:103], v[116:119], a[32:47]
	ds_read_b128 v[100:103], v61 offset:32
	ds_read_b128 v[140:143], v59 offset:9312
	s_waitcnt lgkmcnt(1)
	v_mfma_f32_32x32x16_bf16 a[16:31], v[100:103], v[104:107], a[16:31]
	v_mfma_f32_32x32x16_bf16 a[0:15], v[100:103], v[116:119], a[0:15]
	ds_read_b128 v[100:103], v62 offset:41536
	ds_read_b128 v[104:107], v62 offset:41568
	v_mfma_f32_32x32x16_bf16 a[112:127], v[112:115], v[108:111], a[112:127]
	s_waitcnt lgkmcnt(1)
	v_mfma_f32_32x32x16_bf16 a[96:111], v[112:115], v[100:103], a[96:111]
	ds_read_b128 v[112:115], v59 offset:4672
	ds_read_b128 v[116:119], v59 offset:4704
	s_waitcnt lgkmcnt(1)
	v_mfma_f32_32x32x16_bf16 a[80:95], v[112:115], v[108:111], a[80:95]
	v_mfma_f32_32x32x16_bf16 a[64:79], v[112:115], v[100:103], a[64:79]
	v_mfma_f32_32x32x16_bf16 a[48:63], v[128:131], v[108:111], a[48:63]
	v_mfma_f32_32x32x16_bf16 a[32:47], v[128:131], v[100:103], a[32:47]
	ds_read_b128 v[112:115], v61 offset:64
	ds_read_b128 v[128:131], v61 offset:96
	s_waitcnt lgkmcnt(1)
	v_mfma_f32_32x32x16_bf16 a[16:31], v[112:115], v[108:111], a[16:31]
	v_mfma_f32_32x32x16_bf16 a[0:15], v[112:115], v[100:103], a[0:15]
	global_load_dwordx4 v[100:103], v[32:33], off offset:512
	v_mfma_f32_32x32x16_bf16 a[112:127], v[124:127], v[120:123], a[112:127]
	v_mfma_f32_32x32x16_bf16 a[96:111], v[124:127], v[104:107], a[96:111]
	v_mfma_f32_32x32x16_bf16 a[80:95], v[116:119], v[120:123], a[80:95]
	v_mfma_f32_32x32x16_bf16 a[64:79], v[116:119], v[104:107], a[64:79]
	v_mfma_f32_32x32x16_bf16 a[48:63], v[140:143], v[120:123], a[48:63]
	v_mfma_f32_32x32x16_bf16 a[32:47], v[140:143], v[104:107], a[32:47]
	global_load_dwordx4 v[108:111], v[30:31], off offset:512
	global_load_dwordx4 v[112:115], v[28:29], off offset:512
	global_load_dwordx4 v[116:119], v[2:3], off offset:512
	global_load_dwordx4 v[124:127], v[8:9], off offset:512
	global_load_dwordx4 v[140:143], v[6:7], off offset:512
	global_load_dwordx4 v[144:147], v[4:5], off offset:512
	global_load_dwordx4 v[148:151], v[0:1], off offset:512
	s_waitcnt lgkmcnt(0)
	v_mfma_f32_32x32x16_bf16 a[16:31], v[128:131], v[120:123], a[16:31]
	global_load_dwordx4 v[120:123], v[12:13], off offset:512
	global_load_dwordx4 v[152:155], v[10:11], off offset:512
	global_load_dwordx4 v[156:159], v[26:27], off offset:512
	global_load_dwordx4 v[160:163], v[14:15], off offset:512
	s_barrier
	v_mfma_f32_32x32x16_bf16 a[0:15], v[128:131], v[104:107], a[0:15]
	ds_read_b128 v[104:107], v59 offset:55296
	ds_read_b128 v[128:131], v69
	ds_read_b128 v[164:167], v59 offset:59904
	ds_read_b128 v[168:171], v69 offset:4608
	s_waitcnt lgkmcnt(2)
	v_mfma_f32_32x32x16_bf16 a[112:127], v[104:107], v[128:131], a[112:127]
	s_waitcnt lgkmcnt(0)
	v_mfma_f32_32x32x16_bf16 a[96:111], v[104:107], v[168:171], a[96:111]
	ds_read_b128 v[104:107], v59 offset:64512
	s_waitcnt lgkmcnt(0)
	v_mfma_f32_32x32x16_bf16 a[48:63], v[104:107], v[128:131], a[48:63]
	v_mfma_f32_32x32x16_bf16 a[32:47], v[104:107], v[168:171], a[32:47]
	ds_read_b128 v[104:107], v61 offset:55296
	s_waitcnt vmcnt(4)
	ds_write_b128 v60, v[148:151]
	ds_write_b128 v60, v[144:147] offset:4608
	ds_write_b128 v60, v[140:143] offset:9216
	ds_write_b128 v60, v[124:127] offset:13824
	s_waitcnt vmcnt(2)
	ds_write_b128 v60, v[152:155] offset:18432
	ds_write_b128 v60, v[120:123] offset:23040
	s_waitcnt vmcnt(0)
	ds_write_b128 v60, v[160:163] offset:27648
	ds_write_b128 v60, v[156:159] offset:32256
	ds_write_b128 v60, v[116:119] offset:36864
	ds_write_b128 v60, v[112:115] offset:41472
	ds_write_b128 v60, v[108:111] offset:46080
	ds_write_b128 v60, v[100:103] offset:50688
	v_mfma_f32_32x32x16_bf16 a[80:95], v[164:167], v[128:131], a[80:95]
	v_mfma_f32_32x32x16_bf16 a[64:79], v[164:167], v[168:171], a[64:79]
	s_waitcnt lgkmcnt(12)
	v_mfma_f32_32x32x16_bf16 a[16:31], v[104:107], v[128:131], a[16:31]
	v_mfma_f32_32x32x16_bf16 a[0:15], v[104:107], v[168:171], a[0:15]
	ds_read_b128 v[100:103], v59 offset:55328
	ds_read_b128 v[104:107], v69 offset:32
	ds_read_b128 v[108:111], v69 offset:64
	ds_read_b128 v[112:115], v59 offset:55360
	ds_read_b128 v[116:119], v69 offset:4640
	ds_read_b128 v[120:123], v69 offset:96
	s_waitcnt lgkmcnt(4)
	v_mfma_f32_32x32x16_bf16 a[112:127], v[100:103], v[104:107], a[112:127]
	s_waitcnt lgkmcnt(1)
	v_mfma_f32_32x32x16_bf16 a[96:111], v[100:103], v[116:119], a[96:111]
	ds_read_b128 v[100:103], v59 offset:59936
	ds_read_b128 v[124:127], v59 offset:55392
	s_waitcnt lgkmcnt(1)
	v_mfma_f32_32x32x16_bf16 a[80:95], v[100:103], v[104:107], a[80:95]
	v_mfma_f32_32x32x16_bf16 a[64:79], v[100:103], v[116:119], a[64:79]
	ds_read_b128 v[100:103], v59 offset:64544
	ds_read_b128 v[128:131], v59 offset:64576
	s_waitcnt lgkmcnt(1)
	v_mfma_f32_32x32x16_bf16 a[48:63], v[100:103], v[104:107], a[48:63]
	v_mfma_f32_32x32x16_bf16 a[32:47], v[100:103], v[116:119], a[32:47]
	ds_read_b128 v[100:103], v61 offset:55328
	ds_read_b128 v[140:143], v59 offset:64608
	s_waitcnt lgkmcnt(1)
	v_mfma_f32_32x32x16_bf16 a[16:31], v[100:103], v[104:107], a[16:31]
	v_mfma_f32_32x32x16_bf16 a[0:15], v[100:103], v[116:119], a[0:15]
	ds_read_b128 v[100:103], v69 offset:4672
	ds_read_b128 v[104:107], v69 offset:4704
	v_mfma_f32_32x32x16_bf16 a[112:127], v[112:115], v[108:111], a[112:127]
	s_waitcnt lgkmcnt(1)
	v_mfma_f32_32x32x16_bf16 a[96:111], v[112:115], v[100:103], a[96:111]
	ds_read_b128 v[112:115], v59 offset:59968
	ds_read_b128 v[116:119], v59 offset:60000
	s_waitcnt lgkmcnt(1)
	v_mfma_f32_32x32x16_bf16 a[80:95], v[112:115], v[108:111], a[80:95]
	v_mfma_f32_32x32x16_bf16 a[64:79], v[112:115], v[100:103], a[64:79]
	v_mfma_f32_32x32x16_bf16 a[48:63], v[128:131], v[108:111], a[48:63]
	v_mfma_f32_32x32x16_bf16 a[32:47], v[128:131], v[100:103], a[32:47]
	ds_read_b128 v[112:115], v61 offset:55360
	ds_read_b128 v[128:131], v61 offset:55392
	s_waitcnt lgkmcnt(1)
	v_mfma_f32_32x32x16_bf16 a[16:31], v[112:115], v[108:111], a[16:31]
	v_mfma_f32_32x32x16_bf16 a[0:15], v[112:115], v[100:103], a[0:15]
	v_mfma_f32_32x32x16_bf16 a[112:127], v[124:127], v[120:123], a[112:127]
	v_mfma_f32_32x32x16_bf16 a[96:111], v[124:127], v[104:107], a[96:111]
	v_mfma_f32_32x32x16_bf16 a[80:95], v[116:119], v[120:123], a[80:95]
	v_mfma_f32_32x32x16_bf16 a[64:79], v[116:119], v[104:107], a[64:79]
	global_load_dwordx4 v[100:103], v[4:5], off offset:640
	global_load_dwordx4 v[108:111], v[0:1], off offset:640
	global_load_dwordx4 v[112:115], v[8:9], off offset:640
	global_load_dwordx4 v[116:119], v[6:7], off offset:640
	v_mfma_f32_32x32x16_bf16 a[48:63], v[140:143], v[120:123], a[48:63]
	v_mfma_f32_32x32x16_bf16 a[32:47], v[140:143], v[104:107], a[32:47]
	global_load_dwordx4 v[124:127], v[10:11], off offset:640
	global_load_dwordx4 v[140:143], v[12:13], off offset:640
	global_load_dwordx4 v[144:147], v[26:27], off offset:640
	global_load_dwordx4 v[148:151], v[14:15], off offset:640
	global_load_dwordx4 v[152:155], v[28:29], off offset:640
	global_load_dwordx4 v[156:159], v[2:3], off offset:640
	global_load_dwordx4 v[160:163], v[30:31], off offset:640
	s_waitcnt lgkmcnt(0)
	v_mfma_f32_32x32x16_bf16 a[16:31], v[128:131], v[120:123], a[16:31]
	global_load_dwordx4 v[120:123], v[32:33], off offset:640
	s_barrier
	v_mfma_f32_32x32x16_bf16 a[0:15], v[128:131], v[104:107], a[0:15]
	ds_read_b128 v[104:107], v59
	ds_read_b128 v[128:131], v62 offset:36864
	ds_read_b128 v[164:167], v59 offset:4608
	ds_read_b128 v[168:171], v62 offset:41472
	s_waitcnt lgkmcnt(2)
	v_mfma_f32_32x32x16_bf16 a[112:127], v[104:107], v[128:131], a[112:127]
	s_waitcnt lgkmcnt(0)
	v_mfma_f32_32x32x16_bf16 a[96:111], v[104:107], v[168:171], a[96:111]
	ds_read_b128 v[104:107], v59 offset:9216
	s_waitcnt lgkmcnt(0)
	v_mfma_f32_32x32x16_bf16 a[48:63], v[104:107], v[128:131], a[48:63]
	v_mfma_f32_32x32x16_bf16 a[32:47], v[104:107], v[168:171], a[32:47]
	ds_read_b128 v[104:107], v61
	s_waitcnt vmcnt(10)
	ds_write_b128 v60, v[108:111] offset:55296
	ds_write_b128 v60, v[100:103] offset:59904
	s_waitcnt vmcnt(8)
	ds_write_b128 v60, v[116:119] offset:64512
	ds_write_b128 v63, v[112:115] offset:55296
	s_waitcnt vmcnt(7)
	ds_write_b128 v64, v[124:127] offset:55296
	s_waitcnt vmcnt(6)
	ds_write_b128 v65, v[140:143] offset:55296
	s_waitcnt vmcnt(4)
	ds_write_b128 v66, v[148:151] offset:55296
	ds_write_b128 v67, v[144:147] offset:55296
	s_waitcnt vmcnt(2)
	ds_write_b128 v68, v[156:159]
	ds_write_b128 v68, v[152:155] offset:4608
	s_waitcnt vmcnt(1)
	ds_write_b128 v68, v[160:163] offset:9216
	s_waitcnt vmcnt(0)
	ds_write_b128 v68, v[120:123] offset:13824
	v_mfma_f32_32x32x16_bf16 a[80:95], v[164:167], v[128:131], a[80:95]
	v_mfma_f32_32x32x16_bf16 a[64:79], v[164:167], v[168:171], a[64:79]
	s_waitcnt lgkmcnt(12)
	v_mfma_f32_32x32x16_bf16 a[16:31], v[104:107], v[128:131], a[16:31]
	v_mfma_f32_32x32x16_bf16 a[0:15], v[104:107], v[168:171], a[0:15]
	ds_read_b128 v[100:103], v59 offset:32
	ds_read_b128 v[104:107], v62 offset:36896
	ds_read_b128 v[108:111], v62 offset:36928
	ds_read_b128 v[112:115], v59 offset:64
	ds_read_b128 v[116:119], v62 offset:41504
	ds_read_b128 v[120:123], v62 offset:36960
	s_waitcnt lgkmcnt(4)
	v_mfma_f32_32x32x16_bf16 a[112:127], v[100:103], v[104:107], a[112:127]
	s_waitcnt lgkmcnt(1)
	v_mfma_f32_32x32x16_bf16 a[96:111], v[100:103], v[116:119], a[96:111]
	ds_read_b128 v[100:103], v59 offset:4640
	ds_read_b128 v[124:127], v59 offset:96
	s_waitcnt lgkmcnt(1)
	v_mfma_f32_32x32x16_bf16 a[80:95], v[100:103], v[104:107], a[80:95]
	v_mfma_f32_32x32x16_bf16 a[64:79], v[100:103], v[116:119], a[64:79]
	ds_read_b128 v[100:103], v59 offset:9248
	ds_read_b128 v[128:131], v59 offset:9280
	s_waitcnt lgkmcnt(1)
	v_mfma_f32_32x32x16_bf16 a[48:63], v[100:103], v[104:107], a[48:63]
	v_mfma_f32_32x32x16_bf16 a[32:47], v[100:103], v[116:119], a[32:47]
	ds_read_b128 v[100:103], v61 offset:32
	ds_read_b128 v[140:143], v59 offset:9312
	s_waitcnt lgkmcnt(1)
	v_mfma_f32_32x32x16_bf16 a[16:31], v[100:103], v[104:107], a[16:31]
	v_mfma_f32_32x32x16_bf16 a[0:15], v[100:103], v[116:119], a[0:15]
	ds_read_b128 v[100:103], v62 offset:41536
	ds_read_b128 v[104:107], v62 offset:41568
	v_mfma_f32_32x32x16_bf16 a[112:127], v[112:115], v[108:111], a[112:127]
	s_waitcnt lgkmcnt(1)
	v_mfma_f32_32x32x16_bf16 a[96:111], v[112:115], v[100:103], a[96:111]
	ds_read_b128 v[112:115], v59 offset:4672
	ds_read_b128 v[116:119], v59 offset:4704
	s_waitcnt lgkmcnt(1)
	v_mfma_f32_32x32x16_bf16 a[80:95], v[112:115], v[108:111], a[80:95]
	v_mfma_f32_32x32x16_bf16 a[64:79], v[112:115], v[100:103], a[64:79]
	v_mfma_f32_32x32x16_bf16 a[48:63], v[128:131], v[108:111], a[48:63]
	v_mfma_f32_32x32x16_bf16 a[32:47], v[128:131], v[100:103], a[32:47]
	ds_read_b128 v[112:115], v61 offset:64
	ds_read_b128 v[128:131], v61 offset:96
	s_waitcnt lgkmcnt(1)
	v_mfma_f32_32x32x16_bf16 a[16:31], v[112:115], v[108:111], a[16:31]
	v_mfma_f32_32x32x16_bf16 a[0:15], v[112:115], v[100:103], a[0:15]
	global_load_dwordx4 v[100:103], v[32:33], off offset:768
	v_mfma_f32_32x32x16_bf16 a[112:127], v[124:127], v[120:123], a[112:127]
	v_mfma_f32_32x32x16_bf16 a[96:111], v[124:127], v[104:107], a[96:111]
	v_mfma_f32_32x32x16_bf16 a[80:95], v[116:119], v[120:123], a[80:95]
	v_mfma_f32_32x32x16_bf16 a[64:79], v[116:119], v[104:107], a[64:79]
	v_mfma_f32_32x32x16_bf16 a[48:63], v[140:143], v[120:123], a[48:63]
	v_mfma_f32_32x32x16_bf16 a[32:47], v[140:143], v[104:107], a[32:47]
	global_load_dwordx4 v[108:111], v[30:31], off offset:768
	global_load_dwordx4 v[112:115], v[28:29], off offset:768
	global_load_dwordx4 v[116:119], v[2:3], off offset:768
	global_load_dwordx4 v[124:127], v[8:9], off offset:768
	global_load_dwordx4 v[140:143], v[6:7], off offset:768
	global_load_dwordx4 v[144:147], v[4:5], off offset:768
	global_load_dwordx4 v[148:151], v[0:1], off offset:768
	s_waitcnt lgkmcnt(0)
	v_mfma_f32_32x32x16_bf16 a[16:31], v[128:131], v[120:123], a[16:31]
	global_load_dwordx4 v[120:123], v[12:13], off offset:768
	global_load_dwordx4 v[152:155], v[10:11], off offset:768
	global_load_dwordx4 v[156:159], v[26:27], off offset:768
	global_load_dwordx4 v[160:163], v[14:15], off offset:768
	s_barrier
	v_mfma_f32_32x32x16_bf16 a[0:15], v[128:131], v[104:107], a[0:15]
	ds_read_b128 v[104:107], v59 offset:55296
	ds_read_b128 v[128:131], v69
	ds_read_b128 v[164:167], v59 offset:59904
	ds_read_b128 v[168:171], v69 offset:4608
	s_waitcnt lgkmcnt(2)
	v_mfma_f32_32x32x16_bf16 a[112:127], v[104:107], v[128:131], a[112:127]
	s_waitcnt lgkmcnt(0)
	v_mfma_f32_32x32x16_bf16 a[96:111], v[104:107], v[168:171], a[96:111]
	ds_read_b128 v[104:107], v59 offset:64512
	s_waitcnt lgkmcnt(0)
	v_mfma_f32_32x32x16_bf16 a[48:63], v[104:107], v[128:131], a[48:63]
	v_mfma_f32_32x32x16_bf16 a[32:47], v[104:107], v[168:171], a[32:47]
	ds_read_b128 v[104:107], v61 offset:55296
	s_waitcnt vmcnt(4)
	ds_write_b128 v60, v[148:151]
	ds_write_b128 v60, v[144:147] offset:4608
	ds_write_b128 v60, v[140:143] offset:9216
	ds_write_b128 v60, v[124:127] offset:13824
	s_waitcnt vmcnt(2)
	ds_write_b128 v60, v[152:155] offset:18432
	ds_write_b128 v60, v[120:123] offset:23040
	s_waitcnt vmcnt(0)
	ds_write_b128 v60, v[160:163] offset:27648
	ds_write_b128 v60, v[156:159] offset:32256
	ds_write_b128 v60, v[116:119] offset:36864
	ds_write_b128 v60, v[112:115] offset:41472
	ds_write_b128 v60, v[108:111] offset:46080
	ds_write_b128 v60, v[100:103] offset:50688
	v_mfma_f32_32x32x16_bf16 a[80:95], v[164:167], v[128:131], a[80:95]
	v_mfma_f32_32x32x16_bf16 a[64:79], v[164:167], v[168:171], a[64:79]
	s_waitcnt lgkmcnt(12)
	v_mfma_f32_32x32x16_bf16 a[16:31], v[104:107], v[128:131], a[16:31]
	v_mfma_f32_32x32x16_bf16 a[0:15], v[104:107], v[168:171], a[0:15]
	ds_read_b128 v[100:103], v59 offset:55328
	ds_read_b128 v[104:107], v69 offset:32
	ds_read_b128 v[108:111], v69 offset:64
	ds_read_b128 v[112:115], v59 offset:55360
	ds_read_b128 v[116:119], v69 offset:4640
	ds_read_b128 v[120:123], v69 offset:96
	s_waitcnt lgkmcnt(4)
	v_mfma_f32_32x32x16_bf16 a[112:127], v[100:103], v[104:107], a[112:127]
	s_waitcnt lgkmcnt(1)
	v_mfma_f32_32x32x16_bf16 a[96:111], v[100:103], v[116:119], a[96:111]
	ds_read_b128 v[100:103], v59 offset:59936
	ds_read_b128 v[124:127], v59 offset:55392
	s_waitcnt lgkmcnt(1)
	v_mfma_f32_32x32x16_bf16 a[80:95], v[100:103], v[104:107], a[80:95]
	v_mfma_f32_32x32x16_bf16 a[64:79], v[100:103], v[116:119], a[64:79]
	ds_read_b128 v[100:103], v59 offset:64544
	ds_read_b128 v[128:131], v59 offset:64576
	s_waitcnt lgkmcnt(1)
	v_mfma_f32_32x32x16_bf16 a[48:63], v[100:103], v[104:107], a[48:63]
	v_mfma_f32_32x32x16_bf16 a[32:47], v[100:103], v[116:119], a[32:47]
	ds_read_b128 v[100:103], v61 offset:55328
	ds_read_b128 v[140:143], v59 offset:64608
	s_waitcnt lgkmcnt(1)
	v_mfma_f32_32x32x16_bf16 a[16:31], v[100:103], v[104:107], a[16:31]
	v_mfma_f32_32x32x16_bf16 a[0:15], v[100:103], v[116:119], a[0:15]
	ds_read_b128 v[100:103], v69 offset:4672
	ds_read_b128 v[104:107], v69 offset:4704
	v_mfma_f32_32x32x16_bf16 a[112:127], v[112:115], v[108:111], a[112:127]
	s_waitcnt lgkmcnt(1)
	v_mfma_f32_32x32x16_bf16 a[96:111], v[112:115], v[100:103], a[96:111]
	ds_read_b128 v[112:115], v59 offset:59968
	ds_read_b128 v[116:119], v59 offset:60000
	s_waitcnt lgkmcnt(1)
	v_mfma_f32_32x32x16_bf16 a[80:95], v[112:115], v[108:111], a[80:95]
	v_mfma_f32_32x32x16_bf16 a[64:79], v[112:115], v[100:103], a[64:79]
	v_mfma_f32_32x32x16_bf16 a[48:63], v[128:131], v[108:111], a[48:63]
	v_mfma_f32_32x32x16_bf16 a[32:47], v[128:131], v[100:103], a[32:47]
	ds_read_b128 v[112:115], v61 offset:55360
	ds_read_b128 v[128:131], v61 offset:55392
	s_waitcnt lgkmcnt(1)
	v_mfma_f32_32x32x16_bf16 a[16:31], v[112:115], v[108:111], a[16:31]
	v_mfma_f32_32x32x16_bf16 a[0:15], v[112:115], v[100:103], a[0:15]
	v_mfma_f32_32x32x16_bf16 a[112:127], v[124:127], v[120:123], a[112:127]
	v_mfma_f32_32x32x16_bf16 a[96:111], v[124:127], v[104:107], a[96:111]
	v_mfma_f32_32x32x16_bf16 a[80:95], v[116:119], v[120:123], a[80:95]
	v_mfma_f32_32x32x16_bf16 a[64:79], v[116:119], v[104:107], a[64:79]
	global_load_dwordx4 v[100:103], v[4:5], off offset:896
	global_load_dwordx4 v[108:111], v[0:1], off offset:896
	global_load_dwordx4 v[112:115], v[8:9], off offset:896
	global_load_dwordx4 v[116:119], v[6:7], off offset:896
	v_mfma_f32_32x32x16_bf16 a[48:63], v[140:143], v[120:123], a[48:63]
	v_mfma_f32_32x32x16_bf16 a[32:47], v[140:143], v[104:107], a[32:47]
	global_load_dwordx4 v[124:127], v[10:11], off offset:896
	global_load_dwordx4 v[140:143], v[12:13], off offset:896
	global_load_dwordx4 v[144:147], v[26:27], off offset:896
	global_load_dwordx4 v[148:151], v[14:15], off offset:896
	global_load_dwordx4 v[152:155], v[28:29], off offset:896
	global_load_dwordx4 v[156:159], v[2:3], off offset:896
	global_load_dwordx4 v[160:163], v[30:31], off offset:896
	s_waitcnt lgkmcnt(0)
	v_mfma_f32_32x32x16_bf16 a[16:31], v[128:131], v[120:123], a[16:31]
	global_load_dwordx4 v[120:123], v[32:33], off offset:896
	s_barrier
	v_mfma_f32_32x32x16_bf16 a[0:15], v[128:131], v[104:107], a[0:15]
	ds_read_b128 v[104:107], v59
	ds_read_b128 v[128:131], v62 offset:36864
	ds_read_b128 v[164:167], v59 offset:4608
	ds_read_b128 v[168:171], v62 offset:41472
	s_waitcnt lgkmcnt(2)
	v_mfma_f32_32x32x16_bf16 a[112:127], v[104:107], v[128:131], a[112:127]
	s_waitcnt lgkmcnt(0)
	v_mfma_f32_32x32x16_bf16 a[96:111], v[104:107], v[168:171], a[96:111]
	ds_read_b128 v[104:107], v59 offset:9216
	s_waitcnt lgkmcnt(0)
	v_mfma_f32_32x32x16_bf16 a[48:63], v[104:107], v[128:131], a[48:63]
	v_mfma_f32_32x32x16_bf16 a[32:47], v[104:107], v[168:171], a[32:47]
	ds_read_b128 v[104:107], v61
	s_waitcnt vmcnt(10)
	ds_write_b128 v60, v[108:111] offset:55296
	ds_write_b128 v60, v[100:103] offset:59904
	s_waitcnt vmcnt(8)
	ds_write_b128 v60, v[116:119] offset:64512
	ds_write_b128 v63, v[112:115] offset:55296
	s_waitcnt vmcnt(7)
	ds_write_b128 v64, v[124:127] offset:55296
	s_waitcnt vmcnt(6)
	ds_write_b128 v65, v[140:143] offset:55296
	s_waitcnt vmcnt(4)
	ds_write_b128 v66, v[148:151] offset:55296
	ds_write_b128 v67, v[144:147] offset:55296
	s_waitcnt vmcnt(2)
	ds_write_b128 v68, v[156:159]
	ds_write_b128 v68, v[152:155] offset:4608
	s_waitcnt vmcnt(1)
	ds_write_b128 v68, v[160:163] offset:9216
	s_waitcnt vmcnt(0)
	ds_write_b128 v68, v[120:123] offset:13824
	v_mfma_f32_32x32x16_bf16 a[80:95], v[164:167], v[128:131], a[80:95]
	v_mfma_f32_32x32x16_bf16 a[64:79], v[164:167], v[168:171], a[64:79]
	s_waitcnt lgkmcnt(12)
	v_mfma_f32_32x32x16_bf16 a[16:31], v[104:107], v[128:131], a[16:31]
	v_mfma_f32_32x32x16_bf16 a[0:15], v[104:107], v[168:171], a[0:15]
	ds_read_b128 v[100:103], v59 offset:32
	ds_read_b128 v[104:107], v62 offset:36896
	ds_read_b128 v[108:111], v62 offset:36928
	ds_read_b128 v[112:115], v59 offset:64
	ds_read_b128 v[116:119], v62 offset:41504
	ds_read_b128 v[120:123], v62 offset:36960
	s_waitcnt lgkmcnt(4)
	v_mfma_f32_32x32x16_bf16 a[112:127], v[100:103], v[104:107], a[112:127]
	s_waitcnt lgkmcnt(1)
	v_mfma_f32_32x32x16_bf16 a[96:111], v[100:103], v[116:119], a[96:111]
	ds_read_b128 v[100:103], v59 offset:4640
	ds_read_b128 v[124:127], v59 offset:96
	s_waitcnt lgkmcnt(1)
	v_mfma_f32_32x32x16_bf16 a[80:95], v[100:103], v[104:107], a[80:95]
	v_mfma_f32_32x32x16_bf16 a[64:79], v[100:103], v[116:119], a[64:79]
	ds_read_b128 v[100:103], v59 offset:9248
	ds_read_b128 v[128:131], v59 offset:9280
	s_waitcnt lgkmcnt(1)
	v_mfma_f32_32x32x16_bf16 a[48:63], v[100:103], v[104:107], a[48:63]
	v_mfma_f32_32x32x16_bf16 a[32:47], v[100:103], v[116:119], a[32:47]
	ds_read_b128 v[100:103], v61 offset:32
	ds_read_b128 v[140:143], v59 offset:9312
	s_waitcnt lgkmcnt(1)
	v_mfma_f32_32x32x16_bf16 a[16:31], v[100:103], v[104:107], a[16:31]
	v_mfma_f32_32x32x16_bf16 a[0:15], v[100:103], v[116:119], a[0:15]
	ds_read_b128 v[100:103], v62 offset:41536
	ds_read_b128 v[104:107], v62 offset:41568
	v_mfma_f32_32x32x16_bf16 a[112:127], v[112:115], v[108:111], a[112:127]
	s_waitcnt lgkmcnt(1)
	v_mfma_f32_32x32x16_bf16 a[96:111], v[112:115], v[100:103], a[96:111]
	ds_read_b128 v[112:115], v59 offset:4672
	ds_read_b128 v[116:119], v59 offset:4704
	s_waitcnt lgkmcnt(1)
	v_mfma_f32_32x32x16_bf16 a[80:95], v[112:115], v[108:111], a[80:95]
	v_mfma_f32_32x32x16_bf16 a[64:79], v[112:115], v[100:103], a[64:79]
	v_mfma_f32_32x32x16_bf16 a[48:63], v[128:131], v[108:111], a[48:63]
	v_mfma_f32_32x32x16_bf16 a[32:47], v[128:131], v[100:103], a[32:47]
	ds_read_b128 v[112:115], v61 offset:64
	ds_read_b128 v[128:131], v61 offset:96
	s_waitcnt lgkmcnt(1)
	v_mfma_f32_32x32x16_bf16 a[16:31], v[112:115], v[108:111], a[16:31]
	v_mfma_f32_32x32x16_bf16 a[0:15], v[112:115], v[100:103], a[0:15]
	global_load_dwordx4 v[100:103], v[32:33], off offset:1024
	v_mfma_f32_32x32x16_bf16 a[112:127], v[124:127], v[120:123], a[112:127]
	v_mfma_f32_32x32x16_bf16 a[96:111], v[124:127], v[104:107], a[96:111]
	v_mfma_f32_32x32x16_bf16 a[80:95], v[116:119], v[120:123], a[80:95]
	v_mfma_f32_32x32x16_bf16 a[64:79], v[116:119], v[104:107], a[64:79]
	v_mfma_f32_32x32x16_bf16 a[48:63], v[140:143], v[120:123], a[48:63]
	v_mfma_f32_32x32x16_bf16 a[32:47], v[140:143], v[104:107], a[32:47]
	global_load_dwordx4 v[108:111], v[30:31], off offset:1024
	global_load_dwordx4 v[112:115], v[28:29], off offset:1024
	global_load_dwordx4 v[116:119], v[2:3], off offset:1024
	global_load_dwordx4 v[124:127], v[8:9], off offset:1024
	global_load_dwordx4 v[140:143], v[6:7], off offset:1024
	global_load_dwordx4 v[144:147], v[4:5], off offset:1024
	global_load_dwordx4 v[148:151], v[0:1], off offset:1024
	s_waitcnt lgkmcnt(0)
	v_mfma_f32_32x32x16_bf16 a[16:31], v[128:131], v[120:123], a[16:31]
	global_load_dwordx4 v[120:123], v[12:13], off offset:1024
	global_load_dwordx4 v[152:155], v[10:11], off offset:1024
	global_load_dwordx4 v[156:159], v[26:27], off offset:1024
	global_load_dwordx4 v[160:163], v[14:15], off offset:1024
	s_barrier
	v_mfma_f32_32x32x16_bf16 a[0:15], v[128:131], v[104:107], a[0:15]
	ds_read_b128 v[104:107], v59 offset:55296
	ds_read_b128 v[128:131], v69
	ds_read_b128 v[164:167], v59 offset:59904
	ds_read_b128 v[168:171], v69 offset:4608
	s_waitcnt lgkmcnt(2)
	v_mfma_f32_32x32x16_bf16 a[112:127], v[104:107], v[128:131], a[112:127]
	s_waitcnt lgkmcnt(0)
	v_mfma_f32_32x32x16_bf16 a[96:111], v[104:107], v[168:171], a[96:111]
	ds_read_b128 v[104:107], v59 offset:64512
	s_waitcnt lgkmcnt(0)
	v_mfma_f32_32x32x16_bf16 a[48:63], v[104:107], v[128:131], a[48:63]
	v_mfma_f32_32x32x16_bf16 a[32:47], v[104:107], v[168:171], a[32:47]
	ds_read_b128 v[104:107], v61 offset:55296
	s_waitcnt vmcnt(4)
	ds_write_b128 v60, v[148:151]
	ds_write_b128 v60, v[144:147] offset:4608
	ds_write_b128 v60, v[140:143] offset:9216
	ds_write_b128 v60, v[124:127] offset:13824
	s_waitcnt vmcnt(2)
	ds_write_b128 v60, v[152:155] offset:18432
	ds_write_b128 v60, v[120:123] offset:23040
	s_waitcnt vmcnt(0)
	ds_write_b128 v60, v[160:163] offset:27648
	ds_write_b128 v60, v[156:159] offset:32256
	ds_write_b128 v60, v[116:119] offset:36864
	ds_write_b128 v60, v[112:115] offset:41472
	ds_write_b128 v60, v[108:111] offset:46080
	ds_write_b128 v60, v[100:103] offset:50688
	v_mfma_f32_32x32x16_bf16 a[80:95], v[164:167], v[128:131], a[80:95]
	v_mfma_f32_32x32x16_bf16 a[64:79], v[164:167], v[168:171], a[64:79]
	s_waitcnt lgkmcnt(12)
	v_mfma_f32_32x32x16_bf16 a[16:31], v[104:107], v[128:131], a[16:31]
	v_mfma_f32_32x32x16_bf16 a[0:15], v[104:107], v[168:171], a[0:15]
	ds_read_b128 v[100:103], v59 offset:55328
	ds_read_b128 v[104:107], v69 offset:32
	ds_read_b128 v[108:111], v69 offset:64
	ds_read_b128 v[112:115], v59 offset:55360
	ds_read_b128 v[116:119], v69 offset:4640
	ds_read_b128 v[120:123], v69 offset:96
	s_waitcnt lgkmcnt(4)
	v_mfma_f32_32x32x16_bf16 a[112:127], v[100:103], v[104:107], a[112:127]
	s_waitcnt lgkmcnt(1)
	v_mfma_f32_32x32x16_bf16 a[96:111], v[100:103], v[116:119], a[96:111]
	ds_read_b128 v[100:103], v59 offset:59936
	ds_read_b128 v[124:127], v59 offset:55392
	s_waitcnt lgkmcnt(1)
	v_mfma_f32_32x32x16_bf16 a[80:95], v[100:103], v[104:107], a[80:95]
	v_mfma_f32_32x32x16_bf16 a[64:79], v[100:103], v[116:119], a[64:79]
	ds_read_b128 v[100:103], v59 offset:64544
	ds_read_b128 v[128:131], v59 offset:64576
	s_waitcnt lgkmcnt(1)
	v_mfma_f32_32x32x16_bf16 a[48:63], v[100:103], v[104:107], a[48:63]
	v_mfma_f32_32x32x16_bf16 a[32:47], v[100:103], v[116:119], a[32:47]
	ds_read_b128 v[100:103], v61 offset:55328
	ds_read_b128 v[140:143], v59 offset:64608
	s_waitcnt lgkmcnt(1)
	v_mfma_f32_32x32x16_bf16 a[16:31], v[100:103], v[104:107], a[16:31]
	v_mfma_f32_32x32x16_bf16 a[0:15], v[100:103], v[116:119], a[0:15]
	ds_read_b128 v[100:103], v69 offset:4672
	ds_read_b128 v[104:107], v69 offset:4704
	v_mfma_f32_32x32x16_bf16 a[112:127], v[112:115], v[108:111], a[112:127]
	s_waitcnt lgkmcnt(1)
	v_mfma_f32_32x32x16_bf16 a[96:111], v[112:115], v[100:103], a[96:111]
	ds_read_b128 v[112:115], v59 offset:59968
	ds_read_b128 v[116:119], v59 offset:60000
	s_waitcnt lgkmcnt(1)
	v_mfma_f32_32x32x16_bf16 a[80:95], v[112:115], v[108:111], a[80:95]
	v_mfma_f32_32x32x16_bf16 a[64:79], v[112:115], v[100:103], a[64:79]
	v_mfma_f32_32x32x16_bf16 a[48:63], v[128:131], v[108:111], a[48:63]
	v_mfma_f32_32x32x16_bf16 a[32:47], v[128:131], v[100:103], a[32:47]
	ds_read_b128 v[112:115], v61 offset:55360
	ds_read_b128 v[128:131], v61 offset:55392
	s_waitcnt lgkmcnt(1)
	v_mfma_f32_32x32x16_bf16 a[16:31], v[112:115], v[108:111], a[16:31]
	v_mfma_f32_32x32x16_bf16 a[0:15], v[112:115], v[100:103], a[0:15]
	v_mfma_f32_32x32x16_bf16 a[112:127], v[124:127], v[120:123], a[112:127]
	v_mfma_f32_32x32x16_bf16 a[96:111], v[124:127], v[104:107], a[96:111]
	v_mfma_f32_32x32x16_bf16 a[80:95], v[116:119], v[120:123], a[80:95]
	v_mfma_f32_32x32x16_bf16 a[64:79], v[116:119], v[104:107], a[64:79]
	global_load_dwordx4 v[100:103], v[4:5], off offset:1152
	global_load_dwordx4 v[108:111], v[0:1], off offset:1152
	global_load_dwordx4 v[112:115], v[8:9], off offset:1152
	global_load_dwordx4 v[116:119], v[6:7], off offset:1152
	v_mfma_f32_32x32x16_bf16 a[48:63], v[140:143], v[120:123], a[48:63]
	v_mfma_f32_32x32x16_bf16 a[32:47], v[140:143], v[104:107], a[32:47]
	global_load_dwordx4 v[124:127], v[10:11], off offset:1152
	global_load_dwordx4 v[140:143], v[12:13], off offset:1152
	global_load_dwordx4 v[144:147], v[26:27], off offset:1152
	global_load_dwordx4 v[148:151], v[14:15], off offset:1152
	global_load_dwordx4 v[152:155], v[28:29], off offset:1152
	global_load_dwordx4 v[156:159], v[2:3], off offset:1152
	global_load_dwordx4 v[160:163], v[30:31], off offset:1152
	s_waitcnt lgkmcnt(0)
	v_mfma_f32_32x32x16_bf16 a[16:31], v[128:131], v[120:123], a[16:31]
	global_load_dwordx4 v[120:123], v[32:33], off offset:1152
	s_barrier
	v_mfma_f32_32x32x16_bf16 a[0:15], v[128:131], v[104:107], a[0:15]
	ds_read_b128 v[104:107], v59
	ds_read_b128 v[128:131], v62 offset:36864
	ds_read_b128 v[164:167], v59 offset:4608
	ds_read_b128 v[168:171], v62 offset:41472
	s_waitcnt lgkmcnt(2)
	v_mfma_f32_32x32x16_bf16 a[112:127], v[104:107], v[128:131], a[112:127]
	s_waitcnt lgkmcnt(0)
	v_mfma_f32_32x32x16_bf16 a[96:111], v[104:107], v[168:171], a[96:111]
	ds_read_b128 v[104:107], v59 offset:9216
	s_waitcnt lgkmcnt(0)
	v_mfma_f32_32x32x16_bf16 a[48:63], v[104:107], v[128:131], a[48:63]
	v_mfma_f32_32x32x16_bf16 a[32:47], v[104:107], v[168:171], a[32:47]
	ds_read_b128 v[104:107], v61
	s_waitcnt vmcnt(10)
	ds_write_b128 v60, v[108:111] offset:55296
	ds_write_b128 v60, v[100:103] offset:59904
	s_waitcnt vmcnt(8)
	ds_write_b128 v60, v[116:119] offset:64512
	ds_write_b128 v63, v[112:115] offset:55296
	s_waitcnt vmcnt(7)
	ds_write_b128 v64, v[124:127] offset:55296
	s_waitcnt vmcnt(6)
	ds_write_b128 v65, v[140:143] offset:55296
	s_waitcnt vmcnt(4)
	ds_write_b128 v66, v[148:151] offset:55296
	ds_write_b128 v67, v[144:147] offset:55296
	s_waitcnt vmcnt(2)
	ds_write_b128 v68, v[156:159]
	ds_write_b128 v68, v[152:155] offset:4608
	s_waitcnt vmcnt(1)
	ds_write_b128 v68, v[160:163] offset:9216
	s_waitcnt vmcnt(0)
	ds_write_b128 v68, v[120:123] offset:13824
	v_mfma_f32_32x32x16_bf16 a[80:95], v[164:167], v[128:131], a[80:95]
	v_mfma_f32_32x32x16_bf16 a[64:79], v[164:167], v[168:171], a[64:79]
	s_waitcnt lgkmcnt(12)
	v_mfma_f32_32x32x16_bf16 a[16:31], v[104:107], v[128:131], a[16:31]
	v_mfma_f32_32x32x16_bf16 a[0:15], v[104:107], v[168:171], a[0:15]
	ds_read_b128 v[100:103], v59 offset:32
	ds_read_b128 v[104:107], v62 offset:36896
	ds_read_b128 v[108:111], v62 offset:36928
	ds_read_b128 v[112:115], v59 offset:64
	ds_read_b128 v[116:119], v62 offset:41504
	ds_read_b128 v[120:123], v62 offset:36960
	s_waitcnt lgkmcnt(4)
	v_mfma_f32_32x32x16_bf16 a[112:127], v[100:103], v[104:107], a[112:127]
	s_waitcnt lgkmcnt(1)
	v_mfma_f32_32x32x16_bf16 a[96:111], v[100:103], v[116:119], a[96:111]
	ds_read_b128 v[100:103], v59 offset:4640
	ds_read_b128 v[124:127], v59 offset:96
	s_waitcnt lgkmcnt(1)
	v_mfma_f32_32x32x16_bf16 a[80:95], v[100:103], v[104:107], a[80:95]
	v_mfma_f32_32x32x16_bf16 a[64:79], v[100:103], v[116:119], a[64:79]
	ds_read_b128 v[100:103], v59 offset:9248
	ds_read_b128 v[128:131], v59 offset:9280
	s_waitcnt lgkmcnt(1)
	v_mfma_f32_32x32x16_bf16 a[48:63], v[100:103], v[104:107], a[48:63]
	v_mfma_f32_32x32x16_bf16 a[32:47], v[100:103], v[116:119], a[32:47]
	ds_read_b128 v[100:103], v61 offset:32
	ds_read_b128 v[140:143], v59 offset:9312
	s_waitcnt lgkmcnt(1)
	v_mfma_f32_32x32x16_bf16 a[16:31], v[100:103], v[104:107], a[16:31]
	v_mfma_f32_32x32x16_bf16 a[0:15], v[100:103], v[116:119], a[0:15]
	ds_read_b128 v[100:103], v62 offset:41536
	ds_read_b128 v[104:107], v62 offset:41568
	v_mfma_f32_32x32x16_bf16 a[112:127], v[112:115], v[108:111], a[112:127]
	s_waitcnt lgkmcnt(1)
	v_mfma_f32_32x32x16_bf16 a[96:111], v[112:115], v[100:103], a[96:111]
	ds_read_b128 v[112:115], v59 offset:4672
	ds_read_b128 v[116:119], v59 offset:4704
	s_waitcnt lgkmcnt(1)
	v_mfma_f32_32x32x16_bf16 a[80:95], v[112:115], v[108:111], a[80:95]
	v_mfma_f32_32x32x16_bf16 a[64:79], v[112:115], v[100:103], a[64:79]
	v_mfma_f32_32x32x16_bf16 a[48:63], v[128:131], v[108:111], a[48:63]
	v_mfma_f32_32x32x16_bf16 a[32:47], v[128:131], v[100:103], a[32:47]
	ds_read_b128 v[112:115], v61 offset:64
	ds_read_b128 v[128:131], v61 offset:96
	s_waitcnt lgkmcnt(1)
	v_mfma_f32_32x32x16_bf16 a[16:31], v[112:115], v[108:111], a[16:31]
	v_mfma_f32_32x32x16_bf16 a[0:15], v[112:115], v[100:103], a[0:15]
	global_load_dwordx4 v[100:103], v[32:33], off offset:1280
	v_mfma_f32_32x32x16_bf16 a[112:127], v[124:127], v[120:123], a[112:127]
	v_mfma_f32_32x32x16_bf16 a[96:111], v[124:127], v[104:107], a[96:111]
	v_mfma_f32_32x32x16_bf16 a[80:95], v[116:119], v[120:123], a[80:95]
	v_mfma_f32_32x32x16_bf16 a[64:79], v[116:119], v[104:107], a[64:79]
	v_mfma_f32_32x32x16_bf16 a[48:63], v[140:143], v[120:123], a[48:63]
	v_mfma_f32_32x32x16_bf16 a[32:47], v[140:143], v[104:107], a[32:47]
	global_load_dwordx4 v[108:111], v[30:31], off offset:1280
	global_load_dwordx4 v[112:115], v[28:29], off offset:1280
	global_load_dwordx4 v[116:119], v[2:3], off offset:1280
	global_load_dwordx4 v[124:127], v[8:9], off offset:1280
	global_load_dwordx4 v[140:143], v[6:7], off offset:1280
	global_load_dwordx4 v[144:147], v[4:5], off offset:1280
	global_load_dwordx4 v[148:151], v[0:1], off offset:1280
	s_waitcnt lgkmcnt(0)
	v_mfma_f32_32x32x16_bf16 a[16:31], v[128:131], v[120:123], a[16:31]
	global_load_dwordx4 v[120:123], v[12:13], off offset:1280
	global_load_dwordx4 v[152:155], v[10:11], off offset:1280
	global_load_dwordx4 v[156:159], v[26:27], off offset:1280
	global_load_dwordx4 v[160:163], v[14:15], off offset:1280
	s_barrier
	v_mfma_f32_32x32x16_bf16 a[0:15], v[128:131], v[104:107], a[0:15]
	ds_read_b128 v[104:107], v59 offset:55296
	ds_read_b128 v[128:131], v69
	ds_read_b128 v[164:167], v59 offset:59904
	ds_read_b128 v[168:171], v69 offset:4608
	s_waitcnt lgkmcnt(2)
	v_mfma_f32_32x32x16_bf16 a[112:127], v[104:107], v[128:131], a[112:127]
	s_waitcnt lgkmcnt(0)
	v_mfma_f32_32x32x16_bf16 a[96:111], v[104:107], v[168:171], a[96:111]
	ds_read_b128 v[104:107], v59 offset:64512
	s_waitcnt lgkmcnt(0)
	v_mfma_f32_32x32x16_bf16 a[48:63], v[104:107], v[128:131], a[48:63]
	v_mfma_f32_32x32x16_bf16 a[32:47], v[104:107], v[168:171], a[32:47]
	ds_read_b128 v[104:107], v61 offset:55296
	s_waitcnt vmcnt(4)
	ds_write_b128 v60, v[148:151]
	ds_write_b128 v60, v[144:147] offset:4608
	ds_write_b128 v60, v[140:143] offset:9216
	ds_write_b128 v60, v[124:127] offset:13824
	s_waitcnt vmcnt(2)
	ds_write_b128 v60, v[152:155] offset:18432
	ds_write_b128 v60, v[120:123] offset:23040
	s_waitcnt vmcnt(0)
	ds_write_b128 v60, v[160:163] offset:27648
	ds_write_b128 v60, v[156:159] offset:32256
	ds_write_b128 v60, v[116:119] offset:36864
	ds_write_b128 v60, v[112:115] offset:41472
	ds_write_b128 v60, v[108:111] offset:46080
	ds_write_b128 v60, v[100:103] offset:50688
	v_mfma_f32_32x32x16_bf16 a[80:95], v[164:167], v[128:131], a[80:95]
	v_mfma_f32_32x32x16_bf16 a[64:79], v[164:167], v[168:171], a[64:79]
	s_waitcnt lgkmcnt(12)
	v_mfma_f32_32x32x16_bf16 a[16:31], v[104:107], v[128:131], a[16:31]
	v_mfma_f32_32x32x16_bf16 a[0:15], v[104:107], v[168:171], a[0:15]
	ds_read_b128 v[100:103], v59 offset:55328
	ds_read_b128 v[104:107], v69 offset:32
	ds_read_b128 v[108:111], v69 offset:64
	ds_read_b128 v[112:115], v59 offset:55360
	ds_read_b128 v[116:119], v69 offset:4640
	ds_read_b128 v[120:123], v69 offset:96
	s_waitcnt lgkmcnt(4)
	v_mfma_f32_32x32x16_bf16 a[112:127], v[100:103], v[104:107], a[112:127]
	s_waitcnt lgkmcnt(1)
	v_mfma_f32_32x32x16_bf16 a[96:111], v[100:103], v[116:119], a[96:111]
	ds_read_b128 v[100:103], v59 offset:59936
	ds_read_b128 v[124:127], v59 offset:55392
	s_waitcnt lgkmcnt(1)
	v_mfma_f32_32x32x16_bf16 a[80:95], v[100:103], v[104:107], a[80:95]
	v_mfma_f32_32x32x16_bf16 a[64:79], v[100:103], v[116:119], a[64:79]
	ds_read_b128 v[100:103], v59 offset:64544
	ds_read_b128 v[128:131], v59 offset:64576
	s_waitcnt lgkmcnt(1)
	v_mfma_f32_32x32x16_bf16 a[48:63], v[100:103], v[104:107], a[48:63]
	v_mfma_f32_32x32x16_bf16 a[32:47], v[100:103], v[116:119], a[32:47]
	ds_read_b128 v[100:103], v61 offset:55328
	ds_read_b128 v[140:143], v59 offset:64608
	s_waitcnt lgkmcnt(1)
	v_mfma_f32_32x32x16_bf16 a[16:31], v[100:103], v[104:107], a[16:31]
	v_mfma_f32_32x32x16_bf16 a[0:15], v[100:103], v[116:119], a[0:15]
	ds_read_b128 v[100:103], v69 offset:4672
	ds_read_b128 v[104:107], v69 offset:4704
	v_mfma_f32_32x32x16_bf16 a[112:127], v[112:115], v[108:111], a[112:127]
	s_waitcnt lgkmcnt(1)
	v_mfma_f32_32x32x16_bf16 a[96:111], v[112:115], v[100:103], a[96:111]
	ds_read_b128 v[112:115], v59 offset:59968
	ds_read_b128 v[116:119], v59 offset:60000
	s_waitcnt lgkmcnt(1)
	v_mfma_f32_32x32x16_bf16 a[80:95], v[112:115], v[108:111], a[80:95]
	v_mfma_f32_32x32x16_bf16 a[64:79], v[112:115], v[100:103], a[64:79]
	v_mfma_f32_32x32x16_bf16 a[48:63], v[128:131], v[108:111], a[48:63]
	v_mfma_f32_32x32x16_bf16 a[32:47], v[128:131], v[100:103], a[32:47]
	ds_read_b128 v[112:115], v61 offset:55360
	ds_read_b128 v[128:131], v61 offset:55392
	s_waitcnt lgkmcnt(1)
	v_mfma_f32_32x32x16_bf16 a[16:31], v[112:115], v[108:111], a[16:31]
	v_mfma_f32_32x32x16_bf16 a[0:15], v[112:115], v[100:103], a[0:15]
	v_mfma_f32_32x32x16_bf16 a[112:127], v[124:127], v[120:123], a[112:127]
	v_mfma_f32_32x32x16_bf16 a[96:111], v[124:127], v[104:107], a[96:111]
	v_mfma_f32_32x32x16_bf16 a[80:95], v[116:119], v[120:123], a[80:95]
	v_mfma_f32_32x32x16_bf16 a[64:79], v[116:119], v[104:107], a[64:79]
	global_load_dwordx4 v[100:103], v[4:5], off offset:1408
	global_load_dwordx4 v[108:111], v[0:1], off offset:1408
	global_load_dwordx4 v[112:115], v[8:9], off offset:1408
	global_load_dwordx4 v[116:119], v[6:7], off offset:1408
	v_mfma_f32_32x32x16_bf16 a[48:63], v[140:143], v[120:123], a[48:63]
	v_mfma_f32_32x32x16_bf16 a[32:47], v[140:143], v[104:107], a[32:47]
	global_load_dwordx4 v[124:127], v[10:11], off offset:1408
	global_load_dwordx4 v[140:143], v[12:13], off offset:1408
	global_load_dwordx4 v[144:147], v[26:27], off offset:1408
	global_load_dwordx4 v[148:151], v[14:15], off offset:1408
	global_load_dwordx4 v[152:155], v[28:29], off offset:1408
	global_load_dwordx4 v[156:159], v[2:3], off offset:1408
	global_load_dwordx4 v[160:163], v[30:31], off offset:1408
	s_waitcnt lgkmcnt(0)
	v_mfma_f32_32x32x16_bf16 a[16:31], v[128:131], v[120:123], a[16:31]
	global_load_dwordx4 v[120:123], v[32:33], off offset:1408
	s_barrier
	v_mfma_f32_32x32x16_bf16 a[0:15], v[128:131], v[104:107], a[0:15]
	ds_read_b128 v[104:107], v59
	ds_read_b128 v[128:131], v62 offset:36864
	ds_read_b128 v[164:167], v59 offset:4608
	ds_read_b128 v[168:171], v62 offset:41472
	s_waitcnt lgkmcnt(2)
	v_mfma_f32_32x32x16_bf16 a[112:127], v[104:107], v[128:131], a[112:127]
	s_waitcnt lgkmcnt(0)
	v_mfma_f32_32x32x16_bf16 a[96:111], v[104:107], v[168:171], a[96:111]
	ds_read_b128 v[104:107], v59 offset:9216
	s_waitcnt lgkmcnt(0)
	v_mfma_f32_32x32x16_bf16 a[48:63], v[104:107], v[128:131], a[48:63]
	v_mfma_f32_32x32x16_bf16 a[32:47], v[104:107], v[168:171], a[32:47]
	ds_read_b128 v[104:107], v61
	s_waitcnt vmcnt(10)
	ds_write_b128 v60, v[108:111] offset:55296
	ds_write_b128 v60, v[100:103] offset:59904
	s_waitcnt vmcnt(8)
	ds_write_b128 v60, v[116:119] offset:64512
	ds_write_b128 v63, v[112:115] offset:55296
	s_waitcnt vmcnt(7)
	ds_write_b128 v64, v[124:127] offset:55296
	s_waitcnt vmcnt(6)
	ds_write_b128 v65, v[140:143] offset:55296
	s_waitcnt vmcnt(4)
	ds_write_b128 v66, v[148:151] offset:55296
	ds_write_b128 v67, v[144:147] offset:55296
	s_waitcnt vmcnt(2)
	ds_write_b128 v68, v[156:159]
	ds_write_b128 v68, v[152:155] offset:4608
	s_waitcnt vmcnt(1)
	ds_write_b128 v68, v[160:163] offset:9216
	s_waitcnt vmcnt(0)
	ds_write_b128 v68, v[120:123] offset:13824
	v_mfma_f32_32x32x16_bf16 a[80:95], v[164:167], v[128:131], a[80:95]
	v_mfma_f32_32x32x16_bf16 a[64:79], v[164:167], v[168:171], a[64:79]
	s_waitcnt lgkmcnt(12)
	v_mfma_f32_32x32x16_bf16 a[16:31], v[104:107], v[128:131], a[16:31]
	v_mfma_f32_32x32x16_bf16 a[0:15], v[104:107], v[168:171], a[0:15]
	ds_read_b128 v[100:103], v59 offset:32
	ds_read_b128 v[104:107], v62 offset:36896
	ds_read_b128 v[108:111], v62 offset:36928
	ds_read_b128 v[112:115], v59 offset:64
	ds_read_b128 v[116:119], v62 offset:41504
	ds_read_b128 v[120:123], v62 offset:36960
	s_waitcnt lgkmcnt(4)
	v_mfma_f32_32x32x16_bf16 a[112:127], v[100:103], v[104:107], a[112:127]
	s_waitcnt lgkmcnt(1)
	v_mfma_f32_32x32x16_bf16 a[96:111], v[100:103], v[116:119], a[96:111]
	ds_read_b128 v[100:103], v59 offset:4640
	ds_read_b128 v[124:127], v59 offset:96
	s_waitcnt lgkmcnt(1)
	v_mfma_f32_32x32x16_bf16 a[80:95], v[100:103], v[104:107], a[80:95]
	v_mfma_f32_32x32x16_bf16 a[64:79], v[100:103], v[116:119], a[64:79]
	ds_read_b128 v[100:103], v59 offset:9248
	ds_read_b128 v[128:131], v59 offset:9280
	s_waitcnt lgkmcnt(1)
	v_mfma_f32_32x32x16_bf16 a[48:63], v[100:103], v[104:107], a[48:63]
	v_mfma_f32_32x32x16_bf16 a[32:47], v[100:103], v[116:119], a[32:47]
	ds_read_b128 v[100:103], v61 offset:32
	ds_read_b128 v[140:143], v59 offset:9312
	s_waitcnt lgkmcnt(1)
	v_mfma_f32_32x32x16_bf16 a[16:31], v[100:103], v[104:107], a[16:31]
	v_mfma_f32_32x32x16_bf16 a[0:15], v[100:103], v[116:119], a[0:15]
	ds_read_b128 v[100:103], v62 offset:41536
	ds_read_b128 v[104:107], v62 offset:41568
	v_mfma_f32_32x32x16_bf16 a[112:127], v[112:115], v[108:111], a[112:127]
	s_waitcnt lgkmcnt(1)
	v_mfma_f32_32x32x16_bf16 a[96:111], v[112:115], v[100:103], a[96:111]
	ds_read_b128 v[112:115], v59 offset:4672
	ds_read_b128 v[116:119], v59 offset:4704
	s_waitcnt lgkmcnt(1)
	v_mfma_f32_32x32x16_bf16 a[80:95], v[112:115], v[108:111], a[80:95]
	v_mfma_f32_32x32x16_bf16 a[64:79], v[112:115], v[100:103], a[64:79]
	v_mfma_f32_32x32x16_bf16 a[48:63], v[128:131], v[108:111], a[48:63]
	v_mfma_f32_32x32x16_bf16 a[32:47], v[128:131], v[100:103], a[32:47]
	ds_read_b128 v[112:115], v61 offset:64
	ds_read_b128 v[128:131], v61 offset:96
	s_waitcnt lgkmcnt(1)
	v_mfma_f32_32x32x16_bf16 a[16:31], v[112:115], v[108:111], a[16:31]
	v_mfma_f32_32x32x16_bf16 a[0:15], v[112:115], v[100:103], a[0:15]
	global_load_dwordx4 v[100:103], v[32:33], off offset:1536
	v_mfma_f32_32x32x16_bf16 a[112:127], v[124:127], v[120:123], a[112:127]
	v_mfma_f32_32x32x16_bf16 a[96:111], v[124:127], v[104:107], a[96:111]
	v_mfma_f32_32x32x16_bf16 a[80:95], v[116:119], v[120:123], a[80:95]
	v_mfma_f32_32x32x16_bf16 a[64:79], v[116:119], v[104:107], a[64:79]
	v_mfma_f32_32x32x16_bf16 a[48:63], v[140:143], v[120:123], a[48:63]
	v_mfma_f32_32x32x16_bf16 a[32:47], v[140:143], v[104:107], a[32:47]
	global_load_dwordx4 v[108:111], v[30:31], off offset:1536
	global_load_dwordx4 v[112:115], v[28:29], off offset:1536
	global_load_dwordx4 v[116:119], v[2:3], off offset:1536
	global_load_dwordx4 v[124:127], v[8:9], off offset:1536
	global_load_dwordx4 v[140:143], v[6:7], off offset:1536
	global_load_dwordx4 v[144:147], v[4:5], off offset:1536
	global_load_dwordx4 v[148:151], v[0:1], off offset:1536
	s_waitcnt lgkmcnt(0)
	v_mfma_f32_32x32x16_bf16 a[16:31], v[128:131], v[120:123], a[16:31]
	global_load_dwordx4 v[120:123], v[12:13], off offset:1536
	global_load_dwordx4 v[152:155], v[10:11], off offset:1536
	global_load_dwordx4 v[156:159], v[26:27], off offset:1536
	global_load_dwordx4 v[160:163], v[14:15], off offset:1536
	s_barrier
	v_mfma_f32_32x32x16_bf16 a[0:15], v[128:131], v[104:107], a[0:15]
	ds_read_b128 v[104:107], v59 offset:55296
	ds_read_b128 v[128:131], v69
	ds_read_b128 v[164:167], v59 offset:59904
	ds_read_b128 v[168:171], v69 offset:4608
	s_waitcnt lgkmcnt(2)
	v_mfma_f32_32x32x16_bf16 a[112:127], v[104:107], v[128:131], a[112:127]
	s_waitcnt lgkmcnt(0)
	v_mfma_f32_32x32x16_bf16 a[96:111], v[104:107], v[168:171], a[96:111]
	ds_read_b128 v[104:107], v59 offset:64512
	s_waitcnt lgkmcnt(0)
	v_mfma_f32_32x32x16_bf16 a[48:63], v[104:107], v[128:131], a[48:63]
	v_mfma_f32_32x32x16_bf16 a[32:47], v[104:107], v[168:171], a[32:47]
	ds_read_b128 v[104:107], v61 offset:55296
	s_waitcnt vmcnt(4)
	ds_write_b128 v60, v[148:151]
	ds_write_b128 v60, v[144:147] offset:4608
	ds_write_b128 v60, v[140:143] offset:9216
	ds_write_b128 v60, v[124:127] offset:13824
	s_waitcnt vmcnt(2)
	ds_write_b128 v60, v[152:155] offset:18432
	ds_write_b128 v60, v[120:123] offset:23040
	s_waitcnt vmcnt(0)
	ds_write_b128 v60, v[160:163] offset:27648
	ds_write_b128 v60, v[156:159] offset:32256
	ds_write_b128 v60, v[116:119] offset:36864
	ds_write_b128 v60, v[112:115] offset:41472
	ds_write_b128 v60, v[108:111] offset:46080
	ds_write_b128 v60, v[100:103] offset:50688
	v_mfma_f32_32x32x16_bf16 a[80:95], v[164:167], v[128:131], a[80:95]
	v_mfma_f32_32x32x16_bf16 a[64:79], v[164:167], v[168:171], a[64:79]
	s_waitcnt lgkmcnt(12)
	v_mfma_f32_32x32x16_bf16 a[16:31], v[104:107], v[128:131], a[16:31]
	v_mfma_f32_32x32x16_bf16 a[0:15], v[104:107], v[168:171], a[0:15]
	ds_read_b128 v[100:103], v59 offset:55328
	ds_read_b128 v[104:107], v69 offset:32
	ds_read_b128 v[108:111], v69 offset:64
	ds_read_b128 v[112:115], v59 offset:55360
	ds_read_b128 v[116:119], v69 offset:4640
	ds_read_b128 v[120:123], v69 offset:96
	s_waitcnt lgkmcnt(4)
	v_mfma_f32_32x32x16_bf16 a[112:127], v[100:103], v[104:107], a[112:127]
	s_waitcnt lgkmcnt(1)
	v_mfma_f32_32x32x16_bf16 a[96:111], v[100:103], v[116:119], a[96:111]
	ds_read_b128 v[100:103], v59 offset:59936
	ds_read_b128 v[124:127], v59 offset:55392
	s_waitcnt lgkmcnt(1)
	v_mfma_f32_32x32x16_bf16 a[80:95], v[100:103], v[104:107], a[80:95]
	v_mfma_f32_32x32x16_bf16 a[64:79], v[100:103], v[116:119], a[64:79]
	ds_read_b128 v[100:103], v59 offset:64544
	ds_read_b128 v[128:131], v59 offset:64576
	s_waitcnt lgkmcnt(1)
	v_mfma_f32_32x32x16_bf16 a[48:63], v[100:103], v[104:107], a[48:63]
	v_mfma_f32_32x32x16_bf16 a[32:47], v[100:103], v[116:119], a[32:47]
	ds_read_b128 v[100:103], v61 offset:55328
	ds_read_b128 v[140:143], v59 offset:64608
	s_waitcnt lgkmcnt(1)
	v_mfma_f32_32x32x16_bf16 a[16:31], v[100:103], v[104:107], a[16:31]
	v_mfma_f32_32x32x16_bf16 a[0:15], v[100:103], v[116:119], a[0:15]
	ds_read_b128 v[100:103], v69 offset:4672
	ds_read_b128 v[104:107], v69 offset:4704
	v_mfma_f32_32x32x16_bf16 a[112:127], v[112:115], v[108:111], a[112:127]
	s_waitcnt lgkmcnt(1)
	v_mfma_f32_32x32x16_bf16 a[96:111], v[112:115], v[100:103], a[96:111]
	ds_read_b128 v[112:115], v59 offset:59968
	ds_read_b128 v[116:119], v59 offset:60000
	s_waitcnt lgkmcnt(1)
	v_mfma_f32_32x32x16_bf16 a[80:95], v[112:115], v[108:111], a[80:95]
	v_mfma_f32_32x32x16_bf16 a[64:79], v[112:115], v[100:103], a[64:79]
	v_mfma_f32_32x32x16_bf16 a[48:63], v[128:131], v[108:111], a[48:63]
	v_mfma_f32_32x32x16_bf16 a[32:47], v[128:131], v[100:103], a[32:47]
	ds_read_b128 v[112:115], v61 offset:55360
	ds_read_b128 v[128:131], v61 offset:55392
	s_waitcnt lgkmcnt(1)
	v_mfma_f32_32x32x16_bf16 a[16:31], v[112:115], v[108:111], a[16:31]
	v_mfma_f32_32x32x16_bf16 a[0:15], v[112:115], v[100:103], a[0:15]
	v_mfma_f32_32x32x16_bf16 a[112:127], v[124:127], v[120:123], a[112:127]
	v_mfma_f32_32x32x16_bf16 a[96:111], v[124:127], v[104:107], a[96:111]
	v_mfma_f32_32x32x16_bf16 a[80:95], v[116:119], v[120:123], a[80:95]
	v_mfma_f32_32x32x16_bf16 a[64:79], v[116:119], v[104:107], a[64:79]
	global_load_dwordx4 v[100:103], v[4:5], off offset:1664
	global_load_dwordx4 v[108:111], v[0:1], off offset:1664
	global_load_dwordx4 v[112:115], v[8:9], off offset:1664
	global_load_dwordx4 v[116:119], v[6:7], off offset:1664
	v_mfma_f32_32x32x16_bf16 a[48:63], v[140:143], v[120:123], a[48:63]
	v_mfma_f32_32x32x16_bf16 a[32:47], v[140:143], v[104:107], a[32:47]
	global_load_dwordx4 v[124:127], v[10:11], off offset:1664
	global_load_dwordx4 v[140:143], v[12:13], off offset:1664
	global_load_dwordx4 v[144:147], v[26:27], off offset:1664
	global_load_dwordx4 v[148:151], v[14:15], off offset:1664
	global_load_dwordx4 v[152:155], v[28:29], off offset:1664
	global_load_dwordx4 v[156:159], v[2:3], off offset:1664
	global_load_dwordx4 v[160:163], v[30:31], off offset:1664
	s_waitcnt lgkmcnt(0)
	v_mfma_f32_32x32x16_bf16 a[16:31], v[128:131], v[120:123], a[16:31]
	global_load_dwordx4 v[120:123], v[32:33], off offset:1664
	s_barrier
	v_mfma_f32_32x32x16_bf16 a[0:15], v[128:131], v[104:107], a[0:15]
	ds_read_b128 v[104:107], v59
	ds_read_b128 v[128:131], v62 offset:36864
	ds_read_b128 v[164:167], v59 offset:4608
	ds_read_b128 v[168:171], v62 offset:41472
	s_waitcnt lgkmcnt(2)
	v_mfma_f32_32x32x16_bf16 a[112:127], v[104:107], v[128:131], a[112:127]
	s_waitcnt lgkmcnt(0)
	v_mfma_f32_32x32x16_bf16 a[96:111], v[104:107], v[168:171], a[96:111]
	ds_read_b128 v[104:107], v59 offset:9216
	s_waitcnt lgkmcnt(0)
	v_mfma_f32_32x32x16_bf16 a[48:63], v[104:107], v[128:131], a[48:63]
	v_mfma_f32_32x32x16_bf16 a[32:47], v[104:107], v[168:171], a[32:47]
	ds_read_b128 v[104:107], v61
	s_waitcnt vmcnt(10)
	ds_write_b128 v60, v[108:111] offset:55296
	ds_write_b128 v60, v[100:103] offset:59904
	s_waitcnt vmcnt(8)
	ds_write_b128 v60, v[116:119] offset:64512
	ds_write_b128 v63, v[112:115] offset:55296
	s_waitcnt vmcnt(7)
	ds_write_b128 v64, v[124:127] offset:55296
	s_waitcnt vmcnt(6)
	ds_write_b128 v65, v[140:143] offset:55296
	s_waitcnt vmcnt(4)
	ds_write_b128 v66, v[148:151] offset:55296
	ds_write_b128 v67, v[144:147] offset:55296
	s_waitcnt vmcnt(2)
	ds_write_b128 v68, v[156:159]
	ds_write_b128 v68, v[152:155] offset:4608
	s_waitcnt vmcnt(1)
	ds_write_b128 v68, v[160:163] offset:9216
	s_waitcnt vmcnt(0)
	ds_write_b128 v68, v[120:123] offset:13824
	v_mfma_f32_32x32x16_bf16 a[80:95], v[164:167], v[128:131], a[80:95]
	v_mfma_f32_32x32x16_bf16 a[64:79], v[164:167], v[168:171], a[64:79]
	s_waitcnt lgkmcnt(12)
	v_mfma_f32_32x32x16_bf16 a[16:31], v[104:107], v[128:131], a[16:31]
	v_mfma_f32_32x32x16_bf16 a[0:15], v[104:107], v[168:171], a[0:15]
	ds_read_b128 v[100:103], v59 offset:32
	ds_read_b128 v[104:107], v62 offset:36896
	ds_read_b128 v[108:111], v62 offset:36928
	ds_read_b128 v[112:115], v59 offset:64
	ds_read_b128 v[116:119], v62 offset:41504
	ds_read_b128 v[120:123], v62 offset:36960
	s_waitcnt lgkmcnt(4)
	v_mfma_f32_32x32x16_bf16 a[112:127], v[100:103], v[104:107], a[112:127]
	s_waitcnt lgkmcnt(1)
	v_mfma_f32_32x32x16_bf16 a[96:111], v[100:103], v[116:119], a[96:111]
	ds_read_b128 v[100:103], v59 offset:4640
	ds_read_b128 v[124:127], v59 offset:96
	s_waitcnt lgkmcnt(1)
	v_mfma_f32_32x32x16_bf16 a[80:95], v[100:103], v[104:107], a[80:95]
	v_mfma_f32_32x32x16_bf16 a[64:79], v[100:103], v[116:119], a[64:79]
	ds_read_b128 v[100:103], v59 offset:9248
	ds_read_b128 v[128:131], v59 offset:9280
	s_waitcnt lgkmcnt(1)
	v_mfma_f32_32x32x16_bf16 a[48:63], v[100:103], v[104:107], a[48:63]
	v_mfma_f32_32x32x16_bf16 a[32:47], v[100:103], v[116:119], a[32:47]
	ds_read_b128 v[100:103], v61 offset:32
	ds_read_b128 v[140:143], v59 offset:9312
	s_waitcnt lgkmcnt(1)
	v_mfma_f32_32x32x16_bf16 a[16:31], v[100:103], v[104:107], a[16:31]
	v_mfma_f32_32x32x16_bf16 a[0:15], v[100:103], v[116:119], a[0:15]
	ds_read_b128 v[100:103], v62 offset:41536
	ds_read_b128 v[104:107], v62 offset:41568
	v_mfma_f32_32x32x16_bf16 a[112:127], v[112:115], v[108:111], a[112:127]
	s_waitcnt lgkmcnt(1)
	v_mfma_f32_32x32x16_bf16 a[96:111], v[112:115], v[100:103], a[96:111]
	ds_read_b128 v[112:115], v59 offset:4672
	ds_read_b128 v[116:119], v59 offset:4704
	s_waitcnt lgkmcnt(1)
	v_mfma_f32_32x32x16_bf16 a[80:95], v[112:115], v[108:111], a[80:95]
	v_mfma_f32_32x32x16_bf16 a[64:79], v[112:115], v[100:103], a[64:79]
	v_mfma_f32_32x32x16_bf16 a[48:63], v[128:131], v[108:111], a[48:63]
	v_mfma_f32_32x32x16_bf16 a[32:47], v[128:131], v[100:103], a[32:47]
	ds_read_b128 v[112:115], v61 offset:64
	ds_read_b128 v[128:131], v61 offset:96
	s_waitcnt lgkmcnt(1)
	v_mfma_f32_32x32x16_bf16 a[16:31], v[112:115], v[108:111], a[16:31]
	v_mfma_f32_32x32x16_bf16 a[0:15], v[112:115], v[100:103], a[0:15]
	global_load_dwordx4 v[100:103], v[32:33], off offset:1792
	v_mfma_f32_32x32x16_bf16 a[112:127], v[124:127], v[120:123], a[112:127]
	v_mfma_f32_32x32x16_bf16 a[96:111], v[124:127], v[104:107], a[96:111]
	v_mfma_f32_32x32x16_bf16 a[80:95], v[116:119], v[120:123], a[80:95]
	v_mfma_f32_32x32x16_bf16 a[64:79], v[116:119], v[104:107], a[64:79]
	v_mfma_f32_32x32x16_bf16 a[48:63], v[140:143], v[120:123], a[48:63]
	v_mfma_f32_32x32x16_bf16 a[32:47], v[140:143], v[104:107], a[32:47]
	global_load_dwordx4 v[108:111], v[30:31], off offset:1792
	global_load_dwordx4 v[112:115], v[28:29], off offset:1792
	global_load_dwordx4 v[116:119], v[2:3], off offset:1792
	global_load_dwordx4 v[124:127], v[8:9], off offset:1792
	global_load_dwordx4 v[140:143], v[6:7], off offset:1792
	global_load_dwordx4 v[144:147], v[4:5], off offset:1792
	global_load_dwordx4 v[148:151], v[0:1], off offset:1792
	s_waitcnt lgkmcnt(0)
	v_mfma_f32_32x32x16_bf16 a[16:31], v[128:131], v[120:123], a[16:31]
	global_load_dwordx4 v[120:123], v[12:13], off offset:1792
	global_load_dwordx4 v[152:155], v[10:11], off offset:1792
	global_load_dwordx4 v[156:159], v[26:27], off offset:1792
	global_load_dwordx4 v[160:163], v[14:15], off offset:1792
	s_barrier
	v_mfma_f32_32x32x16_bf16 a[0:15], v[128:131], v[104:107], a[0:15]
	ds_read_b128 v[104:107], v59 offset:55296
	ds_read_b128 v[128:131], v69
	ds_read_b128 v[164:167], v59 offset:59904
	ds_read_b128 v[168:171], v69 offset:4608
	s_waitcnt lgkmcnt(2)
	v_mfma_f32_32x32x16_bf16 a[112:127], v[104:107], v[128:131], a[112:127]
	s_waitcnt lgkmcnt(0)
	v_mfma_f32_32x32x16_bf16 a[96:111], v[104:107], v[168:171], a[96:111]
	ds_read_b128 v[104:107], v59 offset:64512
	s_waitcnt lgkmcnt(0)
	v_mfma_f32_32x32x16_bf16 a[48:63], v[104:107], v[128:131], a[48:63]
	v_mfma_f32_32x32x16_bf16 a[32:47], v[104:107], v[168:171], a[32:47]
	ds_read_b128 v[104:107], v61 offset:55296
	s_waitcnt vmcnt(4)
	ds_write_b128 v60, v[148:151]
	ds_write_b128 v60, v[144:147] offset:4608
	ds_write_b128 v60, v[140:143] offset:9216
	ds_write_b128 v60, v[124:127] offset:13824
	s_waitcnt vmcnt(2)
	ds_write_b128 v60, v[152:155] offset:18432
	ds_write_b128 v60, v[120:123] offset:23040
	s_waitcnt vmcnt(0)
	ds_write_b128 v60, v[160:163] offset:27648
	ds_write_b128 v60, v[156:159] offset:32256
	ds_write_b128 v60, v[116:119] offset:36864
	ds_write_b128 v60, v[112:115] offset:41472
	ds_write_b128 v60, v[108:111] offset:46080
	ds_write_b128 v60, v[100:103] offset:50688
	v_mfma_f32_32x32x16_bf16 a[80:95], v[164:167], v[128:131], a[80:95]
	v_mfma_f32_32x32x16_bf16 a[64:79], v[164:167], v[168:171], a[64:79]
	s_waitcnt lgkmcnt(12)
	v_mfma_f32_32x32x16_bf16 a[16:31], v[104:107], v[128:131], a[16:31]
	v_mfma_f32_32x32x16_bf16 a[0:15], v[104:107], v[168:171], a[0:15]
	ds_read_b128 v[100:103], v59 offset:55328
	ds_read_b128 v[104:107], v69 offset:32
	ds_read_b128 v[108:111], v69 offset:64
	ds_read_b128 v[112:115], v59 offset:55360
	ds_read_b128 v[116:119], v69 offset:4640
	ds_read_b128 v[120:123], v69 offset:96
	s_waitcnt lgkmcnt(4)
	v_mfma_f32_32x32x16_bf16 a[112:127], v[100:103], v[104:107], a[112:127]
	s_waitcnt lgkmcnt(1)
	v_mfma_f32_32x32x16_bf16 a[96:111], v[100:103], v[116:119], a[96:111]
	ds_read_b128 v[100:103], v59 offset:59936
	ds_read_b128 v[124:127], v59 offset:55392
	s_waitcnt lgkmcnt(1)
	v_mfma_f32_32x32x16_bf16 a[80:95], v[100:103], v[104:107], a[80:95]
	v_mfma_f32_32x32x16_bf16 a[64:79], v[100:103], v[116:119], a[64:79]
	ds_read_b128 v[100:103], v59 offset:64544
	ds_read_b128 v[128:131], v59 offset:64576
	s_waitcnt lgkmcnt(1)
	v_mfma_f32_32x32x16_bf16 a[48:63], v[100:103], v[104:107], a[48:63]
	v_mfma_f32_32x32x16_bf16 a[32:47], v[100:103], v[116:119], a[32:47]
	ds_read_b128 v[100:103], v61 offset:55328
	ds_read_b128 v[140:143], v59 offset:64608
	s_waitcnt lgkmcnt(1)
	v_mfma_f32_32x32x16_bf16 a[16:31], v[100:103], v[104:107], a[16:31]
	v_mfma_f32_32x32x16_bf16 a[0:15], v[100:103], v[116:119], a[0:15]
	ds_read_b128 v[100:103], v69 offset:4672
	ds_read_b128 v[104:107], v69 offset:4704
	v_mfma_f32_32x32x16_bf16 a[112:127], v[112:115], v[108:111], a[112:127]
	s_waitcnt lgkmcnt(1)
	v_mfma_f32_32x32x16_bf16 a[96:111], v[112:115], v[100:103], a[96:111]
	ds_read_b128 v[112:115], v59 offset:59968
	ds_read_b128 v[116:119], v59 offset:60000
	s_waitcnt lgkmcnt(1)
	v_mfma_f32_32x32x16_bf16 a[80:95], v[112:115], v[108:111], a[80:95]
	v_mfma_f32_32x32x16_bf16 a[64:79], v[112:115], v[100:103], a[64:79]
	v_mfma_f32_32x32x16_bf16 a[48:63], v[128:131], v[108:111], a[48:63]
	v_mfma_f32_32x32x16_bf16 a[32:47], v[128:131], v[100:103], a[32:47]
	ds_read_b128 v[112:115], v61 offset:55360
	ds_read_b128 v[128:131], v61 offset:55392
	s_waitcnt lgkmcnt(1)
	v_mfma_f32_32x32x16_bf16 a[16:31], v[112:115], v[108:111], a[16:31]
	v_mfma_f32_32x32x16_bf16 a[0:15], v[112:115], v[100:103], a[0:15]
	global_load_dwordx4 v[100:103], v[4:5], off offset:1920
	global_load_dwordx4 v[108:111], v[0:1], off offset:1920
	global_load_dwordx4 v[112:115], v[8:9], off offset:1920
	s_nop 0
	global_load_dwordx4 v[4:7], v[6:7], off offset:1920
	v_mfma_f32_32x32x16_bf16 a[112:127], v[124:127], v[120:123], a[112:127]
	v_mfma_f32_32x32x16_bf16 a[96:111], v[124:127], v[104:107], a[96:111]
	v_mfma_f32_32x32x16_bf16 a[80:95], v[116:119], v[120:123], a[80:95]
	v_mfma_f32_32x32x16_bf16 a[64:79], v[116:119], v[104:107], a[64:79]
	v_mfma_f32_32x32x16_bf16 a[48:63], v[140:143], v[120:123], a[48:63]
	v_mfma_f32_32x32x16_bf16 a[32:47], v[140:143], v[104:107], a[32:47]
	global_load_dwordx4 v[8:11], v[10:11], off offset:1920
	s_nop 0
	global_load_dwordx4 v[116:119], v[12:13], off offset:1920
	global_load_dwordx4 v[124:127], v[26:27], off offset:1920
	s_nop 0
	global_load_dwordx4 v[12:15], v[14:15], off offset:1920
	s_nop 0
	global_load_dwordx4 v[26:29], v[28:29], off offset:1920
	s_nop 0
	global_load_dwordx4 v[0:3], v[2:3], off offset:1920
	s_nop 0
	global_load_dwordx4 v[140:143], v[30:31], off offset:1920
	s_nop 0
	global_load_dwordx4 v[30:33], v[32:33], off offset:1920
	s_waitcnt lgkmcnt(0)
	s_barrier
	v_mfma_f32_32x32x16_bf16 a[16:31], v[128:131], v[120:123], a[16:31]
	v_mfma_f32_32x32x16_bf16 a[0:15], v[128:131], v[104:107], a[0:15]
	ds_read_b128 v[104:107], v59
	ds_read_b128 v[120:123], v62 offset:36864
	ds_read_b128 v[128:131], v59 offset:4608
	ds_read_b128 v[144:147], v62 offset:41472
	s_waitcnt lgkmcnt(2)
	v_mfma_f32_32x32x16_bf16 a[112:127], v[104:107], v[120:123], a[112:127]
	s_waitcnt lgkmcnt(0)
	v_mfma_f32_32x32x16_bf16 a[96:111], v[104:107], v[144:147], a[96:111]
	v_mfma_f32_32x32x16_bf16 a[80:95], v[128:131], v[120:123], a[80:95]
	v_mfma_f32_32x32x16_bf16 a[64:79], v[128:131], v[144:147], a[64:79]
	ds_read_b128 v[104:107], v59 offset:9216
	ds_read_b128 v[128:131], v61
	s_waitcnt vmcnt(10)
	ds_write_b128 v60, v[108:111] offset:55296
	ds_write_b128 v60, v[100:103] offset:59904
	s_waitcnt vmcnt(8)
	ds_write_b128 v60, v[4:7] offset:64512
	ds_write_b128 v63, v[112:115] offset:55296
	s_waitcnt vmcnt(7)
	ds_write_b128 v64, v[8:11] offset:55296
	s_waitcnt vmcnt(6)
	ds_write_b128 v65, v[116:119] offset:55296
	s_waitcnt vmcnt(4)
	ds_write_b128 v66, v[12:15] offset:55296
	ds_write_b128 v67, v[124:127] offset:55296
	s_waitcnt vmcnt(2)
	ds_write_b128 v68, v[0:3]
	ds_write_b128 v68, v[26:29] offset:4608
	s_waitcnt vmcnt(1)
	ds_write_b128 v68, v[140:143] offset:9216
	s_waitcnt vmcnt(0)
	ds_write_b128 v68, v[30:33] offset:13824
	ds_read_b128 v[0:3], v59 offset:32
	ds_read_b128 v[4:7], v62 offset:36896
	ds_read_b128 v[8:11], v62 offset:36928
	ds_read_b128 v[12:15], v59 offset:64
	ds_read_b128 v[26:29], v62 offset:41504
	ds_read_b128 v[30:33], v62 offset:36960
	s_waitcnt lgkmcnt(14)
	v_mfma_f32_32x32x16_bf16 a[48:63], v[104:107], v[120:123], a[48:63]
	v_mfma_f32_32x32x16_bf16 a[32:47], v[104:107], v[144:147], a[32:47]
	s_waitcnt lgkmcnt(4)
	v_mfma_f32_32x32x16_bf16 a[112:127], v[0:3], v[4:7], a[112:127]
	s_waitcnt lgkmcnt(1)
	v_mfma_f32_32x32x16_bf16 a[96:111], v[0:3], v[26:29], a[96:111]
	ds_read_b128 v[0:3], v59 offset:4640
	ds_read_b128 v[100:103], v59 offset:96
	v_mfma_f32_32x32x16_bf16 a[16:31], v[128:131], v[120:123], a[16:31]
	v_mfma_f32_32x32x16_bf16 a[0:15], v[128:131], v[144:147], a[0:15]
	s_waitcnt lgkmcnt(1)
	v_mfma_f32_32x32x16_bf16 a[80:95], v[0:3], v[4:7], a[80:95]
	v_mfma_f32_32x32x16_bf16 a[64:79], v[0:3], v[26:29], a[64:79]
	ds_read_b128 v[0:3], v59 offset:9248
	ds_read_b128 v[104:107], v59 offset:9280
	s_waitcnt lgkmcnt(1)
	v_mfma_f32_32x32x16_bf16 a[48:63], v[0:3], v[4:7], a[48:63]
	v_mfma_f32_32x32x16_bf16 a[32:47], v[0:3], v[26:29], a[32:47]
	ds_read_b128 v[0:3], v61 offset:32
	ds_read_b128 v[108:111], v59 offset:9312
	s_waitcnt lgkmcnt(1)
	v_mfma_f32_32x32x16_bf16 a[16:31], v[0:3], v[4:7], a[16:31]
	v_mfma_f32_32x32x16_bf16 a[0:15], v[0:3], v[26:29], a[0:15]
	ds_read_b128 v[0:3], v62 offset:41536
	ds_read_b128 v[4:7], v62 offset:41568
	v_mfma_f32_32x32x16_bf16 a[112:127], v[12:15], v[8:11], a[112:127]
	s_waitcnt lgkmcnt(1)
	v_mfma_f32_32x32x16_bf16 a[96:111], v[12:15], v[0:3], a[96:111]
	ds_read_b128 v[12:15], v59 offset:4672
	ds_read_b128 v[26:29], v59 offset:4704
	s_waitcnt lgkmcnt(1)
	v_mfma_f32_32x32x16_bf16 a[80:95], v[12:15], v[8:11], a[80:95]
	v_mfma_f32_32x32x16_bf16 a[64:79], v[12:15], v[0:3], a[64:79]
	v_mfma_f32_32x32x16_bf16 a[48:63], v[104:107], v[8:11], a[48:63]
	v_mfma_f32_32x32x16_bf16 a[32:47], v[104:107], v[0:3], a[32:47]
	ds_read_b128 v[12:15], v61 offset:64
	ds_read_b128 v[104:107], v61 offset:96
	s_waitcnt lgkmcnt(0)
	s_barrier
	v_mfma_f32_32x32x16_bf16 a[16:31], v[12:15], v[8:11], a[16:31]
	v_mfma_f32_32x32x16_bf16 a[0:15], v[12:15], v[0:3], a[0:15]
	v_mfma_f32_32x32x16_bf16 a[112:127], v[100:103], v[30:33], a[112:127]
	v_mfma_f32_32x32x16_bf16 a[96:111], v[100:103], v[4:7], a[96:111]
	v_mfma_f32_32x32x16_bf16 a[80:95], v[26:29], v[30:33], a[80:95]
	v_mfma_f32_32x32x16_bf16 a[64:79], v[26:29], v[4:7], a[64:79]
	v_mfma_f32_32x32x16_bf16 a[48:63], v[108:111], v[30:33], a[48:63]
	v_mfma_f32_32x32x16_bf16 a[32:47], v[108:111], v[4:7], a[32:47]
	v_mfma_f32_32x32x16_bf16 a[16:31], v[104:107], v[30:33], a[16:31]
	v_mfma_f32_32x32x16_bf16 a[0:15], v[104:107], v[4:7], a[0:15]
	ds_read_b128 v[0:3], v59 offset:55296
	ds_read_b128 v[4:7], v69
	ds_read_b128 v[8:11], v59 offset:55328
	ds_read_b128 v[12:15], v69 offset:32
	ds_read_b128 v[26:29], v69 offset:4608
	ds_read_b128 v[30:33], v69 offset:4640
	s_waitcnt lgkmcnt(4)
	v_mfma_f32_32x32x16_bf16 a[112:127], v[0:3], v[4:7], a[112:127]
	s_waitcnt lgkmcnt(1)
	v_mfma_f32_32x32x16_bf16 a[96:111], v[0:3], v[26:29], a[96:111]
	ds_read_b128 v[0:3], v59 offset:59904
	ds_read_b128 v[100:103], v59 offset:59936
	s_waitcnt lgkmcnt(1)
	v_mfma_f32_32x32x16_bf16 a[80:95], v[0:3], v[4:7], a[80:95]
	v_mfma_f32_32x32x16_bf16 a[64:79], v[0:3], v[26:29], a[64:79]
	ds_read_b128 v[0:3], v59 offset:64512
	ds_read_b128 v[104:107], v59 offset:64544
	s_waitcnt lgkmcnt(1)
	v_mfma_f32_32x32x16_bf16 a[48:63], v[0:3], v[4:7], a[48:63]
	v_mfma_f32_32x32x16_bf16 a[32:47], v[0:3], v[26:29], a[32:47]
	ds_read_b128 v[0:3], v61 offset:55296
	ds_read_b128 v[108:111], v61 offset:55328
	s_waitcnt lgkmcnt(1)
	v_mfma_f32_32x32x16_bf16 a[0:15], v[0:3], v[26:29], a[0:15]
	v_mfma_f32_32x32x16_bf16 a[112:127], v[8:11], v[12:15], a[112:127]
	v_mfma_f32_32x32x16_bf16 a[96:111], v[8:11], v[30:33], a[96:111]
	v_mfma_f32_32x32x16_bf16 a[16:31], v[0:3], v[4:7], a[16:31]
	v_mfma_f32_32x32x16_bf16 a[80:95], v[100:103], v[12:15], a[80:95]
	v_mfma_f32_32x32x16_bf16 a[64:79], v[100:103], v[30:33], a[64:79]
	v_mfma_f32_32x32x16_bf16 a[32:47], v[104:107], v[30:33], a[32:47]
	s_waitcnt lgkmcnt(0)
	v_mfma_f32_32x32x16_bf16 a[0:15], v[108:111], v[30:33], a[0:15]
	ds_read_b128 v[8:11], v59 offset:55360
	ds_read_b128 v[26:29], v69 offset:64
	ds_read_b128 v[30:33], v59 offset:55392
	ds_read_b128 v[4:7], v69 offset:96
	ds_read_b128 v[100:103], v69 offset:4672
	ds_read_b128 v[0:3], v69 offset:4704
	v_mfma_f32_32x32x16_bf16 a[48:63], v[104:107], v[12:15], a[48:63]
	s_waitcnt lgkmcnt(4)
	v_mfma_f32_32x32x16_bf16 a[112:127], v[8:11], v[26:29], a[112:127]
	s_waitcnt lgkmcnt(1)
	v_mfma_f32_32x32x16_bf16 a[96:111], v[8:11], v[100:103], a[96:111]
	ds_read_b128 v[8:11], v59 offset:59968
	ds_read_b128 v[104:107], v59 offset:60000
	v_mfma_f32_32x32x16_bf16 a[16:31], v[108:111], v[12:15], a[16:31]
	s_waitcnt lgkmcnt(1)
	v_mfma_f32_32x32x16_bf16 a[80:95], v[8:11], v[26:29], a[80:95]
	v_mfma_f32_32x32x16_bf16 a[64:79], v[8:11], v[100:103], a[64:79]
	ds_read_b128 v[8:11], v59 offset:64576
	ds_read_b128 v[12:15], v59 offset:64608
	s_waitcnt lgkmcnt(1)
	v_mfma_f32_32x32x16_bf16 a[48:63], v[8:11], v[26:29], a[48:63]
	v_mfma_f32_32x32x16_bf16 a[32:47], v[8:11], v[100:103], a[32:47]
	ds_read_b128 v[108:111], v61 offset:55360
	ds_read_b128 v[8:11], v61 offset:55392
	s_waitcnt lgkmcnt(0)
	s_barrier
	v_mfma_f32_32x32x16_bf16 a[16:31], v[108:111], v[26:29], a[16:31]
	v_or_b32_e32 v28, s14, v139
	v_lshl_add_u64 v[26:27], v[22:23], 0, s[4:5]
	v_or_b32_e32 v29, s14, v204
	v_mfma_f32_32x32x16_bf16 a[0:15], v[108:111], v[100:103], a[0:15]
	v_mfma_f32_32x32x16_bf16 a[112:127], v[30:33], v[4:7], a[112:127]
	v_mfma_f32_32x32x16_bf16 a[48:63], v[12:15], v[4:7], a[48:63]
	v_mfma_f32_32x32x16_bf16 a[32:47], v[12:15], v[0:3], a[32:47]
	v_lshl_add_u64 v[12:13], v[16:17], 2, v[26:27]
	v_lshlrev_b32_e32 v16, 10, v28
	v_lshl_add_u64 v[14:15], s[16:17], 0, v[24:25]
	v_add_co_u32_e32 v14, vcc, s11, v14
	s_nop 1
	v_addc_co_u32_e32 v15, vcc, 0, v15, vcc
	v_mfma_f32_32x32x16_bf16 a[96:111], v[30:33], v[0:3], a[96:111]
	v_or_b32_e32 v30, s14, v205
	v_lshl_add_u64 v[32:33], v[16:17], 2, v[26:27]
	v_lshlrev_b32_e32 v16, 10, v29
	v_mfma_f32_32x32x16_bf16 a[80:95], v[104:107], v[4:7], a[80:95]
	v_mfma_f32_32x32x16_bf16 a[64:79], v[104:107], v[0:3], a[64:79]
	v_lshl_add_u64 v[104:105], v[16:17], 2, v[26:27]
	v_lshlrev_b32_e32 v16, 10, v30
	v_lshl_add_u64 v[106:107], v[16:17], 2, v[26:27]
	v_mfma_f32_32x32x16_bf16 a[16:31], v[8:11], v[4:7], a[16:31]
	v_mfma_f32_32x32x16_bf16 a[0:15], v[8:11], v[0:3], a[0:15]
	v_mov_b32_e32 v140, v14
	v_mov_b32_e32 v141, v15
	v_mov_b32_e32 v142, v16
	v_mov_b32_e32 v143, v17
	v_mov_b32_e32 v144, v28
	v_mov_b32_e32 v145, v29
	v_mov_b32_e32 v146, v32
	v_mov_b32_e32 v147, v33
	v_mov_b32_e32 v148, v104
	v_mov_b32_e32 v149, v105
	v_mov_b32_e32 v150, v106
	v_mov_b32_e32 v151, v107
	v_mov_b32_e32 v152, v108
	v_mov_b32_e32 v153, v109
	v_mov_b32_e32 v154, v110
	v_mov_b32_e32 v155, v111
	global_load_dwordx4 v[250:253], v[140:141], off
	global_load_dwordx4 v[246:249], v[146:147], off
	global_load_dwordx4 v[242:245], v[148:149], off
	global_load_dwordx4 v[238:241], v[150:151], off
	global_load_dwordx4 v[234:237], v[12:13], off
	v_or_b32_e32 v140, s14, v206
	v_lshlrev_b32_e32 v142, 10, v140
	v_lshl_add_u64 v[140:141], v[142:143], 2, v[26:27]
	v_or_b32_e32 v142, s14, v207
	v_lshlrev_b32_e32 v142, 10, v142
	global_load_dwordx4 v[230:233], v[140:141], off
	v_or_b32_e32 v144, s14, v208
	v_or_b32_e32 v145, s14, v209
	v_lshl_add_u64 v[146:147], v[142:143], 2, v[26:27]
	v_lshlrev_b32_e32 v142, 10, v144
	v_lshl_add_u64 v[148:149], v[142:143], 2, v[26:27]
	v_lshlrev_b32_e32 v142, 10, v145
	v_lshl_add_u64 v[150:151], v[142:143], 2, v[26:27]
	global_load_dwordx4 v[226:229], v[146:147], off
	global_load_dwordx4 v[222:225], v[148:149], off
	global_load_dwordx4 v[218:221], v[150:151], off
	v_or_b32_e32 v140, s14, v210
	v_lshlrev_b32_e32 v142, 10, v140
	v_lshl_add_u64 v[140:141], v[142:143], 2, v[26:27]
	v_or_b32_e32 v142, s14, v35
	v_lshlrev_b32_e32 v142, 10, v142
	global_load_dwordx4 v[214:217], v[140:141], off
	v_or_b32_e32 v144, s14, v36
	v_or_b32_e32 v145, s14, v37
	v_lshl_add_u64 v[146:147], v[142:143], 2, v[26:27]
	v_lshlrev_b32_e32 v142, 10, v144
	v_lshl_add_u64 v[148:149], v[142:143], 2, v[26:27]
	v_lshlrev_b32_e32 v142, 10, v145
	v_lshl_add_u64 v[150:151], v[142:143], 2, v[26:27]
	global_load_dwordx4 v[200:203], v[146:147], off
	global_load_dwordx4 v[196:199], v[148:149], off
	global_load_dwordx4 v[192:195], v[150:151], off
	v_or_b32_e32 v140, s14, v38
	v_lshlrev_b32_e32 v142, 10, v140
	v_lshl_add_u64 v[140:141], v[142:143], 2, v[26:27]
	v_or_b32_e32 v142, s14, v39
	v_lshlrev_b32_e32 v142, 10, v142
	global_load_dwordx4 v[188:191], v[140:141], off
	v_or_b32_e32 v144, s14, v40
	v_or_b32_e32 v145, s14, v41
	v_lshl_add_u64 v[146:147], v[142:143], 2, v[26:27]
	v_lshlrev_b32_e32 v142, 10, v144
	v_lshl_add_u64 v[152:153], v[142:143], 2, v[26:27]
	v_lshlrev_b32_e32 v142, 10, v145
	v_lshl_add_u64 v[154:155], v[142:143], 2, v[26:27]
	global_load_dwordx4 v[184:187], v[146:147], off
	global_load_dwordx4 v[180:183], v[152:153], off
	global_load_dwordx4 v[176:179], v[154:155], off
	ds_write_b32 v58, a112
	ds_write_b32 v58, a113 offset:516
	ds_write_b32 v58, a114 offset:1032
	ds_write_b32 v58, a115 offset:1548
	ds_write_b32 v58, a116 offset:4128
	ds_write_b32 v58, a117 offset:4644
	ds_write_b32 v58, a118 offset:5160
	ds_write_b32 v58, a119 offset:5676
	ds_write_b32 v58, a120 offset:8256
	ds_write_b32 v58, a121 offset:8772
	ds_write_b32 v58, a122 offset:9288
	ds_write_b32 v58, a123 offset:9804
	ds_write_b32 v58, a124 offset:12384
	ds_write_b32 v58, a125 offset:12900
	ds_write_b32 v58, a126 offset:13416
	ds_write_b32 v58, a127 offset:13932
	ds_write_b32 v58, a96 offset:128
	ds_write_b32 v58, a97 offset:644
	ds_write_b32 v58, a98 offset:1160
	ds_write_b32 v58, a99 offset:1676
	ds_write_b32 v58, a100 offset:4256
	ds_write_b32 v58, a101 offset:4772
	ds_write_b32 v58, a102 offset:5288
	ds_write_b32 v58, a103 offset:5804
	ds_write_b32 v58, a104 offset:8384
	ds_write_b32 v58, a105 offset:8900
	ds_write_b32 v58, a106 offset:9416
	ds_write_b32 v58, a107 offset:9932
	ds_write_b32 v58, a108 offset:12512
	ds_write_b32 v58, a109 offset:13028
	ds_write_b32 v58, a110 offset:13544
	ds_write_b32 v58, a111 offset:14060
	ds_write_b32 v58, a80 offset:16512
	ds_write_b32 v58, a81 offset:17028
	ds_write_b32 v58, a82 offset:17544
	ds_write_b32 v58, a83 offset:18060
	ds_write_b32 v58, a84 offset:20640
	ds_write_b32 v58, a85 offset:21156
	ds_write_b32 v58, a86 offset:21672
	ds_write_b32 v58, a87 offset:22188
	ds_write_b32 v58, a88 offset:24768
	ds_write_b32 v58, a89 offset:25284
	ds_write_b32 v58, a90 offset:25800
	ds_write_b32 v58, a91 offset:26316
	ds_write_b32 v58, a92 offset:28896
	ds_write_b32 v58, a93 offset:29412
	ds_write_b32 v58, a94 offset:29928
	ds_write_b32 v58, a95 offset:30444
	ds_write_b32 v58, a64 offset:16640
	ds_write_b32 v58, a65 offset:17156
	ds_write_b32 v58, a66 offset:17672
	ds_write_b32 v58, a67 offset:18188
	ds_write_b32 v58, a68 offset:20768
	ds_write_b32 v58, a69 offset:21284
	ds_write_b32 v58, a70 offset:21800
	ds_write_b32 v58, a71 offset:22316
	ds_write_b32 v58, a72 offset:24896
	ds_write_b32 v58, a73 offset:25412
	ds_write_b32 v58, a74 offset:25928
	ds_write_b32 v58, a75 offset:26444
	ds_write_b32 v58, a76 offset:29024
	ds_write_b32 v58, a77 offset:29540
	ds_write_b32 v58, a78 offset:30056
	ds_write_b32 v58, a79 offset:30572
	ds_write_b32 v58, a48 offset:33024
	ds_write_b32 v58, a49 offset:33540
	ds_write_b32 v58, a50 offset:34056
	ds_write_b32 v58, a51 offset:34572
	ds_write_b32 v58, a52 offset:37152
	ds_write_b32 v58, a53 offset:37668
	ds_write_b32 v58, a54 offset:38184
	ds_write_b32 v58, a55 offset:38700
	ds_write_b32 v58, a56 offset:41280
	ds_write_b32 v58, a57 offset:41796
	ds_write_b32 v58, a58 offset:42312
	ds_write_b32 v58, a59 offset:42828
	ds_write_b32 v58, a60 offset:45408
	ds_write_b32 v58, a61 offset:45924
	ds_write_b32 v58, a62 offset:46440
	ds_write_b32 v58, a63 offset:46956
	ds_write_b32 v58, a32 offset:33152
	ds_write_b32 v58, a33 offset:33668
	ds_write_b32 v58, a34 offset:34184
	ds_write_b32 v58, a35 offset:34700
	ds_write_b32 v58, a36 offset:37280
	ds_write_b32 v58, a37 offset:37796
	ds_write_b32 v58, a38 offset:38312
	ds_write_b32 v58, a39 offset:38828
	ds_write_b32 v58, a40 offset:41408
	ds_write_b32 v58, a41 offset:41924
	ds_write_b32 v58, a42 offset:42440
	ds_write_b32 v58, a43 offset:42956
	ds_write_b32 v58, a44 offset:45536
	ds_write_b32 v58, a45 offset:46052
	ds_write_b32 v58, a46 offset:46568
	ds_write_b32 v58, a47 offset:47084
	ds_write_b32 v58, a16 offset:49536
	ds_write_b32 v58, a17 offset:50052
	ds_write_b32 v58, a18 offset:50568
	ds_write_b32 v58, a19 offset:51084
	ds_write_b32 v58, a20 offset:53664
	ds_write_b32 v58, a21 offset:54180
	ds_write_b32 v58, a22 offset:54696
	ds_write_b32 v58, a23 offset:55212
	ds_write_b32 v58, a24 offset:57792
	ds_write_b32 v58, a25 offset:58308
	ds_write_b32 v58, a26 offset:58824
	ds_write_b32 v58, a27 offset:59340
	ds_write_b32 v58, a28 offset:61920
	ds_write_b32 v58, a29 offset:62436
	ds_write_b32 v58, a30 offset:62952
	ds_write_b32 v58, a31 offset:63468
	ds_write_b32 v58, a0 offset:49664
	ds_write_b32 v58, a1 offset:50180
	ds_write_b32 v58, a2 offset:50696
	ds_write_b32 v58, a3 offset:51212
	ds_write_b32 v58, a4 offset:53792
	ds_write_b32 v58, a5 offset:54308
	ds_write_b32 v58, a6 offset:54824
	ds_write_b32 v58, a7 offset:55340
	ds_write_b32 v58, a8 offset:57920
	ds_write_b32 v58, a9 offset:58436
	ds_write_b32 v58, a10 offset:58952
	ds_write_b32 v58, a11 offset:59468
	ds_write_b32 v58, a12 offset:62048
	ds_write_b32 v58, a13 offset:62564
	ds_write_b32 v58, a14 offset:63080
	ds_write_b32 v58, a15 offset:63596
	s_waitcnt lgkmcnt(0)
	s_barrier
	s_waitcnt vmcnt(16)
	s_nop 1
	v_mov_b64_e32 v[0:1], v[250:251]
	v_mov_b64_e32 v[2:3], v[252:253]
	s_waitcnt vmcnt(15)
	s_nop 1
	v_mov_b64_e32 v[8:9], v[246:247]
	v_mov_b64_e32 v[10:11], v[248:249]
	s_waitcnt vmcnt(14)
	s_nop 1
	v_mov_b64_e32 v[28:29], v[242:243]
	v_mov_b64_e32 v[30:31], v[244:245]
	s_waitcnt vmcnt(13)
	s_nop 1
	v_mov_b64_e32 v[100:101], v[238:239]
	v_mov_b64_e32 v[102:103], v[240:241]
	s_waitcnt vmcnt(12)
	s_nop 1
	v_mov_b64_e32 v[4:5], v[234:235]
	v_mov_b64_e32 v[6:7], v[236:237]
	ds_read2_b32 v[108:109], v70 offset1:1
	ds_read2_b32 v[110:111], v71 offset1:1
	ds_read2_b32 v[112:113], v72 offset1:1
	ds_read2_b32 v[114:115], v73 offset1:1
	ds_read2_b32 v[116:117], v74 offset1:1
	ds_read2_b32 v[118:119], v75 offset1:1
	ds_read2_b32 v[120:121], v76 offset1:1
	ds_read2_b32 v[122:123], v77 offset1:1
	v_or_b32_e32 v14, s14, v206
	v_lshlrev_b32_e32 v16, 10, v14
	v_lshl_add_u64 v[14:15], v[16:17], 2, v[26:27]
	v_or_b32_e32 v16, s14, v207
	v_lshlrev_b32_e32 v16, 10, v16
	s_waitcnt lgkmcnt(6)
	v_pk_fma_f32 v[10:11], v[2:3], v[110:111], v[10:11]
	v_pk_fma_f32 v[8:9], v[0:1], v[108:109], v[8:9]
	s_waitcnt lgkmcnt(4)
	v_pk_fma_f32 v[30:31], v[2:3], v[114:115], v[30:31]
	v_pk_fma_f32 v[28:29], v[0:1], v[112:113], v[28:29]
	s_waitcnt lgkmcnt(2)
	v_pk_fma_f32 v[102:103], v[2:3], v[118:119], v[102:103]
	v_pk_fma_f32 v[100:101], v[0:1], v[116:117], v[100:101]
	global_store_dwordx4 v[32:33], v[8:11], off
	global_store_dwordx4 v[104:105], v[28:31], off
	global_store_dwordx4 v[106:107], v[100:103], off
	s_waitcnt vmcnt(14)
	s_nop 1
	v_mov_b64_e32 v[8:9], v[230:231]
	v_mov_b64_e32 v[10:11], v[232:233]
	v_or_b32_e32 v28, s14, v208
	v_or_b32_e32 v29, s14, v209
	v_lshl_add_u64 v[32:33], v[16:17], 2, v[26:27]
	v_lshlrev_b32_e32 v16, 10, v28
	v_lshl_add_u64 v[104:105], v[16:17], 2, v[26:27]
	v_lshlrev_b32_e32 v16, 10, v29
	v_lshl_add_u64 v[106:107], v[16:17], 2, v[26:27]
	s_waitcnt lgkmcnt(0)
	v_pk_fma_f32 v[10:11], v[2:3], v[122:123], v[10:11]
	v_pk_fma_f32 v[8:9], v[0:1], v[120:121], v[8:9]
	global_store_dwordx4 v[14:15], v[8:11], off
	s_waitcnt vmcnt(14)
	s_nop 1
	v_mov_b64_e32 v[8:9], v[226:227]
	v_mov_b64_e32 v[10:11], v[228:229]
	s_nop 0
	s_waitcnt vmcnt(13)
	s_nop 1
	v_mov_b64_e32 v[28:29], v[222:223]
	v_mov_b64_e32 v[30:31], v[224:225]
	s_waitcnt vmcnt(12)
	s_nop 1
	v_mov_b64_e32 v[100:101], v[218:219]
	v_mov_b64_e32 v[102:103], v[220:221]
	ds_read2_b32 v[108:109], v78 offset1:1
	ds_read2_b32 v[110:111], v79 offset1:1
	ds_read2_b32 v[112:113], v80 offset1:1
	ds_read2_b32 v[114:115], v81 offset1:1
	ds_read2_b32 v[116:117], v82 offset1:1
	ds_read2_b32 v[118:119], v83 offset1:1
	ds_read2_b32 v[120:121], v84 offset1:1
	ds_read2_b32 v[122:123], v85 offset1:1
	v_or_b32_e32 v14, s14, v210
	v_lshlrev_b32_e32 v16, 10, v14
	v_lshl_add_u64 v[14:15], v[16:17], 2, v[26:27]
	v_or_b32_e32 v16, s14, v35
	v_lshlrev_b32_e32 v16, 10, v16
	s_waitcnt lgkmcnt(6)
	v_pk_fma_f32 v[10:11], v[2:3], v[110:111], v[10:11]
	v_pk_fma_f32 v[8:9], v[0:1], v[108:109], v[8:9]
	s_waitcnt lgkmcnt(4)
	v_pk_fma_f32 v[30:31], v[2:3], v[114:115], v[30:31]
	v_pk_fma_f32 v[28:29], v[0:1], v[112:113], v[28:29]
	s_waitcnt lgkmcnt(2)
	v_pk_fma_f32 v[102:103], v[2:3], v[118:119], v[102:103]
	v_pk_fma_f32 v[100:101], v[0:1], v[116:117], v[100:101]
	global_store_dwordx4 v[32:33], v[8:11], off
	global_store_dwordx4 v[104:105], v[28:31], off
	global_store_dwordx4 v[106:107], v[100:103], off
	s_waitcnt vmcnt(14)
	s_nop 1
	v_mov_b64_e32 v[8:9], v[214:215]
	v_mov_b64_e32 v[10:11], v[216:217]
	v_or_b32_e32 v28, s14, v36
	v_or_b32_e32 v29, s14, v37
	v_lshl_add_u64 v[32:33], v[16:17], 2, v[26:27]
	v_lshlrev_b32_e32 v16, 10, v28
	v_lshl_add_u64 v[104:105], v[16:17], 2, v[26:27]
	v_lshlrev_b32_e32 v16, 10, v29
	v_lshl_add_u64 v[106:107], v[16:17], 2, v[26:27]
	s_waitcnt lgkmcnt(0)
	v_pk_fma_f32 v[10:11], v[2:3], v[122:123], v[10:11]
	v_pk_fma_f32 v[8:9], v[0:1], v[120:121], v[8:9]
	global_store_dwordx4 v[14:15], v[8:11], off
	s_waitcnt vmcnt(14)
	s_nop 1
	v_mov_b64_e32 v[8:9], v[200:201]
	v_mov_b64_e32 v[10:11], v[202:203]
	s_nop 0
	s_waitcnt vmcnt(13)
	s_nop 1
	v_mov_b64_e32 v[28:29], v[196:197]
	v_mov_b64_e32 v[30:31], v[198:199]
	s_waitcnt vmcnt(12)
	s_nop 1
	v_mov_b64_e32 v[100:101], v[192:193]
	v_mov_b64_e32 v[102:103], v[194:195]
	ds_read2_b32 v[108:109], v86 offset1:1
	ds_read2_b32 v[110:111], v87 offset1:1
	ds_read2_b32 v[112:113], v88 offset1:1
	ds_read2_b32 v[114:115], v89 offset1:1
	ds_read2_b32 v[116:117], v90 offset1:1
	ds_read2_b32 v[118:119], v91 offset1:1
	ds_read2_b32 v[120:121], v92 offset1:1
	ds_read2_b32 v[122:123], v93 offset1:1
	v_or_b32_e32 v14, s14, v38
	v_lshlrev_b32_e32 v16, 10, v14
	v_lshl_add_u64 v[14:15], v[16:17], 2, v[26:27]
	v_or_b32_e32 v16, s14, v39
	v_lshlrev_b32_e32 v16, 10, v16
	s_waitcnt lgkmcnt(6)
	v_pk_fma_f32 v[10:11], v[2:3], v[110:111], v[10:11]
	v_pk_fma_f32 v[8:9], v[0:1], v[108:109], v[8:9]
	s_waitcnt lgkmcnt(4)
	v_pk_fma_f32 v[30:31], v[2:3], v[114:115], v[30:31]
	v_pk_fma_f32 v[28:29], v[0:1], v[112:113], v[28:29]
	s_waitcnt lgkmcnt(2)
	v_pk_fma_f32 v[102:103], v[2:3], v[118:119], v[102:103]
	v_pk_fma_f32 v[100:101], v[0:1], v[116:117], v[100:101]
	global_store_dwordx4 v[32:33], v[8:11], off
	global_store_dwordx4 v[104:105], v[28:31], off
	global_store_dwordx4 v[106:107], v[100:103], off
	s_waitcnt vmcnt(14)
	s_nop 1
	v_mov_b64_e32 v[8:9], v[188:189]
	v_mov_b64_e32 v[10:11], v[190:191]
	v_or_b32_e32 v28, s14, v40
	v_or_b32_e32 v29, s14, v41
	v_lshl_add_u64 v[32:33], v[16:17], 2, v[26:27]
	v_lshlrev_b32_e32 v16, 10, v28
	v_lshl_add_u64 v[108:109], v[16:17], 2, v[26:27]
	v_lshlrev_b32_e32 v16, 10, v29
	v_lshl_add_u64 v[110:111], v[16:17], 2, v[26:27]
	s_bitset1_b32 s14, 7
	s_add_u32 s13, s2, s13
	s_addc_u32 s15, s3, s12
	s_add_u32 s12, s13, s4
	s_addc_u32 s13, s15, 0
	s_add_i32 s6, s6, s76
	s_cmpk_lt_u32 s6, 0x60
	s_waitcnt lgkmcnt(0)
	v_pk_fma_f32 v[10:11], v[2:3], v[122:123], v[10:11]
	v_pk_fma_f32 v[8:9], v[0:1], v[120:121], v[8:9]
	global_store_dwordx4 v[14:15], v[8:11], off
	s_waitcnt vmcnt(14)
	s_nop 1
	v_mov_b64_e32 v[28:29], v[184:185]
	v_mov_b64_e32 v[30:31], v[186:187]
	s_waitcnt vmcnt(13)
	s_nop 1
	v_mov_b64_e32 v[100:101], v[180:181]
	v_mov_b64_e32 v[102:103], v[182:183]
	s_waitcnt vmcnt(12)
	s_nop 1
	v_mov_b64_e32 v[104:105], v[176:177]
	v_mov_b64_e32 v[106:107], v[178:179]
	v_or_b32_e32 v10, s14, v135
	v_lshl_add_u64 v[8:9], s[12:13], 0, v[24:25]
	v_or_b32_e32 v11, s14, v139
	v_add_co_u32_e32 v112, vcc, s11, v8
	v_lshlrev_b32_e32 v16, 10, v10
	v_or_b32_e32 v14, s14, v204
	v_addc_co_u32_e32 v113, vcc, 0, v9, vcc
	v_lshl_add_u64 v[8:9], v[16:17], 2, v[26:27]
	v_lshlrev_b32_e32 v16, 10, v11
	v_or_b32_e32 v15, s14, v205
	v_lshl_add_u64 v[114:115], v[16:17], 2, v[26:27]
	v_lshlrev_b32_e32 v16, 10, v14
	v_lshl_add_u64 v[116:117], v[16:17], 2, v[26:27]
	v_lshlrev_b32_e32 v16, 10, v15
	ds_read2_b32 v[120:121], v34 offset1:1
	ds_read2_b32 v[122:123], v34 offset0:2 offset1:3
	ds_read2_b32 v[124:125], v94 offset1:1
	ds_read2_b32 v[126:127], v95 offset1:1
	ds_read2_b32 v[128:129], v96 offset1:1
	ds_read2_b32 v[130:131], v97 offset1:1
	ds_read2_b32 v[132:133], v98 offset1:1
	ds_read2_b32 v[136:137], v99 offset1:1
	ds_read2_b32 v[10:11], v42 offset1:1
	ds_read2_b32 v[14:15], v42 offset0:2 offset1:3
	s_waitcnt lgkmcnt(8)
	v_pk_fma_f32 v[6:7], v[2:3], v[122:123], v[6:7]
	v_pk_fma_f32 v[4:5], v[0:1], v[120:121], v[4:5]
	global_store_dwordx4 v[12:13], v[4:7], off
	v_lshl_add_u64 v[118:119], v[16:17], 2, v[26:27]
	v_or_b32_e32 v12, s14, v206
	v_lshlrev_b32_e32 v16, 10, v12
	v_lshl_add_u64 v[12:13], v[16:17], 2, v[26:27]
	v_or_b32_e32 v16, s14, v207
	v_lshlrev_b32_e32 v16, 10, v16
	s_waitcnt lgkmcnt(6)
	v_pk_fma_f32 v[6:7], v[2:3], v[126:127], v[30:31]
	v_pk_fma_f32 v[4:5], v[0:1], v[124:125], v[28:29]
	s_waitcnt lgkmcnt(4)
	v_pk_fma_f32 v[30:31], v[2:3], v[130:131], v[102:103]
	v_pk_fma_f32 v[28:29], v[0:1], v[128:129], v[100:101]
	s_waitcnt lgkmcnt(2)
	v_pk_fma_f32 v[2:3], v[2:3], v[136:137], v[106:107]
	v_pk_fma_f32 v[0:1], v[0:1], v[132:133], v[104:105]
	global_store_dwordx4 v[32:33], v[4:7], off
	global_store_dwordx4 v[108:109], v[28:31], off
	global_store_dwordx4 v[110:111], v[0:3], off
	v_mov_b32_e32 v128, v12
	v_mov_b32_e32 v129, v13
	v_mov_b32_e32 v130, v16
	v_mov_b32_e32 v131, v17
	v_mov_b32_e32 v132, v26
	v_mov_b32_e32 v133, v27
	v_mov_b32_e32 v136, v32
	v_mov_b32_e32 v137, v33
	v_mov_b32_e32 v140, v100
	v_mov_b32_e32 v141, v101
	v_mov_b32_e32 v142, v108
	v_mov_b32_e32 v143, v109
	v_mov_b32_e32 v144, v110
	v_mov_b32_e32 v145, v111
	global_load_dwordx4 v[250:253], v[112:113], off
	global_load_dwordx4 v[246:249], v[114:115], off
	global_load_dwordx4 v[242:245], v[116:117], off
	global_load_dwordx4 v[238:241], v[118:119], off
	global_load_dwordx4 v[234:237], v[8:9], off
	global_load_dwordx4 v[230:233], v[128:129], off
	v_or_b32_e32 v140, s14, v208
	v_or_b32_e32 v141, s14, v209
	v_lshl_add_u64 v[136:137], v[130:131], 2, v[132:133]
	v_lshlrev_b32_e32 v130, 10, v140
	v_lshl_add_u64 v[142:143], v[130:131], 2, v[132:133]
	v_lshlrev_b32_e32 v130, 10, v141
	v_lshl_add_u64 v[144:145], v[130:131], 2, v[132:133]
	global_load_dwordx4 v[226:229], v[136:137], off
	global_load_dwordx4 v[222:225], v[142:143], off
	global_load_dwordx4 v[218:221], v[144:145], off
	v_or_b32_e32 v128, s14, v210
	v_lshlrev_b32_e32 v130, 10, v128
	v_lshl_add_u64 v[128:129], v[130:131], 2, v[132:133]
	v_or_b32_e32 v130, s14, v35
	v_lshlrev_b32_e32 v130, 10, v130
	global_load_dwordx4 v[214:217], v[128:129], off
	v_or_b32_e32 v140, s14, v36
	v_or_b32_e32 v141, s14, v37
	v_lshl_add_u64 v[136:137], v[130:131], 2, v[132:133]
	v_lshlrev_b32_e32 v130, 10, v140
	v_lshl_add_u64 v[142:143], v[130:131], 2, v[132:133]
	v_lshlrev_b32_e32 v130, 10, v141
	v_lshl_add_u64 v[144:145], v[130:131], 2, v[132:133]
	global_load_dwordx4 v[200:203], v[136:137], off
	global_load_dwordx4 v[196:199], v[142:143], off
	global_load_dwordx4 v[192:195], v[144:145], off
	v_or_b32_e32 v128, s14, v38
	v_lshlrev_b32_e32 v130, 10, v128
	v_lshl_add_u64 v[128:129], v[130:131], 2, v[132:133]
	v_add_lshl_u32 v130, s14, v39, 10
	global_load_dwordx4 v[188:191], v[128:129], off
	v_lshl_add_u64 v[136:137], v[130:131], 2, v[132:133]
	v_add_lshl_u32 v130, s14, v40, 10
	v_lshl_add_u64 v[140:141], v[130:131], 2, v[132:133]
	v_add_lshl_u32 v130, s14, v41, 10
	v_lshl_add_u64 v[132:133], v[130:131], 2, v[132:133]
	global_load_dwordx4 v[184:187], v[136:137], off
	global_load_dwordx4 v[180:183], v[140:141], off
	global_load_dwordx4 v[176:179], v[132:133], off
	s_waitcnt vmcnt(16)
	s_nop 1
	v_mov_b64_e32 v[0:1], v[250:251]
	v_mov_b64_e32 v[2:3], v[252:253]
	s_nop 0
	s_waitcnt vmcnt(15)
	s_nop 1
	v_mov_b64_e32 v[28:29], v[246:247]
	v_mov_b64_e32 v[30:31], v[248:249]
	s_waitcnt vmcnt(14)
	s_nop 1
	v_mov_b64_e32 v[100:101], v[242:243]
	v_mov_b64_e32 v[102:103], v[244:245]
	s_waitcnt vmcnt(13)
	s_nop 1
	v_mov_b64_e32 v[104:105], v[238:239]
	v_mov_b64_e32 v[106:107], v[240:241]
	s_waitcnt vmcnt(12)
	s_nop 1
	v_mov_b64_e32 v[4:5], v[234:235]
	v_mov_b64_e32 v[6:7], v[236:237]
	ds_read2_b32 v[32:33], v43 offset1:1
	ds_read2_b32 v[108:109], v43 offset0:2 offset1:3
	ds_read2_b32 v[110:111], v44 offset1:1
	ds_read2_b32 v[112:113], v44 offset0:2 offset1:3
	ds_read2_b32 v[120:121], v45 offset1:1
	ds_read2_b32 v[122:123], v45 offset0:2 offset1:3
	ds_read2_b32 v[124:125], v46 offset1:1
	ds_read2_b32 v[126:127], v46 offset0:2 offset1:3
	s_waitcnt lgkmcnt(6)
	v_pk_fma_f32 v[30:31], v[2:3], v[108:109], v[30:31]
	v_pk_fma_f32 v[28:29], v[0:1], v[32:33], v[28:29]
	s_waitcnt lgkmcnt(4)
	v_pk_fma_f32 v[102:103], v[2:3], v[112:113], v[102:103]
	v_pk_fma_f32 v[100:101], v[0:1], v[110:111], v[100:101]
	s_waitcnt lgkmcnt(2)
	v_pk_fma_f32 v[106:107], v[2:3], v[122:123], v[106:107]
	v_pk_fma_f32 v[104:105], v[0:1], v[120:121], v[104:105]
	global_store_dwordx4 v[114:115], v[28:31], off
	global_store_dwordx4 v[116:117], v[100:103], off
	global_store_dwordx4 v[118:119], v[104:107], off
	s_waitcnt vmcnt(14)
	s_nop 1
	v_mov_b64_e32 v[28:29], v[230:231]
	v_mov_b64_e32 v[30:31], v[232:233]
	v_or_b32_e32 v100, s14, v208
	v_or_b32_e32 v101, s14, v209
	v_lshl_add_u64 v[32:33], v[16:17], 2, v[26:27]
	v_lshlrev_b32_e32 v16, 10, v100
	v_lshl_add_u64 v[108:109], v[16:17], 2, v[26:27]
	v_lshlrev_b32_e32 v16, 10, v101
	v_lshl_add_u64 v[110:111], v[16:17], 2, v[26:27]
	v_pk_fma_f32 v[6:7], v[2:3], v[14:15], v[6:7]
	v_pk_fma_f32 v[4:5], v[0:1], v[10:11], v[4:5]
	s_waitcnt lgkmcnt(0)
	v_pk_fma_f32 v[30:31], v[2:3], v[126:127], v[30:31]
	v_pk_fma_f32 v[28:29], v[0:1], v[124:125], v[28:29]
	global_store_dwordx4 v[12:13], v[28:31], off
	s_waitcnt vmcnt(14)
	s_nop 1
	v_mov_b64_e32 v[28:29], v[226:227]
	v_mov_b64_e32 v[30:31], v[228:229]
	s_nop 0
	s_waitcnt vmcnt(13)
	s_nop 1
	v_mov_b64_e32 v[100:101], v[222:223]
	v_mov_b64_e32 v[102:103], v[224:225]
	s_waitcnt vmcnt(12)
	s_nop 1
	v_mov_b64_e32 v[104:105], v[218:219]
	v_mov_b64_e32 v[106:107], v[220:221]
	ds_read2_b32 v[112:113], v47 offset1:1
	ds_read2_b32 v[114:115], v47 offset0:2 offset1:3
	ds_read2_b32 v[116:117], v48 offset1:1
	ds_read2_b32 v[118:119], v48 offset0:2 offset1:3
	ds_read2_b32 v[120:121], v49 offset1:1
	ds_read2_b32 v[122:123], v49 offset0:2 offset1:3
	ds_read2_b32 v[124:125], v50 offset1:1
	ds_read2_b32 v[126:127], v50 offset0:2 offset1:3
	v_or_b32_e32 v12, s14, v210
	v_lshlrev_b32_e32 v16, 10, v12
	v_lshl_add_u64 v[12:13], v[16:17], 2, v[26:27]
	v_or_b32_e32 v16, s14, v35
	v_lshlrev_b32_e32 v16, 10, v16
	s_waitcnt lgkmcnt(6)
	v_pk_fma_f32 v[30:31], v[2:3], v[114:115], v[30:31]
	v_pk_fma_f32 v[28:29], v[0:1], v[112:113], v[28:29]
	s_waitcnt lgkmcnt(4)
	v_pk_fma_f32 v[102:103], v[2:3], v[118:119], v[102:103]
	v_pk_fma_f32 v[100:101], v[0:1], v[116:117], v[100:101]
	s_waitcnt lgkmcnt(2)
	v_pk_fma_f32 v[106:107], v[2:3], v[122:123], v[106:107]
	v_pk_fma_f32 v[104:105], v[0:1], v[120:121], v[104:105]
	global_store_dwordx4 v[32:33], v[28:31], off
	global_store_dwordx4 v[108:109], v[100:103], off
	global_store_dwordx4 v[110:111], v[104:107], off
	s_waitcnt vmcnt(14)
	s_nop 1
	v_mov_b64_e32 v[28:29], v[214:215]
	v_mov_b64_e32 v[30:31], v[216:217]
	v_or_b32_e32 v100, s14, v36
	v_or_b32_e32 v101, s14, v37
	v_lshl_add_u64 v[32:33], v[16:17], 2, v[26:27]
	v_lshlrev_b32_e32 v16, 10, v100
	v_lshl_add_u64 v[108:109], v[16:17], 2, v[26:27]
	v_lshlrev_b32_e32 v16, 10, v101
	v_lshl_add_u64 v[110:111], v[16:17], 2, v[26:27]
	s_waitcnt lgkmcnt(0)
	v_pk_fma_f32 v[30:31], v[2:3], v[126:127], v[30:31]
	v_pk_fma_f32 v[28:29], v[0:1], v[124:125], v[28:29]
	global_store_dwordx4 v[12:13], v[28:31], off
	s_waitcnt vmcnt(14)
	s_nop 1
	v_mov_b64_e32 v[28:29], v[200:201]
	v_mov_b64_e32 v[30:31], v[202:203]
	s_nop 0
	s_waitcnt vmcnt(13)
	s_nop 1
	v_mov_b64_e32 v[100:101], v[196:197]
	v_mov_b64_e32 v[102:103], v[198:199]
	s_waitcnt vmcnt(12)
	s_nop 1
	v_mov_b64_e32 v[104:105], v[192:193]
	v_mov_b64_e32 v[106:107], v[194:195]
	ds_read2_b32 v[112:113], v51 offset1:1
	ds_read2_b32 v[114:115], v51 offset0:2 offset1:3
	ds_read2_b32 v[116:117], v52 offset1:1
	ds_read2_b32 v[118:119], v52 offset0:2 offset1:3
	ds_read2_b32 v[120:121], v53 offset1:1
	ds_read2_b32 v[122:123], v53 offset0:2 offset1:3
	ds_read2_b32 v[124:125], v54 offset1:1
	ds_read2_b32 v[126:127], v54 offset0:2 offset1:3
	v_or_b32_e32 v12, s14, v38
	v_lshlrev_b32_e32 v16, 10, v12
	v_lshl_add_u64 v[12:13], v[16:17], 2, v[26:27]
	v_add_lshl_u32 v16, s14, v39, 10
	s_waitcnt lgkmcnt(6)
	v_pk_fma_f32 v[30:31], v[2:3], v[114:115], v[30:31]
	v_pk_fma_f32 v[28:29], v[0:1], v[112:113], v[28:29]
	s_waitcnt lgkmcnt(4)
	v_pk_fma_f32 v[102:103], v[2:3], v[118:119], v[102:103]
	v_pk_fma_f32 v[100:101], v[0:1], v[116:117], v[100:101]
	s_waitcnt lgkmcnt(2)
	v_pk_fma_f32 v[106:107], v[2:3], v[122:123], v[106:107]
	v_pk_fma_f32 v[104:105], v[0:1], v[120:121], v[104:105]
	global_store_dwordx4 v[32:33], v[28:31], off
	global_store_dwordx4 v[108:109], v[100:103], off
	global_store_dwordx4 v[110:111], v[104:107], off
	s_waitcnt vmcnt(14)
	s_nop 1
	v_mov_b64_e32 v[28:29], v[188:189]
	v_mov_b64_e32 v[30:31], v[190:191]
	v_lshl_add_u64 v[32:33], v[16:17], 2, v[26:27]
	v_add_lshl_u32 v16, s14, v40, 10
	global_store_dwordx4 v[8:9], v[4:7], off
	v_lshl_add_u64 v[100:101], v[16:17], 2, v[26:27]
	v_add_lshl_u32 v16, s14, v41, 10
	v_lshl_add_u64 v[26:27], v[16:17], 2, v[26:27]
	s_waitcnt lgkmcnt(0)
	v_pk_fma_f32 v[6:7], v[2:3], v[126:127], v[30:31]
	v_pk_fma_f32 v[4:5], v[0:1], v[124:125], v[28:29]
	global_store_dwordx4 v[12:13], v[4:7], off
	s_waitcnt vmcnt(15)
	s_nop 1
	v_mov_b64_e32 v[4:5], v[184:185]
	v_mov_b64_e32 v[6:7], v[186:187]
	s_nop 0
	s_waitcnt vmcnt(14)
	s_nop 1
	v_mov_b64_e32 v[8:9], v[180:181]
	v_mov_b64_e32 v[10:11], v[182:183]
	s_waitcnt vmcnt(13)
	s_nop 1
	v_mov_b64_e32 v[12:13], v[176:177]
	v_mov_b64_e32 v[14:15], v[178:179]
	ds_read2_b32 v[28:29], v55 offset1:1
	ds_read2_b32 v[30:31], v55 offset0:2 offset1:3
	ds_read2_b32 v[102:103], v56 offset1:1
	ds_read2_b32 v[104:105], v56 offset0:2 offset1:3
	ds_read2_b32 v[106:107], v57 offset1:1
	ds_read2_b32 v[108:109], v57 offset0:2 offset1:3
	s_waitcnt lgkmcnt(4)
	v_pk_fma_f32 v[6:7], v[2:3], v[30:31], v[6:7]
	v_pk_fma_f32 v[4:5], v[0:1], v[28:29], v[4:5]
	s_waitcnt lgkmcnt(2)
	v_pk_fma_f32 v[10:11], v[2:3], v[104:105], v[10:11]
	v_pk_fma_f32 v[8:9], v[0:1], v[102:103], v[8:9]
	s_waitcnt lgkmcnt(0)
	v_pk_fma_f32 v[2:3], v[2:3], v[108:109], v[14:15]
	v_pk_fma_f32 v[0:1], v[0:1], v[106:107], v[12:13]
	global_store_dwordx4 v[32:33], v[4:7], off
	global_store_dwordx4 v[100:101], v[8:11], off
	global_store_dwordx4 v[26:27], v[0:3], off
	s_barrier
	s_cbranch_scc1 .LBB0_2329
	s_load_dwordx2 s[2:3], s[0:1], 0x130
